# mixer work queue order: long items first (dense, NA, context attention), short retention-output items last
# baseline (speedup 1.0000x reference)
; DI void phase_mixers(const Params& p, int l, LAS unsigned char* lds) {
;     ...
;     const int nc = (l == 0) ? 18 : 16, n_ro = 20 * nc, n_na = 384, n_ctx = (l == 0) ? 44 : 0;
;     const int e0 = 160, e1 = e0 + n_ro, e2 = e1 + n_na, e3 = e2 + n_ctx;
;     int it = next_item(ctr, slot);
;     while (it < e0) { dense192_item(ws, lds, it / 40, (it >> 3) % 5, CL + (it & 7) * 256, RB); it = next_item(ctr, slot); }
;     while (it < e1) { const int i2 = it - e0, c = (i2 % nc) + (18 - nc), bh = i2 / nc; ret_out_item(p, l, bh / 5, bh % 5, c, lds); it = next_item(ctr, slot); }
.LBB0_1176:
	s_cmpk_gt_u32 s28, 0x3b3
	s_movk_i32 s2, 0x3b3
	s_cbranch_scc1 .LBB0_1277
	s_add_u32 s6, s50, 0x113a0000
	v_mbcnt_hi_u32_b32 v87, -1, v203
	s_addc_u32 s7, s51, 0
	v_and_b32_e32 v0, 64, v87
	v_mov_b32_e32 v69, 0
	s_mov_b32 s3, 0xc2fc0000
	v_mov_b32_e32 v82, 0x42800000
	s_mov_b32 s4, 0x3f2aaaab
	v_mov_b32_e32 v83, 0x3ecc95a3
	s_mov_b32 s5, 0x3f317218
	v_mov_b32_e32 v84, 0x7fc00000
	v_mov_b32_e32 v85, 0xff800000
	s_mov_b32 s20, 0x33800000
	s_movk_i32 s21, 0x3000
	s_movk_i32 s22, 0x1200
	s_mov_b64 s[8:9], 0x1f80
	s_add_i32 s23, 0, 0x11000
	s_add_i32 s27, 0, 0x19800
	s_movk_i32 s30, 0x110
	v_not_b32_e32 v86, 63
	v_mov_b64_e32 v[70:71], s[6:7]
	s_mov_b64 s[10:11], 0x1a80
	s_movk_i32 s31, 0x1000
	v_xor_b32_e32 v88, 16, v87
	v_add_u32_e32 v89, 64, v0
	v_xor_b32_e32 v90, 32, v87
	v_mov_b32_e32 v91, 0x3727c5ac
	s_mov_b32 s34, 0x800000
	s_mov_b64 s[12:13], 0x2980
	s_mov_b64 s[14:15], 0x1d9a0b00
	s_movk_i32 s35, 0x2000
	s_mov_b32 s36, 0x1d9a0000
	s_add_i32 s37, 0, 0x22040
	v_mov_b32_e32 v72, 0x3f317218
	s_branch .LBB0_1180

; DI float ret_lg2(const Params& p, int l, int dir, int h) { return log1pf(-exp2f(p.in[12][(l * 2 + dir) * 5 + h])) * 1.4426950408889634f; }
; DI void phase_mixers(const Params& p, int l, LAS unsigned char* lds) {
;     ...
;     const int nc = (l == 0) ? 18 : 16, n_ro = 20 * nc, n_na = 384, n_ctx = (l == 0) ? 44 : 0;
;     const int e0 = 160, e1 = e0 + n_ro, e2 = e1 + n_na, e3 = e2 + n_ctx;
;     int it = next_item(ctr, slot);
;     while (it < e0) { dense192_item(ws, lds, it / 40, (it >> 3) % 5, CL + (it & 7) * 256, RB); it = next_item(ctr, slot); }
;     while (it < e1) { const int i2 = it - e0, c = (i2 % nc) + (18 - nc), bh = i2 / nc; ret_out_item(p, l, bh / 5, bh % 5, c, lds); it = next_item(ctr, slot); }
.LBB0_1180:
	s_add_i32 s0, s28, 0xfffffdb4
	s_mul_hi_i32 s1, s0, 0x38e38e39
	s_lshr_b32 s16, s1, 31
	s_ashr_i32 s1, s1, 2
	s_add_i32 s1, s1, s16
	s_mul_i32 s16, s1, 18
	s_sub_i32 s19, s0, s16
	s_mul_hi_i32 s16, s0, 0xb60b60b7
	s_add_i32 s16, s16, s0
	s_lshr_b32 s0, s16, 31
	s_ashr_i32 s18, s16, 6
	s_add_i32 s18, s18, s0
	s_mul_hi_i32 s0, s1, 0x66666667
	s_lshr_b32 s16, s0, 31
	s_ashr_i32 s0, s0, 1
	s_add_i32 s0, s0, s16
	s_mul_i32 s0, s0, 5
	s_sub_i32 s16, s1, s0
	s_ashr_i32 s17, s16, 31
	s_lshl_b64 s[0:1], s[16:17], 2
	s_add_u32 s0, s60, s0
	v_mov_b32_e32 v16, v202
	s_addc_u32 s1, s61, s1
	global_load_dword v0, v69, s[0:1]
	global_load_dword v1, v69, s[0:1] offset:20
	v_bfe_u32 v92, v16, 4, 2
	s_waitcnt vmcnt(1)
	v_cmp_gt_f32_e32 vcc, s3, v0
	s_nop 1
	v_cndmask_b32_e32 v2, 0, v82, vcc
	s_waitcnt vmcnt(0)
	v_cmp_gt_f32_e64 s[0:1], s3, v1
	v_add_f32_e32 v0, v0, v2
	v_exp_f32_e32 v0, v0
	v_cndmask_b32_e64 v3, 0, v82, s[0:1]
	v_add_f32_e32 v1, v1, v3
	s_and_b64 s[28:29], vcc, exec
	v_exp_f32_e32 v1, v1
	s_cselect_b32 s17, 0xffffffc0, 0
	s_and_b64 s[0:1], s[0:1], exec
	v_ldexp_f32 v15, v0, s17
	s_cselect_b32 s0, 0xffffffc0, 0
	v_sub_f32_e32 v4, 1.0, v15
	v_ldexp_f32 v14, v1, s0
	v_frexp_mant_f32_e32 v7, v4
	v_cvt_f64_f32_e32 v[0:1], v4
	v_sub_f32_e32 v5, 1.0, v14
	v_add_f32_e32 v6, -1.0, v4
	v_frexp_exp_i32_f64_e32 v0, v[0:1]
	v_cmp_gt_f32_e32 vcc, s4, v7
	v_add_f32_e32 v8, -1.0, v5
	v_frexp_mant_f32_e32 v9, v5
	v_cvt_f64_f32_e32 v[2:3], v5
	v_sub_f32_e32 v10, v6, v4
	v_subbrev_co_u32_e32 v0, vcc, 0, v0, vcc
	v_sub_f32_e64 v6, -v15, v6
	v_sub_f32_e32 v1, v8, v5
	v_frexp_exp_i32_f64_e32 v2, v[2:3]
	v_add_f32_e32 v3, 1.0, v10
	v_cmp_gt_f32_e32 vcc, s4, v9
	v_sub_f32_e64 v8, -v14, v8
	v_add_f32_e32 v1, 1.0, v1
	v_subbrev_co_u32_e32 v17, vcc, 0, v2, vcc
	v_add_f32_e32 v2, v6, v3
	v_sub_u32_e32 v3, 0, v0
	v_add_f32_e32 v1, v8, v1
	v_sub_u32_e32 v6, 0, v17
	v_ldexp_f32 v4, v4, v3
	v_ldexp_f32 v20, v5, v6
	v_ldexp_f32 v21, v1, v6
	v_add_f32_e32 v1, -1.0, v4
	v_add_f32_e32 v5, 1.0, v4
	v_ldexp_f32 v2, v2, v3
	v_add_f32_e32 v3, 1.0, v1
	v_add_f32_e32 v6, -1.0, v5
	v_sub_f32_e32 v3, v4, v3
	v_sub_f32_e32 v4, v4, v6
	v_add_f32_e32 v6, v2, v3
	v_add_f32_e32 v2, v2, v4
	v_add_f32_e32 v8, v5, v2
	v_rcp_f32_e32 v9, v8
	v_add_f32_e32 v3, v1, v6
	v_sub_f32_e32 v4, v8, v5
	v_sub_f32_e32 v1, v3, v1
	v_mul_f32_e32 v11, v3, v9
	v_sub_f32_e32 v10, v2, v4
	v_mul_f32_e32 v4, v8, v11
	v_sub_f32_e32 v1, v6, v1
	v_fma_f32 v6, v11, v8, -v4
	v_fmac_f32_e32 v6, v11, v10
	v_add_f32_e32 v2, v4, v6
	v_sub_f32_e32 v5, v3, v2
	v_mov_b32_e32 v7, v2
	v_pk_add_f32 v[2:3], v[2:3], v[4:5] neg_lo:[0,1] neg_hi:[0,1]
	v_cvt_f32_i32_e32 v0, v0
	v_pk_add_f32 v[2:3], v[2:3], v[6:7] neg_lo:[0,1] neg_hi:[0,1]
	v_cmp_nlt_f32_e32 vcc, 1.0, v15
	v_add_f32_e32 v1, v1, v3
	v_add_f32_e32 v1, v2, v1
	v_add_f32_e32 v3, v5, v1
	v_mul_f32_e32 v2, v9, v3
	v_mul_f32_e32 v4, v8, v2
	v_sub_f32_e32 v5, v5, v3
	v_add_f32_e32 v12, v11, v2
	v_fma_f32 v6, v2, v8, -v4
	v_add_f32_e32 v1, v1, v5
	v_sub_f32_e32 v5, v12, v11
	v_fmac_f32_e32 v6, v2, v10
	v_sub_f32_e32 v8, v2, v5
	v_add_f32_e32 v2, v4, v6
	v_sub_f32_e32 v5, v3, v2
	v_mov_b32_e32 v7, v2
	v_pk_add_f32 v[2:3], v[2:3], v[4:5] neg_lo:[0,1] neg_hi:[0,1]
	v_cmp_lt_f32_e64 s[0:1], |v15|, s20
	v_pk_add_f32 v[2:3], v[2:3], v[6:7] neg_lo:[0,1] neg_hi:[0,1]
	s_lshl_b32 s28, s19, 7
	v_add_f32_e32 v1, v1, v3
	v_add_f32_e32 v1, v2, v1
	v_add_f32_e32 v1, v5, v1
	v_mul_f32_e32 v1, v9, v1
	v_add_f32_e32 v1, v8, v1
	v_add_f32_e32 v2, v12, v1
	v_mul_f32_e32 v4, v2, v2
	v_sub_f32_e32 v5, v2, v12
	v_fmamk_f32 v6, v4, 0x3e9b6dac, v83
	v_sub_f32_e32 v5, v1, v5
	v_mul_f32_e32 v1, v2, v4
	v_fmaak_f32 v73, v4, v6, 0x3f2aaada
	v_ldexp_f32 v7, v5, 1
	v_pk_mul_f32 v[4:5], v[0:1], v[72:73]
	v_ldexp_f32 v3, v2, 1
	v_fma_f32 v2, v0, s5, -v4
	v_fmac_f32_e32 v2, 0xb102e308, v0
	v_pk_add_f32 v[0:1], v[4:5], v[2:3]
	v_mov_b32_e32 v6, v4
	v_sub_f32_e32 v10, v1, v3
	v_pk_add_f32 v[8:9], v[0:1], v[4:5] neg_lo:[0,1] neg_hi:[0,1]
	v_sub_f32_e32 v5, v5, v10
	v_add_f32_e32 v7, v7, v5
	v_pk_add_f32 v[12:13], v[0:1], v[6:7]
	v_mov_b32_e32 v3, v0
	v_mov_b32_e32 v9, v13
	v_pk_add_f32 v[18:19], v[2:3], v[8:9] neg_lo:[0,1] neg_hi:[0,1]
	v_pk_add_f32 v[2:3], v[2:3], v[8:9]
	v_mov_b32_e32 v4, v1
	v_mov_b32_e32 v11, v0
	v_pk_add_f32 v[0:1], v[2:3], v[0:1] op_sel:[1,0] op_sel_hi:[0,1] neg_lo:[0,1] neg_hi:[0,1]
	v_mov_b32_e32 v10, v7
	v_mov_b32_e32 v6, v13
	v_mov_b32_e32 v7, v3
	v_mov_b32_e32 v5, v0
	v_pk_add_f32 v[8:9], v[12:13], v[0:1] op_sel_hi:[1,0] neg_lo:[0,1] neg_hi:[0,1]
	v_pk_add_f32 v[0:1], v[6:7], v[4:5] neg_lo:[0,1] neg_hi:[0,1]
	v_mov_b32_e32 v8, v18
	v_pk_add_f32 v[0:1], v[10:11], v[0:1] neg_lo:[0,1] neg_hi:[0,1]
	v_mov_b32_e32 v19, v3
	v_pk_add_f32 v[4:5], v[8:9], v[0:1]
	s_ashr_i32 s29, s28, 31
	v_pk_add_f32 v[6:7], v[4:5], v[4:5] op_sel:[0,1] op_sel_hi:[1,0]
	s_mul_i32 s17, s18, 5
	v_pk_add_f32 v[2:3], v[2:3], v[6:7] op_sel:[1,0] op_sel_hi:[0,1]
	v_mov_b32_e32 v5, v2
	v_mov_b32_e32 v1, v6
	v_pk_add_f32 v[6:7], v[4:5], v[18:19] neg_lo:[0,1] neg_hi:[0,1]
	s_nop 0
	v_sub_f32_e32 v3, v4, v6
	v_pk_add_f32 v[0:1], v[0:1], v[6:7] neg_lo:[0,1] neg_hi:[0,1]
	v_sub_f32_e32 v3, v18, v3
	v_add_f32_e32 v0, v0, v3
	v_add_f32_e32 v0, v0, v1
	v_add_f32_e32 v0, v2, v0
	v_cndmask_b32_e32 v0, v84, v0, vcc
	v_cmp_neq_f32_e32 vcc, 1.0, v15
	s_nop 1
	v_cndmask_b32_e32 v0, v85, v0, vcc
	v_cndmask_b32_e64 v15, v0, -v15, s[0:1]
	v_add_f32_e32 v0, -1.0, v20
	v_add_f32_e32 v1, 1.0, v0
	v_sub_f32_e32 v1, v20, v1
	v_add_f32_e32 v2, v21, v1
	v_add_f32_e32 v1, 1.0, v20
	v_add_f32_e32 v3, -1.0, v1
	v_sub_f32_e32 v3, v20, v3
	v_add_f32_e32 v3, v21, v3
	v_add_f32_e32 v8, v1, v3
	v_rcp_f32_e32 v10, v8
	v_sub_f32_e32 v1, v8, v1
; #define LAS __attribute__((address_space(3)))
; DI int otid() { int t = threadIdx.x; asm volatile("" : "+v"(t)); return t; }
; DI float ret_lg2(const Params& p, int l, int dir, int h) { return log1pf(-exp2f(p.in[12][(l * 2 + dir) * 5 + h])) * 1.4426950408889634f; }
; DI void ret_out_item(const Params& p, int l, int b, int h, int c, LAS unsigned char* lds) {
;     const int tid = otid(), lane = tid & 63, wid = tid >> 6, r16 = lane & 15, q4 = lane >> 4;
;     unsigned char* ws = p.ws;
;     const bf16_t* P = (const bf16_t*)(ws + WS_P);
;     const float lgf = ret_lg2(p, l, 0, h), lgb = ret_lg2(p, l, 1, h);
;     const size_t rowb = (size_t)b * RB; const int tok0 = c * 128, tl = wid * 16 + r16;
;     const size_t row = rowb + tok0 + tl;
;     constexpr int RS = 272, MB = 128 * RS;
;     {
;         const bf16_t* Sf = (const bf16_t*)(ws + WS_S) + ((size_t)((b * 5 + h) * 2 + 0) * 18 + c) * 16384;
;         const bf16_t* Sb = (const bf16_t*)(ws + WS_S) + ((size_t)((b * 5 + h) * 2 + 1) * 18 + c) * 16384;
;         const bf16_t* Kc = P + (rowb + tok0) * INP + C_RK + h * 128;
;         const bf16_t* Vc = (const bf16_t*)(ws + WS_VTR) + ((size_t)b * 640 + h * 128) * RB + tok0;
;         u32x4 t0[4], t1[4], t2[4], t3[4];
; #pragma unroll
;         for (int i = 0; i < 4; ++i) {
;             const int cid = tid + i * 512, rr = cid >> 4, cc = cid & 15;
;             t0[i] = *(const u32x4*)(Sf + rr * 128 + cc * 8); t1[i] = *(const u32x4*)(Sb + rr * 128 + cc * 8);
;             t2[i] = *(const u32x4*)(Kc + (size_t)rr * INP + cc * 8); t3[i] = *(const u32x4*)(Vc + (size_t)rr * RB + cc * 8);
;         }
	v_sub_f32_e32 v9, v3, v1
	v_add_f32_e32 v1, v0, v2
	v_sub_f32_e32 v0, v1, v0
	v_mul_f32_e32 v12, v1, v10
	v_sub_f32_e32 v11, v2, v0
	v_mul_f32_e32 v2, v8, v12
	v_fma_f32 v4, v12, v8, -v2
	v_fmac_f32_e32 v4, v12, v9
	v_add_f32_e32 v0, v2, v4
	v_sub_f32_e32 v3, v1, v0
	v_pk_add_f32 v[6:7], v[0:1], v[2:3] neg_lo:[0,1] neg_hi:[0,1]
	v_mov_b32_e32 v5, v0
	v_pk_add_f32 v[0:1], v[6:7], v[4:5] neg_lo:[0,1] neg_hi:[0,1]
	s_mul_i32 s0, s18, 0x900
	v_add_f32_e32 v1, v11, v1
	v_add_f32_e32 v0, v0, v1
	v_add_f32_e32 v1, v3, v0
	v_mul_f32_e32 v11, v10, v1
	v_mul_f32_e32 v2, v8, v11
	v_fma_f32 v4, v11, v8, -v2
	v_fmac_f32_e32 v4, v11, v9
	v_sub_f32_e32 v3, v3, v1
	v_add_f32_e32 v8, v0, v3
	v_add_f32_e32 v0, v2, v4
	v_sub_f32_e32 v3, v1, v0
	v_pk_add_f32 v[6:7], v[0:1], v[2:3] neg_lo:[0,1] neg_hi:[0,1]
	v_mov_b32_e32 v5, v0
	v_pk_add_f32 v[0:1], v[6:7], v[4:5] neg_lo:[0,1] neg_hi:[0,1]
	s_mul_hi_i32 s1, s18, 0x900
	v_add_f32_e32 v1, v8, v1
	v_add_f32_e32 v0, v0, v1
	v_add_f32_e32 v1, v12, v11
	s_add_u32 s0, s0, s28
	v_add_f32_e32 v0, v3, v0
	v_sub_f32_e32 v2, v1, v12
	s_addc_u32 s1, s1, s29
	s_add_i32 s17, s17, s16
	v_mul_f32_e32 v0, v10, v0
	v_sub_f32_e32 v2, v11, v2
	s_lshl_b32 s56, s17, 1
	s_mul_i32 s17, s17, 36
	s_ashr_i32 s57, s19, 31
	v_add_f32_e32 v2, v2, v0
	s_mul_hi_i32 s55, s56, 18
	s_add_u32 s54, s17, s19
	v_add_f32_e32 v4, v1, v2
	s_addc_u32 s55, s55, s57
	v_mul_f32_e32 v5, v4, v4
	s_lshl_b64 s[54:55], s[54:55], 15
	v_fmamk_f32 v0, v5, 0x3e9b6dac, v83
	s_add_u32 s54, s92, s54
	v_fmaak_f32 v73, v5, v0, 0x3f2aaada
	v_cvt_f32_i32_e32 v0, v17
	s_addc_u32 s55, s93, s55
	s_or_b32 s17, s56, 1
	v_sub_f32_e32 v1, v4, v1
	s_mul_hi_i32 s62, s17, 18
	s_mul_i32 s17, s17, 18
	v_sub_f32_e32 v1, v2, v1
	s_add_u32 s56, s17, s19
	v_ldexp_f32 v8, v1, 1
	v_mul_f32_e32 v1, v4, v5
	s_addc_u32 s57, s62, s57
	v_pk_mul_f32 v[6:7], v[0:1], v[72:73]
	s_lshl_b64 s[56:57], s[56:57], 15
	v_fma_f32 v2, v0, s5, -v6
	s_add_u32 s56, s92, s56
	s_mul_i32 s17, s1, 0x3000
	s_mul_hi_u32 s19, s0, 0x3000
	v_ldexp_f32 v3, v4, 1
	v_fmac_f32_e32 v2, 0xb102e308, v0
	s_addc_u32 s57, s93, s57
	s_add_i32 s19, s19, s17
	s_mul_i32 s17, s0, 0x3000
	v_pk_add_f32 v[4:5], v[6:7], v[2:3]
	s_add_u32 s68, s6, s17
	v_sub_f32_e32 v0, v5, v3
	s_addc_u32 s19, s7, s19
	s_lshl_b32 s62, s16, 7
	v_sub_f32_e32 v0, v7, v0
	s_ashr_i32 s63, s62, 31
	v_add_f32_e32 v9, v8, v0
	v_mov_b32_e32 v8, v6
	s_lshl_b64 s[16:17], s[62:63], 1
	v_pk_add_f32 v[0:1], v[4:5], v[6:7] neg_lo:[0,1] neg_hi:[0,1]
	v_pk_add_f32 v[66:67], v[4:5], v[8:9]
	s_add_u32 s68, s68, s16
	v_mov_b32_e32 v1, v67
	v_mov_b32_e32 v3, v4
	s_addc_u32 s69, s19, s17
	s_mul_hi_i32 s19, s18, 0x280
	s_mulk_i32 s18, 0x280
	v_pk_add_f32 v[10:11], v[2:3], v[0:1]
	s_add_u32 s18, s18, s62
	v_pk_add_f32 v[6:7], v[2:3], v[0:1] neg_lo:[0,1] neg_hi:[0,1]
	v_pk_add_f32 v[0:1], v[10:11], v[4:5] op_sel:[1,0] op_sel_hi:[0,1] neg_lo:[0,1] neg_hi:[0,1]
	s_addc_u32 s19, s19, s63
	v_pk_add_f32 v[12:13], v[66:67], v[0:1] op_sel_hi:[1,0] neg_lo:[0,1] neg_hi:[0,1]
	s_mulk_i32 s19, 0x1200
	s_mul_hi_u32 s62, s18, 0x1200
	v_lshlrev_b32_e32 v1, 4, v16
	s_add_i32 s62, s62, s19
	s_mulk_i32 s18, 0x1200
	v_and_b32_e32 v68, 0xf0, v1
	s_add_u32 s63, s87, s18
	v_lshl_add_u64 v[18:19], s[68:69], 0, v[68:69]
	v_ashrrev_i32_e32 v17, 4, v16
	s_addc_u32 s62, s91, s62
	s_lshl_b64 s[18:19], s[28:29], 1
	v_lshl_add_u64 v[76:77], v[18:19], 0, s[8:9]
	v_lshlrev_b32_e32 v18, 7, v17
	s_add_u32 s18, s63, s18
	v_ashrrev_i32_e32 v19, 31, v18
	v_add_u32_e32 v1, 0x200, v16
	s_addc_u32 s19, s62, s19
	v_lshl_add_u64 v[2:3], s[54:55], 0, v[68:69]
	v_lshl_add_u64 v[74:75], s[56:57], 0, v[68:69]
	v_lshlrev_b64 v[18:19], 1, v[18:19]
	v_ashrrev_i32_e32 v73, 4, v1
	v_lshl_add_u64 v[78:79], s[18:19], 0, v[68:69]
	v_lshl_add_u64 v[20:21], v[2:3], 0, v[18:19]
	v_lshl_add_u64 v[22:23], v[74:75], 0, v[18:19]
	v_lshlrev_b32_e32 v34, 7, v73
	global_load_dwordx4 v[18:21], v[20:21], off
	s_nop 0
	global_load_dwordx4 v[22:25], v[22:23], off
	v_mad_i64_i32 v[26:27], s[18:19], v17, s21, v[76:77]
	v_mad_i64_i32 v[30:31], s[18:19], v17, s22, v[78:79]
	v_ashrrev_i32_e32 v35, 31, v34
	v_add_u32_e32 v1, 0x400, v16
	global_load_dwordx4 v[26:29], v[26:27], off
	s_nop 0
	global_load_dwordx4 v[30:33], v[30:31], off
	v_lshlrev_b64 v[34:35], 1, v[34:35]
	v_ashrrev_i32_e32 v93, 4, v1
	v_lshl_add_u64 v[36:37], v[2:3], 0, v[34:35]
	v_lshl_add_u64 v[38:39], v[74:75], 0, v[34:35]
	v_lshlrev_b32_e32 v50, 7, v93
	global_load_dwordx4 v[34:37], v[36:37], off
	s_nop 0
	global_load_dwordx4 v[38:41], v[38:39], off
	v_mad_i64_i32 v[42:43], s[18:19], v73, s21, v[76:77]
	v_mad_i64_i32 v[46:47], s[18:19], v73, s22, v[78:79]
	v_ashrrev_i32_e32 v51, 31, v50
	v_add_u32_e32 v1, 0x600, v16
	global_load_dwordx4 v[42:45], v[42:43], off
	s_nop 0
	global_load_dwordx4 v[46:49], v[46:47], off
	v_lshlrev_b64 v[50:51], 1, v[50:51]
	v_ashrrev_i32_e32 v114, 4, v1
	v_lshl_add_u64 v[52:53], v[2:3], 0, v[50:51]
	v_lshl_add_u64 v[54:55], v[74:75], 0, v[50:51]
	v_lshlrev_b32_e32 v80, 7, v114
	global_load_dwordx4 v[50:53], v[52:53], off
	s_nop 0
	global_load_dwordx4 v[54:57], v[54:55], off
	v_mad_i64_i32 v[58:59], s[18:19], v93, s21, v[76:77]
	v_mad_i64_i32 v[62:63], s[18:19], v93, s22, v[78:79]
	v_ashrrev_i32_e32 v81, 31, v80
	global_load_dwordx4 v[58:61], v[58:59], off
	s_nop 0
	global_load_dwordx4 v[62:65], v[62:63], off
	v_lshlrev_b64 v[80:81], 1, v[80:81]
	v_lshl_add_u64 v[2:3], v[2:3], 0, v[80:81]
	v_lshl_add_u64 v[74:75], v[74:75], 0, v[80:81]
	global_load_dwordx4 v[94:97], v[2:3], off
	global_load_dwordx4 v[98:101], v[74:75], off
	v_mad_i64_i32 v[2:3], s[18:19], v114, s21, v[76:77]
	global_load_dwordx4 v[102:105], v[2:3], off
	v_mad_i64_i32 v[2:3], s[18:19], v114, s22, v[78:79]
; #define LAS __attribute__((address_space(3)))
; DI void ret_out_item(const Params& p, int l, int b, int h, int c, LAS unsigned char* lds) {
;     ...
;         u32x4 t0[4], t1[4], t2[4], t3[4];
; #pragma unroll
;         for (int i = 0; i < 4; ++i) {
;             const int cid = tid + i * 512, rr = cid >> 4, cc = cid & 15;
;             t0[i] = *(const u32x4*)(Sf + rr * 128 + cc * 8); t1[i] = *(const u32x4*)(Sb + rr * 128 + cc * 8);
;             t2[i] = *(const u32x4*)(Kc + (size_t)rr * INP + cc * 8); t3[i] = *(const u32x4*)(Vc + (size_t)rr * RB + cc * 8);
;         }
; #pragma unroll
;         for (int i = 0; i < 4; ++i) {
;             const int cid = tid + i * 512, rr = cid >> 4, cc = cid & 15;
;             *(LAS u32x4*)(lds + 0 * MB + rr * RS + cc * 16) = t0[i]; *(LAS u32x4*)(lds + 1 * MB + rr * RS + cc * 16) = t1[i];
;             *(LAS u32x4*)(lds + 2 * MB + rr * RS + cc * 16) = t2[i]; *(LAS u32x4*)(lds + 3 * MB + rr * RS + cc * 16) = t3[i];
;         }
;     }
;     bf16x8 qf[4], qff[4], qfb[4];
;     const float qdf = exp2f(lgf * (float)(tl + 1)), qdb = exp2f(lgb * (float)(128 - tl));
; #pragma unroll
;     for (int ks = 0; ks < 4; ++ks) { qf[ks] = *(const bf16x8*)(P + row * INP + C_RQ + h * 128 + ks * 32 + q4 * 8); qff[ks] = scale1_bf16x8(qf[ks], qdf); qfb[ks] = scale1_bf16x8(qf[ks], qdb); }
	v_mov_b32_e32 v111, v0
	v_ashrrev_i32_e32 v0, 2, v16
	global_load_dwordx4 v[106:109], v[2:3], off
	v_bfi_b32 v78, -16, v0, v16
	v_ashrrev_i32_e32 v79, 31, v78
	v_lshl_add_u64 v[74:75], s[0:1], 0, v[78:79]
	v_mad_u64_u32 v[0:1], s[0:1], v74, s21, v[70:71]
	v_mad_i32_i24 v1, v75, s21, v1
	v_lshlrev_b32_e32 v80, 4, v92
	v_mov_b32_e32 v81, v69
	v_lshl_add_u64 v[76:77], v[0:1], 0, s[16:17]
	v_lshl_add_u64 v[112:113], v[76:77], 0, v[80:81]
	v_add_co_u32_e32 v0, vcc, s31, v112
	v_mov_b32_e32 v66, v67
	s_nop 0
	v_addc_co_u32_e32 v1, vcc, 0, v113, vcc
	global_load_dwordx4 v[120:123], v[0:1], off offset:2752
	global_load_dwordx4 v[124:127], v[0:1], off offset:2816
	global_load_dwordx4 v[128:131], v[0:1], off offset:2880
	global_load_dwordx4 v[0:3], v[0:1], off offset:2688
	v_mov_b32_e32 v67, v11
	v_mov_b32_e32 v110, v5
	v_pk_add_f32 v[66:67], v[66:67], v[110:111] neg_lo:[0,1] neg_hi:[0,1]
	v_mov_b32_e32 v8, v9
	v_mov_b32_e32 v9, v4
	v_pk_add_f32 v[4:5], v[8:9], v[66:67] neg_lo:[0,1] neg_hi:[0,1]
	v_mov_b32_e32 v12, v6
	v_pk_add_f32 v[8:9], v[12:13], v[4:5]
	v_mov_b32_e32 v7, v11
	v_pk_add_f32 v[12:13], v[8:9], v[8:9] op_sel:[0,1] op_sel_hi:[1,0]
	v_cmp_nlt_f32_e32 vcc, 1.0, v14
	v_pk_add_f32 v[10:11], v[10:11], v[12:13] op_sel:[1,0] op_sel_hi:[0,1]
	v_mov_b32_e32 v9, v10
	v_pk_add_f32 v[66:67], v[8:9], v[6:7] neg_lo:[0,1] neg_hi:[0,1]
	v_mov_b32_e32 v5, v12
	v_sub_f32_e32 v7, v8, v66
	v_pk_add_f32 v[4:5], v[4:5], v[66:67] neg_lo:[0,1] neg_hi:[0,1]
	v_sub_f32_e32 v6, v6, v7
	v_add_f32_e32 v4, v4, v6
	v_add_f32_e32 v4, v4, v5
	v_add_u32_e32 v5, 0, v68
	v_mul_lo_u32 v8, v17, s30
	v_add_u32_e32 v6, s23, v68
	v_add_u32_e32 v7, s27, v68
	v_add_u32_e32 v9, v5, v8
	s_waitcnt vmcnt(19)
	ds_write_b128 v9, v[18:21]
	s_waitcnt vmcnt(18)
	ds_write_b128 v9, v[22:25] offset:34816
	v_add_u32_e32 v9, v6, v8
	v_add_u32_e32 v8, v7, v8
	s_waitcnt vmcnt(16)
	ds_write_b128 v8, v[30:33]
	v_mul_lo_u32 v8, v73, s30
	ds_write_b128 v9, v[26:29]
	v_add_u32_e32 v9, v5, v8
	s_waitcnt vmcnt(15)
	ds_write_b128 v9, v[34:37]
	s_waitcnt vmcnt(14)
	ds_write_b128 v9, v[38:41] offset:34816
	v_add_u32_e32 v9, v6, v8
	v_add_u32_e32 v8, v7, v8
	v_add_f32_e32 v4, v10, v4
	v_cndmask_b32_e32 v4, v84, v4, vcc
	v_cmp_neq_f32_e32 vcc, 1.0, v14
	s_waitcnt vmcnt(13)
	ds_write_b128 v9, v[42:45]
	s_waitcnt vmcnt(12)
	ds_write_b128 v8, v[46:49]
	v_mul_lo_u32 v8, v93, s30
	v_add_u32_e32 v9, v5, v8
	s_waitcnt vmcnt(11)
	ds_write_b128 v9, v[50:53]
	s_waitcnt vmcnt(10)
	ds_write_b128 v9, v[54:57] offset:34816
	v_add_u32_e32 v9, v6, v8
	v_add_u32_e32 v8, v7, v8
	v_cndmask_b32_e32 v4, v85, v4, vcc
	v_cmp_lt_f32_e64 s[0:1], |v14|, s20
	s_waitcnt vmcnt(9)
	ds_write_b128 v9, v[58:61]
	s_waitcnt vmcnt(8)
	ds_write_b128 v8, v[62:65]
	v_mul_lo_u32 v8, v114, s30
	v_add_u32_e32 v5, v5, v8
	s_waitcnt vmcnt(7)
	ds_write_b128 v5, v[94:97]
	s_waitcnt vmcnt(6)
	ds_write_b128 v5, v[98:101] offset:34816
	v_add_u32_e32 v5, v6, v8
	v_add_u32_e32 v6, v7, v8
	s_waitcnt vmcnt(5)
	ds_write_b128 v5, v[102:105]
	v_add_u32_e32 v5, 1, v78
	v_cvt_f32_i32_e32 v5, v5
	v_sub_u32_e32 v7, 0x80, v78
	v_cvt_f32_i32_e32 v7, v7
	v_cndmask_b32_e64 v4, v4, -v14, s[0:1]
	v_mul_f32_e32 v79, 0x3fb8aa3b, v15
	s_waitcnt vmcnt(4)
	ds_write_b128 v6, v[106:109]
	v_mul_f32_e32 v6, v79, v5
	v_mul_f32_e32 v73, 0xbfb8aa3b, v4
	v_cmp_gt_f32_e32 vcc, s3, v6
	v_mul_f32_e64 v4, -v73, v7
	v_cmp_gt_f32_e64 s[0:1], s3, v4
	v_cndmask_b32_e32 v6, 0, v82, vcc
	v_fmac_f32_e32 v6, v79, v5
	v_cndmask_b32_e64 v4, 0, v82, s[0:1]
	v_exp_f32_e32 v5, v6
	v_fma_f32 v4, -v73, v7, v4
	v_exp_f32_e32 v4, v4
	v_cndmask_b32_e32 v6, 0, v86, vcc
	v_ldexp_f32 v17, v5, v6
	v_cndmask_b32_e64 v5, 0, v86, s[0:1]
	v_ldexp_f32 v19, v4, v5
	s_waitcnt vmcnt(0)
	v_lshlrev_b32_e32 v4, 16, v0
	v_mul_f32_e32 v5, v17, v4
	v_and_b32_e32 v6, 0xffff0000, v0
	v_mul_f32_e32 v7, v17, v6
	v_cvt_pk_bf16_f32 v48, v5, v7
	v_lshlrev_b32_e32 v5, 16, v1
	v_mul_f32_e32 v7, v17, v5
	v_and_b32_e32 v8, 0xffff0000, v1
	v_mul_f32_e32 v9, v17, v8
	v_cvt_pk_bf16_f32 v49, v7, v9
	v_lshlrev_b32_e32 v7, 16, v2
	v_mul_f32_e32 v9, v17, v7
	v_and_b32_e32 v10, 0xffff0000, v2
	v_mul_f32_e32 v11, v17, v10
	v_cvt_pk_bf16_f32 v50, v9, v11
	v_lshlrev_b32_e32 v9, 16, v3
	v_and_b32_e32 v14, 0xffff0000, v3
	v_mul_f32_e32 v4, v19, v4
	v_mul_f32_e32 v11, v17, v9
	v_mul_f32_e32 v15, v17, v14
	v_cvt_pk_bf16_f32 v51, v11, v15
	v_mul_f32_e32 v6, v19, v6
	v_cvt_pk_bf16_f32 v52, v4, v6
	v_mul_f32_e32 v4, v19, v5
	v_mul_f32_e32 v5, v19, v8
	v_cvt_pk_bf16_f32 v53, v4, v5
	v_mul_f32_e32 v4, v19, v7
	v_mul_f32_e32 v5, v19, v10
	v_lshl_add_u64 v[12:13], v[112:113], 0, s[10:11]
	v_cvt_pk_bf16_f32 v54, v4, v5
	v_mul_f32_e32 v4, v19, v9
	v_mul_f32_e32 v5, v19, v14
	v_cvt_pk_bf16_f32 v55, v4, v5
	s_waitcnt vmcnt(0)
	v_mov_b32_e32 v4, v120
	v_mov_b32_e32 v5, v121
	v_mov_b32_e32 v6, v122
	v_mov_b32_e32 v7, v123
	v_lshlrev_b32_e32 v8, 16, v4
	v_mul_f32_e32 v9, v17, v8
	v_and_b32_e32 v10, 0xffff0000, v4
	v_mul_f32_e32 v11, v17, v10
	v_cvt_pk_bf16_f32 v56, v9, v11
	v_lshlrev_b32_e32 v9, 16, v5
	v_mul_f32_e32 v11, v17, v9
	v_and_b32_e32 v14, 0xffff0000, v5
	v_mul_f32_e32 v15, v17, v14
	v_cvt_pk_bf16_f32 v57, v11, v15
	v_lshlrev_b32_e32 v11, 16, v6
	v_mul_f32_e32 v15, v17, v11
	v_and_b32_e32 v18, 0xffff0000, v6
	v_mul_f32_e32 v20, v17, v18
	v_cvt_pk_bf16_f32 v58, v15, v20
	v_lshlrev_b32_e32 v15, 16, v7
	v_and_b32_e32 v21, 0xffff0000, v7
	v_mul_f32_e32 v8, v19, v8
	v_mul_f32_e32 v20, v17, v15
	v_mul_f32_e32 v22, v17, v21
	v_cvt_pk_bf16_f32 v59, v20, v22
	v_mul_f32_e32 v10, v19, v10
	v_cvt_pk_bf16_f32 v60, v8, v10
	v_mul_f32_e32 v8, v19, v9
	v_mul_f32_e32 v9, v19, v14
	v_cvt_pk_bf16_f32 v61, v8, v9
	v_mul_f32_e32 v8, v19, v11
	v_mul_f32_e32 v9, v19, v18
	v_cvt_pk_bf16_f32 v62, v8, v9
	v_mul_f32_e32 v8, v19, v15
	v_mul_f32_e32 v9, v19, v21
	v_cvt_pk_bf16_f32 v63, v8, v9
	s_waitcnt vmcnt(0)
; #define LAS __attribute__((address_space(3)))
; #define MFMA16(a, b, c) __builtin_amdgcn_mfma_f32_16x16x32_bf16((a), (b), (c), 0, 0, 0)
; DI void ret_out_item(const Params& p, int l, int b, int h, int c, LAS unsigned char* lds) {
;     ...
;     for (int ks = 0; ks < 4; ++ks) { qf[ks] = *(const bf16x8*)(P + row * INP + C_RQ + h * 128 + ks * 32 + q4 * 8); qff[ks] = scale1_bf16x8(qf[ks], qdf); qfb[ks] = scale1_bf16x8(qf[ks], qdb); }
;     f32x4 oacc[8];
; #pragma unroll
;     for (int d = 0; d < 8; ++d) oacc[d] = (f32x4){0.f, 0.f, 0.f, 0.f};
;     __syncthreads();
;     const LAS unsigned char* sfp = lds + 0 * MB + r16 * RS + q4 * 16;
;     const LAS unsigned char* sbp = lds + 1 * MB + r16 * RS + q4 * 16;
;     const LAS unsigned char* kcp = lds + 2 * MB + r16 * RS + q4 * 16;
;     const LAS unsigned char* vtp = lds + 3 * MB + r16 * RS + q4 * 8;
; #pragma unroll
;     for (int d = 0; d < 8; ++d)
; #pragma unroll
;         for (int ks = 0; ks < 4; ++ks) {
;             oacc[d] = MFMA16(*(const LAS bf16x8*)(sfp + d * 16 * RS + ks * 64), qff[ks], oacc[d]);
;             oacc[d] = MFMA16(*(const LAS bf16x8*)(sbp + d * 16 * RS + ks * 64), qfb[ks], oacc[d]);
;         }
	v_mov_b32_e32 v8, v124
	v_mov_b32_e32 v9, v125
	v_mov_b32_e32 v10, v126
	v_mov_b32_e32 v11, v127
	v_lshlrev_b32_e32 v14, 16, v8
	v_mul_f32_e32 v15, v17, v14
	v_and_b32_e32 v18, 0xffff0000, v8
	v_mul_f32_e32 v20, v17, v18
	v_cvt_pk_bf16_f32 v64, v15, v20
	v_lshlrev_b32_e32 v15, 16, v9
	v_mul_f32_e32 v20, v17, v15
	v_and_b32_e32 v21, 0xffff0000, v9
	v_mul_f32_e32 v22, v17, v21
	v_cvt_pk_bf16_f32 v65, v20, v22
	v_lshlrev_b32_e32 v20, 16, v10
	v_mul_f32_e32 v22, v17, v20
	v_and_b32_e32 v23, 0xffff0000, v10
	v_mul_f32_e32 v24, v17, v23
	v_cvt_pk_bf16_f32 v66, v22, v24
	v_lshlrev_b32_e32 v22, 16, v11
	v_and_b32_e32 v25, 0xffff0000, v11
	v_mul_f32_e32 v14, v19, v14
	v_mul_f32_e32 v24, v17, v22
	v_mul_f32_e32 v26, v17, v25
	v_cvt_pk_bf16_f32 v67, v24, v26
	v_mul_f32_e32 v18, v19, v18
	v_cvt_pk_bf16_f32 v94, v14, v18
	v_mul_f32_e32 v14, v19, v15
	v_mul_f32_e32 v15, v19, v21
	v_cvt_pk_bf16_f32 v95, v14, v15
	v_mul_f32_e32 v14, v19, v20
	v_mul_f32_e32 v15, v19, v23
	v_cvt_pk_bf16_f32 v96, v14, v15
	v_mul_f32_e32 v14, v19, v22
	v_mul_f32_e32 v15, v19, v25
	v_cvt_pk_bf16_f32 v97, v14, v15
	s_waitcnt vmcnt(0)
	v_mov_b32_e32 v12, v128
	v_mov_b32_e32 v13, v129
	v_mov_b32_e32 v14, v130
	v_mov_b32_e32 v15, v131
	v_and_b32_e32 v20, 15, v16
	v_mul_u32_u24_e32 v81, 0x110, v20
	v_add3_u32 v68, 0, v81, v80
	s_waitcnt vmcnt(0)
	v_lshlrev_b32_e32 v16, 16, v12
	v_mul_f32_e32 v18, v17, v16
	v_and_b32_e32 v21, 0xffff0000, v12
	v_mul_f32_e32 v22, v17, v21
	v_cvt_pk_bf16_f32 v98, v18, v22
	v_lshlrev_b32_e32 v18, 16, v13
	v_mul_f32_e32 v22, v17, v18
	v_and_b32_e32 v23, 0xffff0000, v13
	v_mul_f32_e32 v24, v17, v23
	v_cvt_pk_bf16_f32 v99, v22, v24
	v_lshlrev_b32_e32 v22, 16, v14
	v_mul_f32_e32 v24, v17, v22
	v_and_b32_e32 v25, 0xffff0000, v14
	v_mul_f32_e32 v26, v17, v25
	v_cvt_pk_bf16_f32 v100, v24, v26
	v_lshlrev_b32_e32 v24, 16, v15
	v_and_b32_e32 v27, 0xffff0000, v15
	v_mul_f32_e32 v26, v17, v24
	v_mul_f32_e32 v17, v17, v27
	v_cvt_pk_bf16_f32 v101, v26, v17
	v_mul_f32_e32 v16, v19, v16
	v_mul_f32_e32 v17, v19, v21
	v_cvt_pk_bf16_f32 v16, v16, v17
	v_mul_f32_e32 v17, v19, v18
	v_mul_f32_e32 v18, v19, v23
	v_cvt_pk_bf16_f32 v17, v17, v18
	v_mul_f32_e32 v18, v19, v22
	v_mul_f32_e32 v21, v19, v25
	v_cvt_pk_bf16_f32 v18, v18, v21
	v_mul_f32_e32 v21, v19, v24
	v_mul_f32_e32 v19, v19, v27
	v_cvt_pk_bf16_f32 v19, v21, v19
	s_waitcnt lgkmcnt(0)
	s_barrier
	ds_read_b128 v[20:23], v68
	ds_read_b128 v[24:27], v68 offset:64
	s_waitcnt lgkmcnt(1)
	v_mfma_f32_16x16x32_bf16 v[20:23], v[20:23], v[48:51], 0
	ds_read_b128 v[28:31], v68 offset:34816
	ds_read_b128 v[32:35], v68 offset:34880
	s_waitcnt lgkmcnt(1)
	v_mfma_f32_16x16x32_bf16 v[20:23], v[28:31], v[52:55], v[20:23]
	v_mfma_f32_16x16x32_bf16 v[20:23], v[24:27], v[56:59], v[20:23]
	ds_read_b128 v[24:27], v68 offset:128
	ds_read_b128 v[28:31], v68 offset:192
	s_waitcnt lgkmcnt(2)
	v_mfma_f32_16x16x32_bf16 v[20:23], v[32:35], v[60:63], v[20:23]
	s_waitcnt lgkmcnt(1)
	v_mfma_f32_16x16x32_bf16 v[20:23], v[24:27], v[64:67], v[20:23]
	ds_read_b128 v[24:27], v68 offset:34944
	ds_read_b128 v[32:35], v68 offset:35008
	s_waitcnt lgkmcnt(1)
	v_mfma_f32_16x16x32_bf16 v[20:23], v[24:27], v[94:97], v[20:23]
	v_mfma_f32_16x16x32_bf16 v[20:23], v[28:31], v[98:101], v[20:23]
	ds_read_b128 v[24:27], v68 offset:4352
	ds_read_b128 v[28:31], v68 offset:4416
	s_waitcnt lgkmcnt(2)
	v_mfma_f32_16x16x32_bf16 v[20:23], v[32:35], v[16:19], v[20:23]
	ds_read_b128 v[32:35], v68 offset:39168
	ds_read_b128 v[36:39], v68 offset:39232
	s_waitcnt lgkmcnt(3)
	v_mfma_f32_16x16x32_bf16 v[24:27], v[24:27], v[48:51], 0
	s_waitcnt lgkmcnt(1)
	v_mfma_f32_16x16x32_bf16 v[24:27], v[32:35], v[52:55], v[24:27]
	v_mfma_f32_16x16x32_bf16 v[24:27], v[28:31], v[56:59], v[24:27]
	ds_read_b128 v[28:31], v68 offset:4480
	ds_read_b128 v[32:35], v68 offset:4544
	s_waitcnt lgkmcnt(2)
	v_mfma_f32_16x16x32_bf16 v[24:27], v[36:39], v[60:63], v[24:27]
	s_waitcnt lgkmcnt(1)
	v_mfma_f32_16x16x32_bf16 v[24:27], v[28:31], v[64:67], v[24:27]
	ds_read_b128 v[28:31], v68 offset:39296
	ds_read_b128 v[36:39], v68 offset:39360
	s_waitcnt lgkmcnt(1)
	v_mfma_f32_16x16x32_bf16 v[24:27], v[28:31], v[94:97], v[24:27]
	v_mfma_f32_16x16x32_bf16 v[24:27], v[32:35], v[98:101], v[24:27]
	ds_read_b128 v[28:31], v68 offset:8704
	ds_read_b128 v[32:35], v68 offset:8768
	s_waitcnt lgkmcnt(2)
	v_mfma_f32_16x16x32_bf16 v[24:27], v[36:39], v[16:19], v[24:27]
	ds_read_b128 v[36:39], v68 offset:43520
	ds_read_b128 v[40:43], v68 offset:43584
	s_waitcnt lgkmcnt(3)
	v_mfma_f32_16x16x32_bf16 v[28:31], v[28:31], v[48:51], 0
	s_waitcnt lgkmcnt(1)
	v_mfma_f32_16x16x32_bf16 v[28:31], v[36:39], v[52:55], v[28:31]
	v_mfma_f32_16x16x32_bf16 v[28:31], v[32:35], v[56:59], v[28:31]
	ds_read_b128 v[32:35], v68 offset:8832
	ds_read_b128 v[36:39], v68 offset:8896
	s_waitcnt lgkmcnt(2)
	v_mfma_f32_16x16x32_bf16 v[28:31], v[40:43], v[60:63], v[28:31]
	s_waitcnt lgkmcnt(1)
	v_mfma_f32_16x16x32_bf16 v[28:31], v[32:35], v[64:67], v[28:31]
	ds_read_b128 v[32:35], v68 offset:43648
	ds_read_b128 v[40:43], v68 offset:43712
	s_waitcnt lgkmcnt(1)
	v_mfma_f32_16x16x32_bf16 v[28:31], v[32:35], v[94:97], v[28:31]
	v_mfma_f32_16x16x32_bf16 v[28:31], v[36:39], v[98:101], v[28:31]
	ds_read_b128 v[32:35], v68 offset:13056
	ds_read_b128 v[36:39], v68 offset:13120
	s_waitcnt lgkmcnt(2)
	v_mfma_f32_16x16x32_bf16 v[28:31], v[40:43], v[16:19], v[28:31]
	ds_read_b128 v[40:43], v68 offset:47872
	ds_read_b128 v[44:47], v68 offset:47936
	s_waitcnt lgkmcnt(3)
	v_mfma_f32_16x16x32_bf16 v[32:35], v[32:35], v[48:51], 0
	s_waitcnt lgkmcnt(1)
	v_mfma_f32_16x16x32_bf16 v[32:35], v[40:43], v[52:55], v[32:35]
	v_mfma_f32_16x16x32_bf16 v[32:35], v[36:39], v[56:59], v[32:35]
	ds_read_b128 v[36:39], v68 offset:13184
	ds_read_b128 v[40:43], v68 offset:13248
	s_waitcnt lgkmcnt(2)
; #define LAS __attribute__((address_space(3)))
; #define MFMA16(a, b, c) __builtin_amdgcn_mfma_f32_16x16x32_bf16((a), (b), (c), 0, 0, 0)
; DI void ret_out_item(const Params& p, int l, int b, int h, int c, LAS unsigned char* lds) {
;     ...
; #pragma unroll
;     for (int d = 0; d < 8; ++d)
; #pragma unroll
;         for (int ks = 0; ks < 4; ++ks) {
;             oacc[d] = MFMA16(*(const LAS bf16x8*)(sfp + d * 16 * RS + ks * 64), qff[ks], oacc[d]);
;             oacc[d] = MFMA16(*(const LAS bf16x8*)(sbp + d * 16 * RS + ks * 64), qfb[ks], oacc[d]);
;         }
; #pragma unroll
;     for (int kc = 0; kc < 4; ++kc) {
;         f32x4 s[2];
; #pragma unroll
;         for (int hf = 0; hf < 2; ++hf) {
;             s[hf] = (f32x4){0.f, 0.f, 0.f, 0.f};
; #pragma unroll
;             for (int ks = 0; ks < 4; ++ks) s[hf] = MFMA16(*(const LAS bf16x8*)(kcp + (2 * kc + hf) * 16 * RS + ks * 64), qf[ks], s[hf]);
; #pragma unroll
;             for (int j = 0; j < 4; ++j) {
;                 const int m = (2 * kc + hf) * 16 + q4 * 4 + j, d = tl - m;
;                 const float w = (d >= 0 ? exp2f(lgf * (float)d) : 0.f) + (d <= 0 ? exp2f(-lgb * (float)d) : 0.f);
;                 s[hf][j] *= w;
;             }
;         }
	v_mfma_f32_16x16x32_bf16 v[32:35], v[44:47], v[60:63], v[32:35]
	s_waitcnt lgkmcnt(1)
	v_mfma_f32_16x16x32_bf16 v[32:35], v[36:39], v[64:67], v[32:35]
	ds_read_b128 v[36:39], v68 offset:48000
	ds_read_b128 v[44:47], v68 offset:48064
	s_waitcnt lgkmcnt(1)
	v_mfma_f32_16x16x32_bf16 v[32:35], v[36:39], v[94:97], v[32:35]
	v_mfma_f32_16x16x32_bf16 v[32:35], v[40:43], v[98:101], v[32:35]
	ds_read_b128 v[36:39], v68 offset:17408
	ds_read_b128 v[40:43], v68 offset:17472
	s_waitcnt lgkmcnt(2)
	v_mfma_f32_16x16x32_bf16 v[32:35], v[44:47], v[16:19], v[32:35]
	ds_read_b128 v[44:47], v68 offset:52224
	ds_read_b128 v[102:105], v68 offset:52288
	s_waitcnt lgkmcnt(3)
	v_mfma_f32_16x16x32_bf16 v[36:39], v[36:39], v[48:51], 0
	s_waitcnt lgkmcnt(1)
	v_mfma_f32_16x16x32_bf16 v[36:39], v[44:47], v[52:55], v[36:39]
	v_mfma_f32_16x16x32_bf16 v[36:39], v[40:43], v[56:59], v[36:39]
	ds_read_b128 v[40:43], v68 offset:17536
	ds_read_b128 v[44:47], v68 offset:17600
	s_waitcnt lgkmcnt(2)
	v_mfma_f32_16x16x32_bf16 v[36:39], v[102:105], v[60:63], v[36:39]
	s_waitcnt lgkmcnt(1)
	v_mfma_f32_16x16x32_bf16 v[36:39], v[40:43], v[64:67], v[36:39]
	ds_read_b128 v[40:43], v68 offset:52352
	ds_read_b128 v[102:105], v68 offset:52416
	s_waitcnt lgkmcnt(1)
	v_mfma_f32_16x16x32_bf16 v[36:39], v[40:43], v[94:97], v[36:39]
	v_mfma_f32_16x16x32_bf16 v[36:39], v[44:47], v[98:101], v[36:39]
	ds_read_b128 v[40:43], v68 offset:21760
	ds_read_b128 v[44:47], v68 offset:21824
	s_waitcnt lgkmcnt(2)
	v_mfma_f32_16x16x32_bf16 v[36:39], v[102:105], v[16:19], v[36:39]
	ds_read_b128 v[102:105], v68 offset:56576
	ds_read_b128 v[106:109], v68 offset:56640
	s_waitcnt lgkmcnt(3)
	v_mfma_f32_16x16x32_bf16 v[40:43], v[40:43], v[48:51], 0
	s_waitcnt lgkmcnt(1)
	v_mfma_f32_16x16x32_bf16 v[40:43], v[102:105], v[52:55], v[40:43]
	v_mfma_f32_16x16x32_bf16 v[40:43], v[44:47], v[56:59], v[40:43]
	ds_read_b128 v[44:47], v68 offset:21888
	ds_read_b128 v[102:105], v68 offset:21952
	s_waitcnt lgkmcnt(2)
	v_mfma_f32_16x16x32_bf16 v[40:43], v[106:109], v[60:63], v[40:43]
	s_waitcnt lgkmcnt(1)
	v_mfma_f32_16x16x32_bf16 v[40:43], v[44:47], v[64:67], v[40:43]
	ds_read_b128 v[44:47], v68 offset:56704
	ds_read_b128 v[106:109], v68 offset:56768
	s_waitcnt lgkmcnt(1)
	v_mfma_f32_16x16x32_bf16 v[40:43], v[44:47], v[94:97], v[40:43]
	v_mfma_f32_16x16x32_bf16 v[40:43], v[102:105], v[98:101], v[40:43]
	ds_read_b128 v[44:47], v68 offset:26112
	ds_read_b128 v[102:105], v68 offset:26176
	s_waitcnt lgkmcnt(2)
	v_mfma_f32_16x16x32_bf16 v[40:43], v[106:109], v[16:19], v[40:43]
	ds_read_b128 v[106:109], v68 offset:60928
	ds_read_b128 v[110:113], v68 offset:60992
	s_waitcnt lgkmcnt(3)
	v_mfma_f32_16x16x32_bf16 v[44:47], v[44:47], v[48:51], 0
	s_waitcnt lgkmcnt(1)
	v_mfma_f32_16x16x32_bf16 v[44:47], v[106:109], v[52:55], v[44:47]
	v_mfma_f32_16x16x32_bf16 v[44:47], v[102:105], v[56:59], v[44:47]
	ds_read_b128 v[102:105], v68 offset:26240
	ds_read_b128 v[106:109], v68 offset:26304
	s_waitcnt lgkmcnt(2)
	v_mfma_f32_16x16x32_bf16 v[44:47], v[110:113], v[60:63], v[44:47]
	s_waitcnt lgkmcnt(1)
	v_mfma_f32_16x16x32_bf16 v[44:47], v[102:105], v[64:67], v[44:47]
	ds_read_b128 v[102:105], v68 offset:61056
	ds_read_b128 v[110:113], v68 offset:61120
	s_waitcnt lgkmcnt(1)
	v_mfma_f32_16x16x32_bf16 v[44:47], v[102:105], v[94:97], v[44:47]
	v_mfma_f32_16x16x32_bf16 v[44:47], v[106:109], v[98:101], v[44:47]
	ds_read_b128 v[102:105], v68 offset:30464
	ds_read_b128 v[106:109], v68 offset:30528
	s_waitcnt lgkmcnt(2)
	v_mfma_f32_16x16x32_bf16 v[44:47], v[110:113], v[16:19], v[44:47]
	s_waitcnt lgkmcnt(1)
	v_mfma_f32_16x16x32_bf16 v[48:51], v[102:105], v[48:51], 0
	ds_read_b128 v[102:105], v68 offset:65280
	ds_read_b128 v[110:113], v68 offset:65344
	s_waitcnt lgkmcnt(1)
	v_mfma_f32_16x16x32_bf16 v[48:51], v[102:105], v[52:55], v[48:51]
	v_mfma_f32_16x16x32_bf16 v[48:51], v[106:109], v[56:59], v[48:51]
	ds_read_b128 v[52:55], v68 offset:30592
	ds_read_b128 v[56:59], v68 offset:30656
	s_waitcnt lgkmcnt(2)
	v_mfma_f32_16x16x32_bf16 v[48:51], v[110:113], v[60:63], v[48:51]
	v_add3_u32 v62, s23, v81, v80
	v_lshlrev_b32_e32 v61, 2, v92
	v_sub_u32_e32 v63, v78, v61
	s_waitcnt lgkmcnt(1)
	v_mfma_f32_16x16x32_bf16 v[48:51], v[52:55], v[64:67], v[48:51]
	ds_read_b128 v[64:67], v68 offset:65408
	ds_read_b128 v[52:55], v68 offset:65472
	v_cvt_f32_u32_e32 v80, v63
	s_waitcnt lgkmcnt(1)
	v_mfma_f32_16x16x32_bf16 v[48:51], v[64:67], v[94:97], v[48:51]
	ds_read_b128 v[64:67], v62
	ds_read_b128 v[94:97], v62 offset:128
	v_lshlrev_b32_e32 v68, 3, v92
	v_mfma_f32_16x16x32_bf16 v[56:59], v[56:59], v[98:101], v[48:51]
	v_add3_u32 v60, s27, v81, v68
	v_mul_f32_e32 v81, v79, v80
	v_cmp_gt_f32_e32 vcc, s3, v81
	s_nop 0
	ds_read_b128 v[48:51], v62 offset:64
	s_waitcnt lgkmcnt(2)
	v_mfma_f32_16x16x32_bf16 v[64:67], v[64:67], v[0:3], 0
	v_cndmask_b32_e32 v81, 0, v82, vcc
	v_fmac_f32_e32 v81, v79, v80
	v_exp_f32_e32 v80, v81
	s_waitcnt lgkmcnt(0)
	v_mfma_f32_16x16x32_bf16 v[48:51], v[48:51], v[4:7], v[64:67]
	s_nop 2
	ds_read_b128 v[64:67], v62 offset:192
	v_cvt_f32_i32_e32 v81, v63
	v_cmp_lt_i32_e64 s[0:1], -1, v63
	v_mfma_f32_16x16x32_bf16 v[48:51], v[94:97], v[8:11], v[48:51]
	ds_read_b128 v[96:99], v62 offset:4480
	s_waitcnt lgkmcnt(1)
; #define LAS __attribute__((address_space(3)))
; DI unsigned cvt_pk_bf16(float lo, float hi) { unsigned r; asm volatile("v_cvt_pk_bf16_f32 %0, %1, %2" : "=v"(r) : "v"(lo), "v"(hi)); return r; }
; #define MFMA16(a, b, c) __builtin_amdgcn_mfma_f32_16x16x32_bf16((a), (b), (c), 0, 0, 0)
; DI void ret_out_item(const Params& p, int l, int b, int h, int c, LAS unsigned char* lds) {
;     ...
;     for (int kc = 0; kc < 4; ++kc) {
;         f32x4 s[2];
; #pragma unroll
;         for (int hf = 0; hf < 2; ++hf) {
;             s[hf] = (f32x4){0.f, 0.f, 0.f, 0.f};
; #pragma unroll
;             for (int ks = 0; ks < 4; ++ks) s[hf] = MFMA16(*(const LAS bf16x8*)(kcp + (2 * kc + hf) * 16 * RS + ks * 64), qf[ks], s[hf]);
; #pragma unroll
;             for (int j = 0; j < 4; ++j) {
;                 const int m = (2 * kc + hf) * 16 + q4 * 4 + j, d = tl - m;
;                 const float w = (d >= 0 ? exp2f(lgf * (float)d) : 0.f) + (d <= 0 ? exp2f(-lgb * (float)d) : 0.f);
;                 s[hf][j] *= w;
;             }
;         }
;         u32x4 w4; w4.x = cvt_pk_bf16(s[0][0], s[0][1]); w4.y = cvt_pk_bf16(s[0][2], s[0][3]); w4.z = cvt_pk_bf16(s[1][0], s[1][1]); w4.w = cvt_pk_bf16(s[1][2], s[1][3]);
;         const bf16x8 pb = __builtin_bit_cast(bf16x8, w4);
; #pragma unroll
;         for (int d = 0; d < 8; ++d) {
;             const u32x2 lo = *(const LAS u32x2*)(vtp + d * 16 * RS + kc * 64), hi = *(const LAS u32x2*)(vtp + d * 16 * RS + kc * 64 + 32);
;             u32x4 a4; a4.x = lo.x; a4.y = lo.y; a4.z = hi.x; a4.w = hi.y;
;             oacc[d] = MFMA16(__builtin_bit_cast(bf16x8, a4), pb, oacc[d]);
	v_mfma_f32_16x16x32_bf16 v[48:51], v[64:67], v[12:15], v[48:51]
	v_mul_f32_e32 v65, v81, v73
	v_cndmask_b32_e32 v64, 0, v86, vcc
	v_cmp_gt_f32_e32 vcc, s3, v65
	v_ldexp_f32 v64, v80, v64
	v_cndmask_b32_e64 v64, 0, v64, s[0:1]
	v_cndmask_b32_e32 v65, 0, v82, vcc
	v_fmac_f32_e32 v65, v81, v73
	v_exp_f32_e32 v65, v65
	v_cndmask_b32_e32 v66, 0, v86, vcc
	v_cmp_gt_i32_e32 vcc, 1, v63
	v_mfma_f32_16x16x32_bf16 v[52:55], v[52:55], v[16:19], v[56:59]
	v_ldexp_f32 v65, v65, v66
	v_xad_u32 v66, v61, -1, v78
	v_cvt_f32_u32_e32 v67, v66
	v_cndmask_b32_e32 v63, 0, v65, vcc
	v_add_f32_e32 v63, v64, v63
	v_cvt_f32_i32_e32 v65, v66
	v_mul_f32_e32 v64, v79, v67
	v_cmp_gt_f32_e32 vcc, s3, v64
	v_mul_f32_e32 v63, v63, v48
	v_cmp_lt_i32_e64 s[0:1], -1, v66
	v_cndmask_b32_e32 v64, 0, v82, vcc
	v_fmac_f32_e32 v64, v79, v67
	v_exp_f32_e32 v64, v64
	v_cndmask_b32_e32 v48, 0, v86, vcc
	v_ldexp_f32 v48, v64, v48
	v_mul_f32_e32 v64, v65, v73
	v_cmp_gt_f32_e32 vcc, s3, v64
	v_cndmask_b32_e64 v48, 0, v48, s[0:1]
	s_nop 0
	v_cndmask_b32_e32 v64, 0, v82, vcc
	v_fmac_f32_e32 v64, v65, v73
	v_exp_f32_e32 v64, v64
	v_cndmask_b32_e32 v65, 0, v86, vcc
	v_cmp_gt_i32_e32 vcc, 1, v66
	v_ldexp_f32 v64, v64, v65
	v_or_b32_e32 v65, 2, v61
	v_sub_u32_e32 v65, v78, v65
	v_cvt_f32_u32_e32 v67, v65
	v_cvt_f32_i32_e32 v66, v65
	v_cndmask_b32_e32 v64, 0, v64, vcc
	v_add_f32_e32 v48, v48, v64
	v_mul_f32_e32 v64, v79, v67
	v_cmp_gt_f32_e32 vcc, s3, v64
	v_mul_f32_e32 v80, v48, v49
	v_mul_f32_e32 v49, v66, v73
	v_cndmask_b32_e32 v64, 0, v82, vcc
	v_cndmask_b32_e32 v48, 0, v86, vcc
	v_cmp_gt_f32_e32 vcc, s3, v49
	v_fmac_f32_e32 v64, v79, v67
	v_exp_f32_e32 v64, v64
	v_cndmask_b32_e32 v49, 0, v82, vcc
	v_fmac_f32_e32 v49, v66, v73
	v_exp_f32_e32 v49, v49
	v_ldexp_f32 v48, v64, v48
	v_cndmask_b32_e32 v64, 0, v86, vcc
	v_cmp_lt_i32_e64 s[0:1], -1, v65
	v_ldexp_f32 v49, v49, v64
	v_or_b32_e32 v64, 3, v61
	v_sub_u32_e32 v81, v78, v64
	v_cvt_f32_u32_e32 v64, v81
	v_cmp_gt_i32_e32 vcc, 1, v65
	v_cndmask_b32_e64 v48, 0, v48, s[0:1]
	v_cvt_f32_i32_e32 v92, v81
	v_cndmask_b32_e32 v49, 0, v49, vcc
	v_add_f32_e32 v48, v48, v49
	v_mul_f32_e32 v49, v79, v64
	v_cmp_gt_f32_e32 vcc, s3, v49
	v_mul_f32_e32 v100, v48, v50
	v_cmp_lt_i32_e64 s[0:1], -1, v81
	v_cndmask_b32_e32 v49, 0, v82, vcc
	v_fmac_f32_e32 v49, v79, v64
	v_exp_f32_e32 v49, v49
	v_cndmask_b32_e32 v48, 0, v86, vcc
	ds_read_b128 v[64:67], v62 offset:4352
	v_ldexp_f32 v48, v49, v48
	v_mul_f32_e32 v49, v92, v73
	v_cmp_gt_f32_e32 vcc, s3, v49
	v_cndmask_b32_e64 v48, 0, v48, s[0:1]
	s_nop 0
	v_cndmask_b32_e32 v49, 0, v82, vcc
	v_fmac_f32_e32 v49, v92, v73
	ds_read_b128 v[92:95], v62 offset:4416
	v_exp_f32_e32 v49, v49
	v_cndmask_b32_e32 v50, 0, v86, vcc
	s_waitcnt lgkmcnt(1)
	v_mfma_f32_16x16x32_bf16 v[64:67], v[64:67], v[0:3], 0
	v_cmp_gt_i32_e32 vcc, 1, v81
	v_ldexp_f32 v49, v49, v50
	s_nop 0
	v_cndmask_b32_e32 v49, 0, v49, vcc
	v_add_f32_e32 v48, v48, v49
	v_or_b32_e32 v49, 16, v61
	v_sub_u32_e32 v81, v78, v49
	s_waitcnt lgkmcnt(0)
	v_mfma_f32_16x16x32_bf16 v[64:67], v[92:95], v[4:7], v[64:67]
	v_cvt_f32_u32_e32 v101, v81
	ds_read_b128 v[92:95], v62 offset:4544
	v_mul_f32_e32 v102, v48, v51
	v_mfma_f32_16x16x32_bf16 v[48:51], v[96:99], v[8:11], v[64:67]
	v_cmp_lt_i32_e64 s[0:1], -1, v81
	s_nop 2
	v_mul_f32_e32 v64, v79, v101
	v_cmp_gt_f32_e32 vcc, s3, v64
	v_cvt_f32_i32_e32 v65, v81
	s_waitcnt lgkmcnt(0)
	v_mfma_f32_16x16x32_bf16 v[48:51], v[92:95], v[12:15], v[48:51]
	v_cndmask_b32_e32 v64, 0, v82, vcc
	v_fmac_f32_e32 v64, v79, v101
	v_exp_f32_e32 v64, v64
	v_cndmask_b32_e32 v66, 0, v86, vcc
	v_ldexp_f32 v64, v64, v66
	v_mul_f32_e32 v66, v65, v73
	v_cmp_gt_f32_e32 vcc, s3, v66
	v_cndmask_b32_e64 v64, 0, v64, s[0:1]
	s_nop 0
	v_cndmask_b32_e32 v66, 0, v82, vcc
	v_fmac_f32_e32 v66, v65, v73
	v_exp_f32_e32 v65, v66
	v_cndmask_b32_e32 v66, 0, v86, vcc
	v_cmp_gt_i32_e32 vcc, 1, v81
	v_ldexp_f32 v65, v65, v66
	v_or_b32_e32 v66, 17, v61
	v_sub_u32_e32 v66, v78, v66
	v_cvt_f32_u32_e32 v67, v66
	v_cndmask_b32_e32 v65, 0, v65, vcc
	v_add_f32_e32 v64, v64, v65
	v_mul_f32_e32 v64, v64, v48
	v_mul_f32_e32 v65, v79, v67
	v_cmp_gt_f32_e32 vcc, s3, v65
	v_cmp_lt_i32_e64 s[0:1], -1, v66
	s_nop 0
	v_cndmask_b32_e32 v65, 0, v82, vcc
	v_fmac_f32_e32 v65, v79, v67
	v_exp_f32_e32 v65, v65
	v_cvt_f32_i32_e32 v67, v66
	v_cndmask_b32_e32 v48, 0, v86, vcc
	v_ldexp_f32 v48, v65, v48
	v_mul_f32_e32 v65, v67, v73
	v_cmp_gt_f32_e32 vcc, s3, v65
	v_cndmask_b32_e64 v48, 0, v48, s[0:1]
	s_nop 0
	v_cndmask_b32_e32 v65, 0, v82, vcc
	v_fmac_f32_e32 v65, v67, v73
	v_exp_f32_e32 v65, v65
	v_cndmask_b32_e32 v67, 0, v86, vcc
	v_cmp_gt_i32_e32 vcc, 1, v66
	v_ldexp_f32 v65, v65, v67
	v_or_b32_e32 v67, 18, v61
	v_sub_u32_e32 v67, v78, v67
	v_cvt_f32_u32_e32 v81, v67
	v_cndmask_b32_e32 v65, 0, v65, vcc
	v_cvt_f32_i32_e32 v66, v67
	v_add_f32_e32 v48, v48, v65
	v_mul_f32_e32 v65, v79, v81
	v_cmp_gt_f32_e32 vcc, s3, v65
	v_cmp_lt_i32_e64 s[0:1], -1, v67
	s_nop 0
	v_cndmask_b32_e32 v65, 0, v82, vcc
	v_fmac_f32_e32 v65, v79, v81
	v_mul_f32_e32 v81, v48, v49
	v_mul_f32_e32 v49, v66, v73
	v_cndmask_b32_e32 v48, 0, v86, vcc
	v_cmp_gt_f32_e32 vcc, s3, v49
	v_exp_f32_e32 v65, v65
	s_nop 0
	v_cndmask_b32_e32 v49, 0, v82, vcc
	v_fmac_f32_e32 v49, v66, v73
	v_exp_f32_e32 v49, v49
	v_ldexp_f32 v48, v65, v48
	v_cndmask_b32_e32 v65, 0, v86, vcc
	v_cmp_gt_i32_e32 vcc, 1, v67
	v_ldexp_f32 v49, v49, v65
	v_or_b32_e32 v65, 19, v61
	v_sub_u32_e32 v65, v78, v65
	v_cvt_f32_u32_e32 v66, v65
	v_cndmask_b32_e64 v48, 0, v48, s[0:1]
	v_cndmask_b32_e32 v49, 0, v49, vcc
	v_add_f32_e32 v48, v48, v49
	v_mul_f32_e32 v49, v79, v66
	v_cmp_gt_f32_e32 vcc, s3, v49
	v_mul_f32_e32 v67, v48, v50
	v_cmp_lt_i32_e64 s[0:1], -1, v65
	v_cndmask_b32_e32 v49, 0, v82, vcc
	v_fmac_f32_e32 v49, v79, v66
	v_exp_f32_e32 v49, v49
	v_cvt_f32_i32_e32 v66, v65
	v_cndmask_b32_e32 v48, 0, v86, vcc
	v_ldexp_f32 v48, v49, v48
	v_mul_f32_e32 v49, v66, v73
	v_cmp_gt_f32_e32 vcc, s3, v49
	v_cndmask_b32_e64 v48, 0, v48, s[0:1]
	s_nop 0
	v_cndmask_b32_e32 v49, 0, v82, vcc
	v_fmac_f32_e32 v49, v66, v73
	v_exp_f32_e32 v49, v49
	v_cndmask_b32_e32 v50, 0, v86, vcc
	v_cmp_gt_i32_e32 vcc, 1, v65
	v_ldexp_f32 v49, v49, v50
	s_nop 0
	v_cndmask_b32_e32 v49, 0, v49, vcc
	v_add_f32_e32 v48, v48, v49
	v_mul_f32_e32 v51, v48, v51
	v_cvt_pk_bf16_f32 v48, v63, v80
	v_cvt_pk_bf16_f32 v49, v100, v102
	v_cvt_pk_bf16_f32 v50, v64, v81
	v_cvt_pk_bf16_f32 v51, v67, v51
	ds_read2_b64 v[64:67], v60 offset1:4
	v_add_u32_e32 v63, 0x1000, v60
	ds_read2_b64 v[16:19], v63 offset0:32 offset1:36
	s_waitcnt lgkmcnt(1)
; #define LAS __attribute__((address_space(3)))
; DI unsigned cvt_pk_bf16(float lo, float hi) { unsigned r; asm volatile("v_cvt_pk_bf16_f32 %0, %1, %2" : "=v"(r) : "v"(lo), "v"(hi)); return r; }
; #define MFMA16(a, b, c) __builtin_amdgcn_mfma_f32_16x16x32_bf16((a), (b), (c), 0, 0, 0)
; DI void ret_out_item(const Params& p, int l, int b, int h, int c, LAS unsigned char* lds) {
;     ...
;     for (int kc = 0; kc < 4; ++kc) {
;         f32x4 s[2];
; #pragma unroll
;         for (int hf = 0; hf < 2; ++hf) {
;             s[hf] = (f32x4){0.f, 0.f, 0.f, 0.f};
; #pragma unroll
;             for (int ks = 0; ks < 4; ++ks) s[hf] = MFMA16(*(const LAS bf16x8*)(kcp + (2 * kc + hf) * 16 * RS + ks * 64), qf[ks], s[hf]);
; #pragma unroll
;             for (int j = 0; j < 4; ++j) {
;                 const int m = (2 * kc + hf) * 16 + q4 * 4 + j, d = tl - m;
;                 const float w = (d >= 0 ? exp2f(lgf * (float)d) : 0.f) + (d <= 0 ? exp2f(-lgb * (float)d) : 0.f);
;                 s[hf][j] *= w;
;             }
;         }
;         u32x4 w4; w4.x = cvt_pk_bf16(s[0][0], s[0][1]); w4.y = cvt_pk_bf16(s[0][2], s[0][3]); w4.z = cvt_pk_bf16(s[1][0], s[1][1]); w4.w = cvt_pk_bf16(s[1][2], s[1][3]);
;         const bf16x8 pb = __builtin_bit_cast(bf16x8, w4);
; #pragma unroll
;         for (int d = 0; d < 8; ++d) {
;             const u32x2 lo = *(const LAS u32x2*)(vtp + d * 16 * RS + kc * 64), hi = *(const LAS u32x2*)(vtp + d * 16 * RS + kc * 64 + 32);
;             u32x4 a4; a4.x = lo.x; a4.y = lo.y; a4.z = hi.x; a4.w = hi.y;
;             oacc[d] = MFMA16(__builtin_bit_cast(bf16x8, a4), pb, oacc[d]);
	v_mfma_f32_16x16x32_bf16 v[20:23], v[64:67], v[48:51], v[20:23]
	v_add_u32_e32 v64, 0x2000, v60
	ds_read2_b64 v[56:59], v64 offset0:64 offset1:68
	v_add_u32_e32 v65, 0x3000, v60
	s_waitcnt lgkmcnt(1)
	v_mfma_f32_16x16x32_bf16 v[24:27], v[16:19], v[48:51], v[24:27]
	ds_read2_b64 v[16:19], v65 offset0:96 offset1:100
	v_add_u32_e32 v66, 0x4000, v60
	v_add_u32_e32 v67, 0x5000, v60
	s_waitcnt lgkmcnt(1)
	v_mfma_f32_16x16x32_bf16 v[28:31], v[56:59], v[48:51], v[28:31]
	ds_read2_b64 v[56:59], v66 offset0:128 offset1:132
	v_add_u32_e32 v80, 0x6000, v60
	ds_read_b128 v[92:95], v62 offset:8832
	s_waitcnt lgkmcnt(2)
	v_mfma_f32_16x16x32_bf16 v[32:35], v[16:19], v[48:51], v[32:35]
	ds_read2_b64 v[16:19], v67 offset0:160 offset1:164
	v_add_u32_e32 v81, 0x7000, v60
	s_waitcnt lgkmcnt(2)
	v_mfma_f32_16x16x32_bf16 v[36:39], v[56:59], v[48:51], v[36:39]
	ds_read2_b64 v[56:59], v80 offset0:192 offset1:196
	s_waitcnt lgkmcnt(1)
	v_mfma_f32_16x16x32_bf16 v[40:43], v[16:19], v[48:51], v[40:43]
	ds_read_b128 v[16:19], v62 offset:8704
	s_waitcnt lgkmcnt(1)
	v_mfma_f32_16x16x32_bf16 v[44:47], v[56:59], v[48:51], v[44:47]
	ds_read_b128 v[56:59], v62 offset:8768
	s_waitcnt lgkmcnt(1)
	v_mfma_f32_16x16x32_bf16 v[16:19], v[16:19], v[0:3], 0
	s_waitcnt lgkmcnt(0)
	v_mfma_f32_16x16x32_bf16 v[16:19], v[56:59], v[4:7], v[16:19]
	v_or_b32_e32 v56, 32, v61
	v_sub_u32_e32 v100, v78, v56
	v_cvt_f32_u32_e32 v101, v100
	v_mfma_f32_16x16x32_bf16 v[16:19], v[92:95], v[8:11], v[16:19]
	v_cvt_f32_i32_e32 v93, v100
	v_cmp_lt_i32_e64 s[0:1], -1, v100
	v_mul_f32_e32 v92, v79, v101
	v_cmp_gt_f32_e32 vcc, s3, v92
	ds_read_b128 v[96:99], v62 offset:8896
	ds_read2_b64 v[56:59], v81 offset0:224 offset1:228
	v_cndmask_b32_e32 v92, 0, v82, vcc
	v_fmac_f32_e32 v92, v79, v101
	v_exp_f32_e32 v92, v92
	v_cndmask_b32_e32 v94, 0, v86, vcc
	s_waitcnt lgkmcnt(1)
	v_mfma_f32_16x16x32_bf16 v[16:19], v[96:99], v[12:15], v[16:19]
	v_ldexp_f32 v92, v92, v94
	v_mul_f32_e32 v94, v93, v73
	v_cmp_gt_f32_e32 vcc, s3, v94
	v_cndmask_b32_e64 v92, 0, v92, s[0:1]
	s_waitcnt lgkmcnt(0)
	v_mfma_f32_16x16x32_bf16 v[48:51], v[56:59], v[48:51], v[52:55]
	v_cndmask_b32_e32 v94, 0, v82, vcc
	v_fmac_f32_e32 v94, v93, v73
	v_exp_f32_e32 v93, v94
	v_cndmask_b32_e32 v94, 0, v86, vcc
	v_cmp_gt_i32_e32 vcc, 1, v100
	ds_read_b128 v[100:103], v62 offset:13184
	v_ldexp_f32 v93, v93, v94
	v_or_b32_e32 v94, 33, v61
	v_sub_u32_e32 v94, v78, v94
	v_cvt_f32_u32_e32 v95, v94
	v_cndmask_b32_e32 v93, 0, v93, vcc
	v_add_f32_e32 v92, v92, v93
	v_mul_f32_e32 v104, v92, v16
	v_mul_f32_e32 v93, v79, v95
	v_cmp_gt_f32_e32 vcc, s3, v93
	v_cmp_lt_i32_e64 s[0:1], -1, v94
	s_nop 0
	v_cndmask_b32_e32 v93, 0, v82, vcc
	v_fmac_f32_e32 v93, v79, v95
	v_cvt_f32_i32_e32 v95, v94
	v_cndmask_b32_e32 v16, 0, v86, vcc
	v_exp_f32_e32 v93, v93
	v_mul_f32_e32 v92, v95, v73
	v_cmp_gt_f32_e32 vcc, s3, v92
	v_ldexp_f32 v16, v93, v16
	v_cndmask_b32_e64 v16, 0, v16, s[0:1]
	v_cndmask_b32_e32 v92, 0, v82, vcc
	v_fmac_f32_e32 v92, v95, v73
	v_exp_f32_e32 v92, v92
	v_cndmask_b32_e32 v93, 0, v86, vcc
	v_cmp_gt_i32_e32 vcc, 1, v94
	v_ldexp_f32 v92, v92, v93
	v_or_b32_e32 v93, 34, v61
	v_sub_u32_e32 v93, v78, v93
	v_cvt_f32_u32_e32 v95, v93
	v_cvt_f32_i32_e32 v94, v93
	v_cndmask_b32_e32 v92, 0, v92, vcc
	v_add_f32_e32 v16, v16, v92
	v_mul_f32_e32 v92, v79, v95
	v_cmp_gt_f32_e32 vcc, s3, v92
	v_mul_f32_e32 v105, v16, v17
	v_mul_f32_e32 v17, v94, v73
	v_cndmask_b32_e32 v92, 0, v82, vcc
	v_cndmask_b32_e32 v16, 0, v86, vcc
	v_cmp_gt_f32_e32 vcc, s3, v17
	v_fmac_f32_e32 v92, v79, v95
	v_exp_f32_e32 v92, v92
	v_cndmask_b32_e32 v17, 0, v82, vcc
	v_fmac_f32_e32 v17, v94, v73
	v_exp_f32_e32 v17, v17
	v_ldexp_f32 v16, v92, v16
	v_cndmask_b32_e32 v92, 0, v86, vcc
	v_cmp_lt_i32_e64 s[0:1], -1, v93
	v_ldexp_f32 v17, v17, v92
	v_or_b32_e32 v92, 35, v61
	v_sub_u32_e32 v106, v78, v92
	v_cvt_f32_u32_e32 v92, v106
	v_cmp_gt_i32_e32 vcc, 1, v93
	v_cndmask_b32_e64 v16, 0, v16, s[0:1]
	v_cvt_f32_i32_e32 v96, v106
	v_cndmask_b32_e32 v17, 0, v17, vcc
	v_add_f32_e32 v16, v16, v17
	v_mul_f32_e32 v17, v79, v92
	v_cmp_gt_f32_e32 vcc, s3, v17
	v_mul_f32_e32 v107, v16, v18
	v_cmp_lt_i32_e64 s[0:1], -1, v106
	v_cndmask_b32_e32 v17, 0, v82, vcc
	v_fmac_f32_e32 v17, v79, v92
	v_exp_f32_e32 v17, v17
	v_cndmask_b32_e32 v16, 0, v86, vcc
	ds_read_b128 v[92:95], v62 offset:13056
	v_ldexp_f32 v16, v17, v16
	v_mul_f32_e32 v17, v96, v73
	v_cmp_gt_f32_e32 vcc, s3, v17
	v_cndmask_b32_e64 v16, 0, v16, s[0:1]
	s_nop 0
	v_cndmask_b32_e32 v17, 0, v82, vcc
	v_fmac_f32_e32 v17, v96, v73
	ds_read_b128 v[96:99], v62 offset:13120
	v_exp_f32_e32 v17, v17
	v_cndmask_b32_e32 v18, 0, v86, vcc
	s_waitcnt lgkmcnt(1)
	v_mfma_f32_16x16x32_bf16 v[92:95], v[92:95], v[0:3], 0
	v_cmp_gt_i32_e32 vcc, 1, v106
	v_ldexp_f32 v17, v17, v18
	s_nop 0
	v_cndmask_b32_e32 v17, 0, v17, vcc
	v_add_f32_e32 v16, v16, v17
	v_or_b32_e32 v17, 48, v61
	v_sub_u32_e32 v106, v78, v17
	s_waitcnt lgkmcnt(0)
	v_mfma_f32_16x16x32_bf16 v[92:95], v[96:99], v[4:7], v[92:95]
	v_cvt_f32_u32_e32 v108, v106
	ds_read_b128 v[96:99], v62 offset:13248
	v_mul_f32_e32 v109, v16, v19
	v_mfma_f32_16x16x32_bf16 v[16:19], v[100:103], v[8:11], v[92:95]
	v_cmp_lt_i32_e64 s[0:1], -1, v106
	s_nop 2
	v_mul_f32_e32 v92, v79, v108
	v_cmp_gt_f32_e32 vcc, s3, v92
	v_cvt_f32_i32_e32 v93, v106
	s_waitcnt lgkmcnt(0)
; #define LAS __attribute__((address_space(3)))
; DI unsigned cvt_pk_bf16(float lo, float hi) { unsigned r; asm volatile("v_cvt_pk_bf16_f32 %0, %1, %2" : "=v"(r) : "v"(lo), "v"(hi)); return r; }
; #define MFMA16(a, b, c) __builtin_amdgcn_mfma_f32_16x16x32_bf16((a), (b), (c), 0, 0, 0)
; DI void ret_out_item(const Params& p, int l, int b, int h, int c, LAS unsigned char* lds) {
;     ...
;     for (int kc = 0; kc < 4; ++kc) {
;         f32x4 s[2];
; #pragma unroll
;         for (int hf = 0; hf < 2; ++hf) {
;             s[hf] = (f32x4){0.f, 0.f, 0.f, 0.f};
; #pragma unroll
;             for (int ks = 0; ks < 4; ++ks) s[hf] = MFMA16(*(const LAS bf16x8*)(kcp + (2 * kc + hf) * 16 * RS + ks * 64), qf[ks], s[hf]);
; #pragma unroll
;             for (int j = 0; j < 4; ++j) {
;                 const int m = (2 * kc + hf) * 16 + q4 * 4 + j, d = tl - m;
;                 const float w = (d >= 0 ? exp2f(lgf * (float)d) : 0.f) + (d <= 0 ? exp2f(-lgb * (float)d) : 0.f);
;                 s[hf][j] *= w;
;             }
;         }
;         u32x4 w4; w4.x = cvt_pk_bf16(s[0][0], s[0][1]); w4.y = cvt_pk_bf16(s[0][2], s[0][3]); w4.z = cvt_pk_bf16(s[1][0], s[1][1]); w4.w = cvt_pk_bf16(s[1][2], s[1][3]);
;         const bf16x8 pb = __builtin_bit_cast(bf16x8, w4);
; #pragma unroll
;         for (int d = 0; d < 8; ++d) {
;             const u32x2 lo = *(const LAS u32x2*)(vtp + d * 16 * RS + kc * 64), hi = *(const LAS u32x2*)(vtp + d * 16 * RS + kc * 64 + 32);
;             u32x4 a4; a4.x = lo.x; a4.y = lo.y; a4.z = hi.x; a4.w = hi.y;
;             oacc[d] = MFMA16(__builtin_bit_cast(bf16x8, a4), pb, oacc[d]);
	v_mfma_f32_16x16x32_bf16 v[16:19], v[96:99], v[12:15], v[16:19]
	v_cndmask_b32_e32 v92, 0, v82, vcc
	v_fmac_f32_e32 v92, v79, v108
	v_exp_f32_e32 v92, v92
	v_cndmask_b32_e32 v94, 0, v86, vcc
	v_ldexp_f32 v92, v92, v94
	v_mul_f32_e32 v94, v93, v73
	v_cmp_gt_f32_e32 vcc, s3, v94
	v_cndmask_b32_e64 v92, 0, v92, s[0:1]
	s_nop 0
	v_cndmask_b32_e32 v94, 0, v82, vcc
	v_fmac_f32_e32 v94, v93, v73
	v_exp_f32_e32 v93, v94
	v_cndmask_b32_e32 v94, 0, v86, vcc
	v_cmp_gt_i32_e32 vcc, 1, v106
	v_ldexp_f32 v93, v93, v94
	v_or_b32_e32 v94, 49, v61
	v_sub_u32_e32 v94, v78, v94
	v_cvt_f32_u32_e32 v95, v94
	v_cndmask_b32_e32 v93, 0, v93, vcc
	v_add_f32_e32 v92, v92, v93
	v_mul_f32_e32 v92, v92, v16
	v_mul_f32_e32 v93, v79, v95
	v_cmp_gt_f32_e32 vcc, s3, v93
	v_cmp_lt_i32_e64 s[0:1], -1, v94
	s_nop 0
	v_cndmask_b32_e32 v93, 0, v82, vcc
	v_fmac_f32_e32 v93, v79, v95
	v_exp_f32_e32 v93, v93
	v_cvt_f32_i32_e32 v95, v94
	v_cndmask_b32_e32 v16, 0, v86, vcc
	v_ldexp_f32 v16, v93, v16
	v_mul_f32_e32 v93, v95, v73
	v_cmp_gt_f32_e32 vcc, s3, v93
	v_cndmask_b32_e64 v16, 0, v16, s[0:1]
	s_nop 0
	v_cndmask_b32_e32 v93, 0, v82, vcc
	v_fmac_f32_e32 v93, v95, v73
	v_exp_f32_e32 v93, v93
	v_cndmask_b32_e32 v95, 0, v86, vcc
	v_cmp_gt_i32_e32 vcc, 1, v94
	v_ldexp_f32 v93, v93, v95
	v_or_b32_e32 v95, 50, v61
	v_sub_u32_e32 v95, v78, v95
	v_cvt_f32_u32_e32 v96, v95
	v_cndmask_b32_e32 v93, 0, v93, vcc
	v_cvt_f32_i32_e32 v94, v95
	v_add_f32_e32 v16, v16, v93
	v_mul_f32_e32 v93, v79, v96
	v_cmp_gt_f32_e32 vcc, s3, v93
	v_cmp_lt_i32_e64 s[0:1], -1, v95
	s_nop 0
	v_cndmask_b32_e32 v93, 0, v82, vcc
	v_fmac_f32_e32 v93, v79, v96
	v_mul_f32_e32 v96, v16, v17
	v_mul_f32_e32 v17, v94, v73
	v_cndmask_b32_e32 v16, 0, v86, vcc
	v_cmp_gt_f32_e32 vcc, s3, v17
	v_exp_f32_e32 v93, v93
	s_nop 0
	v_cndmask_b32_e32 v17, 0, v82, vcc
	v_fmac_f32_e32 v17, v94, v73
	v_exp_f32_e32 v17, v17
	v_ldexp_f32 v16, v93, v16
	v_cndmask_b32_e32 v93, 0, v86, vcc
	v_cmp_gt_i32_e32 vcc, 1, v95
	v_ldexp_f32 v17, v17, v93
	v_or_b32_e32 v93, 51, v61
	v_sub_u32_e32 v93, v78, v93
	v_cvt_f32_u32_e32 v94, v93
	v_cndmask_b32_e64 v16, 0, v16, s[0:1]
	v_cndmask_b32_e32 v17, 0, v17, vcc
	v_add_f32_e32 v16, v16, v17
	v_mul_f32_e32 v17, v79, v94
	v_cmp_gt_f32_e32 vcc, s3, v17
	v_mul_f32_e32 v95, v16, v18
	v_cmp_lt_i32_e64 s[0:1], -1, v93
	v_cndmask_b32_e32 v17, 0, v82, vcc
	v_fmac_f32_e32 v17, v79, v94
	v_exp_f32_e32 v17, v17
	v_cvt_f32_i32_e32 v94, v93
	v_cndmask_b32_e32 v16, 0, v86, vcc
	v_ldexp_f32 v16, v17, v16
	v_mul_f32_e32 v17, v94, v73
	v_cmp_gt_f32_e32 vcc, s3, v17
	v_cndmask_b32_e64 v16, 0, v16, s[0:1]
	s_nop 0
	v_cndmask_b32_e32 v17, 0, v82, vcc
	v_fmac_f32_e32 v17, v94, v73
	v_exp_f32_e32 v17, v17
	v_cndmask_b32_e32 v18, 0, v86, vcc
	v_cmp_gt_i32_e32 vcc, 1, v93
	v_ldexp_f32 v17, v17, v18
	s_nop 0
	v_cndmask_b32_e32 v17, 0, v17, vcc
	v_add_f32_e32 v16, v16, v17
	v_mul_f32_e32 v19, v16, v19
	v_cvt_pk_bf16_f32 v16, v104, v105
	v_cvt_pk_bf16_f32 v17, v107, v109
	v_cvt_pk_bf16_f32 v18, v92, v96
	v_cvt_pk_bf16_f32 v19, v95, v19
	ds_read2_b64 v[52:55], v63 offset0:40 offset1:44
	ds_read2_b64 v[56:59], v64 offset0:72 offset1:76
	s_waitcnt lgkmcnt(1)
	v_mfma_f32_16x16x32_bf16 v[24:27], v[52:55], v[16:19], v[24:27]
	ds_read2_b64 v[52:55], v65 offset0:104 offset1:108
	ds_read2_b64 v[92:95], v60 offset0:8 offset1:12
	s_waitcnt lgkmcnt(2)
	v_mfma_f32_16x16x32_bf16 v[28:31], v[56:59], v[16:19], v[28:31]
	ds_read2_b64 v[56:59], v66 offset0:136 offset1:140
	s_waitcnt lgkmcnt(2)
	v_mfma_f32_16x16x32_bf16 v[32:35], v[52:55], v[16:19], v[32:35]
	ds_read2_b64 v[52:55], v67 offset0:168 offset1:172
	s_waitcnt lgkmcnt(1)
	v_mfma_f32_16x16x32_bf16 v[36:39], v[56:59], v[16:19], v[36:39]
	ds_read2_b64 v[56:59], v80 offset0:200 offset1:204
	s_waitcnt lgkmcnt(1)
	v_mfma_f32_16x16x32_bf16 v[40:43], v[52:55], v[16:19], v[40:43]
	ds_read_b128 v[52:55], v62 offset:17408
	s_waitcnt lgkmcnt(1)
	v_mfma_f32_16x16x32_bf16 v[44:47], v[56:59], v[16:19], v[44:47]
	ds_read_b128 v[56:59], v62 offset:17472
	s_waitcnt lgkmcnt(1)
	v_mfma_f32_16x16x32_bf16 v[52:55], v[52:55], v[0:3], 0
	v_mfma_f32_16x16x32_bf16 v[20:23], v[92:95], v[16:19], v[20:23]
	ds_read_b128 v[92:95], v62 offset:17536
	s_waitcnt lgkmcnt(1)
	v_mfma_f32_16x16x32_bf16 v[56:59], v[56:59], v[4:7], v[52:55]
	s_nop 3
	v_or_b32_e32 v52, 64, v61
	v_sub_u32_e32 v100, v78, v52
	v_cvt_f32_u32_e32 v101, v100
	s_waitcnt lgkmcnt(0)
	v_mfma_f32_16x16x32_bf16 v[56:59], v[92:95], v[8:11], v[56:59]
	v_cvt_f32_i32_e32 v93, v100
	v_cmp_lt_i32_e64 s[0:1], -1, v100
	v_mul_f32_e32 v92, v79, v101
	v_cmp_gt_f32_e32 vcc, s3, v92
	ds_read_b128 v[96:99], v62 offset:17600
	ds_read2_b64 v[52:55], v81 offset0:232 offset1:236
	v_cndmask_b32_e32 v92, 0, v82, vcc
	v_fmac_f32_e32 v92, v79, v101
	v_exp_f32_e32 v92, v92
	v_cndmask_b32_e32 v94, 0, v86, vcc
	s_waitcnt lgkmcnt(1)
	v_mfma_f32_16x16x32_bf16 v[56:59], v[96:99], v[12:15], v[56:59]
	v_ldexp_f32 v92, v92, v94
	v_mul_f32_e32 v94, v93, v73
	v_cmp_gt_f32_e32 vcc, s3, v94
	v_cndmask_b32_e64 v92, 0, v92, s[0:1]
	s_waitcnt lgkmcnt(0)
; #define LAS __attribute__((address_space(3)))
; DI unsigned cvt_pk_bf16(float lo, float hi) { unsigned r; asm volatile("v_cvt_pk_bf16_f32 %0, %1, %2" : "=v"(r) : "v"(lo), "v"(hi)); return r; }
; #define MFMA16(a, b, c) __builtin_amdgcn_mfma_f32_16x16x32_bf16((a), (b), (c), 0, 0, 0)
; DI void ret_out_item(const Params& p, int l, int b, int h, int c, LAS unsigned char* lds) {
;     ...
;     for (int kc = 0; kc < 4; ++kc) {
;         f32x4 s[2];
; #pragma unroll
;         for (int hf = 0; hf < 2; ++hf) {
;             s[hf] = (f32x4){0.f, 0.f, 0.f, 0.f};
; #pragma unroll
;             for (int ks = 0; ks < 4; ++ks) s[hf] = MFMA16(*(const LAS bf16x8*)(kcp + (2 * kc + hf) * 16 * RS + ks * 64), qf[ks], s[hf]);
; #pragma unroll
;             for (int j = 0; j < 4; ++j) {
;                 const int m = (2 * kc + hf) * 16 + q4 * 4 + j, d = tl - m;
;                 const float w = (d >= 0 ? exp2f(lgf * (float)d) : 0.f) + (d <= 0 ? exp2f(-lgb * (float)d) : 0.f);
;                 s[hf][j] *= w;
;             }
;         }
;         u32x4 w4; w4.x = cvt_pk_bf16(s[0][0], s[0][1]); w4.y = cvt_pk_bf16(s[0][2], s[0][3]); w4.z = cvt_pk_bf16(s[1][0], s[1][1]); w4.w = cvt_pk_bf16(s[1][2], s[1][3]);
;         const bf16x8 pb = __builtin_bit_cast(bf16x8, w4);
; #pragma unroll
;         for (int d = 0; d < 8; ++d) {
;             const u32x2 lo = *(const LAS u32x2*)(vtp + d * 16 * RS + kc * 64), hi = *(const LAS u32x2*)(vtp + d * 16 * RS + kc * 64 + 32);
;             u32x4 a4; a4.x = lo.x; a4.y = lo.y; a4.z = hi.x; a4.w = hi.y;
;             oacc[d] = MFMA16(__builtin_bit_cast(bf16x8, a4), pb, oacc[d]);
	v_mfma_f32_16x16x32_bf16 v[48:51], v[52:55], v[16:19], v[48:51]
	v_cndmask_b32_e32 v94, 0, v82, vcc
	v_fmac_f32_e32 v94, v93, v73
	v_exp_f32_e32 v93, v94
	v_cndmask_b32_e32 v94, 0, v86, vcc
	v_cmp_gt_i32_e32 vcc, 1, v100
	ds_read_b128 v[100:103], v62 offset:21888
	v_ldexp_f32 v93, v93, v94
	v_or_b32_e32 v94, 0x41, v61
	v_sub_u32_e32 v94, v78, v94
	v_cvt_f32_u32_e32 v95, v94
	v_cndmask_b32_e32 v93, 0, v93, vcc
	v_add_f32_e32 v92, v92, v93
	v_mul_f32_e32 v104, v92, v56
	v_mul_f32_e32 v93, v79, v95
	v_cmp_gt_f32_e32 vcc, s3, v93
	v_cmp_lt_i32_e64 s[0:1], -1, v94
	s_nop 0
	v_cndmask_b32_e32 v93, 0, v82, vcc
	v_fmac_f32_e32 v93, v79, v95
	v_cvt_f32_i32_e32 v95, v94
	v_cndmask_b32_e32 v56, 0, v86, vcc
	v_exp_f32_e32 v93, v93
	v_mul_f32_e32 v92, v95, v73
	v_cmp_gt_f32_e32 vcc, s3, v92
	v_ldexp_f32 v56, v93, v56
	v_cndmask_b32_e64 v56, 0, v56, s[0:1]
	v_cndmask_b32_e32 v92, 0, v82, vcc
	v_fmac_f32_e32 v92, v95, v73
	v_exp_f32_e32 v92, v92
	v_cndmask_b32_e32 v93, 0, v86, vcc
	v_cmp_gt_i32_e32 vcc, 1, v94
	v_ldexp_f32 v92, v92, v93
	v_or_b32_e32 v93, 0x42, v61
	v_sub_u32_e32 v93, v78, v93
	v_cvt_f32_u32_e32 v95, v93
	v_cvt_f32_i32_e32 v94, v93
	v_cndmask_b32_e32 v92, 0, v92, vcc
	v_add_f32_e32 v56, v56, v92
	v_mul_f32_e32 v92, v79, v95
	v_cmp_gt_f32_e32 vcc, s3, v92
	v_mul_f32_e32 v105, v56, v57
	v_mul_f32_e32 v57, v94, v73
	v_cndmask_b32_e32 v92, 0, v82, vcc
	v_cndmask_b32_e32 v56, 0, v86, vcc
	v_cmp_gt_f32_e32 vcc, s3, v57
	v_fmac_f32_e32 v92, v79, v95
	v_exp_f32_e32 v92, v92
	v_cndmask_b32_e32 v57, 0, v82, vcc
	v_fmac_f32_e32 v57, v94, v73
	v_exp_f32_e32 v57, v57
	v_ldexp_f32 v56, v92, v56
	v_cndmask_b32_e32 v92, 0, v86, vcc
	v_cmp_lt_i32_e64 s[0:1], -1, v93
	v_ldexp_f32 v57, v57, v92
	v_or_b32_e32 v92, 0x43, v61
	v_sub_u32_e32 v106, v78, v92
	v_cvt_f32_u32_e32 v92, v106
	v_cmp_gt_i32_e32 vcc, 1, v93
	v_cndmask_b32_e64 v56, 0, v56, s[0:1]
	v_cvt_f32_i32_e32 v96, v106
	v_cndmask_b32_e32 v57, 0, v57, vcc
	v_add_f32_e32 v56, v56, v57
	v_mul_f32_e32 v57, v79, v92
	v_cmp_gt_f32_e32 vcc, s3, v57
	v_mul_f32_e32 v107, v56, v58
	v_cmp_lt_i32_e64 s[0:1], -1, v106
	v_cndmask_b32_e32 v57, 0, v82, vcc
	v_fmac_f32_e32 v57, v79, v92
	v_exp_f32_e32 v57, v57
	v_cndmask_b32_e32 v56, 0, v86, vcc
	ds_read_b128 v[92:95], v62 offset:21760
	v_ldexp_f32 v56, v57, v56
	v_mul_f32_e32 v57, v96, v73
	v_cmp_gt_f32_e32 vcc, s3, v57
	v_cndmask_b32_e64 v56, 0, v56, s[0:1]
	s_nop 0
	v_cndmask_b32_e32 v57, 0, v82, vcc
	v_fmac_f32_e32 v57, v96, v73
	ds_read_b128 v[96:99], v62 offset:21824
	v_exp_f32_e32 v57, v57
	v_cndmask_b32_e32 v58, 0, v86, vcc
	s_waitcnt lgkmcnt(1)
	v_mfma_f32_16x16x32_bf16 v[92:95], v[92:95], v[0:3], 0
	v_cmp_gt_i32_e32 vcc, 1, v106
	v_ldexp_f32 v57, v57, v58
	s_nop 0
	v_cndmask_b32_e32 v57, 0, v57, vcc
	v_add_f32_e32 v56, v56, v57
	v_or_b32_e32 v57, 0x50, v61
	v_sub_u32_e32 v106, v78, v57
	s_waitcnt lgkmcnt(0)
	v_mfma_f32_16x16x32_bf16 v[92:95], v[96:99], v[4:7], v[92:95]
	v_cvt_f32_u32_e32 v108, v106
	ds_read_b128 v[96:99], v62 offset:21952
	v_mul_f32_e32 v109, v56, v59
	v_mfma_f32_16x16x32_bf16 v[56:59], v[100:103], v[8:11], v[92:95]
	v_cmp_lt_i32_e64 s[0:1], -1, v106
	s_nop 2
	v_mul_f32_e32 v92, v79, v108
	v_cmp_gt_f32_e32 vcc, s3, v92
	v_cvt_f32_i32_e32 v93, v106
	s_waitcnt lgkmcnt(0)
	v_mfma_f32_16x16x32_bf16 v[56:59], v[96:99], v[12:15], v[56:59]
	v_cndmask_b32_e32 v92, 0, v82, vcc
	v_fmac_f32_e32 v92, v79, v108
	v_exp_f32_e32 v92, v92
	v_cndmask_b32_e32 v94, 0, v86, vcc
	v_ldexp_f32 v92, v92, v94
	v_mul_f32_e32 v94, v93, v73
	v_cmp_gt_f32_e32 vcc, s3, v94
	v_cndmask_b32_e64 v92, 0, v92, s[0:1]
	s_nop 0
	v_cndmask_b32_e32 v94, 0, v82, vcc
	v_fmac_f32_e32 v94, v93, v73
	v_exp_f32_e32 v93, v94
	v_cndmask_b32_e32 v94, 0, v86, vcc
	v_cmp_gt_i32_e32 vcc, 1, v106
	v_ldexp_f32 v93, v93, v94
	v_or_b32_e32 v94, 0x51, v61
	v_sub_u32_e32 v94, v78, v94
	v_cvt_f32_u32_e32 v95, v94
	v_cndmask_b32_e32 v93, 0, v93, vcc
	v_add_f32_e32 v92, v92, v93
	v_mul_f32_e32 v92, v92, v56
	v_mul_f32_e32 v93, v79, v95
	v_cmp_gt_f32_e32 vcc, s3, v93
	v_cmp_lt_i32_e64 s[0:1], -1, v94
	s_nop 0
	v_cndmask_b32_e32 v93, 0, v82, vcc
	v_fmac_f32_e32 v93, v79, v95
	v_exp_f32_e32 v93, v93
	v_cvt_f32_i32_e32 v95, v94
	v_cndmask_b32_e32 v56, 0, v86, vcc
	v_ldexp_f32 v56, v93, v56
	v_mul_f32_e32 v93, v95, v73
	v_cmp_gt_f32_e32 vcc, s3, v93
	v_cndmask_b32_e64 v56, 0, v56, s[0:1]
	s_nop 0
	v_cndmask_b32_e32 v93, 0, v82, vcc
	v_fmac_f32_e32 v93, v95, v73
	v_exp_f32_e32 v93, v93
	v_cndmask_b32_e32 v95, 0, v86, vcc
	v_cmp_gt_i32_e32 vcc, 1, v94
	v_ldexp_f32 v93, v93, v95
	v_or_b32_e32 v95, 0x52, v61
	v_sub_u32_e32 v95, v78, v95
	v_cvt_f32_u32_e32 v96, v95
	v_cndmask_b32_e32 v93, 0, v93, vcc
	v_cvt_f32_i32_e32 v94, v95
	v_add_f32_e32 v56, v56, v93
	v_mul_f32_e32 v93, v79, v96
	v_cmp_gt_f32_e32 vcc, s3, v93
	v_cmp_lt_i32_e64 s[0:1], -1, v95
	s_nop 0
	v_cndmask_b32_e32 v93, 0, v82, vcc
	v_fmac_f32_e32 v93, v79, v96
	v_mul_f32_e32 v96, v56, v57
	v_mul_f32_e32 v57, v94, v73
	v_cndmask_b32_e32 v56, 0, v86, vcc
	v_cmp_gt_f32_e32 vcc, s3, v57
	v_exp_f32_e32 v93, v93
	s_nop 0
	v_cndmask_b32_e32 v57, 0, v82, vcc
	v_fmac_f32_e32 v57, v94, v73
	v_exp_f32_e32 v57, v57
	v_ldexp_f32 v56, v93, v56
	v_cndmask_b32_e32 v93, 0, v86, vcc
	v_cmp_gt_i32_e32 vcc, 1, v95
	v_ldexp_f32 v57, v57, v93
	v_or_b32_e32 v93, 0x53, v61
	v_sub_u32_e32 v93, v78, v93
	v_cvt_f32_u32_e32 v94, v93
	v_cndmask_b32_e64 v56, 0, v56, s[0:1]
	v_cndmask_b32_e32 v57, 0, v57, vcc
	v_add_f32_e32 v56, v56, v57
	v_mul_f32_e32 v57, v79, v94
	v_cmp_gt_f32_e32 vcc, s3, v57
	v_mul_f32_e32 v95, v56, v58
	v_cmp_lt_i32_e64 s[0:1], -1, v93
	v_cndmask_b32_e32 v57, 0, v82, vcc
	v_fmac_f32_e32 v57, v79, v94
	v_exp_f32_e32 v57, v57
	v_cvt_f32_i32_e32 v94, v93
	v_cndmask_b32_e32 v56, 0, v86, vcc
	v_ldexp_f32 v56, v57, v56
	v_mul_f32_e32 v57, v94, v73
	v_cmp_gt_f32_e32 vcc, s3, v57
	v_cndmask_b32_e64 v56, 0, v56, s[0:1]
	s_nop 0
	v_cndmask_b32_e32 v57, 0, v82, vcc
	v_fmac_f32_e32 v57, v94, v73
	v_exp_f32_e32 v57, v57
	v_cndmask_b32_e32 v58, 0, v86, vcc
	v_cmp_gt_i32_e32 vcc, 1, v93
	v_ldexp_f32 v57, v57, v58
	s_nop 0
	v_cndmask_b32_e32 v57, 0, v57, vcc
	v_add_f32_e32 v56, v56, v57
	v_mul_f32_e32 v59, v56, v59
	v_cvt_pk_bf16_f32 v56, v104, v105
	v_cvt_pk_bf16_f32 v57, v107, v109
	v_cvt_pk_bf16_f32 v58, v92, v96
	v_cvt_pk_bf16_f32 v59, v95, v59
	ds_read2_b64 v[92:95], v60 offset0:16 offset1:20
	ds_read2_b64 v[52:55], v63 offset0:48 offset1:52
	s_waitcnt lgkmcnt(1)
; #define LAS __attribute__((address_space(3)))
; DI unsigned cvt_pk_bf16(float lo, float hi) { unsigned r; asm volatile("v_cvt_pk_bf16_f32 %0, %1, %2" : "=v"(r) : "v"(lo), "v"(hi)); return r; }
; #define MFMA16(a, b, c) __builtin_amdgcn_mfma_f32_16x16x32_bf16((a), (b), (c), 0, 0, 0)
; DI void ret_out_item(const Params& p, int l, int b, int h, int c, LAS unsigned char* lds) {
;     ...
;     for (int kc = 0; kc < 4; ++kc) {
;         f32x4 s[2];
; #pragma unroll
;         for (int hf = 0; hf < 2; ++hf) {
;             s[hf] = (f32x4){0.f, 0.f, 0.f, 0.f};
; #pragma unroll
;             for (int ks = 0; ks < 4; ++ks) s[hf] = MFMA16(*(const LAS bf16x8*)(kcp + (2 * kc + hf) * 16 * RS + ks * 64), qf[ks], s[hf]);
; #pragma unroll
;             for (int j = 0; j < 4; ++j) {
;                 const int m = (2 * kc + hf) * 16 + q4 * 4 + j, d = tl - m;
;                 const float w = (d >= 0 ? exp2f(lgf * (float)d) : 0.f) + (d <= 0 ? exp2f(-lgb * (float)d) : 0.f);
;                 s[hf][j] *= w;
;             }
;         }
;         u32x4 w4; w4.x = cvt_pk_bf16(s[0][0], s[0][1]); w4.y = cvt_pk_bf16(s[0][2], s[0][3]); w4.z = cvt_pk_bf16(s[1][0], s[1][1]); w4.w = cvt_pk_bf16(s[1][2], s[1][3]);
;         const bf16x8 pb = __builtin_bit_cast(bf16x8, w4);
; #pragma unroll
;         for (int d = 0; d < 8; ++d) {
;             const u32x2 lo = *(const LAS u32x2*)(vtp + d * 16 * RS + kc * 64), hi = *(const LAS u32x2*)(vtp + d * 16 * RS + kc * 64 + 32);
;             u32x4 a4; a4.x = lo.x; a4.y = lo.y; a4.z = hi.x; a4.w = hi.y;
;             oacc[d] = MFMA16(__builtin_bit_cast(bf16x8, a4), pb, oacc[d]);
	v_mfma_f32_16x16x32_bf16 v[16:19], v[92:95], v[56:59], v[20:23]
	ds_read2_b64 v[92:95], v64 offset0:80 offset1:84
	s_waitcnt lgkmcnt(1)
	v_mfma_f32_16x16x32_bf16 v[20:23], v[52:55], v[56:59], v[24:27]
	ds_read2_b64 v[52:55], v66 offset0:144 offset1:148
	s_nop 1
	ds_read2_b64 v[24:27], v65 offset0:112 offset1:116
	s_waitcnt lgkmcnt(0)
	v_mfma_f32_16x16x32_bf16 v[32:35], v[24:27], v[56:59], v[32:35]
	ds_read2_b64 v[24:27], v67 offset0:176 offset1:180
	v_mfma_f32_16x16x32_bf16 v[36:39], v[52:55], v[56:59], v[36:39]
	ds_read2_b64 v[52:55], v80 offset0:208 offset1:212
	s_waitcnt lgkmcnt(1)
	v_mfma_f32_16x16x32_bf16 v[40:43], v[24:27], v[56:59], v[40:43]
	ds_read2_b64 v[24:27], v81 offset0:240 offset1:244
	s_waitcnt lgkmcnt(1)
	v_mfma_f32_16x16x32_bf16 v[44:47], v[52:55], v[56:59], v[44:47]
	ds_read_b128 v[52:55], v62 offset:26112
	s_waitcnt lgkmcnt(1)
	v_mfma_f32_16x16x32_bf16 v[48:51], v[24:27], v[56:59], v[48:51]
	ds_read_b128 v[24:27], v62 offset:26176
	s_waitcnt lgkmcnt(1)
	v_mfma_f32_16x16x32_bf16 v[52:55], v[52:55], v[0:3], 0
	v_mfma_f32_16x16x32_bf16 v[28:31], v[92:95], v[56:59], v[28:31]
	ds_read_b128 v[56:59], v62 offset:26240
	s_waitcnt lgkmcnt(1)
	v_mfma_f32_16x16x32_bf16 v[24:27], v[24:27], v[4:7], v[52:55]
	s_nop 3
	v_or_b32_e32 v52, 0x60, v61
	v_sub_u32_e32 v92, v78, v52
	ds_read_b128 v[52:55], v62 offset:26304
	v_cvt_f32_u32_e32 v93, v92
	s_waitcnt lgkmcnt(1)
	v_mfma_f32_16x16x32_bf16 v[24:27], v[56:59], v[8:11], v[24:27]
	v_cvt_f32_i32_e32 v57, v92
	v_cmp_lt_i32_e64 s[0:1], -1, v92
	v_mul_f32_e32 v56, v79, v93
	v_cmp_gt_f32_e32 vcc, s3, v56
	s_waitcnt lgkmcnt(0)
	v_mfma_f32_16x16x32_bf16 v[24:27], v[52:55], v[12:15], v[24:27]
	v_mul_f32_e32 v53, v57, v73
	v_cndmask_b32_e32 v56, 0, v82, vcc
	v_cndmask_b32_e32 v52, 0, v86, vcc
	v_cmp_gt_f32_e32 vcc, s3, v53
	v_fmac_f32_e32 v56, v79, v93
	v_exp_f32_e32 v56, v56
	v_cndmask_b32_e32 v53, 0, v82, vcc
	v_fmac_f32_e32 v53, v57, v73
	v_exp_f32_e32 v53, v53
	v_cndmask_b32_e32 v54, 0, v86, vcc
	v_ldexp_f32 v52, v56, v52
	v_cmp_gt_i32_e32 vcc, 1, v92
	v_ldexp_f32 v53, v53, v54
	v_or_b32_e32 v54, 0x61, v61
	v_sub_u32_e32 v54, v78, v54
	v_cvt_f32_u32_e32 v55, v54
	v_cndmask_b32_e64 v52, 0, v52, s[0:1]
	v_cndmask_b32_e32 v53, 0, v53, vcc
	v_add_f32_e32 v52, v52, v53
	v_mul_f32_e32 v53, v79, v55
	v_cmp_gt_f32_e32 vcc, s3, v53
	v_mul_f32_e32 v24, v52, v24
	v_cmp_lt_i32_e64 s[0:1], -1, v54
	v_cndmask_b32_e32 v53, 0, v82, vcc
	v_fmac_f32_e32 v53, v79, v55
	v_exp_f32_e32 v53, v53
	v_cvt_f32_i32_e32 v55, v54
	v_cndmask_b32_e32 v52, 0, v86, vcc
	v_ldexp_f32 v52, v53, v52
	v_mul_f32_e32 v53, v55, v73
	v_cmp_gt_f32_e32 vcc, s3, v53
	v_cndmask_b32_e64 v52, 0, v52, s[0:1]
	s_nop 0
	v_cndmask_b32_e32 v53, 0, v82, vcc
	v_fmac_f32_e32 v53, v55, v73
	v_exp_f32_e32 v53, v53
	v_cndmask_b32_e32 v55, 0, v86, vcc
	v_cmp_gt_i32_e32 vcc, 1, v54
	v_ldexp_f32 v53, v53, v55
	v_or_b32_e32 v55, 0x62, v61
	v_sub_u32_e32 v55, v78, v55
	v_cvt_f32_u32_e32 v56, v55
	v_cndmask_b32_e32 v53, 0, v53, vcc
	v_add_f32_e32 v52, v52, v53
	v_cvt_f32_i32_e32 v54, v55
	v_mul_f32_e32 v53, v79, v56
	v_cmp_gt_f32_e32 vcc, s3, v53
	v_mul_f32_e32 v25, v52, v25
	v_cmp_lt_i32_e64 s[0:1], -1, v55
	v_cndmask_b32_e32 v53, 0, v82, vcc
	v_fmac_f32_e32 v53, v79, v56
	v_exp_f32_e32 v53, v53
	v_cndmask_b32_e32 v52, 0, v86, vcc
	v_ldexp_f32 v52, v53, v52
	v_mul_f32_e32 v53, v54, v73
	v_cmp_gt_f32_e32 vcc, s3, v53
	v_cndmask_b32_e64 v52, 0, v52, s[0:1]
	s_nop 0
	v_cndmask_b32_e32 v53, 0, v82, vcc
	v_fmac_f32_e32 v53, v54, v73
	v_exp_f32_e32 v53, v53
	v_cndmask_b32_e32 v54, 0, v86, vcc
	v_cmp_gt_i32_e32 vcc, 1, v55
	v_ldexp_f32 v53, v53, v54
	v_or_b32_e32 v54, 0x63, v61
	v_sub_u32_e32 v92, v78, v54
	v_cvt_f32_u32_e32 v54, v92
	v_cndmask_b32_e32 v53, 0, v53, vcc
	v_add_f32_e32 v52, v52, v53
	v_cvt_f32_i32_e32 v56, v92
	v_mul_f32_e32 v53, v79, v54
	v_cmp_gt_f32_e32 vcc, s3, v53
	v_mul_f32_e32 v26, v52, v26
	v_mul_f32_e32 v57, v56, v73
	v_cndmask_b32_e32 v53, 0, v82, vcc
	v_fmac_f32_e32 v53, v79, v54
	v_exp_f32_e32 v53, v53
	v_cndmask_b32_e32 v52, 0, v86, vcc
	v_cmp_gt_f32_e32 vcc, s3, v57
	v_cmp_lt_i32_e64 s[0:1], -1, v92
	v_ldexp_f32 v93, v53, v52
	ds_read_b128 v[52:55], v62 offset:30464
	v_cndmask_b32_e32 v57, 0, v82, vcc
	v_fmac_f32_e32 v57, v56, v73
	v_exp_f32_e32 v94, v57
	ds_read_b128 v[56:59], v62 offset:30528
	s_waitcnt lgkmcnt(1)
	v_mfma_f32_16x16x32_bf16 v[0:3], v[52:55], v[0:3], 0
	ds_read_b128 v[52:55], v62 offset:30592
	v_cndmask_b32_e32 v95, 0, v86, vcc
	v_ldexp_f32 v94, v94, v95
	s_waitcnt lgkmcnt(1)
	v_mfma_f32_16x16x32_bf16 v[0:3], v[56:59], v[4:7], v[0:3]
	v_or_b32_e32 v4, 0x70, v61
	v_sub_u32_e32 v56, v78, v4
	ds_read_b128 v[4:7], v62 offset:30656
	v_cvt_f32_u32_e32 v57, v56
	s_waitcnt lgkmcnt(1)
	v_mfma_f32_16x16x32_bf16 v[0:3], v[52:55], v[8:11], v[0:3]
	v_cvt_f32_i32_e32 v9, v56
	v_cmp_gt_i32_e32 vcc, 1, v92
	v_mul_f32_e32 v8, v79, v57
	s_waitcnt lgkmcnt(0)
; #define LAS __attribute__((address_space(3)))
; DI unsigned cvt_pk_bf16(float lo, float hi) { unsigned r; asm volatile("v_cvt_pk_bf16_f32 %0, %1, %2" : "=v"(r) : "v"(lo), "v"(hi)); return r; }
; #define MFMA16(a, b, c) __builtin_amdgcn_mfma_f32_16x16x32_bf16((a), (b), (c), 0, 0, 0)
; DI void ret_out_item(const Params& p, int l, int b, int h, int c, LAS unsigned char* lds) {
;     ...
;     for (int kc = 0; kc < 4; ++kc) {
;         f32x4 s[2];
; #pragma unroll
;         for (int hf = 0; hf < 2; ++hf) {
;             s[hf] = (f32x4){0.f, 0.f, 0.f, 0.f};
; #pragma unroll
;             for (int ks = 0; ks < 4; ++ks) s[hf] = MFMA16(*(const LAS bf16x8*)(kcp + (2 * kc + hf) * 16 * RS + ks * 64), qf[ks], s[hf]);
; #pragma unroll
;             for (int j = 0; j < 4; ++j) {
;                 const int m = (2 * kc + hf) * 16 + q4 * 4 + j, d = tl - m;
;                 const float w = (d >= 0 ? exp2f(lgf * (float)d) : 0.f) + (d <= 0 ? exp2f(-lgb * (float)d) : 0.f);
;                 s[hf][j] *= w;
;             }
;         }
;         u32x4 w4; w4.x = cvt_pk_bf16(s[0][0], s[0][1]); w4.y = cvt_pk_bf16(s[0][2], s[0][3]); w4.z = cvt_pk_bf16(s[1][0], s[1][1]); w4.w = cvt_pk_bf16(s[1][2], s[1][3]);
;         const bf16x8 pb = __builtin_bit_cast(bf16x8, w4);
; #pragma unroll
;         for (int d = 0; d < 8; ++d) {
;             const u32x2 lo = *(const LAS u32x2*)(vtp + d * 16 * RS + kc * 64), hi = *(const LAS u32x2*)(vtp + d * 16 * RS + kc * 64 + 32);
;             u32x4 a4; a4.x = lo.x; a4.y = lo.y; a4.z = hi.x; a4.w = hi.y;
;             oacc[d] = MFMA16(__builtin_bit_cast(bf16x8, a4), pb, oacc[d]);
;         }
;     }
;     float sum = 0.f;
; #pragma unroll
;     for (int d = 0; d < 8; ++d) sum += oacc[d][0] + oacc[d][1] + oacc[d][2] + oacc[d][3];
;     sum += __shfl_xor(sum, 16); sum += __shfl_xor(sum, 32);
	v_mfma_f32_16x16x32_bf16 v[0:3], v[4:7], v[12:15], v[0:3]
	v_cndmask_b32_e32 v92, 0, v94, vcc
	v_cmp_gt_f32_e32 vcc, s3, v8
	v_mul_f32_e32 v5, v9, v73
	v_cndmask_b32_e64 v93, 0, v93, s[0:1]
	v_cndmask_b32_e32 v8, 0, v82, vcc
	v_cndmask_b32_e32 v4, 0, v86, vcc
	v_cmp_gt_f32_e32 vcc, s3, v5
	v_fmac_f32_e32 v8, v79, v57
	v_exp_f32_e32 v8, v8
	v_cndmask_b32_e32 v5, 0, v82, vcc
	v_fmac_f32_e32 v5, v9, v73
	v_exp_f32_e32 v5, v5
	v_cndmask_b32_e32 v6, 0, v86, vcc
	v_ldexp_f32 v4, v8, v4
	v_cmp_lt_i32_e64 s[0:1], -1, v56
	v_ldexp_f32 v5, v5, v6
	v_or_b32_e32 v6, 0x71, v61
	v_sub_u32_e32 v6, v78, v6
	v_cvt_f32_u32_e32 v7, v6
	v_cmp_gt_i32_e32 vcc, 1, v56
	v_cndmask_b32_e64 v4, 0, v4, s[0:1]
	v_cmp_lt_i32_e64 s[0:1], -1, v6
	v_cndmask_b32_e32 v5, 0, v5, vcc
	v_add_f32_e32 v4, v4, v5
	v_mul_f32_e32 v5, v79, v7
	v_cmp_gt_f32_e32 vcc, s3, v5
	v_mul_f32_e32 v4, v4, v0
	v_add_f32_e32 v92, v93, v92
	v_cndmask_b32_e32 v5, 0, v82, vcc
	v_fmac_f32_e32 v5, v79, v7
	v_exp_f32_e32 v5, v5
	v_cvt_f32_i32_e32 v7, v6
	v_cndmask_b32_e32 v0, 0, v86, vcc
	v_mul_f32_e32 v27, v92, v27
	v_ldexp_f32 v0, v5, v0
	v_mul_f32_e32 v5, v7, v73
	v_cmp_gt_f32_e32 vcc, s3, v5
	v_cndmask_b32_e64 v0, 0, v0, s[0:1]
	s_nop 0
	v_cndmask_b32_e32 v5, 0, v82, vcc
	v_fmac_f32_e32 v5, v7, v73
	v_exp_f32_e32 v5, v5
	v_cndmask_b32_e32 v7, 0, v86, vcc
	v_cmp_gt_i32_e32 vcc, 1, v6
	v_ldexp_f32 v5, v5, v7
	v_or_b32_e32 v7, 0x72, v61
	v_sub_u32_e32 v7, v78, v7
	v_cvt_f32_u32_e32 v8, v7
	v_cndmask_b32_e32 v5, 0, v5, vcc
	v_cvt_f32_i32_e32 v6, v7
	v_add_f32_e32 v0, v0, v5
	v_mul_f32_e32 v5, v79, v8
	v_cmp_gt_f32_e32 vcc, s3, v5
	v_cmp_lt_i32_e64 s[0:1], -1, v7
	s_nop 0
	v_cndmask_b32_e32 v5, 0, v82, vcc
	v_fmac_f32_e32 v5, v79, v8
	v_mul_f32_e32 v8, v0, v1
	v_mul_f32_e32 v1, v6, v73
	v_cndmask_b32_e32 v0, 0, v86, vcc
	v_cmp_gt_f32_e32 vcc, s3, v1
	v_exp_f32_e32 v5, v5
	s_nop 0
	v_cndmask_b32_e32 v1, 0, v82, vcc
	v_fmac_f32_e32 v1, v6, v73
	v_exp_f32_e32 v1, v1
	v_ldexp_f32 v0, v5, v0
	v_cndmask_b32_e32 v5, 0, v86, vcc
	v_cmp_gt_i32_e32 vcc, 1, v7
	v_ldexp_f32 v1, v1, v5
	v_or_b32_e32 v5, 0x73, v61
	v_sub_u32_e32 v5, v78, v5
	v_cvt_f32_u32_e32 v6, v5
	v_cndmask_b32_e64 v0, 0, v0, s[0:1]
	v_cndmask_b32_e32 v1, 0, v1, vcc
	v_add_f32_e32 v0, v0, v1
	v_mul_f32_e32 v1, v79, v6
	v_cmp_gt_f32_e32 vcc, s3, v1
	v_mul_f32_e32 v7, v0, v2
	v_cmp_lt_i32_e64 s[0:1], -1, v5
	v_cndmask_b32_e32 v1, 0, v82, vcc
	v_fmac_f32_e32 v1, v79, v6
	v_exp_f32_e32 v1, v1
	v_cvt_f32_i32_e32 v6, v5
	v_cndmask_b32_e32 v0, 0, v86, vcc
	v_ldexp_f32 v0, v1, v0
	v_mul_f32_e32 v1, v6, v73
	v_cmp_gt_f32_e32 vcc, s3, v1
	v_cndmask_b32_e64 v0, 0, v0, s[0:1]
	s_nop 0
	v_cndmask_b32_e32 v1, 0, v82, vcc
	v_fmac_f32_e32 v1, v6, v73
	v_exp_f32_e32 v1, v1
	v_cndmask_b32_e32 v2, 0, v86, vcc
	v_cmp_gt_i32_e32 vcc, 1, v5
	v_ldexp_f32 v1, v1, v2
	s_nop 0
	v_cndmask_b32_e32 v1, 0, v1, vcc
	v_add_f32_e32 v0, v0, v1
	v_mul_f32_e32 v3, v0, v3
	v_cvt_pk_bf16_f32 v0, v24, v25
	v_cvt_pk_bf16_f32 v1, v26, v27
	v_cvt_pk_bf16_f32 v2, v4, v8
	v_cvt_pk_bf16_f32 v3, v7, v3
	ds_read2_b64 v[4:7], v60 offset0:24 offset1:28
	s_waitcnt lgkmcnt(0)
	v_mfma_f32_16x16x32_bf16 v[52:55], v[4:7], v[0:3], v[16:19]
	ds_read2_b64 v[4:7], v63 offset0:56 offset1:60
	v_cmp_lt_i32_e32 vcc, v88, v89
	s_waitcnt lgkmcnt(0)
	v_mfma_f32_16x16x32_bf16 v[24:27], v[4:7], v[0:3], v[20:23]
	ds_read2_b64 v[4:7], v64 offset0:88 offset1:92
	s_waitcnt lgkmcnt(0)
	v_mfma_f32_16x16x32_bf16 v[20:23], v[4:7], v[0:3], v[28:31]
	ds_read2_b64 v[4:7], v65 offset0:120 offset1:124
	s_nop 1
	ds_read2_b64 v[28:31], v81 offset0:248 offset1:252
	s_waitcnt lgkmcnt(1)
	v_mfma_f32_16x16x32_bf16 v[16:19], v[4:7], v[0:3], v[32:35]
	ds_read2_b64 v[4:7], v66 offset0:152 offset1:156
	s_waitcnt lgkmcnt(0)
	v_mfma_f32_16x16x32_bf16 v[12:15], v[4:7], v[0:3], v[36:39]
	ds_read2_b64 v[4:7], v67 offset0:184 offset1:188
	s_waitcnt lgkmcnt(0)
	v_mfma_f32_16x16x32_bf16 v[8:11], v[4:7], v[0:3], v[40:43]
	ds_read2_b64 v[4:7], v80 offset0:216 offset1:220
	s_nop 1
	v_lshl_add_u64 v[42:43], v[76:77], 0, v[68:69]
	s_waitcnt lgkmcnt(0)
	v_mfma_f32_16x16x32_bf16 v[4:7], v[4:7], v[0:3], v[44:47]
	v_mfma_f32_16x16x32_bf16 v[0:3], v[28:31], v[0:3], v[48:51]
	v_mov_b32_e32 v28, v52
	v_mov_b32_e32 v29, v24
	v_mov_b32_e32 v30, v53
	v_mov_b32_e32 v31, v25
	v_pk_add_f32 v[28:29], v[28:29], v[30:31]
	v_mov_b32_e32 v30, v54
	v_mov_b32_e32 v31, v26
	v_pk_add_f32 v[28:29], v[30:31], v[28:29]
	v_mov_b32_e32 v30, v55
	v_mov_b32_e32 v31, v27
	v_pk_add_f32 v[28:29], v[30:31], v[28:29]
	v_mov_b32_e32 v30, v21
	v_add_f32_e32 v28, 0, v28
	v_add_f32_e32 v32, v28, v29
	v_mov_b32_e32 v28, v20
	v_mov_b32_e32 v29, v16
	v_mov_b32_e32 v31, v17
	v_pk_add_f32 v[28:29], v[28:29], v[30:31]
	v_mov_b32_e32 v30, v22
	v_mov_b32_e32 v31, v18
	v_pk_add_f32 v[28:29], v[30:31], v[28:29]
	v_mov_b32_e32 v30, v23
	v_mov_b32_e32 v31, v19
	v_pk_add_f32 v[28:29], v[30:31], v[28:29]
	v_mov_b32_e32 v30, v13
	v_add_f32_e32 v28, v32, v28
	v_add_f32_e32 v32, v28, v29
	v_mov_b32_e32 v28, v12
	v_mov_b32_e32 v29, v8
	v_mov_b32_e32 v31, v9
	v_pk_add_f32 v[28:29], v[28:29], v[30:31]
	v_mov_b32_e32 v30, v14
	v_mov_b32_e32 v31, v10
	v_pk_add_f32 v[28:29], v[30:31], v[28:29]
	v_mov_b32_e32 v30, v15
	v_mov_b32_e32 v31, v11
	v_pk_add_f32 v[28:29], v[30:31], v[28:29]
	v_mov_b32_e32 v30, v5
	v_add_f32_e32 v28, v32, v28
	v_add_f32_e32 v32, v28, v29
	v_mov_b32_e32 v28, v4
	v_mov_b32_e32 v29, v0
	v_mov_b32_e32 v31, v1
	v_pk_add_f32 v[28:29], v[28:29], v[30:31]
	v_mov_b32_e32 v30, v6
	v_mov_b32_e32 v31, v2
	v_pk_add_f32 v[28:29], v[30:31], v[28:29]
	v_mov_b32_e32 v30, v7
	v_mov_b32_e32 v31, v3
	v_pk_add_f32 v[28:29], v[30:31], v[28:29]
	s_nop 0
	v_add_f32_e32 v28, v32, v28
	v_add_f32_e32 v28, v28, v29
	v_cndmask_b32_e32 v29, v87, v88, vcc
	v_lshlrev_b32_e32 v50, 2, v29
	ds_bpermute_b32 v29, v50, v28
	v_cmp_lt_i32_e32 vcc, v90, v89
	s_waitcnt lgkmcnt(0)
; DI float silu(float v) { return v * __builtin_amdgcn_rcpf(1.f + __builtin_amdgcn_exp2f(-1.4426950408889634f * v)); }
; DI void st_bf16x4(bf16_t* p, f32x4 v) { u32x2 w; w.x = cvt_pk_bf16(v[0], v[1]); w.y = cvt_pk_bf16(v[2], v[3]); *(u32x2*)p = w; }
; DI void ret_out_item(const Params& p, int l, int b, int h, int c, LAS unsigned char* lds) {
;     ...
;     float sum = 0.f;
; #pragma unroll
;     for (int d = 0; d < 8; ++d) sum += oacc[d][0] + oacc[d][1] + oacc[d][2] + oacc[d][3];
;     sum += __shfl_xor(sum, 16); sum += __shfl_xor(sum, 32);
;     const float mu = sum * (1.f / 128.f);
;     float sq = 0.f;
; #pragma unroll
;     for (int d = 0; d < 8; ++d) { oacc[d] -= mu; sq += oacc[d][0] * oacc[d][0] + oacc[d][1] * oacc[d][1] + oacc[d][2] * oacc[d][2] + oacc[d][3] * oacc[d][3]; }
;     sq += __shfl_xor(sq, 16); sq += __shfl_xor(sq, 32);
;     const float rs = rsqrtf(sq * (1.f / 128.f) + 1e-5f);
;     const bf16_t* gp = P + row * INP + C_RG + h * 128 + q4 * 4;
;     bf16_t* op = (bf16_t*)(ws + WS_YMIX) + row * DM + 1408 + h * 128 + q4 * 4;
; #pragma unroll
;     for (int d = 0; d < 8; ++d) {
;         const u32x2 g2 = *(const u32x2*)(gp + d * 16);
;         f32x4 g; g[0] = __uint_as_float(g2.x << 16); g[1] = __uint_as_float(g2.x & 0xffff0000u); g[2] = __uint_as_float(g2.y << 16); g[3] = __uint_as_float(g2.y & 0xffff0000u);
;         f32x4 y;
; #pragma unroll
;         for (int j = 0; j < 4; ++j) y[j] = oacc[d][j] * rs * silu(g[j]);
;         st_bf16x4(op + d * 16, y);
	v_add_f32_e32 v28, v28, v29
	v_cndmask_b32_e32 v29, v87, v90, vcc
	v_lshlrev_b32_e32 v51, 2, v29
	ds_bpermute_b32 v29, v51, v28
	s_waitcnt lgkmcnt(0)
	v_add_f32_e32 v56, v28, v29
	v_add_co_u32_e32 v28, vcc, s35, v42
	v_fmamk_f32 v38, v56, 0xbc000000, v53
	s_nop 0
	v_addc_co_u32_e32 v29, vcc, 0, v43, vcc
	global_load_dwordx2 v[44:45], v[28:29], off offset:2432
	global_load_dwordx2 v[140:141], v[28:29], off offset:2464
	global_load_dwordx2 v[142:143], v[28:29], off offset:2496
	global_load_dwordx2 v[144:145], v[28:29], off offset:2528
	global_load_dwordx2 v[146:147], v[28:29], off offset:2560
	global_load_dwordx2 v[148:149], v[28:29], off offset:2592
	global_load_dwordx2 v[150:151], v[28:29], off offset:2624
	global_load_dwordx2 v[152:153], v[28:29], off offset:2656
	v_fmamk_f32 v39, v56, 0xbc000000, v25
	v_fmac_f32_e32 v24, 0xbc000000, v56
	v_fmac_f32_e32 v52, 0xbc000000, v56
	v_fmamk_f32 v31, v56, 0xbc000000, v27
	v_fmamk_f32 v35, v56, 0xbc000000, v26
	v_mov_b32_e32 v53, v24
	v_pk_mul_f32 v[26:27], v[38:39], v[38:39]
	v_fmamk_f32 v34, v56, 0xbc000000, v54
	v_pk_fma_f32 v[26:27], v[52:53], v[52:53], v[26:27]
	v_fmamk_f32 v30, v56, 0xbc000000, v55
	v_pk_fma_f32 v[26:27], v[34:35], v[34:35], v[26:27]
	v_fmamk_f32 v29, v56, 0xbc000000, v13
	v_fmac_f32_e32 v12, 0xbc000000, v56
	v_fmamk_f32 v28, v56, 0xbc000000, v9
	v_pk_fma_f32 v[46:47], v[30:31], v[30:31], v[26:27]
	v_fmamk_f32 v37, v56, 0xbc000000, v22
	v_fmamk_f32 v41, v56, 0xbc000000, v21
	v_fmac_f32_e32 v20, 0xbc000000, v56
	v_fmamk_f32 v40, v56, 0xbc000000, v17
	v_fmamk_f32 v22, v56, 0xbc000000, v11
	v_fmamk_f32 v26, v56, 0xbc000000, v10
	v_fmac_f32_e32 v8, 0xbc000000, v56
	v_mov_b32_e32 v9, v12
	v_pk_mul_f32 v[10:11], v[28:29], v[28:29]
	v_fmamk_f32 v32, v56, 0xbc000000, v19
	v_fmamk_f32 v36, v56, 0xbc000000, v18
	v_fmac_f32_e32 v16, 0xbc000000, v56
	v_mov_b32_e32 v17, v20
	v_pk_mul_f32 v[18:19], v[40:41], v[40:41]
	v_fmamk_f32 v27, v56, 0xbc000000, v14
	v_pk_fma_f32 v[10:11], v[8:9], v[8:9], v[10:11]
	v_fmamk_f32 v33, v56, 0xbc000000, v23
	v_pk_fma_f32 v[18:19], v[16:17], v[16:17], v[18:19]
	v_fmamk_f32 v23, v56, 0xbc000000, v15
	v_pk_fma_f32 v[10:11], v[26:27], v[26:27], v[10:11]
	v_fmamk_f32 v15, v56, 0xbc000000, v5
	v_fmac_f32_e32 v4, 0xbc000000, v56
	v_fmamk_f32 v14, v56, 0xbc000000, v1
	v_pk_fma_f32 v[18:19], v[36:37], v[36:37], v[18:19]
	v_pk_fma_f32 v[48:49], v[22:23], v[22:23], v[10:11]
	v_fmamk_f32 v11, v56, 0xbc000000, v6
	v_fmamk_f32 v6, v56, 0xbc000000, v3
	v_fmamk_f32 v10, v56, 0xbc000000, v2
	v_fmac_f32_e32 v0, 0xbc000000, v56
	v_mov_b32_e32 v1, v4
	v_pk_mul_f32 v[2:3], v[14:15], v[14:15]
	v_pk_fma_f32 v[18:19], v[32:33], v[32:33], v[18:19]
	v_pk_fma_f32 v[2:3], v[0:1], v[0:1], v[2:3]
	v_add_f32_e32 v1, v46, v47
	v_add_f32_e32 v1, v19, v1
	v_add_f32_e32 v1, v18, v1
	v_fmamk_f32 v7, v56, 0xbc000000, v7
	v_pk_fma_f32 v[2:3], v[10:11], v[10:11], v[2:3]
	v_add_f32_e32 v1, v49, v1
	v_pk_fma_f32 v[2:3], v[6:7], v[6:7], v[2:3]
	v_add_f32_e32 v1, v48, v1
	v_add_f32_e32 v1, v3, v1
	v_add_f32_e32 v1, v2, v1
	ds_bpermute_b32 v2, v50, v1
	v_lshl_add_u64 v[18:19], v[42:43], 0, s[12:13]
	v_mov_b32_e32 v49, v52
	s_waitcnt lgkmcnt(0)
	v_add_f32_e32 v1, v1, v2
	ds_bpermute_b32 v2, v51, v1
	v_mov_b32_e32 v51, v24
	s_waitcnt lgkmcnt(0)
	v_add_f32_e32 v1, v1, v2
	v_fmamk_f32 v1, v1, 0x3c000000, v91
	v_mul_f32_e32 v2, 0x4b800000, v1
	v_cmp_gt_f32_e32 vcc, s34, v1
	s_waitcnt vmcnt(7)
	v_and_b32_e32 v42, 0xffff0000, v44
	v_cndmask_b32_e32 v1, v1, v2, vcc
	v_rsq_f32_e32 v1, v1
	v_and_b32_e32 v46, 0xffff0000, v45
	v_mul_f32_e32 v2, 0x45800000, v1
	v_cndmask_b32_e32 v3, v1, v2, vcc
	v_lshlrev_b32_e32 v2, 16, v44
	v_mul_f32_e32 v1, 0xbfb8aa3b, v2
	v_exp_f32_e32 v1, v1
	v_lshlrev_b32_e32 v44, 16, v45
	v_mov_b32_e32 v43, v3
	v_mov_b32_e32 v45, v3
	v_add_f32_e32 v1, 1.0, v1
	v_rcp_f32_e32 v48, v1
	v_mul_f32_e32 v1, 0xbfb8aa3b, v42
	v_exp_f32_e32 v1, v1
	v_mov_b32_e32 v47, v3
	v_pk_mul_f32 v[48:49], v[48:49], v[2:3]
	v_add_f32_e32 v1, 1.0, v1
	v_mul_f32_e32 v2, v48, v49
	v_rcp_f32_e32 v48, v1
	v_mul_f32_e32 v1, 0xbfb8aa3b, v44
	v_exp_f32_e32 v1, v1
	v_mov_b32_e32 v49, v38
	v_pk_mul_f32 v[42:43], v[48:49], v[42:43]
	v_add_f32_e32 v1, 1.0, v1
	v_mul_f32_e32 v5, v42, v43
	v_rcp_f32_e32 v42, v1
	v_mul_f32_e32 v1, 0xbfb8aa3b, v46
	v_exp_f32_e32 v1, v1
	v_mov_b32_e32 v43, v34
	v_pk_mul_f32 v[42:43], v[42:43], v[44:45]
	v_mov_b32_e32 v45, v30
	v_add_f32_e32 v1, 1.0, v1
	v_rcp_f32_e32 v44, v1
	v_mul_f32_e32 v1, v42, v43
	v_pk_mul_f32 v[42:43], v[44:45], v[46:47]
	s_nop 0
	v_mul_f32_e32 v9, v42, v43
	v_cvt_pk_bf16_f32 v42, v2, v5
	v_cvt_pk_bf16_f32 v43, v1, v9
	s_waitcnt vmcnt(6)
	v_mov_b32_e32 v44, v140
	v_mov_b32_e32 v45, v141
	v_lshlrev_b64 v[46:47], 12, v[74:75]
	v_lshl_add_u64 v[46:47], s[50:51], 0, v[46:47]
	v_lshl_add_u64 v[46:47], v[46:47], 0, s[16:17]
	v_lshl_add_u64 v[46:47], v[46:47], 0, v[68:69]
	v_add_co_u32_e32 v48, vcc, s36, v46
	v_lshlrev_b32_e32 v2, 16, v44
	v_mul_f32_e32 v1, 0xbfb8aa3b, v2
	v_exp_f32_e32 v1, v1
	v_addc_co_u32_e32 v49, vcc, 0, v47, vcc
	global_store_dwordx2 v[48:49], v[42:43], off offset:2816
	v_add_f32_e32 v1, 1.0, v1
	v_rcp_f32_e32 v50, v1
	v_and_b32_e32 v42, 0xffff0000, v44
	v_lshlrev_b32_e32 v44, 16, v45
	v_mul_f32_e32 v5, 0xbfb8aa3b, v42
	v_and_b32_e32 v48, 0xffff0000, v45
	v_exp_f32_e32 v5, v5
	v_pk_mul_f32 v[24:25], v[50:51], v[2:3]
	v_mul_f32_e32 v2, 0xbfb8aa3b, v44
	v_exp_f32_e32 v2, v2
	v_mul_f32_e32 v9, 0xbfb8aa3b, v48
	v_exp_f32_e32 v9, v9
	v_add_f32_e32 v1, 1.0, v5
	v_rcp_f32_e32 v38, v1
	v_add_f32_e32 v2, 1.0, v2
	v_rcp_f32_e32 v34, v2
	v_add_f32_e32 v2, 1.0, v9
	v_rcp_f32_e32 v30, v2
	v_mov_b32_e32 v43, v3
	v_mul_f32_e32 v1, v24, v25
	v_pk_mul_f32 v[24:25], v[38:39], v[42:43]
	v_mov_b32_e32 v45, v3
	v_mul_f32_e32 v5, v24, v25
	v_pk_mul_f32 v[24:25], v[34:35], v[44:45]
	v_mov_b32_e32 v49, v3
	v_mul_f32_e32 v2, v24, v25
	v_pk_mul_f32 v[24:25], v[30:31], v[48:49]
	v_cvt_pk_bf16_f32 v30, v1, v5
	v_mov_b32_e32 v43, v20
	v_mul_f32_e32 v9, v24, v25
	v_cvt_pk_bf16_f32 v31, v2, v9
	s_waitcnt vmcnt(6)
; #define LAS __attribute__((address_space(3)))
; DI float silu(float v) { return v * __builtin_amdgcn_rcpf(1.f + __builtin_amdgcn_exp2f(-1.4426950408889634f * v)); }
; DI unsigned xb_add(unsigned* p, unsigned v) { return __hip_atomic_fetch_add(p, v, __ATOMIC_RELAXED, __HIP_MEMORY_SCOPE_AGENT); }
; DI void st_bf16x4(bf16_t* p, f32x4 v) { u32x2 w; w.x = cvt_pk_bf16(v[0], v[1]); w.y = cvt_pk_bf16(v[2], v[3]); *(u32x2*)p = w; }
; DI int next_item(unsigned* ctr, volatile LAS int* slot) {
;     __syncthreads();
;     if (threadIdx.x == 0) *slot = (int)xb_add(ctr, 1u);
;     __syncthreads();
; DI void ret_out_item(const Params& p, int l, int b, int h, int c, LAS unsigned char* lds) {
;     ...
;     const bf16_t* gp = P + row * INP + C_RG + h * 128 + q4 * 4;
;     bf16_t* op = (bf16_t*)(ws + WS_YMIX) + row * DM + 1408 + h * 128 + q4 * 4;
; #pragma unroll
;     for (int d = 0; d < 8; ++d) {
;         const u32x2 g2 = *(const u32x2*)(gp + d * 16);
;         f32x4 g; g[0] = __uint_as_float(g2.x << 16); g[1] = __uint_as_float(g2.x & 0xffff0000u); g[2] = __uint_as_float(g2.y << 16); g[3] = __uint_as_float(g2.y & 0xffff0000u);
;         f32x4 y;
; #pragma unroll
;         for (int j = 0; j < 4; ++j) y[j] = oacc[d][j] * rs * silu(g[j]);
;         st_bf16x4(op + d * 16, y);
;     }
	v_mov_b32_e32 v34, v142
	v_mov_b32_e32 v35, v143
	v_lshl_add_u64 v[24:25], v[46:47], 0, s[14:15]
	global_store_dwordx2 v[24:25], v[30:31], off offset:32
	v_mov_b32_e32 v31, v3
	v_mov_b32_e32 v39, v3
	v_lshlrev_b32_e32 v2, 16, v34
	v_mul_f32_e32 v1, 0xbfb8aa3b, v2
	v_exp_f32_e32 v1, v1
	v_and_b32_e32 v30, 0xffff0000, v34
	v_lshlrev_b32_e32 v34, 16, v35
	v_and_b32_e32 v38, 0xffff0000, v35
	v_add_f32_e32 v1, 1.0, v1
	v_rcp_f32_e32 v42, v1
	v_mul_f32_e32 v1, 0xbfb8aa3b, v30
	v_exp_f32_e32 v1, v1
	v_mov_b32_e32 v35, v3
	v_pk_mul_f32 v[20:21], v[42:43], v[2:3]
	v_add_f32_e32 v1, 1.0, v1
	v_mul_f32_e32 v2, v20, v21
	v_rcp_f32_e32 v20, v1
	v_mul_f32_e32 v1, 0xbfb8aa3b, v34
	v_exp_f32_e32 v1, v1
	v_mov_b32_e32 v21, v41
	v_pk_mul_f32 v[20:21], v[20:21], v[30:31]
	v_mov_b32_e32 v31, v33
	v_add_f32_e32 v1, 1.0, v1
	v_mul_f32_e32 v5, v20, v21
	v_rcp_f32_e32 v20, v1
	v_mul_f32_e32 v1, 0xbfb8aa3b, v38
	v_exp_f32_e32 v1, v1
	v_mov_b32_e32 v21, v37
	v_pk_mul_f32 v[20:21], v[20:21], v[34:35]
	v_mov_b32_e32 v33, v12
	v_add_f32_e32 v1, 1.0, v1
	v_rcp_f32_e32 v30, v1
	v_mul_f32_e32 v1, v20, v21
	v_pk_mul_f32 v[20:21], v[30:31], v[38:39]
	s_nop 0
	v_mul_f32_e32 v9, v20, v21
	v_cvt_pk_bf16_f32 v20, v2, v5
	v_cvt_pk_bf16_f32 v21, v1, v9
	s_waitcnt vmcnt(6)
	v_mov_b32_e32 v30, v144
	v_mov_b32_e32 v31, v145
	v_mov_b32_e32 v39, v16
	global_store_dwordx2 v[24:25], v[20:21], off offset:64
	v_mov_b32_e32 v21, v3
	v_lshlrev_b32_e32 v2, 16, v30
	v_mul_f32_e32 v1, 0xbfb8aa3b, v2
	v_exp_f32_e32 v1, v1
	v_and_b32_e32 v20, 0xffff0000, v30
	v_lshlrev_b32_e32 v30, 16, v31
	v_and_b32_e32 v34, 0xffff0000, v31
	v_add_f32_e32 v1, 1.0, v1
	v_rcp_f32_e32 v38, v1
	v_mul_f32_e32 v1, 0xbfb8aa3b, v20
	v_exp_f32_e32 v1, v1
	v_mov_b32_e32 v31, v3
	v_pk_mul_f32 v[16:17], v[38:39], v[2:3]
	v_add_f32_e32 v1, 1.0, v1
	v_mul_f32_e32 v2, v16, v17
	v_rcp_f32_e32 v16, v1
	v_mul_f32_e32 v1, 0xbfb8aa3b, v30
	v_exp_f32_e32 v1, v1
	v_mov_b32_e32 v17, v40
	v_pk_mul_f32 v[16:17], v[16:17], v[20:21]
	v_mov_b32_e32 v21, v32
	v_add_f32_e32 v1, 1.0, v1
	v_mul_f32_e32 v5, v16, v17
	v_rcp_f32_e32 v16, v1
	v_mul_f32_e32 v1, 0xbfb8aa3b, v34
	v_exp_f32_e32 v1, v1
	v_mov_b32_e32 v17, v36
	v_pk_mul_f32 v[16:17], v[16:17], v[30:31]
	v_add_f32_e32 v1, 1.0, v1
	v_rcp_f32_e32 v20, v1
	v_mul_f32_e32 v1, v16, v17
	v_pk_mul_f32 v[16:17], v[20:21], v[34:35]
	s_nop 0
	v_mul_f32_e32 v9, v16, v17
	v_cvt_pk_bf16_f32 v16, v2, v5
	v_cvt_pk_bf16_f32 v17, v1, v9
	s_waitcnt vmcnt(6)
	v_mov_b32_e32 v20, v146
	v_mov_b32_e32 v21, v147
	v_lshlrev_b32_e32 v2, 16, v20
	v_mul_f32_e32 v1, 0xbfb8aa3b, v2
	v_exp_f32_e32 v1, v1
	global_store_dwordx2 v[24:25], v[16:17], off offset:96
	v_and_b32_e32 v16, 0xffff0000, v20
	v_lshlrev_b32_e32 v20, 16, v21
	v_add_f32_e32 v1, 1.0, v1
	v_rcp_f32_e32 v32, v1
	v_mul_f32_e32 v1, 0xbfb8aa3b, v16
	v_exp_f32_e32 v1, v1
	v_mov_b32_e32 v17, v3
	v_pk_mul_f32 v[12:13], v[32:33], v[2:3]
	v_and_b32_e32 v30, 0xffff0000, v21
	v_add_f32_e32 v1, 1.0, v1
	v_mul_f32_e32 v2, v12, v13
	v_rcp_f32_e32 v12, v1
	v_mul_f32_e32 v1, 0xbfb8aa3b, v20
	v_exp_f32_e32 v1, v1
	v_mov_b32_e32 v13, v29
	v_pk_mul_f32 v[12:13], v[12:13], v[16:17]
	v_mov_b32_e32 v21, v3
	v_add_f32_e32 v1, 1.0, v1
	v_mul_f32_e32 v5, v12, v13
	v_rcp_f32_e32 v12, v1
	v_mul_f32_e32 v1, 0xbfb8aa3b, v30
	v_exp_f32_e32 v1, v1
	v_mov_b32_e32 v13, v27
	v_pk_mul_f32 v[12:13], v[12:13], v[20:21]
	v_mov_b32_e32 v17, v23
	v_add_f32_e32 v1, 1.0, v1
	v_rcp_f32_e32 v16, v1
	v_mul_f32_e32 v1, v12, v13
	v_mov_b32_e32 v20, v3
	v_pk_mul_f32 v[12:13], v[16:17], v[30:31]
	s_nop 0
	v_mul_f32_e32 v9, v12, v13
	v_cvt_pk_bf16_f32 v12, v2, v5
	v_cvt_pk_bf16_f32 v13, v1, v9
	s_waitcnt vmcnt(6)
	v_mov_b32_e32 v16, v148
	v_mov_b32_e32 v17, v149
	v_mov_b32_e32 v30, v3
	global_store_dwordx2 v[24:25], v[12:13], off offset:128
	v_mov_b32_e32 v12, v3
	v_lshlrev_b32_e32 v13, 16, v16
	v_and_b32_e32 v21, 0xffff0000, v16
	v_mul_f32_e32 v1, 0xbfb8aa3b, v13
	v_exp_f32_e32 v1, v1
	v_mul_f32_e32 v2, 0xbfb8aa3b, v21
	v_exp_f32_e32 v2, v2
	v_lshlrev_b32_e32 v31, 16, v17
	v_add_f32_e32 v1, 1.0, v1
	v_rcp_f32_e32 v9, v1
	v_add_f32_e32 v1, 1.0, v2
	v_rcp_f32_e32 v29, v1
	v_and_b32_e32 v17, 0xffff0000, v17
	v_pk_mul_f32 v[8:9], v[8:9], v[12:13]
	v_mul_f32_e32 v2, 0xbfb8aa3b, v31
	v_mul_f32_e32 v1, v8, v9
	v_pk_mul_f32 v[8:9], v[28:29], v[20:21]
	v_exp_f32_e32 v2, v2
	v_mul_f32_e32 v5, v8, v9
	v_mul_f32_e32 v8, 0xbfb8aa3b, v17
	v_exp_f32_e32 v8, v8
	v_add_f32_e32 v2, 1.0, v2
	v_rcp_f32_e32 v27, v2
	v_mov_b32_e32 v16, v3
	v_add_f32_e32 v2, 1.0, v8
	v_rcp_f32_e32 v23, v2
	v_pk_mul_f32 v[8:9], v[26:27], v[30:31]
	s_nop 0
	v_mul_f32_e32 v2, v8, v9
	v_pk_mul_f32 v[8:9], v[22:23], v[16:17]
	s_nop 0
	v_mul_f32_e32 v9, v8, v9
	v_cvt_pk_bf16_f32 v8, v1, v5
	v_cvt_pk_bf16_f32 v9, v2, v9
	s_waitcnt vmcnt(6)
	v_mov_b32_e32 v12, v150
	v_mov_b32_e32 v13, v151
	v_and_b32_e32 v17, 0xffff0000, v12
	global_store_dwordx2 v[24:25], v[8:9], off offset:160
	v_lshlrev_b32_e32 v9, 16, v12
	v_mul_f32_e32 v1, 0xbfb8aa3b, v9
	v_exp_f32_e32 v1, v1
	v_mov_b32_e32 v8, v3
	v_lshlrev_b32_e32 v21, 16, v13
	v_and_b32_e32 v13, 0xffff0000, v13
	v_add_f32_e32 v1, 1.0, v1
	v_rcp_f32_e32 v5, v1
	v_mul_f32_e32 v1, 0xbfb8aa3b, v17
	v_exp_f32_e32 v1, v1
	v_mov_b32_e32 v12, v3
	v_pk_mul_f32 v[4:5], v[4:5], v[8:9]
	v_mov_b32_e32 v8, v7
	v_add_f32_e32 v1, 1.0, v1
	v_mul_f32_e32 v2, v4, v5
	v_rcp_f32_e32 v5, v1
	v_mul_f32_e32 v1, 0xbfb8aa3b, v21
	v_exp_f32_e32 v1, v1
	v_mov_b32_e32 v4, v15
	v_pk_mul_f32 v[4:5], v[4:5], v[16:17]
	v_add_f32_e32 v1, 1.0, v1
	v_mul_f32_e32 v15, v4, v5
	v_rcp_f32_e32 v5, v1
	v_mul_f32_e32 v1, 0xbfb8aa3b, v13
	v_exp_f32_e32 v1, v1
	v_mov_b32_e32 v4, v11
	v_pk_mul_f32 v[4:5], v[4:5], v[20:21]
	v_add_f32_e32 v1, 1.0, v1
	v_rcp_f32_e32 v9, v1
	v_mul_f32_e32 v1, v4, v5
	v_pk_mul_f32 v[4:5], v[8:9], v[12:13]
	s_nop 0
	v_mul_f32_e32 v5, v4, v5
	v_cvt_pk_bf16_f32 v4, v2, v15
	v_cvt_pk_bf16_f32 v5, v1, v5
	s_waitcnt vmcnt(6)
	v_mov_b32_e32 v8, v152
	v_mov_b32_e32 v9, v153
	v_and_b32_e32 v13, 0xffff0000, v8
	global_store_dwordx2 v[24:25], v[4:5], off offset:192
	v_lshlrev_b32_e32 v5, 16, v8
	v_mul_f32_e32 v1, 0xbfb8aa3b, v5
	v_exp_f32_e32 v1, v1
	v_mul_f32_e32 v2, 0xbfb8aa3b, v13
	v_exp_f32_e32 v2, v2
	v_mov_b32_e32 v4, v3
	v_add_f32_e32 v1, 1.0, v1
	v_rcp_f32_e32 v1, v1
	v_add_f32_e32 v2, 1.0, v2
	v_rcp_f32_e32 v15, v2
	v_lshlrev_b32_e32 v17, 16, v9
	v_pk_mul_f32 v[0:1], v[0:1], v[4:5]
	v_and_b32_e32 v9, 0xffff0000, v9
	v_mul_f32_e32 v2, v0, v1
	v_pk_mul_f32 v[0:1], v[14:15], v[12:13]
	v_mul_f32_e32 v4, 0xbfb8aa3b, v17
	v_exp_f32_e32 v4, v4
	v_mul_f32_e32 v5, v0, v1
	v_mul_f32_e32 v0, 0xbfb8aa3b, v9
	v_exp_f32_e32 v0, v0
	v_add_f32_e32 v1, 1.0, v4
	v_rcp_f32_e32 v11, v1
	v_mov_b32_e32 v8, v3
	v_add_f32_e32 v0, 1.0, v0
	v_rcp_f32_e32 v7, v0
	v_pk_mul_f32 v[0:1], v[10:11], v[16:17]
	s_nop 0
	v_mul_f32_e32 v4, v0, v1
	v_pk_mul_f32 v[0:1], v[6:7], v[8:9]
	s_nop 0
	v_mul_f32_e32 v1, v0, v1
	v_cvt_pk_bf16_f32 v0, v2, v5
	v_cvt_pk_bf16_f32 v1, v4, v1
	global_store_dwordx2 v[24:25], v[0:1], off offset:224
	s_barrier
; #define LAS __attribute__((address_space(3)))
; DI int otid() { int t = threadIdx.x; asm volatile("" : "+v"(t)); return t; }
; DI unsigned xb_add(unsigned* p, unsigned v) { return __hip_atomic_fetch_add(p, v, __ATOMIC_RELAXED, __HIP_MEMORY_SCOPE_AGENT); }
; DI int next_item(unsigned* ctr, volatile LAS int* slot) {
;     __syncthreads();
;     if (threadIdx.x == 0) *slot = (int)xb_add(ctr, 1u);
;     __syncthreads();
;     return *slot;
; DI void na_block_item(const Params& p, int l, int b, int h, int rp, LAS unsigned char* lds) {
;     const int tid = otid(), lane = tid & 63, wid = tid >> 6, r16 = lane & 15, q4 = lane >> 4;
;     unsigned char* ws = p.ws;
;     const bf16_t* P = (const bf16_t*)(ws + WS_P);
;     constexpr int KROW = 272, KTILE = 64 * KROW, VROW = 144, VTILE = 128 * VROW;
;     const int gr = 2 * rp + (wid >> 2), jq = wid & 3;
;     const int gc = jq * 16 + r16, r0w = min(max(gr - 4, 0), 24), band = min(max(jq * 16 - 8, 0), 32), cs = min(max(gc - 8, 0), 48);
;     const int r0a = min(max(2 * rp - 4, 0), 24), r0b = min(max(2 * rp - 3, 0), 24), nloc = r0b + 8 - r0a, ntl = nloc + 4;
;     const size_t rowb = (size_t)b * RB, rowq = rowb + CL + gr * 64 + gc;
;     const float sl2 = 0.08838834764831845f * 1.4426950408889634f;
;     const float* rpb = p.in[11] + (size_t)(l * 6 + h) * 15 * 31;
	s_and_saveexec_b64 s[0:1], s[24:25]
	s_cbranch_execz .LBB0_1179
	s_mov_b64 s[18:19], exec
	v_mbcnt_lo_u32_b32 v0, s18, 0
	v_mbcnt_hi_u32_b32 v0, s19, v0
	v_cmp_eq_u32_e32 vcc, 0, v0
	s_and_saveexec_b64 s[16:17], vcc
	s_cbranch_execz .LBB0_1178
	s_bcnt1_i32_b64 s18, s[18:19]
	v_mov_b32_e32 v1, s18
	global_atomic_add v1, v69, v1, s[42:43] sc0
	s_branch .LBB0_1178
.LBB0_1183:
	s_cmpk_gt_u32 s28, 0x21f
	s_cbranch_scc1 .LBB0_1234
	s_mov_b32 s29, s28
	s_mov_b32 s22, 0x3e0293ee
	s_mov_b32 s23, 0x3fb8aa3b
	v_and_b32_e32 v196, 15, v202
	v_bfe_u32 v197, v202, 4, 2
	v_lshrrev_b32_e32 v198, 6, v202
	s_nop 0
	v_readfirstlane_b32 s74, v198
	v_mov_b32_e32 v199, v202
	v_lshrrev_b32_e32 v200, 4, v199
	v_and_b32_e32 v201, 15, v199
	v_lshlrev_b32_e32 v201, 4, v201
	v_mul_u32_u24_e32 v230, 0x3000, v200
	v_add_u32_e32 v230, v230, v201
	v_mul_u32_u24_e32 v234, 0x110, v200
	v_add_u32_e32 v234, v234, v201
	v_lshrrev_b32_e32 v200, 3, v199
	v_and_b32_e32 v201, 7, v199
	v_lshlrev_b32_e32 v201, 4, v201
	v_mul_u32_u24_e32 v232, 0x1200, v200
	v_add_u32_e32 v232, v232, v201
	v_mul_u32_u24_e32 v236, 0x90, v200
	v_add_u32_e32 v236, v236, v201
	v_add_u32_e32 v236, 0xcc00, v236
	v_add_u32_e32 v199, 0x200, v202
	v_lshrrev_b32_e32 v200, 4, v199
	v_and_b32_e32 v201, 15, v199
	v_lshlrev_b32_e32 v201, 4, v201
	v_mul_u32_u24_e32 v231, 0x3000, v200
	v_add_u32_e32 v231, v231, v201
	v_mul_u32_u24_e32 v235, 0x110, v200
	v_add_u32_e32 v235, v235, v201
	v_lshrrev_b32_e32 v200, 3, v199
	v_and_b32_e32 v201, 7, v199
	v_lshlrev_b32_e32 v201, 4, v201
	v_mul_u32_u24_e32 v233, 0x1200, v200
	v_add_u32_e32 v233, v233, v201
	v_mul_u32_u24_e32 v237, 0x90, v200
	v_add_u32_e32 v237, v237, v201
	v_add_u32_e32 v237, 0xcc00, v237
	v_mul_u32_u24_e32 v199, 0x110, v196
	v_lshl_add_u32 v238, v197, 4, v199
	v_mul_u32_u24_e32 v199, 0x90, v196
	v_lshl_add_u32 v199, v197, 3, v199
	v_add_u32_e32 v239, 0xcc00, v199
	v_mul_u32_u24_e32 v199, 0x3000, v196
	v_lshl_add_u32 v251, v197, 4, v199
	v_lshlrev_b32_e32 v199, 12, v196
	v_lshl_add_u32 v246, v197, 3, v199
	s_and_b32 s73, s74, 3
	s_lshl_b32 s73, s73, 4
	s_sub_i32 s56, s73, 8
	s_max_i32 s56, s56, 0
	s_min_i32 s56, s56, 32
	v_add_u32_e32 v220, s73, v196
	v_subrev_u32_e32 v221, 8, v220
	v_max_i32_e32 v221, 0, v221
	v_min_i32_e32 v221, 48, v221
	v_add_u32_e32 v222, 16, v221
	v_lshlrev_b32_e32 v223, 2, v197
	v_mov_b32_e32 v224, 0xf149f2ca
	v_mov_b32_e32 v225, 0x7f7fffff
	s_add_u32 s57, s56, 0
	v_add_u32_e32 v199, s57, v223
	v_sub_u32_e32 v200, v199, v220
	v_add_u32_e32 v200, 15, v200
	v_max_i32_e32 v200, 0, v200
	v_min_i32_e32 v200, 30, v200
	v_lshlrev_b32_e32 v200, 2, v200
	v_add_u32_e32 v132, 0x1a400, v200
	v_cmp_ge_i32_e32 vcc, v199, v221
	v_cmp_lt_i32_e64 s[0:1], v199, v222
	s_and_b64 vcc, vcc, s[0:1]
	v_cndmask_b32_e32 v140, v224, v225, vcc
	s_add_u32 s57, s56, 1
	v_add_u32_e32 v199, s57, v223
	v_sub_u32_e32 v200, v199, v220
	v_add_u32_e32 v200, 15, v200
	v_max_i32_e32 v200, 0, v200
	v_min_i32_e32 v200, 30, v200
	v_lshlrev_b32_e32 v200, 2, v200
	v_add_u32_e32 v133, 0x1a400, v200
	v_cmp_ge_i32_e32 vcc, v199, v221
	v_cmp_lt_i32_e64 s[0:1], v199, v222
	s_and_b64 vcc, vcc, s[0:1]
	v_cndmask_b32_e32 v141, v224, v225, vcc
	s_add_u32 s57, s56, 2
	v_add_u32_e32 v199, s57, v223
	v_sub_u32_e32 v200, v199, v220
	v_add_u32_e32 v200, 15, v200
	v_max_i32_e32 v200, 0, v200
	v_min_i32_e32 v200, 30, v200
	v_lshlrev_b32_e32 v200, 2, v200
	v_add_u32_e32 v134, 0x1a400, v200
	v_cmp_ge_i32_e32 vcc, v199, v221
	v_cmp_lt_i32_e64 s[0:1], v199, v222
	s_and_b64 vcc, vcc, s[0:1]
	v_cndmask_b32_e32 v142, v224, v225, vcc
	s_add_u32 s57, s56, 3
	v_add_u32_e32 v199, s57, v223
	v_sub_u32_e32 v200, v199, v220
	v_add_u32_e32 v200, 15, v200
	v_max_i32_e32 v200, 0, v200
	v_min_i32_e32 v200, 30, v200
	v_lshlrev_b32_e32 v200, 2, v200
	v_add_u32_e32 v135, 0x1a400, v200
	v_cmp_ge_i32_e32 vcc, v199, v221
	v_cmp_lt_i32_e64 s[0:1], v199, v222
	s_and_b64 vcc, vcc, s[0:1]
	v_cndmask_b32_e32 v143, v224, v225, vcc
	s_add_u32 s57, s56, 16
	v_add_u32_e32 v199, s57, v223
	v_sub_u32_e32 v200, v199, v220
	v_add_u32_e32 v200, 15, v200
	v_max_i32_e32 v200, 0, v200
	v_min_i32_e32 v200, 30, v200
	v_lshlrev_b32_e32 v200, 2, v200
	v_add_u32_e32 v136, 0x1a400, v200
	v_cmp_ge_i32_e32 vcc, v199, v221
	v_cmp_lt_i32_e64 s[0:1], v199, v222
	s_and_b64 vcc, vcc, s[0:1]
	v_cndmask_b32_e32 v144, v224, v225, vcc
	s_add_u32 s57, s56, 17
	v_add_u32_e32 v199, s57, v223
	v_sub_u32_e32 v200, v199, v220
	v_add_u32_e32 v200, 15, v200
	v_max_i32_e32 v200, 0, v200
	v_min_i32_e32 v200, 30, v200
	v_lshlrev_b32_e32 v200, 2, v200
	v_add_u32_e32 v137, 0x1a400, v200
	v_cmp_ge_i32_e32 vcc, v199, v221
	v_cmp_lt_i32_e64 s[0:1], v199, v222
	s_and_b64 vcc, vcc, s[0:1]
	v_cndmask_b32_e32 v145, v224, v225, vcc
	s_add_u32 s57, s56, 18
	v_add_u32_e32 v199, s57, v223
	v_sub_u32_e32 v200, v199, v220
	v_add_u32_e32 v200, 15, v200
	v_max_i32_e32 v200, 0, v200
	v_min_i32_e32 v200, 30, v200
	v_lshlrev_b32_e32 v200, 2, v200
	v_add_u32_e32 v138, 0x1a400, v200
	v_cmp_ge_i32_e32 vcc, v199, v221
	v_cmp_lt_i32_e64 s[0:1], v199, v222
	s_and_b64 vcc, vcc, s[0:1]
	v_cndmask_b32_e32 v146, v224, v225, vcc
	s_add_u32 s57, s56, 19
	v_add_u32_e32 v199, s57, v223
	v_sub_u32_e32 v200, v199, v220
	v_add_u32_e32 v200, 15, v200
	v_max_i32_e32 v200, 0, v200
	v_min_i32_e32 v200, 30, v200
	v_lshlrev_b32_e32 v200, 2, v200
	v_add_u32_e32 v139, 0x1a400, v200
	v_cmp_ge_i32_e32 vcc, v199, v221
	v_cmp_lt_i32_e64 s[0:1], v199, v222
	s_and_b64 vcc, vcc, s[0:1]
	v_cndmask_b32_e32 v147, v224, v225, vcc
	v_readlane_b32 s10, v255, 62
	v_readlane_b32 s11, v255, 63
	s_nop 4
	s_load_dwordx2 s[8:9], s[10:11], 0x58
	s_waitcnt lgkmcnt(0)
	v_writelane_b32 v254, s8, 0
	v_writelane_b32 v254, s9, 1
	v_writelane_b32 v254, s74, 2
; #define LAS __attribute__((address_space(3)))
; DI int otid() { int t = threadIdx.x; asm volatile("" : "+v"(t)); return t; }
; #define NA_LOAD(t, ks_, vs_) do { const int tb_ = NA_TB(t); \
;         _Pragma("unroll") for (int i = 0; i < 2; ++i) { const int cid = tid + i * 512; \
;             ks_[i] = *(const u32x4*)(kg + (size_t)(tb_ + (cid >> 4)) * INP + (cid & 15) * 8); \
;             vs_[i] = *(const u32x4*)(vg + (size_t)(cid >> 3) * RB + tb_ + (cid & 7) * 8); } } while (0)
; DI void na_block_item(const Params& p, int l, int b, int h, int rp, LAS unsigned char* lds) {
;     const int tid = otid(), lane = tid & 63, wid = tid >> 6, r16 = lane & 15, q4 = lane >> 4;
;     unsigned char* ws = p.ws;
;     const bf16_t* P = (const bf16_t*)(ws + WS_P);
;     constexpr int KROW = 272, KTILE = 64 * KROW, VROW = 144, VTILE = 128 * VROW;
;     const int gr = 2 * rp + (wid >> 2), jq = wid & 3;
;     const int gc = jq * 16 + r16, r0w = min(max(gr - 4, 0), 24), band = min(max(jq * 16 - 8, 0), 32), cs = min(max(gc - 8, 0), 48);
;     const int r0a = min(max(2 * rp - 4, 0), 24), r0b = min(max(2 * rp - 3, 0), 24), nloc = r0b + 8 - r0a, ntl = nloc + 4;
;     const size_t rowb = (size_t)b * RB, rowq = rowb + CL + gr * 64 + gc;
;     const float sl2 = 0.08838834764831845f * 1.4426950408889634f;
;     const float* rpb = p.in[11] + (size_t)(l * 6 + h) * 15 * 31;
;     bf16x8 qf[4];
; #pragma unroll
;     for (int ks = 0; ks < 4; ++ks) qf[ks] = *(const bf16x8*)(P + rowq * INP + C_NAQ + h * 128 + ks * 32 + q4 * 8);
;     f32x4 oacc[8];
; #pragma unroll
;     for (int d = 0; d < 8; ++d) oacc[d] = (f32x4){0.f, 0.f, 0.f, 0.f};
;     float mrun = -1e30f, lsum = 0.f;
;     const bf16_t* kg = P + rowb * INP + C_NAK + h * 128;
;     const bf16_t* vg = (const bf16_t*)(ws + WS_VTNA) + ((size_t)b * 768 + h * 128) * RB;
;     u32x4 kstA[2], vstA[2], kstB[2], vstB[2];
;     ...
;     LAS float* s_rpb = (LAS float*)(lds + 3 * KTILE + 3 * VTILE);
;     if (tid < 465) s_rpb[tid] = rpb[tid];
;     NA_LOAD(0, kstA, vstA); NA_LOAD(1, kstB, vstB);
;     NA_STORE(0, kstA, vstA);
;     NA_LOAD(2, kstA, vstA);
;     __syncthreads();
na0_item:
	s_sub_u32 s57, s29, 0xa0
	s_and_b32 s71, s57, 15
	s_lshr_b32 s57, s57, 4
	s_mul_i32 s73, s57, 43
	s_lshr_b32 s73, s73, 8
	s_mul_i32 s63, s73, 6
	s_sub_u32 s72, s57, s63
	s_lshl_b32 s57, s71, 1
	s_sub_i32 s36, s57, 4
	s_max_i32 s36, s36, 0
	s_min_i32 s36, s36, 24
	s_sub_i32 s63, s57, 3
	s_max_i32 s63, s63, 0
	s_min_i32 s63, s63, 24
	s_sub_u32 s30, s63, s36
	s_add_u32 s30, s30, 8
	s_add_u32 s31, s30, 4
	v_readlane_b32 s74, v254, 2
	s_lshr_b32 s63, s74, 2
	s_add_u32 s37, s57, s63
	s_sub_i32 s54, s37, 4
	s_max_i32 s54, s54, 0
	s_min_i32 s54, s54, 24
	s_mul_i32 s68, s73, 0x900
	s_mul_i32 s57, s68, 0x3000
	s_lshl_b32 s63, s72, 8
	s_add_u32 s57, s57, s63
	s_add_u32 s57, s57, 0x113a0600
	s_add_u32 s2, s50, s57
	s_addc_u32 s3, s51, 0
	s_mul_i32 s57, s73, 0x300
	s_lshl_b32 s69, s72, 7
	s_add_u32 s57, s57, s69
	s_mul_i32 s57, s57, 0x1200
	s_add_u32 s57, s57, 0x17fa0000
	s_add_u32 s4, s50, s57
	s_addc_u32 s5, s51, 0
	s_and_b32 s69, s74, 3
	s_lshl_b32 s69, s69, 4
	s_lshl_b32 s70, s37, 6
	s_add_u32 s69, s69, s70
	s_add_u32 s69, s69, s68
	s_addk_i32 s69, 0x100
	s_mul_i32 s57, s69, 0x3000
	s_add_u32 s57, s57, s63
	s_add_u32 s57, s57, 0x113a0000
	s_add_u32 s6, s50, s57
	s_addc_u32 s7, s51, 0
	global_load_dwordx4 v[0:3], v251, s[6:7] offset:0
	global_load_dwordx4 v[4:7], v251, s[6:7] offset:64
	global_load_dwordx4 v[8:11], v251, s[6:7] offset:128
	global_load_dwordx4 v[12:15], v251, s[6:7] offset:192
	s_lshl_b32 s57, s69, 12
	s_add_u32 s57, s57, s63
	s_add_u32 s57, s57, 0x1d9a0000
	s_add_u32 s10, s50, s57
	s_addc_u32 s11, s51, 0
	v_readlane_b32 s6, v254, 0
	v_readlane_b32 s7, v254, 1
	s_mul_i32 s57, s72, 0x744
	s_add_u32 s57, s57, 0x0
	s_nop 2
	s_add_u32 s6, s6, s57
	s_addc_u32 s7, s7, 0
	v_lshlrev_b32_e32 v196, 2, v202
	v_cmp_gt_u32_e32 vcc, 0x1d1, v202
	s_and_saveexec_b64 s[0:1], vcc
	global_load_dword v197, v196, s[6:7]
	s_or_b64 exec, exec, s[0:1]
	s_mov_b32 s70, 0
	s_add_u32 s57, s36, s70
	s_lshl_b32 s57, s57, 6
	s_addk_i32 s57, 0x100
	s_sub_u32 s63, s70, s30
	s_lshl_b32 s63, s63, 6
	s_cmp_lt_u32 s70, s30
	s_cselect_b32 s57, s57, s63
	s_mul_i32 s63, s57, 0x3000
	s_add_u32 s6, s2, s63
	s_addc_u32 s7, s3, 0
	s_lshl_b32 s63, s57, 1
	s_add_u32 s8, s4, s63
	s_addc_u32 s9, s5, 0
	global_load_dwordx4 v[148:151], v230, s[6:7]
	global_load_dwordx4 v[152:155], v231, s[6:7]
	global_load_dwordx4 v[156:159], v232, s[8:9]
	global_load_dwordx4 v[160:163], v233, s[8:9]
	s_mov_b32 s70, 1
	s_add_u32 s57, s36, s70
	s_lshl_b32 s57, s57, 6
	s_addk_i32 s57, 0x100
	s_sub_u32 s63, s70, s30
	s_lshl_b32 s63, s63, 6
	s_cmp_lt_u32 s70, s30
	s_cselect_b32 s57, s57, s63
	s_mul_i32 s63, s57, 0x3000
	s_add_u32 s6, s2, s63
	s_addc_u32 s7, s3, 0
	s_lshl_b32 s63, s57, 1
	s_add_u32 s8, s4, s63
	s_addc_u32 s9, s5, 0
	global_load_dwordx4 v[164:167], v230, s[6:7]
	global_load_dwordx4 v[168:171], v231, s[6:7]
	global_load_dwordx4 v[172:175], v232, s[8:9]
	global_load_dwordx4 v[176:179], v233, s[8:9]
	s_mov_b32 s70, 2
	s_add_u32 s57, s36, s70
	s_lshl_b32 s57, s57, 6
	s_addk_i32 s57, 0x100
	s_sub_u32 s63, s70, s30
	s_lshl_b32 s63, s63, 6
	s_cmp_lt_u32 s70, s30
	s_cselect_b32 s57, s57, s63
	s_mul_i32 s63, s57, 0x3000
	s_add_u32 s6, s2, s63
	s_addc_u32 s7, s3, 0
	s_lshl_b32 s63, s57, 1
	s_add_u32 s8, s4, s63
	s_addc_u32 s9, s5, 0
	global_load_dwordx4 v[180:183], v230, s[6:7]
	global_load_dwordx4 v[184:187], v231, s[6:7]
	global_load_dwordx4 v[188:191], v232, s[8:9]
	global_load_dwordx4 v[192:195], v233, s[8:9]
	s_mov_b32 s70, 3
	s_add_u32 s57, s36, s70
	s_lshl_b32 s57, s57, 6
	s_addk_i32 s57, 0x100
	s_sub_u32 s63, s70, s30
	s_lshl_b32 s63, s63, 6
	s_cmp_lt_u32 s70, s30
	s_cselect_b32 s57, s57, s63
	s_mul_i32 s63, s57, 0x3000
	s_add_u32 s6, s2, s63
	s_addc_u32 s7, s3, 0
	s_lshl_b32 s63, s57, 1
	s_add_u32 s8, s4, s63
	s_addc_u32 s9, s5, 0
	global_load_dwordx4 v[204:207], v230, s[6:7]
	global_load_dwordx4 v[208:211], v231, s[6:7]
	global_load_dwordx4 v[212:215], v232, s[8:9]
	global_load_dwordx4 v[216:219], v233, s[8:9]
	v_mov_b32_e32 v16, 0
	v_mov_b32_e32 v17, 0
	v_mov_b32_e32 v18, 0
	v_mov_b32_e32 v19, 0
	v_mov_b32_e32 v20, 0
	v_mov_b32_e32 v21, 0
	v_mov_b32_e32 v22, 0
	v_mov_b32_e32 v23, 0
	v_mov_b32_e32 v24, 0
	v_mov_b32_e32 v25, 0
	v_mov_b32_e32 v26, 0
	v_mov_b32_e32 v27, 0
	v_mov_b32_e32 v28, 0
	v_mov_b32_e32 v29, 0
	v_mov_b32_e32 v30, 0
	v_mov_b32_e32 v31, 0
	v_mov_b32_e32 v32, 0
	v_mov_b32_e32 v33, 0
	v_mov_b32_e32 v34, 0
	v_mov_b32_e32 v35, 0
	v_mov_b32_e32 v36, 0
	v_mov_b32_e32 v37, 0
	v_mov_b32_e32 v38, 0
	v_mov_b32_e32 v39, 0
	v_mov_b32_e32 v40, 0
	v_mov_b32_e32 v41, 0
	v_mov_b32_e32 v42, 0
	v_mov_b32_e32 v43, 0
	v_mov_b32_e32 v44, 0
	v_mov_b32_e32 v45, 0
	v_mov_b32_e32 v46, 0
	v_mov_b32_e32 v47, 0
	v_mov_b32_e32 v242, 0xf149f2ca
	v_mov_b32_e32 v243, 0
	s_waitcnt vmcnt(12)
	v_cmp_gt_u32_e32 vcc, 0x1d1, v202
	s_and_saveexec_b64 s[0:1], vcc
	v_add_u32_e32 v196, 0x1a400, v196
	ds_write_b32 v196, v197
	s_or_b64 exec, exec, s[0:1]
	ds_write_b128 v234, v[148:151]
	ds_write_b128 v235, v[152:155]
	ds_write_b128 v236, v[156:159]
	ds_write_b128 v237, v[160:163]
	s_waitcnt lgkmcnt(0)
	s_mov_b32 s70, 4
	s_add_u32 s57, s36, s70
	s_lshl_b32 s57, s57, 6
	s_addk_i32 s57, 0x100
	s_sub_u32 s63, s70, s30
	s_lshl_b32 s63, s63, 6
	s_cmp_lt_u32 s70, s30
	s_cselect_b32 s57, s57, s63
	s_mul_i32 s63, s57, 0x3000
	s_add_u32 s6, s2, s63
	s_addc_u32 s7, s3, 0
	s_lshl_b32 s63, s57, 1
	s_add_u32 s8, s4, s63
	s_addc_u32 s9, s5, 0
	global_load_dwordx4 v[148:151], v230, s[6:7]
	global_load_dwordx4 v[152:155], v231, s[6:7]
	global_load_dwordx4 v[156:159], v232, s[8:9]
	global_load_dwordx4 v[160:163], v233, s[8:9]
	s_barrier
	s_mov_b32 s27, 0

; #define LAS __attribute__((address_space(3)))
; DI unsigned xb_add(unsigned* p, unsigned v) { return __hip_atomic_fetch_add(p, v, __ATOMIC_RELAXED, __HIP_MEMORY_SCOPE_AGENT); }
; DI int next_item(unsigned* ctr, volatile LAS int* slot) {
;     __syncthreads();
;     if (threadIdx.x == 0) *slot = (int)xb_add(ctr, 1u);
;     __syncthreads();
;     return *slot;
; DI void phase_mixers(const Params& p, int l, LAS unsigned char* lds) {
;     ...
;     int it = next_item(ctr, slot);
;     while (it < e0) { dense192_item(ws, lds, it / 40, (it >> 3) % 5, CL + (it & 7) * 256, RB); it = next_item(ctr, slot); }
;     while (it < e1) { const int i2 = it - e0, c = (i2 % nc) + (18 - nc), bh = i2 / nc; ret_out_item(p, l, bh / 5, bh % 5, c, lds); it = next_item(ctr, slot); }
;     while (it < e2) { const int i2 = it - e1; na_block_item(p, l, i2 / 96, (i2 >> 4) % 6, i2 & 15, lds); it = next_item(ctr, slot); }
;     if (l == 0) {
;         while (it < e2 + 20) { const int i2 = it - e2; dense192_item(ws, lds, i2 / 5, i2 % 5, 0, CL); it = next_item(ctr, slot); }
na0_nq:
	s_or_b64 exec, exec, s[0:1]
	v_mov_b32_e32 v197, 0x22040
	s_waitcnt vmcnt(0) lgkmcnt(0)
	s_barrier
	ds_read_b32 v196, v197
	s_waitcnt lgkmcnt(0)
	v_readfirstlane_b32 s29, v196
	s_cmp_lt_u32 s29, 0x220
	s_cbranch_scc1 na0_item
	s_mov_b32 s28, s29
	v_mov_b32_e32 v133, 0
.LBB0_1234:
	s_cmpk_gt_u32 s28, 0x233
	s_cbranch_scc1 .LBB0_1268
	s_add_u32 s2, s50, 0x1a3a0000
	s_addc_u32 s3, s51, 0
	s_add_u32 s4, s50, 0x1b480000
	s_addc_u32 s5, s51, 0
	s_add_u32 s27, s50, 0x1cb00000
	s_addc_u32 s30, s51, 0
	s_add_u32 s31, s50, 0x1bfc0000
	s_addc_u32 s34, s51, 0
	s_add_u32 s10, s50, 0x1bfc0080
	s_addc_u32 s11, s51, 0
	s_add_u32 s12, s50, 0x1b494000
	s_movk_i32 s14, 0xff00
	s_addc_u32 s13, s51, 0
	s_movk_i32 s35, 0xffe0
	v_mov_b32_e32 v133, 0
	s_movk_i32 s36, 0x780
	s_mov_b32 s37, 0x2aaaaaab
	s_mov_b32 s15, -1
	s_movk_i32 s70, 0x500
	s_movk_i32 s71, 0x1200
	s_movk_i32 s72, 0x190
	s_movk_i32 s73, 0x90
	s_mov_b32 s74, 0x3dd53b94
	s_mov_b32 s75, 0xc800
	s_mov_b64 s[16:17], 0x80
	s_mov_b64 s[18:19], 0x14000
	s_mov_b64 s[20:21], 0x1d9a0600
	s_add_i32 s76, 0, 0x22040
	v_mbcnt_hi_u32_b32 v182, -1, v203
	v_mov_b32_e32 v183, 0x1900
	v_mov_b32_e32 v184, 0x3200
	v_mov_b32_e32 v185, 0x4b00
	s_branch .LBB0_1238

; #define LAS __attribute__((address_space(3)))
; DI int otid() { int t = threadIdx.x; asm volatile("" : "+v"(t)); return t; }
; template <int DK>
; DI void dense_attn_item(LAS unsigned char* lds, const bf16_t* Qb, int ldq, const bf16_t* Kb, int ldk, const bf16_t* Kpe, const bf16_t* Vt, int nkeys, float sl2, bf16_t* Ob) {
;     const int tid = otid(), lane = tid & 63, wid = tid >> 6, r16 = lane & 15, q4 = lane >> 4;
;     constexpr int KS = DK / 32, KCH = DK / 8, KROW = DK * 2 + 16, KTILE = 64 * KROW, VROW = 144, VTILE = 128 * VROW, NKL = (64 * KCH) / 512;
;     bf16x8 qf[2][KS];
; #pragma unroll
;     for (int qg = 0; qg < 2; ++qg)
; #pragma unroll
;         for (int ks = 0; ks < KS; ++ks) qf[qg][ks] = *(const bf16x8*)(Qb + (size_t)(wid * 32 + qg * 16 + r16) * ldq + ks * 32 + q4 * 8);
;     f32x4 oacc[2][8];
; #pragma unroll
;     for (int qg = 0; qg < 2; ++qg)
; #pragma unroll
;         for (int d = 0; d < 8; ++d) oacc[qg][d] = (f32x4){0.f, 0.f, 0.f, 0.f};
;     float mrun[2] = {-1e30f, -1e30f}, lsum[2] = {0.f, 0.f};
;     u32x4 kst[NKL], vst[2];
;     const int ntiles = nkeys >> 6;
; DI void dense192_item(unsigned char* ws, LAS unsigned char* lds, int b, int h, int q0, int nk) {
;     const size_t rowb = (size_t)b * RB, row0 = rowb + q0;
;     dense_attn_item<192>(lds, (const bf16_t*)(ws + WS_QM) + row0 * 960 + h * 192, 960, (const bf16_t*)(ws + WS_KM) + rowb * 640 + h * 128, 640, (const bf16_t*)(ws + WS_KPE) + rowb * 64,
;                          (const bf16_t*)(ws + WS_VTM) + ((size_t)b * 640 + h * 128) * RB, nk, 0.07216878364870322f * 1.4426950408889634f, (bf16_t*)(ws + WS_YMIX) + row0 * DM + 768 + h * 128);
.LBB0_1237:
	s_or_b64 exec, exec, s[0:1]
	v_mov_b32_e32 v0, s76
	s_waitcnt lgkmcnt(0)
	s_barrier
	ds_read_b32 v0, v0
	s_movk_i32 s0, 0x233
	s_waitcnt lgkmcnt(0)
	v_cmp_lt_i32_e32 vcc, s0, v0
	v_readfirstlane_b32 s28, v0
	s_cbranch_vccnz .LBB0_1268
.LBB0_1238:
	s_add_i32 s0, s28, 0xfffffde0
	s_mul_hi_i32 s1, s0, 0x66666667
	s_lshr_b32 s6, s1, 31
	s_ashr_i32 s77, s1, 1
	s_add_i32 s77, s77, s6
	s_mul_i32 s1, s77, 5
	s_sub_i32 s6, s0, s1
	s_mul_i32 s1, s77, 0x438000
	s_mul_hi_i32 s0, s77, 0x438000
	s_add_u32 s7, s2, s1
	s_addc_u32 s8, s3, s0
	s_mul_i32 s0, s6, 0xc0
	s_ashr_i32 s1, s0, 31
	s_lshl_b64 s[0:1], s[0:1], 1
	v_mov_b32_e32 v69, v202
	s_add_u32 s0, s7, s0
	s_addc_u32 s1, s8, s1
	v_and_b32_e32 v66, 15, v69
	v_bfe_u32 v68, v69, 4, 2
	v_ashrrev_i32_e32 v0, 1, v69
	v_and_or_b32 v136, v0, s35, v66
	v_lshlrev_b32_e32 v142, 4, v68
	v_mov_b32_e32 v143, v133
	v_lshl_add_u64 v[16:17], s[0:1], 0, v[142:143]
	v_or_b32_e32 v134, 16, v136
	v_mad_i64_i32 v[0:1], s[0:1], v136, s36, v[16:17]
	v_mad_i64_i32 v[16:17], s[0:1], v134, s36, v[16:17]
	global_load_dwordx4 v[28:31], v[0:1], off
	global_load_dwordx4 v[24:27], v[0:1], off offset:64
	global_load_dwordx4 v[12:15], v[0:1], off offset:128
	global_load_dwordx4 v[8:11], v[0:1], off offset:192
	global_load_dwordx4 v[4:7], v[0:1], off offset:256
	s_nop 0
	global_load_dwordx4 v[0:3], v[0:1], off offset:320
	s_nop 0
	global_load_dwordx4 v[44:47], v[16:17], off
	global_load_dwordx4 v[40:43], v[16:17], off offset:64
	global_load_dwordx4 v[36:39], v[16:17], off offset:128
	global_load_dwordx4 v[32:35], v[16:17], off offset:192
	global_load_dwordx4 v[20:23], v[16:17], off offset:256
	s_nop 0
	global_load_dwordx4 v[16:19], v[16:17], off offset:320
	s_mul_i32 s54, s77, 0x2d0000
	s_mul_hi_i32 s55, s77, 0x2d0000
	s_add_u32 s0, s4, s54
	s_addc_u32 s1, s5, s55
	s_lshl_b32 s56, s6, 7
	s_ashr_i32 s57, s56, 31
	s_waitcnt vmcnt(20)
	v_mul_hi_i32 v48, v69, s37
	s_lshl_b64 s[22:23], s[56:57], 1
	v_lshrrev_b32_e32 v49, 31, v48
	v_ashrrev_i32_e32 v48, 2, v48
	s_add_u32 s62, s0, s22
	v_add_u32_e32 v144, v48, v49
	s_addc_u32 s63, s1, s23
	s_mul_i32 s0, s77, 0x48000
	v_mul_lo_u32 v48, v144, 24
	s_mul_hi_i32 s1, s77, 0x48000
	s_add_u32 s0, s27, s0
	v_sub_u32_e32 v70, v69, v48
	s_addc_u32 s1, s30, s1
	v_cmp_lt_i32_e32 vcc, 15, v70
	v_ashrrev_i32_e32 v145, 31, v144
	v_lshlrev_b32_e32 v56, 3, v70
	s_and_saveexec_b64 s[6:7], vcc
	s_xor_b64 s[6:7], exec, s[6:7]
	v_lshlrev_b64 v[48:49], 7, v[144:145]
	v_lshl_add_u64 v[48:49], s[0:1], 0, v[48:49]
	v_mov_b32_e32 v57, v133
	v_lshl_add_u64 v[48:49], v[56:57], 1, v[48:49]
	v_lshl_add_u64 v[48:49], v[48:49], 0, s[14:15]
	s_or_saveexec_b64 s[6:7], s[6:7]
	v_ashrrev_i32_e32 v67, 31, v56
	s_xor_b64 exec, exec, s[6:7]
	v_mov_b64_e32 v[48:49], s[62:63]
	v_mad_i64_i32 v[48:49], s[8:9], v144, s70, v[48:49]
	v_mov_b32_e32 v57, v67
	v_lshl_add_u64 v[48:49], v[56:57], 1, v[48:49]
	s_or_b64 exec, exec, s[6:7]
	global_load_dwordx4 v[48:51], v[48:49], off
	v_add_u32_e32 v72, 0x200, v69
	v_mul_hi_i32 v52, v72, s37
	v_lshrrev_b32_e32 v53, 31, v52
	v_ashrrev_i32_e32 v52, 2, v52
	v_add_u32_e32 v146, v52, v53
	v_mul_lo_u32 v52, v146, 24
	v_sub_u32_e32 v57, v72, v52
	v_cmp_lt_i32_e64 s[6:7], 15, v57
	v_ashrrev_i32_e32 v147, 31, v146
	v_lshlrev_b32_e32 v58, 3, v57
	s_and_saveexec_b64 s[8:9], s[6:7]
	s_xor_b64 s[8:9], exec, s[8:9]
	v_lshlrev_b64 v[52:53], 7, v[146:147]
	v_lshl_add_u64 v[52:53], s[0:1], 0, v[52:53]
	v_mov_b32_e32 v59, v133
	v_lshl_add_u64 v[52:53], v[58:59], 1, v[52:53]
	v_lshl_add_u64 v[52:53], v[52:53], 0, s[14:15]
	s_or_saveexec_b64 s[8:9], s[8:9]
	v_ashrrev_i32_e32 v71, 31, v58
	s_xor_b64 exec, exec, s[8:9]
	v_mov_b64_e32 v[52:53], s[62:63]
	v_mad_i64_i32 v[52:53], s[28:29], v146, s70, v[52:53]
	v_mov_b32_e32 v59, v71
	v_lshl_add_u64 v[52:53], v[58:59], 1, v[52:53]
	s_or_b64 exec, exec, s[8:9]
	global_load_dwordx4 v[52:55], v[52:53], off
	v_add_u32_e32 v59, 0x400, v69
	v_mul_hi_i32 v60, v59, s37
	v_lshrrev_b32_e32 v61, 31, v60
	v_ashrrev_i32_e32 v60, 2, v60
	v_add_u32_e32 v148, v60, v61
	v_mul_lo_u32 v60, v148, 24
	v_sub_u32_e32 v59, v59, v60
	v_cmp_lt_i32_e64 s[8:9], 15, v59
	v_ashrrev_i32_e32 v149, 31, v148
	v_lshlrev_b32_e32 v132, 3, v59
	s_and_saveexec_b64 s[28:29], s[8:9]
	s_xor_b64 s[68:69], exec, s[28:29]
	v_lshlrev_b64 v[60:61], 7, v[148:149]
	v_lshl_add_u64 v[60:61], s[0:1], 0, v[60:61]
	v_lshl_add_u64 v[60:61], v[132:133], 1, v[60:61]
	v_lshl_add_u64 v[64:65], v[60:61], 0, s[14:15]
	v_mad_i64_i32 v[60:61], s[28:29], v148, s70, 0
	s_or_saveexec_b64 s[68:69], s[68:69]
	v_mov_b64_e32 v[62:63], v[132:133]
	s_xor_b64 exec, exec, s[68:69]
	v_mov_b64_e32 v[62:63], s[62:63]
	v_mad_i64_i32 v[64:65], s[28:29], v148, s70, v[62:63]
	v_ashrrev_i32_e32 v63, 31, v132
	v_mov_b32_e32 v62, v132
	v_mad_i64_i32 v[60:61], s[28:29], v148, s70, 0
	v_lshl_add_u64 v[64:65], v[62:63], 1, v[64:65]
	s_or_b64 exec, exec, s[68:69]
	s_mul_i32 s29, s77, 0x280
	s_mul_hi_i32 s28, s77, 0x280
	s_add_u32 s29, s29, s56
	s_addc_u32 s28, s28, s57
	s_mulk_i32 s28, 0x1200
	s_mul_hi_u32 s57, s29, 0x1200
	s_add_i32 s57, s57, s28
	s_mulk_i32 s29, 0x1200
	s_add_u32 s28, s31, s29
	global_load_dwordx4 v[74:77], v[64:65], off
	v_lshlrev_b32_e32 v64, 4, v69
	s_addc_u32 s29, s34, s57
	v_and_b32_e32 v64, 0x70, v64
	v_mov_b32_e32 v65, v133
	v_lshl_add_u64 v[78:79], s[28:29], 0, v[64:65]
	v_ashrrev_i32_e32 v65, 3, v69
	v_mad_i64_i32 v[80:81], s[28:29], v65, s71, v[78:79]
	v_ashrrev_i32_e32 v69, 3, v72
	v_mad_i64_i32 v[72:73], s[28:29], v69, s71, v[78:79]
	global_load_dwordx4 v[78:81], v[80:81], off
	s_nop 0
	global_load_dwordx4 v[82:85], v[72:73], off
	v_lshlrev_b32_e32 v186, 4, v70
	v_and_b32_e32 v70, 64, v182
	v_lshlrev_b32_e32 v138, 3, v68
	v_mul_lo_u32 v149, v144, s72
	v_lshlrev_b32_e32 v188, 4, v57
	v_lshlrev_b32_e32 v190, 4, v59
	v_xor_b32_e32 v68, 16, v182
	v_mov_b32_e32 v57, v133
	v_mov_b32_e32 v59, v133
	v_add_u32_e32 v70, 64, v70
	v_mul_lo_u32 v187, v146, s72
	v_xor_b32_e32 v72, 32, v182
	v_lshl_add_u64 v[150:151], v[132:133], 1, s[0:1]
	v_mul_u32_u24_e32 v191, 0x190, v66
	v_mad_u32_u24 v192, v66, s72, v183
	v_mul_u32_u24_e32 v139, 0x90, v66
	v_mad_u32_u24 v193, v66, s72, v184
	v_mad_u32_u24 v194, v66, s72, v185
	s_mul_hi_i32 s57, s56, 0x1200
	s_mulk_i32 s56, 0x1200
	v_add3_u32 v66, 0, v149, v186
	v_lshl_add_u64 v[152:153], v[56:57], 1, s[0:1]
	v_lshl_add_u64 v[154:155], v[58:59], 1, s[0:1]
	v_mov_b32_e32 v59, v71
	v_cmp_lt_i32_e64 s[0:1], v68, v70
	v_lshl_add_u64 v[60:61], v[62:63], 1, v[60:61]
	v_add3_u32 v73, 0, v187, v188
	v_mov_b64_e32 v[62:63], s[56:57]
	s_waitcnt vmcnt(4)
; template <int DK>
; DI void dense_attn_item(LAS unsigned char* lds, const bf16_t* Qb, int ldq, const bf16_t* Kb, int ldk, const bf16_t* Kpe, const bf16_t* Vt, int nkeys, float sl2, bf16_t* Ob) {
;     ...
;     f32x4 oacc[2][8];
; #pragma unroll
;     for (int qg = 0; qg < 2; ++qg)
; #pragma unroll
;         for (int d = 0; d < 8; ++d) oacc[qg][d] = (f32x4){0.f, 0.f, 0.f, 0.f};
;     float mrun[2] = {-1e30f, -1e30f}, lsum[2] = {0.f, 0.f};
;     u32x4 kst[NKL], vst[2];
;     const int ntiles = nkeys >> 6;
;     ...
;     DA_LOAD(0); DA_STORE(0);
;     __syncthreads();
	ds_write_b128 v66, v[48:51]
	s_waitcnt vmcnt(3)
	ds_write_b128 v73, v[52:55]
	v_cndmask_b32_e64 v54, v182, v68, s[0:1]
	v_cmp_lt_i32_e64 s[0:1], v72, v70
	v_lshlrev_b64 v[52:53], 1, v[58:59]
	v_mov_b32_e32 v57, v67
	v_cndmask_b32_e64 v55, v182, v72, s[0:1]
	v_mad_i64_i32 v[48:49], s[0:1], v65, s71, v[62:63]
	v_mad_i64_i32 v[50:51], s[0:1], v69, s71, v[62:63]
	v_mad_i64_i32 v[52:53], s[0:1], v146, s70, v[52:53]
	v_or_b32_e32 v48, v48, v64
	s_add_u32 s0, s12, s22
	v_lshl_add_u64 v[156:157], s[10:11], 0, v[48:49]
	s_addc_u32 s1, s13, s23
	v_mov_b64_e32 v[48:49], s[22:23]
	v_lshl_add_u64 v[160:161], s[0:1], 0, v[60:61]
	v_lshl_add_u64 v[162:163], s[0:1], 0, v[52:53]
	v_mad_i64_i32 v[48:49], s[0:1], v144, s70, v[48:49]
	v_mul_lo_u32 v189, v148, s72
	v_mul_lo_u32 v195, v65, s73
	v_mul_lo_u32 v196, v69, s73
	v_add_u32_e32 v197, 0, v64
	v_lshl_add_u64 v[48:49], v[56:57], 1, v[48:49]
	v_add3_u32 v86, 0, v189, v190
	v_add_u32_e32 v58, v197, v195
	v_add_u32_e32 v59, v197, v196
	v_or_b32_e32 v50, v50, v64
	v_lshl_add_u64 v[164:165], s[12:13], 0, v[48:49]
	v_mov_b32_e32 v48, 0
	v_ashrrev_i32_e32 v137, 31, v136
	v_ashrrev_i32_e32 v135, 31, v134
	s_mov_b32 s28, 0
	v_add_u32_e32 v147, 0, v138
	v_lshlrev_b32_e32 v145, 2, v54
	v_lshlrev_b32_e32 v143, 2, v55
	v_lshl_add_u64 v[158:159], s[10:11], 0, v[50:51]
	s_waitcnt vmcnt(2)
	ds_write_b128 v86, v[74:77]
	s_waitcnt vmcnt(1)
	ds_write_b128 v58, v[78:81] offset:51200
	s_waitcnt vmcnt(0)
	ds_write_b128 v59, v[82:85] offset:51200
	v_mov_b32_e32 v198, 0xf149f2ca
	v_mov_b32_e32 v199, 0xf149f2ca
	v_mov_b32_e32 v49, v48
	v_mov_b32_e32 v50, v48
	v_mov_b32_e32 v51, v48
	v_mov_b32_e32 v52, v48
	v_mov_b32_e32 v53, v48
	v_mov_b32_e32 v54, v48
	v_mov_b32_e32 v55, v48
	v_mov_b32_e32 v56, v48
	v_mov_b32_e32 v57, v48
	v_mov_b32_e32 v58, v48
	v_mov_b32_e32 v59, v48
	v_mov_b32_e32 v60, v48
	v_mov_b32_e32 v61, v48
	v_mov_b32_e32 v62, v48
	v_mov_b32_e32 v63, v48
	v_mov_b32_e32 v64, v48
	v_mov_b32_e32 v65, v48
	v_mov_b32_e32 v66, v48
	v_mov_b32_e32 v67, v48
	v_mov_b32_e32 v68, v48
	v_mov_b32_e32 v69, v48
	v_mov_b32_e32 v70, v48
	v_mov_b32_e32 v71, v48
	v_mov_b32_e32 v72, v48
	v_mov_b32_e32 v73, v48
	v_mov_b32_e32 v74, v48
	v_mov_b32_e32 v75, v48
	v_mov_b32_e32 v80, v48
	v_mov_b32_e32 v81, v48
	v_mov_b32_e32 v82, v48
	v_mov_b32_e32 v83, v48
	v_mov_b32_e32 v100, v48
	v_mov_b32_e32 v101, v48
	v_mov_b32_e32 v102, v48
	v_mov_b32_e32 v103, v48
	v_mov_b32_e32 v104, v48
	v_mov_b32_e32 v105, v48
	v_mov_b32_e32 v106, v48
	v_mov_b32_e32 v107, v48
	v_mov_b32_e32 v108, v48
	v_mov_b32_e32 v109, v48
	v_mov_b32_e32 v110, v48
	v_mov_b32_e32 v111, v48
	v_mov_b32_e32 v112, v48
	v_mov_b32_e32 v113, v48
	v_mov_b32_e32 v114, v48
	v_mov_b32_e32 v115, v48
	v_mov_b32_e32 v116, v48
	v_mov_b32_e32 v117, v48
	v_mov_b32_e32 v118, v48
	v_mov_b32_e32 v119, v48
	v_mov_b32_e32 v120, v48
	v_mov_b32_e32 v121, v48
	v_mov_b32_e32 v122, v48
	v_mov_b32_e32 v123, v48
	v_mov_b32_e32 v124, v48
	v_mov_b32_e32 v125, v48
	v_mov_b32_e32 v126, v48
	v_mov_b32_e32 v127, v48
	v_mov_b32_e32 v128, v48
	v_mov_b32_e32 v129, v48
	v_mov_b32_e32 v130, v48
	v_mov_b32_e32 v131, v48
	v_mov_b32_e32 v140, v48
	v_mov_b32_e32 v141, v48
	s_waitcnt lgkmcnt(0)
	s_barrier

; DI void phase_mixers(const Params& p, int l, LAS unsigned char* lds) {
;     ...
;         while (it < e3) {
;             const int i2 = it - e2 - 20, h = i2 % 6, b = i2 / 6; const size_t rowb = (size_t)b * RB;
;             const bf16_t* P = (const bf16_t*)(ws + WS_P);
;             dense_attn_item<128>(lds, P + rowb * INP + C_NAQ + h * 128, INP, P + rowb * INP + C_NAK + h * 128, INP, nullptr,
;                                  (const bf16_t*)(ws + WS_VTNA) + ((size_t)b * 768 + h * 128) * RB, CL, 0.08838834764831845f * 1.4426950408889634f, (bf16_t*)(ws + WS_YMIX) + rowb * DM + h * 128);
;             it = next_item(ctr, slot);
;         }
.LBB0_1268:
	s_cmpk_gt_u32 s28, 0x24b
	s_cbranch_scc1 .LBB0_1176
	s_add_u32 s2, s50, 0x113a0000
	s_addc_u32 s3, s51, 0
	s_add_u32 s4, s50, 0x17fa0000
	s_addc_u32 s5, s51, 0
	v_mbcnt_hi_u32_b32 v151, -1, v203
	s_add_u32 s14, s50, 0x1d9a0000
	v_and_b32_e32 v0, 64, v151
	s_addc_u32 s15, s51, 0
	s_movk_i32 s16, 0x1200
	s_movk_i32 s17, 0xffe0
	v_mov_b32_e32 v113, 0
	s_movk_i32 s18, 0x3000
	s_movk_i32 s19, 0x110
	s_movk_i32 s20, 0x90
	v_mov_b32_e32 v143, 0x1100
	v_mov_b32_e32 v148, 0x2200
	v_mov_b32_e32 v149, 0x3300
	v_mov_b32_e32 v150, 0x1200
	s_mov_b32 s21, 0x3e0293ee
	s_mov_b64 s[0:1], 0x80
	s_mov_b64 s[6:7], 0xc0000
	s_add_i32 s22, 0, 0x22040
	s_movk_i32 s23, 0x24c
	v_xor_b32_e32 v152, 16, v151
	v_add_u32_e32 v153, 64, v0
	v_xor_b32_e32 v154, 32, v151
	s_branch .LBB0_1272

; #define LAS __attribute__((address_space(3)))
; DI int otid() { int t = threadIdx.x; asm volatile("" : "+v"(t)); return t; }
; template <int DK>
; DI void dense_attn_item(LAS unsigned char* lds, const bf16_t* Qb, int ldq, const bf16_t* Kb, int ldk, const bf16_t* Kpe, const bf16_t* Vt, int nkeys, float sl2, bf16_t* Ob) {
;     const int tid = otid(), lane = tid & 63, wid = tid >> 6, r16 = lane & 15, q4 = lane >> 4;
;     constexpr int KS = DK / 32, KCH = DK / 8, KROW = DK * 2 + 16, KTILE = 64 * KROW, VROW = 144, VTILE = 128 * VROW, NKL = (64 * KCH) / 512;
;     bf16x8 qf[2][KS];
; #pragma unroll
;     for (int qg = 0; qg < 2; ++qg)
; #pragma unroll
;         for (int ks = 0; ks < KS; ++ks) qf[qg][ks] = *(const bf16x8*)(Qb + (size_t)(wid * 32 + qg * 16 + r16) * ldq + ks * 32 + q4 * 8);
;     f32x4 oacc[2][8];
; #pragma unroll
;     for (int qg = 0; qg < 2; ++qg)
; #pragma unroll
;         for (int d = 0; d < 8; ++d) oacc[qg][d] = (f32x4){0.f, 0.f, 0.f, 0.f};
;     float mrun[2] = {-1e30f, -1e30f}, lsum[2] = {0.f, 0.f};
;     u32x4 kst[NKL], vst[2];
;     const int ntiles = nkeys >> 6;
;     ...
;     DA_LOAD(0); DA_STORE(0);
;     __syncthreads();
; DI void phase_mixers(const Params& p, int l, LAS unsigned char* lds) {
;     ...
;             const int i2 = it - e2 - 20, h = i2 % 6, b = i2 / 6; const size_t rowb = (size_t)b * RB;
;             const bf16_t* P = (const bf16_t*)(ws + WS_P);
;             dense_attn_item<128>(lds, P + rowb * INP + C_NAQ + h * 128, INP, P + rowb * INP + C_NAK + h * 128, INP, nullptr,
;                                  (const bf16_t*)(ws + WS_VTNA) + ((size_t)b * 768 + h * 128) * RB, CL, 0.08838834764831845f * 1.4426950408889634f, (bf16_t*)(ws + WS_YMIX) + rowb * DM + h * 128);
.LBB0_1272:
	v_mov_b32_e32 v6, v202
	s_add_i32 s8, s28, 0xfffffdcc
	s_mul_hi_i32 s9, s8, 0x2aaaaaab
	v_ashrrev_i32_e32 v0, 31, v6
	v_lshrrev_b32_e32 v0, 28, v0
	s_lshr_b32 s10, s9, 31
	v_add_u32_e32 v4, v6, v0
	s_add_i32 s27, s9, s10
	v_ashrrev_i32_e32 v54, 4, v4
	v_and_b32_e32 v4, -16, v4
	s_mul_i32 s9, s27, 6
	v_sub_u32_e32 v7, v6, v4
	s_sub_i32 s8, s8, s9
	s_mul_i32 s35, s27, 0x1b00000
	v_lshlrev_b32_e32 v4, 3, v7
	s_mul_hi_i32 s34, s27, 0x1b00000
	s_add_u32 s12, s2, s35
	v_ashrrev_i32_e32 v5, 31, v4
	v_add_u32_e32 v8, 0x200, v6
	s_addc_u32 s13, s3, s34
	s_lshl_b32 s10, s8, 7
	s_waitcnt vmcnt(8)
	v_lshlrev_b64 v[48:49], 1, v[4:5]
	v_ashrrev_i32_e32 v4, 31, v8
	s_ashr_i32 s11, s10, 31
	v_lshrrev_b32_e32 v4, 28, v4
	s_lshl_b64 s[8:9], s[10:11], 1
	v_add_u32_e32 v4, v8, v4
	s_add_u32 s12, s12, s8
	v_ashrrev_i32_e32 v55, 4, v4
	v_and_b32_e32 v4, -16, v4
	s_addc_u32 s13, s13, s9
	s_mul_i32 s29, s27, 0x300
	v_sub_u32_e32 v9, v8, v4
	s_mul_hi_i32 s28, s27, 0x300
	s_add_u32 s29, s29, s10
	v_lshlrev_b32_e32 v4, 3, v9
	s_addc_u32 s11, s28, s11
	v_mov_b64_e32 v[0:1], s[12:13]
	v_ashrrev_i32_e32 v5, 31, v4
	s_mulk_i32 s11, 0x1200
	s_mul_hi_u32 s28, s29, 0x1200
	v_mad_i64_i32 v[2:3], s[30:31], v54, s18, v[0:1]
	v_mad_i64_i32 v[0:1], s[30:31], v55, s18, v[0:1]
	v_lshlrev_b64 v[50:51], 1, v[4:5]
	s_add_i32 s11, s28, s11
	s_mulk_i32 s29, 0x1200
	v_lshl_add_u64 v[2:3], v[2:3], 0, v[48:49]
	v_lshl_add_u64 v[0:1], v[0:1], 0, v[50:51]
	s_add_u32 s28, s4, s29
	global_load_dwordx4 v[32:35], v[2:3], off offset:1536
	global_load_dwordx4 v[36:39], v[0:1], off offset:1536
	v_lshlrev_b32_e32 v0, 4, v6
	s_addc_u32 s29, s5, s11
	v_and_b32_e32 v52, 0x70, v0
	v_mov_b32_e32 v53, v113
	v_lshl_add_u64 v[0:1], s[28:29], 0, v[52:53]
	v_ashrrev_i32_e32 v53, 3, v6
	v_ashrrev_i32_e32 v56, 3, v8
	v_mad_i64_i32 v[2:3], s[28:29], v53, s16, v[0:1]
	v_mad_i64_i32 v[0:1], s[28:29], v56, s16, v[0:1]
	global_load_dwordx4 v[40:43], v[2:3], off
	global_load_dwordx4 v[44:47], v[0:1], off
	v_and_b32_e32 v57, 15, v6
	v_bfe_u32 v157, v6, 4, 2
	v_ashrrev_i32_e32 v0, 1, v6
	v_and_or_b32 v116, v0, s17, v57
	v_lshlrev_b32_e32 v112, 4, v157
	v_or_b32_e32 v114, 16, v116
	v_lshl_add_u64 v[0:1], s[12:13], 0, v[112:113]
	v_lshlrev_b32_e32 v166, 4, v9
	v_mad_i64_i32 v[2:3], s[12:13], v116, s18, v[0:1]
	v_mad_i64_i32 v[8:9], s[12:13], v114, s18, v[0:1]
	v_lshlrev_b32_e32 v164, 4, v7
	global_load_dwordx4 v[20:23], v[2:3], off
	global_load_dwordx4 v[16:19], v[2:3], off offset:64
	global_load_dwordx4 v[4:7], v[2:3], off offset:128
	s_nop 0
	global_load_dwordx4 v[0:3], v[2:3], off offset:192
	s_nop 0
	global_load_dwordx4 v[28:31], v[8:9], off
	global_load_dwordx4 v[24:27], v[8:9], off offset:64
	global_load_dwordx4 v[12:15], v[8:9], off offset:128
	s_nop 0
	global_load_dwordx4 v[8:11], v[8:9], off offset:192
	v_mul_lo_u32 v163, v54, s19
	v_mul_lo_u32 v160, v53, s20
	v_add_u32_e32 v161, 0, v52
	v_mul_lo_u32 v162, v56, s20
	v_mul_lo_u32 v165, v55, s19
	v_add3_u32 v59, 0, v163, v164
	v_add_u32_e32 v58, v161, v160
	v_add3_u32 v60, 0, v165, v166
	v_cmp_lt_i32_e32 vcc, v152, v153
	s_mul_i32 s12, s27, 0x360000
	s_mul_hi_i32 s11, s27, 0x360000
	s_add_u32 s12, s12, 0x17fa0080
	s_addc_u32 s13, s11, 0
	v_ashrrev_i32_e32 v117, 31, v116
	v_ashrrev_i32_e32 v115, 31, v114
	v_lshl_add_u32 v158, v157, 3, 0
	v_mul_u32_u24_e32 v167, 0x110, v57
	v_mad_u32_u24 v168, v57, s19, v143
	v_mul_u32_u24_e32 v159, 0x90, v57
	s_waitcnt vmcnt(11)
	ds_write_b128 v59, v[32:35]
	s_waitcnt vmcnt(10)
	ds_write_b128 v60, v[36:39]
	s_waitcnt vmcnt(9)
	ds_write_b128 v58, v[40:43] offset:34816
	v_add_u32_e32 v32, v161, v162
	v_mad_u32_u24 v169, v57, s19, v148
	s_waitcnt vmcnt(8)
	ds_write_b128 v32, v[44:47] offset:34816
	v_cndmask_b32_e32 v32, v151, v152, vcc
	v_cmp_lt_i32_e32 vcc, v154, v153
	v_lshlrev_b32_e32 v156, 2, v32
	v_mad_u32_u24 v170, v57, s19, v149
	v_cndmask_b32_e32 v32, v151, v154, vcc
	v_lshlrev_b32_e32 v155, 2, v32
	v_mov_b64_e32 v[32:33], s[12:13]
	v_mad_i64_i32 v[34:35], s[12:13], v53, s16, v[32:33]
	v_mad_i64_i32 v[32:33], s[12:13], v56, s16, v[32:33]
	v_mad_i64_i32 v[120:121], s[12:13], s10, v150, v[34:35]
	v_mad_i64_i32 v[122:123], s[10:11], s10, v150, v[32:33]
	s_add_u32 s10, s35, 0x11460600
	s_addc_u32 s11, s34, 0
	v_mov_b64_e32 v[32:33], s[10:11]
	v_mad_i64_i32 v[32:33], s[12:13], v55, s18, v[32:33]
	s_add_u32 s10, s8, s10
	v_lshl_add_u64 v[32:33], v[32:33], 0, v[50:51]
	s_addc_u32 s11, s9, s11
	v_lshl_add_u64 v[124:125], v[32:33], 0, s[8:9]
	v_mov_b64_e32 v[32:33], s[10:11]
	v_mad_i64_i32 v[32:33], s[10:11], v54, s18, v[32:33]
	v_or_b32_e32 v120, v120, v52
	v_or_b32_e32 v122, v122, v52
	v_lshl_add_u64 v[126:127], v[32:33], 0, v[48:49]
	v_mov_b32_e32 v134, 0xf149f2ca
	v_mov_b32_e32 v128, 0xf149f2ca
	s_mov_b32 s10, 0
	v_mov_b32_e32 v32, 0
	v_mov_b32_e32 v33, v113
	v_mov_b32_e32 v34, v113
	v_mov_b32_e32 v35, v113
	v_mov_b32_e32 v36, 0
	v_mov_b32_e32 v37, v113
	v_mov_b32_e32 v38, v113
	v_mov_b32_e32 v39, v113
	v_mov_b32_e32 v56, 0
	v_mov_b32_e32 v57, v113
	v_mov_b32_e32 v58, v113
	v_mov_b32_e32 v59, v113
	v_mov_b32_e32 v60, 0
	v_mov_b32_e32 v61, v113
	v_mov_b32_e32 v62, v113
	v_mov_b32_e32 v63, v113
	v_mov_b32_e32 v64, 0
	v_mov_b32_e32 v65, v113
	v_mov_b32_e32 v66, v113
	v_mov_b32_e32 v67, v113
	v_mov_b32_e32 v68, 0
	v_mov_b32_e32 v69, v113
	v_mov_b32_e32 v70, v113
	v_mov_b32_e32 v71, v113
	v_mov_b32_e32 v72, 0
	v_mov_b32_e32 v73, v113
	v_mov_b32_e32 v74, v113
	v_mov_b32_e32 v75, v113
	v_mov_b32_e32 v76, 0
	v_mov_b32_e32 v77, v113
	v_mov_b32_e32 v78, v113
	v_mov_b32_e32 v79, v113
	v_mov_b32_e32 v80, 0
	v_mov_b32_e32 v81, v113
	v_mov_b32_e32 v82, v113
	v_mov_b32_e32 v83, v113
	v_mov_b32_e32 v84, 0
	v_mov_b32_e32 v85, v113
	v_mov_b32_e32 v86, v113
	v_mov_b32_e32 v87, v113
	v_mov_b32_e32 v88, 0
	v_mov_b32_e32 v89, v113
	v_mov_b32_e32 v90, v113
	v_mov_b32_e32 v91, v113
	v_mov_b32_e32 v92, 0
	v_mov_b32_e32 v93, v113
	v_mov_b32_e32 v94, v113
	v_mov_b32_e32 v95, v113
	v_mov_b32_e32 v96, 0
	v_mov_b32_e32 v97, v113
	v_mov_b32_e32 v98, v113
	v_mov_b32_e32 v99, v113
	v_mov_b32_e32 v100, 0
	v_mov_b32_e32 v101, v113
	v_mov_b32_e32 v102, v113
	v_mov_b32_e32 v103, v113
	v_mov_b32_e32 v104, 0
	v_mov_b32_e32 v105, v113
	v_mov_b32_e32 v106, v113
	v_mov_b32_e32 v107, v113
	v_mov_b32_e32 v108, 0
	v_mov_b32_e32 v109, v113
	v_mov_b32_e32 v110, v113
	v_mov_b32_e32 v111, v113
	v_mov_b32_e32 v118, 0
	v_mov_b32_e32 v119, v113
	s_waitcnt lgkmcnt(0)
	s_barrier

; DI void phase_mixers(const Params& p, int l, LAS unsigned char* lds) {
;     ...
;     int it = next_item(ctr, slot);
;     while (it < e0) { dense192_item(ws, lds, it / 40, (it >> 3) % 5, CL + (it & 7) * 256, RB); it = next_item(ctr, slot); }
;     while (it < e1) { const int i2 = it - e0, c = (i2 % nc) + (18 - nc), bh = i2 / nc; ret_out_item(p, l, bh / 5, bh % 5, c, lds); it = next_item(ctr, slot); }
.LBB0_2623:
	s_cmpk_gt_u32 s0, 0x35f
	s_movk_i32 s6, 0x35f
	s_cbranch_scc1 .LBB0_2681
	s_add_u32 s2, s50, 0x113a0000
	v_mbcnt_hi_u32_b32 v87, -1, v203
	s_addc_u32 s3, s51, 0
	v_and_b32_e32 v0, 64, v87
	v_mov_b32_e32 v69, 0
	s_mov_b32 s7, 0xc2fc0000
	v_mov_b32_e32 v82, 0x42800000
	s_mov_b32 s18, 0x3f2aaaab
	v_mov_b32_e32 v83, 0x3ecc95a3
	s_mov_b32 s19, 0x3f317218
	v_mov_b32_e32 v84, 0x7fc00000
	v_mov_b32_e32 v85, 0xff800000
	s_mov_b32 s20, 0x33800000
	s_movk_i32 s21, 0x3000
	s_movk_i32 s22, 0x1200
	s_mov_b64 s[4:5], 0x1f80
	s_add_i32 s23, 0, 0x11000
	s_add_i32 s27, 0, 0x19800
	s_movk_i32 s30, 0x110
	v_not_b32_e32 v86, 63
	v_mov_b64_e32 v[70:71], s[2:3]
	s_mov_b64 s[8:9], 0x1a80
	s_movk_i32 s31, 0x1000
	v_xor_b32_e32 v88, 16, v87
	v_add_u32_e32 v89, 64, v0
	v_xor_b32_e32 v90, 32, v87
	v_mov_b32_e32 v91, 0x3727c5ac
	s_mov_b32 s36, 0x800000
	s_mov_b64 s[10:11], 0x2980
	s_mov_b64 s[12:13], 0x1d9a0b00
	s_movk_i32 s37, 0x2000
	s_mov_b32 s54, 0x1d9a0000
	s_add_i32 s56, 0, 0x22040
	v_mov_b32_e32 v72, 0x3f317218
	s_branch .LBB0_2627

; #define LAS __attribute__((address_space(3)))
; DI int otid() { int t = threadIdx.x; asm volatile("" : "+v"(t)); return t; }
; DI float ret_lg2(const Params& p, int l, int dir, int h) { return log1pf(-exp2f(p.in[12][(l * 2 + dir) * 5 + h])) * 1.4426950408889634f; }
; DI void ret_out_item(const Params& p, int l, int b, int h, int c, LAS unsigned char* lds) {
;     const int tid = otid(), lane = tid & 63, wid = tid >> 6, r16 = lane & 15, q4 = lane >> 4;
;     unsigned char* ws = p.ws;
;     const bf16_t* P = (const bf16_t*)(ws + WS_P);
;     const float lgf = ret_lg2(p, l, 0, h), lgb = ret_lg2(p, l, 1, h);
;     const size_t rowb = (size_t)b * RB; const int tok0 = c * 128, tl = wid * 16 + r16;
.LBB0_2627:
	s_addk_i32 s0, 0xfde0
	s_ashr_i32 s1, s0, 31
	s_lshr_b32 s1, s1, 28
	s_add_i32 s1, s0, s1
	s_ashr_i32 s14, s1, 4
	s_and_b32 s1, s1, -16
	s_sub_i32 s17, s0, s1
	s_mul_hi_i32 s0, s0, 0x66666667
	s_lshr_b32 s1, s0, 31
	s_ashr_i32 s16, s0, 5
	s_mul_hi_i32 s0, s14, 0x66666667
	s_add_i32 s16, s16, s1
	s_lshr_b32 s1, s0, 31
	s_ashr_i32 s0, s0, 1
	s_add_i32 s0, s0, s1
	s_mul_i32 s0, s0, 5
	s_sub_i32 s14, s14, s0
	s_ashr_i32 s15, s14, 31
	s_add_i32 s17, s17, 2
	s_lshl_b64 s[0:1], s[14:15], 2
	s_add_u32 s0, s60, s0
	v_mov_b32_e32 v16, v202
	s_addc_u32 s1, s61, s1
	global_load_dword v0, v69, s[0:1] offset:40
	global_load_dword v1, v69, s[0:1] offset:60
	v_bfe_u32 v92, v16, 4, 2
	s_waitcnt vmcnt(1)
	v_cmp_gt_f32_e32 vcc, s7, v0
	s_nop 1
	v_cndmask_b32_e32 v2, 0, v82, vcc
	s_waitcnt vmcnt(0)
	v_cmp_gt_f32_e64 s[0:1], s7, v1
	v_add_f32_e32 v0, v0, v2
	v_exp_f32_e32 v0, v0
	v_cndmask_b32_e64 v3, 0, v82, s[0:1]
	v_add_f32_e32 v1, v1, v3
	s_and_b64 s[28:29], vcc, exec
	v_exp_f32_e32 v1, v1
	s_cselect_b32 s15, 0xffffffc0, 0
	s_and_b64 s[0:1], s[0:1], exec
	v_ldexp_f32 v15, v0, s15
	s_cselect_b32 s0, 0xffffffc0, 0
	v_sub_f32_e32 v4, 1.0, v15
	v_ldexp_f32 v14, v1, s0
	v_frexp_mant_f32_e32 v7, v4
	v_cvt_f64_f32_e32 v[0:1], v4
	v_sub_f32_e32 v5, 1.0, v14
	v_add_f32_e32 v6, -1.0, v4
	v_frexp_exp_i32_f64_e32 v0, v[0:1]
	v_cmp_gt_f32_e32 vcc, s18, v7
	v_add_f32_e32 v8, -1.0, v5
	v_frexp_mant_f32_e32 v9, v5
	v_cvt_f64_f32_e32 v[2:3], v5
	v_sub_f32_e32 v10, v6, v4
	v_subbrev_co_u32_e32 v0, vcc, 0, v0, vcc
	v_sub_f32_e64 v6, -v15, v6
	v_sub_f32_e32 v1, v8, v5
	v_frexp_exp_i32_f64_e32 v2, v[2:3]
	v_add_f32_e32 v3, 1.0, v10
	v_cmp_gt_f32_e32 vcc, s18, v9
	v_sub_f32_e64 v8, -v14, v8
	v_add_f32_e32 v1, 1.0, v1
	v_subbrev_co_u32_e32 v17, vcc, 0, v2, vcc
	v_add_f32_e32 v2, v6, v3
	v_sub_u32_e32 v3, 0, v0
	v_add_f32_e32 v1, v8, v1
	v_sub_u32_e32 v6, 0, v17
	v_ldexp_f32 v4, v4, v3
	v_ldexp_f32 v20, v5, v6
	v_ldexp_f32 v21, v1, v6
	v_add_f32_e32 v1, -1.0, v4
	v_add_f32_e32 v5, 1.0, v4
	v_ldexp_f32 v2, v2, v3
	v_add_f32_e32 v3, 1.0, v1
	v_add_f32_e32 v6, -1.0, v5
	v_sub_f32_e32 v3, v4, v3
	v_sub_f32_e32 v4, v4, v6
	v_add_f32_e32 v6, v2, v3
	v_add_f32_e32 v2, v2, v4
	v_add_f32_e32 v8, v5, v2
	v_rcp_f32_e32 v9, v8
	v_add_f32_e32 v3, v1, v6
	v_sub_f32_e32 v4, v8, v5
	v_sub_f32_e32 v1, v3, v1
	v_mul_f32_e32 v11, v3, v9
	v_sub_f32_e32 v10, v2, v4
	v_mul_f32_e32 v4, v8, v11
	v_sub_f32_e32 v1, v6, v1
	v_fma_f32 v6, v11, v8, -v4
	v_fmac_f32_e32 v6, v11, v10
	v_add_f32_e32 v2, v4, v6
	v_sub_f32_e32 v5, v3, v2
	v_mov_b32_e32 v7, v2
	v_pk_add_f32 v[2:3], v[2:3], v[4:5] neg_lo:[0,1] neg_hi:[0,1]
	v_cvt_f32_i32_e32 v0, v0
	v_pk_add_f32 v[2:3], v[2:3], v[6:7] neg_lo:[0,1] neg_hi:[0,1]
	v_cmp_nlt_f32_e32 vcc, 1.0, v15
	v_add_f32_e32 v1, v1, v3
	v_add_f32_e32 v1, v2, v1
	v_add_f32_e32 v3, v5, v1
	v_mul_f32_e32 v2, v9, v3
	v_mul_f32_e32 v4, v8, v2
	v_sub_f32_e32 v5, v5, v3
	v_add_f32_e32 v12, v11, v2
	v_fma_f32 v6, v2, v8, -v4
	v_add_f32_e32 v1, v1, v5
	v_sub_f32_e32 v5, v12, v11
	v_fmac_f32_e32 v6, v2, v10
	v_sub_f32_e32 v8, v2, v5
	v_add_f32_e32 v2, v4, v6
	v_sub_f32_e32 v5, v3, v2
	v_mov_b32_e32 v7, v2
	v_pk_add_f32 v[2:3], v[2:3], v[4:5] neg_lo:[0,1] neg_hi:[0,1]
	v_add_f32_e32 v22, -1.0, v20
	v_pk_add_f32 v[2:3], v[2:3], v[6:7] neg_lo:[0,1] neg_hi:[0,1]
	v_cmp_lt_f32_e64 s[0:1], |v15|, s20
	v_add_f32_e32 v1, v1, v3
	v_add_f32_e32 v1, v2, v1
	v_add_f32_e32 v1, v5, v1
	v_mul_f32_e32 v1, v9, v1
	v_add_f32_e32 v1, v8, v1
	v_add_f32_e32 v2, v12, v1
	v_mul_f32_e32 v4, v2, v2
	v_sub_f32_e32 v5, v2, v12
	v_fmamk_f32 v6, v4, 0x3e9b6dac, v83
	v_sub_f32_e32 v5, v1, v5
	v_mul_f32_e32 v1, v2, v4
	v_fmaak_f32 v73, v4, v6, 0x3f2aaada
	v_ldexp_f32 v7, v5, 1
	v_pk_mul_f32 v[4:5], v[0:1], v[72:73]
	v_ldexp_f32 v3, v2, 1
	v_fma_f32 v2, v0, s19, -v4
	v_fmac_f32_e32 v2, 0xb102e308, v0
	v_pk_add_f32 v[0:1], v[4:5], v[2:3]
	v_mov_b32_e32 v6, v4
	v_sub_f32_e32 v10, v1, v3
	v_pk_add_f32 v[8:9], v[0:1], v[4:5] neg_lo:[0,1] neg_hi:[0,1]
	v_sub_f32_e32 v5, v5, v10
	v_add_f32_e32 v7, v7, v5
	v_pk_add_f32 v[12:13], v[0:1], v[6:7]
	v_mov_b32_e32 v3, v0
	v_mov_b32_e32 v9, v13
	v_pk_add_f32 v[18:19], v[2:3], v[8:9] neg_lo:[0,1] neg_hi:[0,1]
	v_pk_add_f32 v[2:3], v[2:3], v[8:9]
	v_mov_b32_e32 v4, v1
	v_mov_b32_e32 v11, v0
	v_pk_add_f32 v[0:1], v[2:3], v[0:1] op_sel:[1,0] op_sel_hi:[0,1] neg_lo:[0,1] neg_hi:[0,1]
	v_mov_b32_e32 v10, v7
	v_mov_b32_e32 v6, v13
	v_mov_b32_e32 v7, v3
	v_mov_b32_e32 v5, v0
	v_pk_add_f32 v[8:9], v[12:13], v[0:1] op_sel_hi:[1,0] neg_lo:[0,1] neg_hi:[0,1]
	v_pk_add_f32 v[0:1], v[6:7], v[4:5] neg_lo:[0,1] neg_hi:[0,1]
	v_mov_b32_e32 v8, v18
	v_pk_add_f32 v[0:1], v[10:11], v[0:1] neg_lo:[0,1] neg_hi:[0,1]
	v_mov_b32_e32 v19, v3
	v_pk_add_f32 v[4:5], v[8:9], v[0:1]
	s_lshl_b32 s28, s17, 7
	v_pk_add_f32 v[6:7], v[4:5], v[4:5] op_sel:[0,1] op_sel_hi:[1,0]
	s_ashr_i32 s29, s28, 31
	v_pk_add_f32 v[2:3], v[2:3], v[6:7] op_sel:[1,0] op_sel_hi:[0,1]
	v_mov_b32_e32 v5, v2
	v_mov_b32_e32 v1, v6
	v_pk_add_f32 v[6:7], v[4:5], v[18:19] neg_lo:[0,1] neg_hi:[0,1]
	s_mul_i32 s15, s16, 5
	v_sub_f32_e32 v3, v4, v6
	v_pk_add_f32 v[0:1], v[0:1], v[6:7] neg_lo:[0,1] neg_hi:[0,1]
	v_sub_f32_e32 v3, v18, v3
	v_add_f32_e32 v0, v0, v3
	v_add_f32_e32 v0, v0, v1
	v_add_f32_e32 v1, 1.0, v20
	v_add_f32_e32 v0, v2, v0
	v_add_f32_e32 v2, -1.0, v1
	v_sub_f32_e32 v2, v20, v2
	v_cndmask_b32_e32 v0, v84, v0, vcc
	v_cmp_neq_f32_e32 vcc, 1.0, v15
	v_add_f32_e32 v2, v21, v2
	v_add_f32_e32 v8, v1, v2
	v_cndmask_b32_e32 v0, v85, v0, vcc
	v_cndmask_b32_e64 v15, v0, -v15, s[0:1]
	v_add_f32_e32 v0, 1.0, v22
	v_rcp_f32_e32 v10, v8
	v_sub_f32_e32 v0, v20, v0
	v_add_f32_e32 v0, v21, v0
	v_sub_f32_e32 v1, v8, v1
	v_sub_f32_e32 v9, v2, v1
; #define LAS __attribute__((address_space(3)))
; DI int otid() { int t = threadIdx.x; asm volatile("" : "+v"(t)); return t; }
; DI float ret_lg2(const Params& p, int l, int dir, int h) { return log1pf(-exp2f(p.in[12][(l * 2 + dir) * 5 + h])) * 1.4426950408889634f; }
; DI void ret_out_item(const Params& p, int l, int b, int h, int c, LAS unsigned char* lds) {
;     const int tid = otid(), lane = tid & 63, wid = tid >> 6, r16 = lane & 15, q4 = lane >> 4;
;     unsigned char* ws = p.ws;
;     const bf16_t* P = (const bf16_t*)(ws + WS_P);
;     const float lgf = ret_lg2(p, l, 0, h), lgb = ret_lg2(p, l, 1, h);
;     const size_t rowb = (size_t)b * RB; const int tok0 = c * 128, tl = wid * 16 + r16;
;     const size_t row = rowb + tok0 + tl;
;     constexpr int RS = 272, MB = 128 * RS;
;     {
;         const bf16_t* Sf = (const bf16_t*)(ws + WS_S) + ((size_t)((b * 5 + h) * 2 + 0) * 18 + c) * 16384;
;         const bf16_t* Sb = (const bf16_t*)(ws + WS_S) + ((size_t)((b * 5 + h) * 2 + 1) * 18 + c) * 16384;
;         const bf16_t* Kc = P + (rowb + tok0) * INP + C_RK + h * 128;
;         const bf16_t* Vc = (const bf16_t*)(ws + WS_VTR) + ((size_t)b * 640 + h * 128) * RB + tok0;
;         u32x4 t0[4], t1[4], t2[4], t3[4];
; #pragma unroll
;         for (int i = 0; i < 4; ++i) {
;             const int cid = tid + i * 512, rr = cid >> 4, cc = cid & 15;
;             t0[i] = *(const u32x4*)(Sf + rr * 128 + cc * 8); t1[i] = *(const u32x4*)(Sb + rr * 128 + cc * 8);
;             t2[i] = *(const u32x4*)(Kc + (size_t)rr * INP + cc * 8); t3[i] = *(const u32x4*)(Vc + (size_t)rr * RB + cc * 8);
;         }
	v_add_f32_e32 v1, v22, v0
	v_sub_f32_e32 v2, v1, v22
	v_mul_f32_e32 v12, v1, v10
	v_sub_f32_e32 v11, v0, v2
	v_mul_f32_e32 v2, v8, v12
	v_fma_f32 v4, v12, v8, -v2
	v_fmac_f32_e32 v4, v12, v9
	v_add_f32_e32 v0, v2, v4
	v_sub_f32_e32 v3, v1, v0
	v_pk_add_f32 v[6:7], v[0:1], v[2:3] neg_lo:[0,1] neg_hi:[0,1]
	v_mov_b32_e32 v5, v0
	v_pk_add_f32 v[0:1], v[6:7], v[4:5] neg_lo:[0,1] neg_hi:[0,1]
	s_mul_i32 s0, s16, 0x900
	v_add_f32_e32 v1, v11, v1
	v_add_f32_e32 v0, v0, v1
	v_add_f32_e32 v1, v3, v0
	v_mul_f32_e32 v11, v10, v1
	v_mul_f32_e32 v2, v8, v11
	v_fma_f32 v4, v11, v8, -v2
	v_fmac_f32_e32 v4, v11, v9
	v_sub_f32_e32 v3, v3, v1
	v_add_f32_e32 v8, v0, v3
	v_add_f32_e32 v0, v2, v4
	v_sub_f32_e32 v3, v1, v0
	v_pk_add_f32 v[6:7], v[0:1], v[2:3] neg_lo:[0,1] neg_hi:[0,1]
	v_mov_b32_e32 v5, v0
	v_pk_add_f32 v[0:1], v[6:7], v[4:5] neg_lo:[0,1] neg_hi:[0,1]
	s_mul_hi_i32 s1, s16, 0x900
	v_add_f32_e32 v1, v8, v1
	v_add_f32_e32 v0, v0, v1
	v_add_f32_e32 v1, v12, v11
	s_add_u32 s0, s0, s28
	v_add_f32_e32 v0, v3, v0
	v_sub_f32_e32 v2, v1, v12
	s_addc_u32 s1, s1, s29
	s_add_i32 s15, s15, s14
	v_mul_f32_e32 v0, v10, v0
	v_sub_f32_e32 v2, v11, v2
	s_lshl_b32 s57, s15, 1
	s_mul_i32 s15, s15, 36
	s_ashr_i32 s63, s17, 31
	v_add_f32_e32 v2, v2, v0
	s_mul_hi_i32 s43, s57, 18
	s_add_u32 s42, s15, s17
	v_add_f32_e32 v4, v1, v2
	s_addc_u32 s43, s43, s63
	v_mul_f32_e32 v5, v4, v4
	s_lshl_b64 s[42:43], s[42:43], 15
	v_fmamk_f32 v0, v5, 0x3e9b6dac, v83
	s_add_u32 s42, s92, s42
	v_fmaak_f32 v73, v5, v0, 0x3f2aaada
	v_cvt_f32_i32_e32 v0, v17
	s_addc_u32 s43, s93, s43
	s_or_b32 s15, s57, 1
	v_sub_f32_e32 v1, v4, v1
	s_mul_hi_i32 s57, s15, 18
	s_mul_i32 s15, s15, 18
	v_sub_f32_e32 v1, v2, v1
	s_add_u32 s62, s15, s17
	v_ldexp_f32 v8, v1, 1
	v_mul_f32_e32 v1, v4, v5
	s_addc_u32 s63, s57, s63
	v_pk_mul_f32 v[6:7], v[0:1], v[72:73]
	s_lshl_b64 s[62:63], s[62:63], 15
	v_fma_f32 v2, v0, s19, -v6
	s_add_u32 s62, s92, s62
	s_mul_i32 s15, s1, 0x3000
	s_mul_hi_u32 s17, s0, 0x3000
	v_ldexp_f32 v3, v4, 1
	v_fmac_f32_e32 v2, 0xb102e308, v0
	s_addc_u32 s63, s93, s63
	s_add_i32 s17, s17, s15
	s_mul_i32 s15, s0, 0x3000
	v_pk_add_f32 v[4:5], v[6:7], v[2:3]
	s_add_u32 s57, s2, s15
	v_sub_f32_e32 v0, v5, v3
	s_addc_u32 s17, s3, s17
	s_lshl_b32 s68, s14, 7
	v_sub_f32_e32 v0, v7, v0
	s_ashr_i32 s69, s68, 31
	v_add_f32_e32 v9, v8, v0
	v_mov_b32_e32 v8, v6
	s_lshl_b64 s[14:15], s[68:69], 1
	v_pk_add_f32 v[0:1], v[4:5], v[6:7] neg_lo:[0,1] neg_hi:[0,1]
	v_pk_add_f32 v[66:67], v[4:5], v[8:9]
	s_add_u32 s70, s57, s14
	v_mov_b32_e32 v1, v67
	v_mov_b32_e32 v3, v4
	s_addc_u32 s71, s17, s15
	s_mul_hi_i32 s17, s16, 0x280
	s_mulk_i32 s16, 0x280
	v_pk_add_f32 v[10:11], v[2:3], v[0:1]
	s_add_u32 s16, s16, s68
	v_pk_add_f32 v[6:7], v[2:3], v[0:1] neg_lo:[0,1] neg_hi:[0,1]
	v_pk_add_f32 v[0:1], v[10:11], v[4:5] op_sel:[1,0] op_sel_hi:[0,1] neg_lo:[0,1] neg_hi:[0,1]
	s_addc_u32 s17, s17, s69
	v_pk_add_f32 v[12:13], v[66:67], v[0:1] op_sel_hi:[1,0] neg_lo:[0,1] neg_hi:[0,1]
	s_mulk_i32 s17, 0x1200
	s_mul_hi_u32 s57, s16, 0x1200
	v_lshlrev_b32_e32 v1, 4, v16
	s_add_i32 s57, s57, s17
	s_mulk_i32 s16, 0x1200
	v_and_b32_e32 v68, 0xf0, v1
	s_add_u32 s68, s87, s16
	v_lshl_add_u64 v[18:19], s[70:71], 0, v[68:69]
	v_ashrrev_i32_e32 v17, 4, v16
	s_addc_u32 s57, s91, s57
	s_lshl_b64 s[16:17], s[28:29], 1
	v_lshl_add_u64 v[76:77], v[18:19], 0, s[4:5]
	v_lshlrev_b32_e32 v18, 7, v17
	s_add_u32 s16, s68, s16
	v_ashrrev_i32_e32 v19, 31, v18
	v_add_u32_e32 v1, 0x200, v16
	s_addc_u32 s17, s57, s17
	v_lshl_add_u64 v[2:3], s[42:43], 0, v[68:69]
	v_lshl_add_u64 v[74:75], s[62:63], 0, v[68:69]
	v_lshlrev_b64 v[18:19], 1, v[18:19]
	v_ashrrev_i32_e32 v73, 4, v1
	v_lshl_add_u64 v[78:79], s[16:17], 0, v[68:69]
	v_lshl_add_u64 v[20:21], v[2:3], 0, v[18:19]
	v_lshl_add_u64 v[22:23], v[74:75], 0, v[18:19]
	v_lshlrev_b32_e32 v34, 7, v73
	global_load_dwordx4 v[18:21], v[20:21], off
	s_nop 0
	global_load_dwordx4 v[22:25], v[22:23], off
	v_mad_i64_i32 v[26:27], s[16:17], v17, s21, v[76:77]
	v_mad_i64_i32 v[30:31], s[16:17], v17, s22, v[78:79]
	v_ashrrev_i32_e32 v35, 31, v34
	v_add_u32_e32 v1, 0x400, v16
	global_load_dwordx4 v[26:29], v[26:27], off
	s_nop 0
	global_load_dwordx4 v[30:33], v[30:31], off
	v_lshlrev_b64 v[34:35], 1, v[34:35]
	v_ashrrev_i32_e32 v93, 4, v1
	v_lshl_add_u64 v[36:37], v[2:3], 0, v[34:35]
	v_lshl_add_u64 v[38:39], v[74:75], 0, v[34:35]
	v_lshlrev_b32_e32 v50, 7, v93
	global_load_dwordx4 v[34:37], v[36:37], off
	s_nop 0
	global_load_dwordx4 v[38:41], v[38:39], off
	v_mad_i64_i32 v[42:43], s[16:17], v73, s21, v[76:77]
	v_mad_i64_i32 v[46:47], s[16:17], v73, s22, v[78:79]
	v_ashrrev_i32_e32 v51, 31, v50
	v_add_u32_e32 v1, 0x600, v16
	global_load_dwordx4 v[42:45], v[42:43], off
	s_nop 0
	global_load_dwordx4 v[46:49], v[46:47], off
	v_lshlrev_b64 v[50:51], 1, v[50:51]
	v_ashrrev_i32_e32 v114, 4, v1
	v_lshl_add_u64 v[52:53], v[2:3], 0, v[50:51]
	v_lshl_add_u64 v[54:55], v[74:75], 0, v[50:51]
	v_lshlrev_b32_e32 v80, 7, v114
	global_load_dwordx4 v[50:53], v[52:53], off
	s_nop 0
	global_load_dwordx4 v[54:57], v[54:55], off
	v_mad_i64_i32 v[58:59], s[16:17], v93, s21, v[76:77]
	v_mad_i64_i32 v[62:63], s[16:17], v93, s22, v[78:79]
	v_ashrrev_i32_e32 v81, 31, v80
	global_load_dwordx4 v[58:61], v[58:59], off
	s_nop 0
	global_load_dwordx4 v[62:65], v[62:63], off
	v_lshlrev_b64 v[80:81], 1, v[80:81]
	v_lshl_add_u64 v[2:3], v[2:3], 0, v[80:81]
	v_lshl_add_u64 v[74:75], v[74:75], 0, v[80:81]
	global_load_dwordx4 v[94:97], v[2:3], off
	global_load_dwordx4 v[98:101], v[74:75], off
	v_mad_i64_i32 v[2:3], s[16:17], v114, s21, v[76:77]
	global_load_dwordx4 v[102:105], v[2:3], off
	v_mad_i64_i32 v[2:3], s[16:17], v114, s22, v[78:79]
; #define LAS __attribute__((address_space(3)))
; DI void ret_out_item(const Params& p, int l, int b, int h, int c, LAS unsigned char* lds) {
;     ...
;         u32x4 t0[4], t1[4], t2[4], t3[4];
; #pragma unroll
;         for (int i = 0; i < 4; ++i) {
;             const int cid = tid + i * 512, rr = cid >> 4, cc = cid & 15;
;             t0[i] = *(const u32x4*)(Sf + rr * 128 + cc * 8); t1[i] = *(const u32x4*)(Sb + rr * 128 + cc * 8);
;             t2[i] = *(const u32x4*)(Kc + (size_t)rr * INP + cc * 8); t3[i] = *(const u32x4*)(Vc + (size_t)rr * RB + cc * 8);
;         }
; #pragma unroll
;         for (int i = 0; i < 4; ++i) {
;             const int cid = tid + i * 512, rr = cid >> 4, cc = cid & 15;
;             *(LAS u32x4*)(lds + 0 * MB + rr * RS + cc * 16) = t0[i]; *(LAS u32x4*)(lds + 1 * MB + rr * RS + cc * 16) = t1[i];
;             *(LAS u32x4*)(lds + 2 * MB + rr * RS + cc * 16) = t2[i]; *(LAS u32x4*)(lds + 3 * MB + rr * RS + cc * 16) = t3[i];
;         }
;     }
;     bf16x8 qf[4], qff[4], qfb[4];
;     const float qdf = exp2f(lgf * (float)(tl + 1)), qdb = exp2f(lgb * (float)(128 - tl));
; #pragma unroll
;     for (int ks = 0; ks < 4; ++ks) { qf[ks] = *(const bf16x8*)(P + row * INP + C_RQ + h * 128 + ks * 32 + q4 * 8); qff[ks] = scale1_bf16x8(qf[ks], qdf); qfb[ks] = scale1_bf16x8(qf[ks], qdb); }
	v_mov_b32_e32 v111, v0
	v_ashrrev_i32_e32 v0, 2, v16
	global_load_dwordx4 v[106:109], v[2:3], off
	v_bfi_b32 v78, -16, v0, v16
	v_ashrrev_i32_e32 v79, 31, v78
	v_lshl_add_u64 v[74:75], s[0:1], 0, v[78:79]
	v_mad_u64_u32 v[0:1], s[0:1], v74, s21, v[70:71]
	v_mad_i32_i24 v1, v75, s21, v1
	v_lshlrev_b32_e32 v80, 4, v92
	v_mov_b32_e32 v81, v69
	v_lshl_add_u64 v[76:77], v[0:1], 0, s[14:15]
	v_lshl_add_u64 v[112:113], v[76:77], 0, v[80:81]
	v_add_co_u32_e32 v0, vcc, s31, v112
	v_mov_b32_e32 v66, v67
	s_nop 0
	v_addc_co_u32_e32 v1, vcc, 0, v113, vcc
	global_load_dwordx4 v[120:123], v[0:1], off offset:2752
	global_load_dwordx4 v[124:127], v[0:1], off offset:2816
	global_load_dwordx4 v[128:131], v[0:1], off offset:2880
	global_load_dwordx4 v[0:3], v[0:1], off offset:2688
	v_mov_b32_e32 v67, v11
	v_mov_b32_e32 v110, v5
	v_pk_add_f32 v[66:67], v[66:67], v[110:111] neg_lo:[0,1] neg_hi:[0,1]
	v_mov_b32_e32 v8, v9
	v_mov_b32_e32 v9, v4
	v_pk_add_f32 v[4:5], v[8:9], v[66:67] neg_lo:[0,1] neg_hi:[0,1]
	v_mov_b32_e32 v12, v6
	v_pk_add_f32 v[8:9], v[12:13], v[4:5]
	v_mov_b32_e32 v7, v11
	v_pk_add_f32 v[12:13], v[8:9], v[8:9] op_sel:[0,1] op_sel_hi:[1,0]
	v_cmp_nlt_f32_e32 vcc, 1.0, v14
	v_pk_add_f32 v[10:11], v[10:11], v[12:13] op_sel:[1,0] op_sel_hi:[0,1]
	v_mov_b32_e32 v9, v10
	v_pk_add_f32 v[66:67], v[8:9], v[6:7] neg_lo:[0,1] neg_hi:[0,1]
	v_mov_b32_e32 v5, v12
	v_sub_f32_e32 v7, v8, v66
	v_pk_add_f32 v[4:5], v[4:5], v[66:67] neg_lo:[0,1] neg_hi:[0,1]
	v_sub_f32_e32 v6, v6, v7
	v_add_f32_e32 v4, v4, v6
	v_add_f32_e32 v4, v4, v5
	v_add_u32_e32 v5, 0, v68
	v_mul_lo_u32 v8, v17, s30
	v_add_u32_e32 v6, s23, v68
	v_add_u32_e32 v7, s27, v68
	v_add_u32_e32 v9, v5, v8
	s_waitcnt vmcnt(19)
	ds_write_b128 v9, v[18:21]
	s_waitcnt vmcnt(18)
	ds_write_b128 v9, v[22:25] offset:34816
	v_add_u32_e32 v9, v6, v8
	v_add_u32_e32 v8, v7, v8
	s_waitcnt vmcnt(16)
	ds_write_b128 v8, v[30:33]
	v_mul_lo_u32 v8, v73, s30
	ds_write_b128 v9, v[26:29]
	v_add_u32_e32 v9, v5, v8
	s_waitcnt vmcnt(15)
	ds_write_b128 v9, v[34:37]
	s_waitcnt vmcnt(14)
	ds_write_b128 v9, v[38:41] offset:34816
	v_add_u32_e32 v9, v6, v8
	v_add_u32_e32 v8, v7, v8
	v_add_f32_e32 v4, v10, v4
	v_cndmask_b32_e32 v4, v84, v4, vcc
	v_cmp_neq_f32_e32 vcc, 1.0, v14
	s_waitcnt vmcnt(13)
	ds_write_b128 v9, v[42:45]
	s_waitcnt vmcnt(12)
	ds_write_b128 v8, v[46:49]
	v_mul_lo_u32 v8, v93, s30
	v_add_u32_e32 v9, v5, v8
	s_waitcnt vmcnt(11)
	ds_write_b128 v9, v[50:53]
	s_waitcnt vmcnt(10)
	ds_write_b128 v9, v[54:57] offset:34816
	v_add_u32_e32 v9, v6, v8
	v_add_u32_e32 v8, v7, v8
	v_cndmask_b32_e32 v4, v85, v4, vcc
	v_cmp_lt_f32_e64 s[0:1], |v14|, s20
	s_waitcnt vmcnt(9)
	ds_write_b128 v9, v[58:61]
	s_waitcnt vmcnt(8)
	ds_write_b128 v8, v[62:65]
	v_mul_lo_u32 v8, v114, s30
	v_add_u32_e32 v5, v5, v8
	s_waitcnt vmcnt(7)
	ds_write_b128 v5, v[94:97]
	s_waitcnt vmcnt(6)
	ds_write_b128 v5, v[98:101] offset:34816
	v_add_u32_e32 v5, v6, v8
	v_add_u32_e32 v6, v7, v8
	s_waitcnt vmcnt(5)
	ds_write_b128 v5, v[102:105]
	v_add_u32_e32 v5, 1, v78
	v_cvt_f32_i32_e32 v5, v5
	v_sub_u32_e32 v7, 0x80, v78
	v_cvt_f32_i32_e32 v7, v7
	v_cndmask_b32_e64 v4, v4, -v14, s[0:1]
	v_mul_f32_e32 v79, 0x3fb8aa3b, v15
	s_waitcnt vmcnt(4)
	ds_write_b128 v6, v[106:109]
	v_mul_f32_e32 v6, v79, v5
	v_mul_f32_e32 v73, 0xbfb8aa3b, v4
	v_cmp_gt_f32_e32 vcc, s7, v6
	v_mul_f32_e64 v4, -v73, v7
	v_cmp_gt_f32_e64 s[0:1], s7, v4
	v_cndmask_b32_e32 v6, 0, v82, vcc
	v_fmac_f32_e32 v6, v79, v5
	v_cndmask_b32_e64 v4, 0, v82, s[0:1]
	v_exp_f32_e32 v5, v6
	v_fma_f32 v4, -v73, v7, v4
	v_exp_f32_e32 v4, v4
	v_cndmask_b32_e32 v6, 0, v86, vcc
	v_ldexp_f32 v17, v5, v6
	v_cndmask_b32_e64 v5, 0, v86, s[0:1]
	v_ldexp_f32 v19, v4, v5
	s_waitcnt vmcnt(0)
	v_lshlrev_b32_e32 v4, 16, v0
	v_mul_f32_e32 v5, v17, v4
	v_and_b32_e32 v6, 0xffff0000, v0
	v_mul_f32_e32 v7, v17, v6
	v_cvt_pk_bf16_f32 v48, v5, v7
	v_lshlrev_b32_e32 v5, 16, v1
	v_mul_f32_e32 v7, v17, v5
	v_and_b32_e32 v8, 0xffff0000, v1
	v_mul_f32_e32 v9, v17, v8
	v_cvt_pk_bf16_f32 v49, v7, v9
	v_lshlrev_b32_e32 v7, 16, v2
	v_mul_f32_e32 v9, v17, v7
	v_and_b32_e32 v10, 0xffff0000, v2
	v_mul_f32_e32 v11, v17, v10
	v_cvt_pk_bf16_f32 v50, v9, v11
	v_lshlrev_b32_e32 v9, 16, v3
	v_and_b32_e32 v14, 0xffff0000, v3
	v_mul_f32_e32 v4, v19, v4
	v_mul_f32_e32 v11, v17, v9
	v_mul_f32_e32 v15, v17, v14
	v_cvt_pk_bf16_f32 v51, v11, v15
	v_mul_f32_e32 v6, v19, v6
	v_cvt_pk_bf16_f32 v52, v4, v6
	v_mul_f32_e32 v4, v19, v5
	v_mul_f32_e32 v5, v19, v8
	v_cvt_pk_bf16_f32 v53, v4, v5
	v_mul_f32_e32 v4, v19, v7
	v_mul_f32_e32 v5, v19, v10
	v_lshl_add_u64 v[12:13], v[112:113], 0, s[8:9]
	v_cvt_pk_bf16_f32 v54, v4, v5
	v_mul_f32_e32 v4, v19, v9
	v_mul_f32_e32 v5, v19, v14
	v_cvt_pk_bf16_f32 v55, v4, v5
	s_waitcnt vmcnt(0)
	v_mov_b32_e32 v4, v120
	v_mov_b32_e32 v5, v121
	v_mov_b32_e32 v6, v122
	v_mov_b32_e32 v7, v123
	v_lshlrev_b32_e32 v8, 16, v4
	v_mul_f32_e32 v9, v17, v8
	v_and_b32_e32 v10, 0xffff0000, v4
	v_mul_f32_e32 v11, v17, v10
	v_cvt_pk_bf16_f32 v56, v9, v11
	v_lshlrev_b32_e32 v9, 16, v5
	v_mul_f32_e32 v11, v17, v9
	v_and_b32_e32 v14, 0xffff0000, v5
	v_mul_f32_e32 v15, v17, v14
	v_cvt_pk_bf16_f32 v57, v11, v15
	v_lshlrev_b32_e32 v11, 16, v6
	v_mul_f32_e32 v15, v17, v11
	v_and_b32_e32 v18, 0xffff0000, v6
	v_mul_f32_e32 v20, v17, v18
	v_cvt_pk_bf16_f32 v58, v15, v20
	v_lshlrev_b32_e32 v15, 16, v7
	v_and_b32_e32 v21, 0xffff0000, v7
	v_mul_f32_e32 v8, v19, v8
	v_mul_f32_e32 v20, v17, v15
	v_mul_f32_e32 v22, v17, v21
	v_cvt_pk_bf16_f32 v59, v20, v22
	v_mul_f32_e32 v10, v19, v10
	v_cvt_pk_bf16_f32 v60, v8, v10
	v_mul_f32_e32 v8, v19, v9
	v_mul_f32_e32 v9, v19, v14
	v_cvt_pk_bf16_f32 v61, v8, v9
	v_mul_f32_e32 v8, v19, v11
	v_mul_f32_e32 v9, v19, v18
	v_cvt_pk_bf16_f32 v62, v8, v9
	v_mul_f32_e32 v8, v19, v15
	v_mul_f32_e32 v9, v19, v21
	v_cvt_pk_bf16_f32 v63, v8, v9
	s_waitcnt vmcnt(0)
; #define LAS __attribute__((address_space(3)))
; #define MFMA16(a, b, c) __builtin_amdgcn_mfma_f32_16x16x32_bf16((a), (b), (c), 0, 0, 0)
; DI void ret_out_item(const Params& p, int l, int b, int h, int c, LAS unsigned char* lds) {
;     ...
;     for (int ks = 0; ks < 4; ++ks) { qf[ks] = *(const bf16x8*)(P + row * INP + C_RQ + h * 128 + ks * 32 + q4 * 8); qff[ks] = scale1_bf16x8(qf[ks], qdf); qfb[ks] = scale1_bf16x8(qf[ks], qdb); }
;     f32x4 oacc[8];
; #pragma unroll
;     for (int d = 0; d < 8; ++d) oacc[d] = (f32x4){0.f, 0.f, 0.f, 0.f};
;     __syncthreads();
;     const LAS unsigned char* sfp = lds + 0 * MB + r16 * RS + q4 * 16;
;     const LAS unsigned char* sbp = lds + 1 * MB + r16 * RS + q4 * 16;
;     const LAS unsigned char* kcp = lds + 2 * MB + r16 * RS + q4 * 16;
;     const LAS unsigned char* vtp = lds + 3 * MB + r16 * RS + q4 * 8;
; #pragma unroll
;     for (int d = 0; d < 8; ++d)
; #pragma unroll
;         for (int ks = 0; ks < 4; ++ks) {
;             oacc[d] = MFMA16(*(const LAS bf16x8*)(sfp + d * 16 * RS + ks * 64), qff[ks], oacc[d]);
;             oacc[d] = MFMA16(*(const LAS bf16x8*)(sbp + d * 16 * RS + ks * 64), qfb[ks], oacc[d]);
;         }
	v_mov_b32_e32 v8, v124
	v_mov_b32_e32 v9, v125
	v_mov_b32_e32 v10, v126
	v_mov_b32_e32 v11, v127
	v_lshlrev_b32_e32 v14, 16, v8
	v_mul_f32_e32 v15, v17, v14
	v_and_b32_e32 v18, 0xffff0000, v8
	v_mul_f32_e32 v20, v17, v18
	v_cvt_pk_bf16_f32 v64, v15, v20
	v_lshlrev_b32_e32 v15, 16, v9
	v_mul_f32_e32 v20, v17, v15
	v_and_b32_e32 v21, 0xffff0000, v9
	v_mul_f32_e32 v22, v17, v21
	v_cvt_pk_bf16_f32 v65, v20, v22
	v_lshlrev_b32_e32 v20, 16, v10
	v_mul_f32_e32 v22, v17, v20
	v_and_b32_e32 v23, 0xffff0000, v10
	v_mul_f32_e32 v24, v17, v23
	v_cvt_pk_bf16_f32 v66, v22, v24
	v_lshlrev_b32_e32 v22, 16, v11
	v_and_b32_e32 v25, 0xffff0000, v11
	v_mul_f32_e32 v14, v19, v14
	v_mul_f32_e32 v24, v17, v22
	v_mul_f32_e32 v26, v17, v25
	v_cvt_pk_bf16_f32 v67, v24, v26
	v_mul_f32_e32 v18, v19, v18
	v_cvt_pk_bf16_f32 v94, v14, v18
	v_mul_f32_e32 v14, v19, v15
	v_mul_f32_e32 v15, v19, v21
	v_cvt_pk_bf16_f32 v95, v14, v15
	v_mul_f32_e32 v14, v19, v20
	v_mul_f32_e32 v15, v19, v23
	v_cvt_pk_bf16_f32 v96, v14, v15
	v_mul_f32_e32 v14, v19, v22
	v_mul_f32_e32 v15, v19, v25
	v_cvt_pk_bf16_f32 v97, v14, v15
	s_waitcnt vmcnt(0)
	v_mov_b32_e32 v12, v128
	v_mov_b32_e32 v13, v129
	v_mov_b32_e32 v14, v130
	v_mov_b32_e32 v15, v131
	v_and_b32_e32 v20, 15, v16
	v_mul_u32_u24_e32 v81, 0x110, v20
	v_add3_u32 v68, 0, v81, v80
	s_waitcnt vmcnt(0)
	v_lshlrev_b32_e32 v16, 16, v12
	v_mul_f32_e32 v18, v17, v16
	v_and_b32_e32 v21, 0xffff0000, v12
	v_mul_f32_e32 v22, v17, v21
	v_cvt_pk_bf16_f32 v98, v18, v22
	v_lshlrev_b32_e32 v18, 16, v13
	v_mul_f32_e32 v22, v17, v18
	v_and_b32_e32 v23, 0xffff0000, v13
	v_mul_f32_e32 v24, v17, v23
	v_cvt_pk_bf16_f32 v99, v22, v24
	v_lshlrev_b32_e32 v22, 16, v14
	v_mul_f32_e32 v24, v17, v22
	v_and_b32_e32 v25, 0xffff0000, v14
	v_mul_f32_e32 v26, v17, v25
	v_cvt_pk_bf16_f32 v100, v24, v26
	v_lshlrev_b32_e32 v24, 16, v15
	v_and_b32_e32 v27, 0xffff0000, v15
	v_mul_f32_e32 v26, v17, v24
	v_mul_f32_e32 v17, v17, v27
	v_cvt_pk_bf16_f32 v101, v26, v17
	v_mul_f32_e32 v16, v19, v16
	v_mul_f32_e32 v17, v19, v21
	v_cvt_pk_bf16_f32 v16, v16, v17
	v_mul_f32_e32 v17, v19, v18
	v_mul_f32_e32 v18, v19, v23
	v_cvt_pk_bf16_f32 v17, v17, v18
	v_mul_f32_e32 v18, v19, v22
	v_mul_f32_e32 v21, v19, v25
	v_cvt_pk_bf16_f32 v18, v18, v21
	v_mul_f32_e32 v21, v19, v24
	v_mul_f32_e32 v19, v19, v27
	v_cvt_pk_bf16_f32 v19, v21, v19
	s_waitcnt lgkmcnt(0)
	s_barrier
	ds_read_b128 v[20:23], v68
	ds_read_b128 v[24:27], v68 offset:64
	s_waitcnt lgkmcnt(1)
	v_mfma_f32_16x16x32_bf16 v[20:23], v[20:23], v[48:51], 0
	ds_read_b128 v[28:31], v68 offset:34816
	ds_read_b128 v[32:35], v68 offset:34880
	s_waitcnt lgkmcnt(1)
	v_mfma_f32_16x16x32_bf16 v[20:23], v[28:31], v[52:55], v[20:23]
	v_mfma_f32_16x16x32_bf16 v[20:23], v[24:27], v[56:59], v[20:23]
	ds_read_b128 v[24:27], v68 offset:128
	ds_read_b128 v[28:31], v68 offset:192
	s_waitcnt lgkmcnt(2)
	v_mfma_f32_16x16x32_bf16 v[20:23], v[32:35], v[60:63], v[20:23]
	s_waitcnt lgkmcnt(1)
	v_mfma_f32_16x16x32_bf16 v[20:23], v[24:27], v[64:67], v[20:23]
	ds_read_b128 v[24:27], v68 offset:34944
	ds_read_b128 v[32:35], v68 offset:35008
	s_waitcnt lgkmcnt(1)
	v_mfma_f32_16x16x32_bf16 v[20:23], v[24:27], v[94:97], v[20:23]
	v_mfma_f32_16x16x32_bf16 v[20:23], v[28:31], v[98:101], v[20:23]
	ds_read_b128 v[24:27], v68 offset:4352
	ds_read_b128 v[28:31], v68 offset:4416
	s_waitcnt lgkmcnt(2)
	v_mfma_f32_16x16x32_bf16 v[20:23], v[32:35], v[16:19], v[20:23]
	ds_read_b128 v[32:35], v68 offset:39168
	ds_read_b128 v[36:39], v68 offset:39232
	s_waitcnt lgkmcnt(3)
	v_mfma_f32_16x16x32_bf16 v[24:27], v[24:27], v[48:51], 0
	s_waitcnt lgkmcnt(1)
	v_mfma_f32_16x16x32_bf16 v[24:27], v[32:35], v[52:55], v[24:27]
	v_mfma_f32_16x16x32_bf16 v[24:27], v[28:31], v[56:59], v[24:27]
	ds_read_b128 v[28:31], v68 offset:4480
	ds_read_b128 v[32:35], v68 offset:4544
	s_waitcnt lgkmcnt(2)
	v_mfma_f32_16x16x32_bf16 v[24:27], v[36:39], v[60:63], v[24:27]
	s_waitcnt lgkmcnt(1)
	v_mfma_f32_16x16x32_bf16 v[24:27], v[28:31], v[64:67], v[24:27]
	ds_read_b128 v[28:31], v68 offset:39296
	ds_read_b128 v[36:39], v68 offset:39360
	s_waitcnt lgkmcnt(1)
	v_mfma_f32_16x16x32_bf16 v[24:27], v[28:31], v[94:97], v[24:27]
	v_mfma_f32_16x16x32_bf16 v[24:27], v[32:35], v[98:101], v[24:27]
	ds_read_b128 v[28:31], v68 offset:8704
	ds_read_b128 v[32:35], v68 offset:8768
	s_waitcnt lgkmcnt(2)
	v_mfma_f32_16x16x32_bf16 v[24:27], v[36:39], v[16:19], v[24:27]
	ds_read_b128 v[36:39], v68 offset:43520
	ds_read_b128 v[40:43], v68 offset:43584
	s_waitcnt lgkmcnt(3)
	v_mfma_f32_16x16x32_bf16 v[28:31], v[28:31], v[48:51], 0
	s_waitcnt lgkmcnt(1)
	v_mfma_f32_16x16x32_bf16 v[28:31], v[36:39], v[52:55], v[28:31]
	v_mfma_f32_16x16x32_bf16 v[28:31], v[32:35], v[56:59], v[28:31]
	ds_read_b128 v[32:35], v68 offset:8832
	ds_read_b128 v[36:39], v68 offset:8896
	s_waitcnt lgkmcnt(2)
	v_mfma_f32_16x16x32_bf16 v[28:31], v[40:43], v[60:63], v[28:31]
	s_waitcnt lgkmcnt(1)
	v_mfma_f32_16x16x32_bf16 v[28:31], v[32:35], v[64:67], v[28:31]
	ds_read_b128 v[32:35], v68 offset:43648
	ds_read_b128 v[40:43], v68 offset:43712
	s_waitcnt lgkmcnt(1)
	v_mfma_f32_16x16x32_bf16 v[28:31], v[32:35], v[94:97], v[28:31]
	v_mfma_f32_16x16x32_bf16 v[28:31], v[36:39], v[98:101], v[28:31]
	ds_read_b128 v[32:35], v68 offset:13056
	ds_read_b128 v[36:39], v68 offset:13120
	s_waitcnt lgkmcnt(2)
	v_mfma_f32_16x16x32_bf16 v[28:31], v[40:43], v[16:19], v[28:31]
	ds_read_b128 v[40:43], v68 offset:47872
	ds_read_b128 v[44:47], v68 offset:47936
	s_waitcnt lgkmcnt(3)
	v_mfma_f32_16x16x32_bf16 v[32:35], v[32:35], v[48:51], 0
	s_waitcnt lgkmcnt(1)
	v_mfma_f32_16x16x32_bf16 v[32:35], v[40:43], v[52:55], v[32:35]
	v_mfma_f32_16x16x32_bf16 v[32:35], v[36:39], v[56:59], v[32:35]
	ds_read_b128 v[36:39], v68 offset:13184
	ds_read_b128 v[40:43], v68 offset:13248
	s_waitcnt lgkmcnt(2)
; #define LAS __attribute__((address_space(3)))
; #define MFMA16(a, b, c) __builtin_amdgcn_mfma_f32_16x16x32_bf16((a), (b), (c), 0, 0, 0)
; DI void ret_out_item(const Params& p, int l, int b, int h, int c, LAS unsigned char* lds) {
;     ...
; #pragma unroll
;     for (int d = 0; d < 8; ++d)
; #pragma unroll
;         for (int ks = 0; ks < 4; ++ks) {
;             oacc[d] = MFMA16(*(const LAS bf16x8*)(sfp + d * 16 * RS + ks * 64), qff[ks], oacc[d]);
;             oacc[d] = MFMA16(*(const LAS bf16x8*)(sbp + d * 16 * RS + ks * 64), qfb[ks], oacc[d]);
;         }
; #pragma unroll
;     for (int kc = 0; kc < 4; ++kc) {
;         f32x4 s[2];
; #pragma unroll
;         for (int hf = 0; hf < 2; ++hf) {
;             s[hf] = (f32x4){0.f, 0.f, 0.f, 0.f};
; #pragma unroll
;             for (int ks = 0; ks < 4; ++ks) s[hf] = MFMA16(*(const LAS bf16x8*)(kcp + (2 * kc + hf) * 16 * RS + ks * 64), qf[ks], s[hf]);
; #pragma unroll
;             for (int j = 0; j < 4; ++j) {
;                 const int m = (2 * kc + hf) * 16 + q4 * 4 + j, d = tl - m;
;                 const float w = (d >= 0 ? exp2f(lgf * (float)d) : 0.f) + (d <= 0 ? exp2f(-lgb * (float)d) : 0.f);
;                 s[hf][j] *= w;
;             }
	v_mfma_f32_16x16x32_bf16 v[32:35], v[44:47], v[60:63], v[32:35]
	s_waitcnt lgkmcnt(1)
	v_mfma_f32_16x16x32_bf16 v[32:35], v[36:39], v[64:67], v[32:35]
	ds_read_b128 v[36:39], v68 offset:48000
	ds_read_b128 v[44:47], v68 offset:48064
	s_waitcnt lgkmcnt(1)
	v_mfma_f32_16x16x32_bf16 v[32:35], v[36:39], v[94:97], v[32:35]
	v_mfma_f32_16x16x32_bf16 v[32:35], v[40:43], v[98:101], v[32:35]
	ds_read_b128 v[36:39], v68 offset:17408
	ds_read_b128 v[40:43], v68 offset:17472
	s_waitcnt lgkmcnt(2)
	v_mfma_f32_16x16x32_bf16 v[32:35], v[44:47], v[16:19], v[32:35]
	ds_read_b128 v[44:47], v68 offset:52224
	ds_read_b128 v[102:105], v68 offset:52288
	s_waitcnt lgkmcnt(3)
	v_mfma_f32_16x16x32_bf16 v[36:39], v[36:39], v[48:51], 0
	s_waitcnt lgkmcnt(1)
	v_mfma_f32_16x16x32_bf16 v[36:39], v[44:47], v[52:55], v[36:39]
	v_mfma_f32_16x16x32_bf16 v[36:39], v[40:43], v[56:59], v[36:39]
	ds_read_b128 v[40:43], v68 offset:17536
	ds_read_b128 v[44:47], v68 offset:17600
	s_waitcnt lgkmcnt(2)
	v_mfma_f32_16x16x32_bf16 v[36:39], v[102:105], v[60:63], v[36:39]
	s_waitcnt lgkmcnt(1)
	v_mfma_f32_16x16x32_bf16 v[36:39], v[40:43], v[64:67], v[36:39]
	ds_read_b128 v[40:43], v68 offset:52352
	ds_read_b128 v[102:105], v68 offset:52416
	s_waitcnt lgkmcnt(1)
	v_mfma_f32_16x16x32_bf16 v[36:39], v[40:43], v[94:97], v[36:39]
	v_mfma_f32_16x16x32_bf16 v[36:39], v[44:47], v[98:101], v[36:39]
	ds_read_b128 v[40:43], v68 offset:21760
	ds_read_b128 v[44:47], v68 offset:21824
	s_waitcnt lgkmcnt(2)
	v_mfma_f32_16x16x32_bf16 v[36:39], v[102:105], v[16:19], v[36:39]
	ds_read_b128 v[102:105], v68 offset:56576
	ds_read_b128 v[106:109], v68 offset:56640
	s_waitcnt lgkmcnt(3)
	v_mfma_f32_16x16x32_bf16 v[40:43], v[40:43], v[48:51], 0
	s_waitcnt lgkmcnt(1)
	v_mfma_f32_16x16x32_bf16 v[40:43], v[102:105], v[52:55], v[40:43]
	v_mfma_f32_16x16x32_bf16 v[40:43], v[44:47], v[56:59], v[40:43]
	ds_read_b128 v[44:47], v68 offset:21888
	ds_read_b128 v[102:105], v68 offset:21952
	s_waitcnt lgkmcnt(2)
	v_mfma_f32_16x16x32_bf16 v[40:43], v[106:109], v[60:63], v[40:43]
	s_waitcnt lgkmcnt(1)
	v_mfma_f32_16x16x32_bf16 v[40:43], v[44:47], v[64:67], v[40:43]
	ds_read_b128 v[44:47], v68 offset:56704
	ds_read_b128 v[106:109], v68 offset:56768
	s_waitcnt lgkmcnt(1)
	v_mfma_f32_16x16x32_bf16 v[40:43], v[44:47], v[94:97], v[40:43]
	v_mfma_f32_16x16x32_bf16 v[40:43], v[102:105], v[98:101], v[40:43]
	ds_read_b128 v[44:47], v68 offset:26112
	ds_read_b128 v[102:105], v68 offset:26176
	s_waitcnt lgkmcnt(2)
	v_mfma_f32_16x16x32_bf16 v[40:43], v[106:109], v[16:19], v[40:43]
	ds_read_b128 v[106:109], v68 offset:60928
	ds_read_b128 v[110:113], v68 offset:60992
	s_waitcnt lgkmcnt(3)
	v_mfma_f32_16x16x32_bf16 v[44:47], v[44:47], v[48:51], 0
	s_waitcnt lgkmcnt(1)
	v_mfma_f32_16x16x32_bf16 v[44:47], v[106:109], v[52:55], v[44:47]
	v_mfma_f32_16x16x32_bf16 v[44:47], v[102:105], v[56:59], v[44:47]
	ds_read_b128 v[102:105], v68 offset:26240
	ds_read_b128 v[106:109], v68 offset:26304
	s_waitcnt lgkmcnt(2)
	v_mfma_f32_16x16x32_bf16 v[44:47], v[110:113], v[60:63], v[44:47]
	s_waitcnt lgkmcnt(1)
	v_mfma_f32_16x16x32_bf16 v[44:47], v[102:105], v[64:67], v[44:47]
	ds_read_b128 v[102:105], v68 offset:61056
	ds_read_b128 v[110:113], v68 offset:61120
	s_waitcnt lgkmcnt(1)
	v_mfma_f32_16x16x32_bf16 v[44:47], v[102:105], v[94:97], v[44:47]
	v_mfma_f32_16x16x32_bf16 v[44:47], v[106:109], v[98:101], v[44:47]
	ds_read_b128 v[102:105], v68 offset:30464
	ds_read_b128 v[106:109], v68 offset:30528
	s_waitcnt lgkmcnt(2)
	v_mfma_f32_16x16x32_bf16 v[44:47], v[110:113], v[16:19], v[44:47]
	s_waitcnt lgkmcnt(1)
	v_mfma_f32_16x16x32_bf16 v[48:51], v[102:105], v[48:51], 0
	ds_read_b128 v[102:105], v68 offset:65280
	ds_read_b128 v[110:113], v68 offset:65344
	s_waitcnt lgkmcnt(1)
	v_mfma_f32_16x16x32_bf16 v[48:51], v[102:105], v[52:55], v[48:51]
	v_mfma_f32_16x16x32_bf16 v[48:51], v[106:109], v[56:59], v[48:51]
	ds_read_b128 v[52:55], v68 offset:30592
	ds_read_b128 v[56:59], v68 offset:30656
	s_waitcnt lgkmcnt(2)
	v_mfma_f32_16x16x32_bf16 v[48:51], v[110:113], v[60:63], v[48:51]
	v_add3_u32 v62, s23, v81, v80
	v_lshlrev_b32_e32 v61, 2, v92
	v_sub_u32_e32 v63, v78, v61
	s_waitcnt lgkmcnt(1)
	v_mfma_f32_16x16x32_bf16 v[48:51], v[52:55], v[64:67], v[48:51]
	ds_read_b128 v[64:67], v68 offset:65408
	ds_read_b128 v[52:55], v68 offset:65472
	v_cvt_f32_u32_e32 v80, v63
	s_waitcnt lgkmcnt(1)
	v_mfma_f32_16x16x32_bf16 v[48:51], v[64:67], v[94:97], v[48:51]
	ds_read_b128 v[64:67], v62
	ds_read_b128 v[94:97], v62 offset:128
	v_lshlrev_b32_e32 v68, 3, v92
	v_mfma_f32_16x16x32_bf16 v[56:59], v[56:59], v[98:101], v[48:51]
	v_add3_u32 v60, s27, v81, v68
	v_mul_f32_e32 v81, v79, v80
	v_cmp_gt_f32_e32 vcc, s7, v81
	s_nop 0
	ds_read_b128 v[48:51], v62 offset:64
	s_waitcnt lgkmcnt(2)
	v_mfma_f32_16x16x32_bf16 v[64:67], v[64:67], v[0:3], 0
	v_cndmask_b32_e32 v81, 0, v82, vcc
	v_fmac_f32_e32 v81, v79, v80
	v_exp_f32_e32 v80, v81
	s_waitcnt lgkmcnt(0)
	v_mfma_f32_16x16x32_bf16 v[48:51], v[48:51], v[4:7], v[64:67]
	s_nop 2
	ds_read_b128 v[64:67], v62 offset:192
	v_cvt_f32_i32_e32 v81, v63
	v_cmp_lt_i32_e64 s[0:1], -1, v63
	v_mfma_f32_16x16x32_bf16 v[48:51], v[94:97], v[8:11], v[48:51]
	ds_read_b128 v[96:99], v62 offset:4480
	s_waitcnt lgkmcnt(1)
; #define LAS __attribute__((address_space(3)))
; DI unsigned cvt_pk_bf16(float lo, float hi) { unsigned r; asm volatile("v_cvt_pk_bf16_f32 %0, %1, %2" : "=v"(r) : "v"(lo), "v"(hi)); return r; }
; #define MFMA16(a, b, c) __builtin_amdgcn_mfma_f32_16x16x32_bf16((a), (b), (c), 0, 0, 0)
; DI void ret_out_item(const Params& p, int l, int b, int h, int c, LAS unsigned char* lds) {
;     ...
;             for (int ks = 0; ks < 4; ++ks) s[hf] = MFMA16(*(const LAS bf16x8*)(kcp + (2 * kc + hf) * 16 * RS + ks * 64), qf[ks], s[hf]);
; #pragma unroll
;             for (int j = 0; j < 4; ++j) {
;                 const int m = (2 * kc + hf) * 16 + q4 * 4 + j, d = tl - m;
;                 const float w = (d >= 0 ? exp2f(lgf * (float)d) : 0.f) + (d <= 0 ? exp2f(-lgb * (float)d) : 0.f);
;                 s[hf][j] *= w;
;             }
;         }
;         u32x4 w4; w4.x = cvt_pk_bf16(s[0][0], s[0][1]); w4.y = cvt_pk_bf16(s[0][2], s[0][3]); w4.z = cvt_pk_bf16(s[1][0], s[1][1]); w4.w = cvt_pk_bf16(s[1][2], s[1][3]);
;         const bf16x8 pb = __builtin_bit_cast(bf16x8, w4);
; #pragma unroll
;         for (int d = 0; d < 8; ++d) {
;             const u32x2 lo = *(const LAS u32x2*)(vtp + d * 16 * RS + kc * 64), hi = *(const LAS u32x2*)(vtp + d * 16 * RS + kc * 64 + 32);
;             u32x4 a4; a4.x = lo.x; a4.y = lo.y; a4.z = hi.x; a4.w = hi.y;
;             oacc[d] = MFMA16(__builtin_bit_cast(bf16x8, a4), pb, oacc[d]);
;         }
	v_mfma_f32_16x16x32_bf16 v[48:51], v[64:67], v[12:15], v[48:51]
	v_mul_f32_e32 v65, v81, v73
	v_cndmask_b32_e32 v64, 0, v86, vcc
	v_cmp_gt_f32_e32 vcc, s7, v65
	v_ldexp_f32 v64, v80, v64
	v_cndmask_b32_e64 v64, 0, v64, s[0:1]
	v_cndmask_b32_e32 v65, 0, v82, vcc
	v_fmac_f32_e32 v65, v81, v73
	v_exp_f32_e32 v65, v65
	v_cndmask_b32_e32 v66, 0, v86, vcc
	v_cmp_gt_i32_e32 vcc, 1, v63
	v_mfma_f32_16x16x32_bf16 v[52:55], v[52:55], v[16:19], v[56:59]
	v_ldexp_f32 v65, v65, v66
	v_xad_u32 v66, v61, -1, v78
	v_cvt_f32_u32_e32 v67, v66
	v_cndmask_b32_e32 v63, 0, v65, vcc
	v_add_f32_e32 v63, v64, v63
	v_cvt_f32_i32_e32 v65, v66
	v_mul_f32_e32 v64, v79, v67
	v_cmp_gt_f32_e32 vcc, s7, v64
	v_mul_f32_e32 v63, v63, v48
	v_cmp_lt_i32_e64 s[0:1], -1, v66
	v_cndmask_b32_e32 v64, 0, v82, vcc
	v_fmac_f32_e32 v64, v79, v67
	v_exp_f32_e32 v64, v64
	v_cndmask_b32_e32 v48, 0, v86, vcc
	v_ldexp_f32 v48, v64, v48
	v_mul_f32_e32 v64, v65, v73
	v_cmp_gt_f32_e32 vcc, s7, v64
	v_cndmask_b32_e64 v48, 0, v48, s[0:1]
	s_nop 0
	v_cndmask_b32_e32 v64, 0, v82, vcc
	v_fmac_f32_e32 v64, v65, v73
	v_exp_f32_e32 v64, v64
	v_cndmask_b32_e32 v65, 0, v86, vcc
	v_cmp_gt_i32_e32 vcc, 1, v66
	v_ldexp_f32 v64, v64, v65
	v_or_b32_e32 v65, 2, v61
	v_sub_u32_e32 v65, v78, v65
	v_cvt_f32_u32_e32 v67, v65
	v_cvt_f32_i32_e32 v66, v65
	v_cndmask_b32_e32 v64, 0, v64, vcc
	v_add_f32_e32 v48, v48, v64
	v_mul_f32_e32 v64, v79, v67
	v_cmp_gt_f32_e32 vcc, s7, v64
	v_mul_f32_e32 v80, v48, v49
	v_mul_f32_e32 v49, v66, v73
	v_cndmask_b32_e32 v64, 0, v82, vcc
	v_cndmask_b32_e32 v48, 0, v86, vcc
	v_cmp_gt_f32_e32 vcc, s7, v49
	v_fmac_f32_e32 v64, v79, v67
	v_exp_f32_e32 v64, v64
	v_cndmask_b32_e32 v49, 0, v82, vcc
	v_fmac_f32_e32 v49, v66, v73
	v_exp_f32_e32 v49, v49
	v_ldexp_f32 v48, v64, v48
	v_cndmask_b32_e32 v64, 0, v86, vcc
	v_cmp_lt_i32_e64 s[0:1], -1, v65
	v_ldexp_f32 v49, v49, v64
	v_or_b32_e32 v64, 3, v61
	v_sub_u32_e32 v81, v78, v64
	v_cvt_f32_u32_e32 v64, v81
	v_cmp_gt_i32_e32 vcc, 1, v65
	v_cndmask_b32_e64 v48, 0, v48, s[0:1]
	v_cvt_f32_i32_e32 v92, v81
	v_cndmask_b32_e32 v49, 0, v49, vcc
	v_add_f32_e32 v48, v48, v49
	v_mul_f32_e32 v49, v79, v64
	v_cmp_gt_f32_e32 vcc, s7, v49
	v_mul_f32_e32 v100, v48, v50
	v_cmp_lt_i32_e64 s[0:1], -1, v81
	v_cndmask_b32_e32 v49, 0, v82, vcc
	v_fmac_f32_e32 v49, v79, v64
	v_exp_f32_e32 v49, v49
	v_cndmask_b32_e32 v48, 0, v86, vcc
	ds_read_b128 v[64:67], v62 offset:4352
	v_ldexp_f32 v48, v49, v48
	v_mul_f32_e32 v49, v92, v73
	v_cmp_gt_f32_e32 vcc, s7, v49
	v_cndmask_b32_e64 v48, 0, v48, s[0:1]
	s_nop 0
	v_cndmask_b32_e32 v49, 0, v82, vcc
	v_fmac_f32_e32 v49, v92, v73
	ds_read_b128 v[92:95], v62 offset:4416
	v_exp_f32_e32 v49, v49
	v_cndmask_b32_e32 v50, 0, v86, vcc
	s_waitcnt lgkmcnt(1)
	v_mfma_f32_16x16x32_bf16 v[64:67], v[64:67], v[0:3], 0
	v_cmp_gt_i32_e32 vcc, 1, v81
	v_ldexp_f32 v49, v49, v50
	s_nop 0
	v_cndmask_b32_e32 v49, 0, v49, vcc
	v_add_f32_e32 v48, v48, v49
	v_or_b32_e32 v49, 16, v61
	v_sub_u32_e32 v81, v78, v49
	s_waitcnt lgkmcnt(0)
	v_mfma_f32_16x16x32_bf16 v[64:67], v[92:95], v[4:7], v[64:67]
	v_cvt_f32_u32_e32 v101, v81
	ds_read_b128 v[92:95], v62 offset:4544
	v_mul_f32_e32 v102, v48, v51
	v_mfma_f32_16x16x32_bf16 v[48:51], v[96:99], v[8:11], v[64:67]
	v_cmp_lt_i32_e64 s[0:1], -1, v81
	s_nop 2
	v_mul_f32_e32 v64, v79, v101
	v_cmp_gt_f32_e32 vcc, s7, v64
	v_cvt_f32_i32_e32 v65, v81
	s_waitcnt lgkmcnt(0)
	v_mfma_f32_16x16x32_bf16 v[48:51], v[92:95], v[12:15], v[48:51]
	v_cndmask_b32_e32 v64, 0, v82, vcc
	v_fmac_f32_e32 v64, v79, v101
	v_exp_f32_e32 v64, v64
	v_cndmask_b32_e32 v66, 0, v86, vcc
	v_ldexp_f32 v64, v64, v66
	v_mul_f32_e32 v66, v65, v73
	v_cmp_gt_f32_e32 vcc, s7, v66
	v_cndmask_b32_e64 v64, 0, v64, s[0:1]
	s_nop 0
	v_cndmask_b32_e32 v66, 0, v82, vcc
	v_fmac_f32_e32 v66, v65, v73
	v_exp_f32_e32 v65, v66
	v_cndmask_b32_e32 v66, 0, v86, vcc
	v_cmp_gt_i32_e32 vcc, 1, v81
	v_ldexp_f32 v65, v65, v66
	v_or_b32_e32 v66, 17, v61
	v_sub_u32_e32 v66, v78, v66
	v_cvt_f32_u32_e32 v67, v66
	v_cndmask_b32_e32 v65, 0, v65, vcc
	v_add_f32_e32 v64, v64, v65
	v_mul_f32_e32 v64, v64, v48
	v_mul_f32_e32 v65, v79, v67
	v_cmp_gt_f32_e32 vcc, s7, v65
	v_cmp_lt_i32_e64 s[0:1], -1, v66
	s_nop 0
	v_cndmask_b32_e32 v65, 0, v82, vcc
	v_fmac_f32_e32 v65, v79, v67
	v_exp_f32_e32 v65, v65
	v_cvt_f32_i32_e32 v67, v66
	v_cndmask_b32_e32 v48, 0, v86, vcc
	v_ldexp_f32 v48, v65, v48
	v_mul_f32_e32 v65, v67, v73
	v_cmp_gt_f32_e32 vcc, s7, v65
	v_cndmask_b32_e64 v48, 0, v48, s[0:1]
	s_nop 0
	v_cndmask_b32_e32 v65, 0, v82, vcc
	v_fmac_f32_e32 v65, v67, v73
	v_exp_f32_e32 v65, v65
	v_cndmask_b32_e32 v67, 0, v86, vcc
	v_cmp_gt_i32_e32 vcc, 1, v66
	v_ldexp_f32 v65, v65, v67
	v_or_b32_e32 v67, 18, v61
	v_sub_u32_e32 v67, v78, v67
	v_cvt_f32_u32_e32 v81, v67
	v_cndmask_b32_e32 v65, 0, v65, vcc
	v_cvt_f32_i32_e32 v66, v67
	v_add_f32_e32 v48, v48, v65
	v_mul_f32_e32 v65, v79, v81
	v_cmp_gt_f32_e32 vcc, s7, v65
	v_cmp_lt_i32_e64 s[0:1], -1, v67
	s_nop 0
	v_cndmask_b32_e32 v65, 0, v82, vcc
	v_fmac_f32_e32 v65, v79, v81
	v_mul_f32_e32 v81, v48, v49
	v_mul_f32_e32 v49, v66, v73
	v_cndmask_b32_e32 v48, 0, v86, vcc
	v_cmp_gt_f32_e32 vcc, s7, v49
	v_exp_f32_e32 v65, v65
	s_nop 0
	v_cndmask_b32_e32 v49, 0, v82, vcc
	v_fmac_f32_e32 v49, v66, v73
	v_exp_f32_e32 v49, v49
	v_ldexp_f32 v48, v65, v48
	v_cndmask_b32_e32 v65, 0, v86, vcc
	v_cmp_gt_i32_e32 vcc, 1, v67
	v_ldexp_f32 v49, v49, v65
	v_or_b32_e32 v65, 19, v61
	v_sub_u32_e32 v65, v78, v65
	v_cvt_f32_u32_e32 v66, v65
	v_cndmask_b32_e64 v48, 0, v48, s[0:1]
	v_cndmask_b32_e32 v49, 0, v49, vcc
	v_add_f32_e32 v48, v48, v49
	v_mul_f32_e32 v49, v79, v66
	v_cmp_gt_f32_e32 vcc, s7, v49
	v_mul_f32_e32 v67, v48, v50
	v_cmp_lt_i32_e64 s[0:1], -1, v65
	v_cndmask_b32_e32 v49, 0, v82, vcc
	v_fmac_f32_e32 v49, v79, v66
	v_exp_f32_e32 v49, v49
	v_cvt_f32_i32_e32 v66, v65
	v_cndmask_b32_e32 v48, 0, v86, vcc
	v_ldexp_f32 v48, v49, v48
	v_mul_f32_e32 v49, v66, v73
	v_cmp_gt_f32_e32 vcc, s7, v49
	v_cndmask_b32_e64 v48, 0, v48, s[0:1]
	s_nop 0
	v_cndmask_b32_e32 v49, 0, v82, vcc
	v_fmac_f32_e32 v49, v66, v73
	v_exp_f32_e32 v49, v49
	v_cndmask_b32_e32 v50, 0, v86, vcc
	v_cmp_gt_i32_e32 vcc, 1, v65
	v_ldexp_f32 v49, v49, v50
	s_nop 0
	v_cndmask_b32_e32 v49, 0, v49, vcc
	v_add_f32_e32 v48, v48, v49
	v_mul_f32_e32 v51, v48, v51
	v_cvt_pk_bf16_f32 v48, v63, v80
	v_cvt_pk_bf16_f32 v49, v100, v102
	v_cvt_pk_bf16_f32 v50, v64, v81
	v_cvt_pk_bf16_f32 v51, v67, v51
	ds_read2_b64 v[64:67], v60 offset1:4
	v_add_u32_e32 v63, 0x1000, v60
	ds_read2_b64 v[16:19], v63 offset0:32 offset1:36
	s_waitcnt lgkmcnt(1)
; #define LAS __attribute__((address_space(3)))
; DI unsigned cvt_pk_bf16(float lo, float hi) { unsigned r; asm volatile("v_cvt_pk_bf16_f32 %0, %1, %2" : "=v"(r) : "v"(lo), "v"(hi)); return r; }
; #define MFMA16(a, b, c) __builtin_amdgcn_mfma_f32_16x16x32_bf16((a), (b), (c), 0, 0, 0)
; DI void ret_out_item(const Params& p, int l, int b, int h, int c, LAS unsigned char* lds) {
;     ...
;     for (int kc = 0; kc < 4; ++kc) {
;         f32x4 s[2];
; #pragma unroll
;         for (int hf = 0; hf < 2; ++hf) {
;             s[hf] = (f32x4){0.f, 0.f, 0.f, 0.f};
; #pragma unroll
;             for (int ks = 0; ks < 4; ++ks) s[hf] = MFMA16(*(const LAS bf16x8*)(kcp + (2 * kc + hf) * 16 * RS + ks * 64), qf[ks], s[hf]);
; #pragma unroll
;             for (int j = 0; j < 4; ++j) {
;                 const int m = (2 * kc + hf) * 16 + q4 * 4 + j, d = tl - m;
;                 const float w = (d >= 0 ? exp2f(lgf * (float)d) : 0.f) + (d <= 0 ? exp2f(-lgb * (float)d) : 0.f);
;                 s[hf][j] *= w;
;             }
;         }
;         u32x4 w4; w4.x = cvt_pk_bf16(s[0][0], s[0][1]); w4.y = cvt_pk_bf16(s[0][2], s[0][3]); w4.z = cvt_pk_bf16(s[1][0], s[1][1]); w4.w = cvt_pk_bf16(s[1][2], s[1][3]);
;         const bf16x8 pb = __builtin_bit_cast(bf16x8, w4);
; #pragma unroll
;         for (int d = 0; d < 8; ++d) {
;             const u32x2 lo = *(const LAS u32x2*)(vtp + d * 16 * RS + kc * 64), hi = *(const LAS u32x2*)(vtp + d * 16 * RS + kc * 64 + 32);
;             u32x4 a4; a4.x = lo.x; a4.y = lo.y; a4.z = hi.x; a4.w = hi.y;
;             oacc[d] = MFMA16(__builtin_bit_cast(bf16x8, a4), pb, oacc[d]);
;         }
	v_mfma_f32_16x16x32_bf16 v[20:23], v[64:67], v[48:51], v[20:23]
	v_add_u32_e32 v64, 0x2000, v60
	ds_read2_b64 v[56:59], v64 offset0:64 offset1:68
	v_add_u32_e32 v65, 0x3000, v60
	s_waitcnt lgkmcnt(1)
	v_mfma_f32_16x16x32_bf16 v[24:27], v[16:19], v[48:51], v[24:27]
	ds_read2_b64 v[16:19], v65 offset0:96 offset1:100
	v_add_u32_e32 v66, 0x4000, v60
	v_add_u32_e32 v67, 0x5000, v60
	s_waitcnt lgkmcnt(1)
	v_mfma_f32_16x16x32_bf16 v[28:31], v[56:59], v[48:51], v[28:31]
	ds_read2_b64 v[56:59], v66 offset0:128 offset1:132
	v_add_u32_e32 v80, 0x6000, v60
	ds_read_b128 v[92:95], v62 offset:8832
	s_waitcnt lgkmcnt(2)
	v_mfma_f32_16x16x32_bf16 v[32:35], v[16:19], v[48:51], v[32:35]
	ds_read2_b64 v[16:19], v67 offset0:160 offset1:164
	v_add_u32_e32 v81, 0x7000, v60
	s_waitcnt lgkmcnt(2)
	v_mfma_f32_16x16x32_bf16 v[36:39], v[56:59], v[48:51], v[36:39]
	ds_read2_b64 v[56:59], v80 offset0:192 offset1:196
	s_waitcnt lgkmcnt(1)
	v_mfma_f32_16x16x32_bf16 v[40:43], v[16:19], v[48:51], v[40:43]
	ds_read_b128 v[16:19], v62 offset:8704
	s_waitcnt lgkmcnt(1)
	v_mfma_f32_16x16x32_bf16 v[44:47], v[56:59], v[48:51], v[44:47]
	ds_read_b128 v[56:59], v62 offset:8768
	s_waitcnt lgkmcnt(1)
	v_mfma_f32_16x16x32_bf16 v[16:19], v[16:19], v[0:3], 0
	s_waitcnt lgkmcnt(0)
	v_mfma_f32_16x16x32_bf16 v[16:19], v[56:59], v[4:7], v[16:19]
	v_or_b32_e32 v56, 32, v61
	v_sub_u32_e32 v100, v78, v56
	v_cvt_f32_u32_e32 v101, v100
	v_mfma_f32_16x16x32_bf16 v[16:19], v[92:95], v[8:11], v[16:19]
	v_cvt_f32_i32_e32 v93, v100
	v_cmp_lt_i32_e64 s[0:1], -1, v100
	v_mul_f32_e32 v92, v79, v101
	v_cmp_gt_f32_e32 vcc, s7, v92
	ds_read_b128 v[96:99], v62 offset:8896
	ds_read2_b64 v[56:59], v81 offset0:224 offset1:228
	v_cndmask_b32_e32 v92, 0, v82, vcc
	v_fmac_f32_e32 v92, v79, v101
	v_exp_f32_e32 v92, v92
	v_cndmask_b32_e32 v94, 0, v86, vcc
	s_waitcnt lgkmcnt(1)
	v_mfma_f32_16x16x32_bf16 v[16:19], v[96:99], v[12:15], v[16:19]
	v_ldexp_f32 v92, v92, v94
	v_mul_f32_e32 v94, v93, v73
	v_cmp_gt_f32_e32 vcc, s7, v94
	v_cndmask_b32_e64 v92, 0, v92, s[0:1]
	s_waitcnt lgkmcnt(0)
	v_mfma_f32_16x16x32_bf16 v[48:51], v[56:59], v[48:51], v[52:55]
	v_cndmask_b32_e32 v94, 0, v82, vcc
	v_fmac_f32_e32 v94, v93, v73
	v_exp_f32_e32 v93, v94
	v_cndmask_b32_e32 v94, 0, v86, vcc
	v_cmp_gt_i32_e32 vcc, 1, v100
	ds_read_b128 v[100:103], v62 offset:13184
	v_ldexp_f32 v93, v93, v94
	v_or_b32_e32 v94, 33, v61
	v_sub_u32_e32 v94, v78, v94
	v_cvt_f32_u32_e32 v95, v94
	v_cndmask_b32_e32 v93, 0, v93, vcc
	v_add_f32_e32 v92, v92, v93
	v_mul_f32_e32 v104, v92, v16
	v_mul_f32_e32 v93, v79, v95
	v_cmp_gt_f32_e32 vcc, s7, v93
	v_cmp_lt_i32_e64 s[0:1], -1, v94
	s_nop 0
	v_cndmask_b32_e32 v93, 0, v82, vcc
	v_fmac_f32_e32 v93, v79, v95
	v_cvt_f32_i32_e32 v95, v94
	v_cndmask_b32_e32 v16, 0, v86, vcc
	v_exp_f32_e32 v93, v93
	v_mul_f32_e32 v92, v95, v73
	v_cmp_gt_f32_e32 vcc, s7, v92
	v_ldexp_f32 v16, v93, v16
	v_cndmask_b32_e64 v16, 0, v16, s[0:1]
	v_cndmask_b32_e32 v92, 0, v82, vcc
	v_fmac_f32_e32 v92, v95, v73
	v_exp_f32_e32 v92, v92
	v_cndmask_b32_e32 v93, 0, v86, vcc
	v_cmp_gt_i32_e32 vcc, 1, v94
	v_ldexp_f32 v92, v92, v93
	v_or_b32_e32 v93, 34, v61
	v_sub_u32_e32 v93, v78, v93
	v_cvt_f32_u32_e32 v95, v93
	v_cvt_f32_i32_e32 v94, v93
	v_cndmask_b32_e32 v92, 0, v92, vcc
	v_add_f32_e32 v16, v16, v92
	v_mul_f32_e32 v92, v79, v95
	v_cmp_gt_f32_e32 vcc, s7, v92
	v_mul_f32_e32 v105, v16, v17
	v_mul_f32_e32 v17, v94, v73
	v_cndmask_b32_e32 v92, 0, v82, vcc
	v_cndmask_b32_e32 v16, 0, v86, vcc
	v_cmp_gt_f32_e32 vcc, s7, v17
	v_fmac_f32_e32 v92, v79, v95
	v_exp_f32_e32 v92, v92
	v_cndmask_b32_e32 v17, 0, v82, vcc
	v_fmac_f32_e32 v17, v94, v73
	v_exp_f32_e32 v17, v17
	v_ldexp_f32 v16, v92, v16
	v_cndmask_b32_e32 v92, 0, v86, vcc
	v_cmp_lt_i32_e64 s[0:1], -1, v93
	v_ldexp_f32 v17, v17, v92
	v_or_b32_e32 v92, 35, v61
	v_sub_u32_e32 v106, v78, v92
	v_cvt_f32_u32_e32 v92, v106
	v_cmp_gt_i32_e32 vcc, 1, v93
	v_cndmask_b32_e64 v16, 0, v16, s[0:1]
	v_cvt_f32_i32_e32 v96, v106
	v_cndmask_b32_e32 v17, 0, v17, vcc
	v_add_f32_e32 v16, v16, v17
	v_mul_f32_e32 v17, v79, v92
	v_cmp_gt_f32_e32 vcc, s7, v17
	v_mul_f32_e32 v107, v16, v18
	v_cmp_lt_i32_e64 s[0:1], -1, v106
	v_cndmask_b32_e32 v17, 0, v82, vcc
	v_fmac_f32_e32 v17, v79, v92
	v_exp_f32_e32 v17, v17
	v_cndmask_b32_e32 v16, 0, v86, vcc
	ds_read_b128 v[92:95], v62 offset:13056
	v_ldexp_f32 v16, v17, v16
	v_mul_f32_e32 v17, v96, v73
	v_cmp_gt_f32_e32 vcc, s7, v17
	v_cndmask_b32_e64 v16, 0, v16, s[0:1]
	s_nop 0
	v_cndmask_b32_e32 v17, 0, v82, vcc
	v_fmac_f32_e32 v17, v96, v73
	ds_read_b128 v[96:99], v62 offset:13120
	v_exp_f32_e32 v17, v17
	v_cndmask_b32_e32 v18, 0, v86, vcc
	s_waitcnt lgkmcnt(1)
	v_mfma_f32_16x16x32_bf16 v[92:95], v[92:95], v[0:3], 0
	v_cmp_gt_i32_e32 vcc, 1, v106
	v_ldexp_f32 v17, v17, v18
	s_nop 0
	v_cndmask_b32_e32 v17, 0, v17, vcc
	v_add_f32_e32 v16, v16, v17
	v_or_b32_e32 v17, 48, v61
	v_sub_u32_e32 v106, v78, v17
	s_waitcnt lgkmcnt(0)
	v_mfma_f32_16x16x32_bf16 v[92:95], v[96:99], v[4:7], v[92:95]
	v_cvt_f32_u32_e32 v108, v106
	ds_read_b128 v[96:99], v62 offset:13248
	v_mul_f32_e32 v109, v16, v19
	v_mfma_f32_16x16x32_bf16 v[16:19], v[100:103], v[8:11], v[92:95]
	v_cmp_lt_i32_e64 s[0:1], -1, v106
	s_nop 2
	v_mul_f32_e32 v92, v79, v108
	v_cmp_gt_f32_e32 vcc, s7, v92
	v_cvt_f32_i32_e32 v93, v106
	s_waitcnt lgkmcnt(0)
; #define LAS __attribute__((address_space(3)))
; DI unsigned cvt_pk_bf16(float lo, float hi) { unsigned r; asm volatile("v_cvt_pk_bf16_f32 %0, %1, %2" : "=v"(r) : "v"(lo), "v"(hi)); return r; }
; #define MFMA16(a, b, c) __builtin_amdgcn_mfma_f32_16x16x32_bf16((a), (b), (c), 0, 0, 0)
; DI void ret_out_item(const Params& p, int l, int b, int h, int c, LAS unsigned char* lds) {
;     ...
;     for (int kc = 0; kc < 4; ++kc) {
;         f32x4 s[2];
; #pragma unroll
;         for (int hf = 0; hf < 2; ++hf) {
;             s[hf] = (f32x4){0.f, 0.f, 0.f, 0.f};
; #pragma unroll
;             for (int ks = 0; ks < 4; ++ks) s[hf] = MFMA16(*(const LAS bf16x8*)(kcp + (2 * kc + hf) * 16 * RS + ks * 64), qf[ks], s[hf]);
; #pragma unroll
;             for (int j = 0; j < 4; ++j) {
;                 const int m = (2 * kc + hf) * 16 + q4 * 4 + j, d = tl - m;
;                 const float w = (d >= 0 ? exp2f(lgf * (float)d) : 0.f) + (d <= 0 ? exp2f(-lgb * (float)d) : 0.f);
;                 s[hf][j] *= w;
;             }
;         }
;         u32x4 w4; w4.x = cvt_pk_bf16(s[0][0], s[0][1]); w4.y = cvt_pk_bf16(s[0][2], s[0][3]); w4.z = cvt_pk_bf16(s[1][0], s[1][1]); w4.w = cvt_pk_bf16(s[1][2], s[1][3]);
;         const bf16x8 pb = __builtin_bit_cast(bf16x8, w4);
; #pragma unroll
;         for (int d = 0; d < 8; ++d) {
;             const u32x2 lo = *(const LAS u32x2*)(vtp + d * 16 * RS + kc * 64), hi = *(const LAS u32x2*)(vtp + d * 16 * RS + kc * 64 + 32);
;             u32x4 a4; a4.x = lo.x; a4.y = lo.y; a4.z = hi.x; a4.w = hi.y;
;             oacc[d] = MFMA16(__builtin_bit_cast(bf16x8, a4), pb, oacc[d]);
;         }
	v_mfma_f32_16x16x32_bf16 v[16:19], v[96:99], v[12:15], v[16:19]
	v_cndmask_b32_e32 v92, 0, v82, vcc
	v_fmac_f32_e32 v92, v79, v108
	v_exp_f32_e32 v92, v92
	v_cndmask_b32_e32 v94, 0, v86, vcc
	v_ldexp_f32 v92, v92, v94
	v_mul_f32_e32 v94, v93, v73
	v_cmp_gt_f32_e32 vcc, s7, v94
	v_cndmask_b32_e64 v92, 0, v92, s[0:1]
	s_nop 0
	v_cndmask_b32_e32 v94, 0, v82, vcc
	v_fmac_f32_e32 v94, v93, v73
	v_exp_f32_e32 v93, v94
	v_cndmask_b32_e32 v94, 0, v86, vcc
	v_cmp_gt_i32_e32 vcc, 1, v106
	v_ldexp_f32 v93, v93, v94
	v_or_b32_e32 v94, 49, v61
	v_sub_u32_e32 v94, v78, v94
	v_cvt_f32_u32_e32 v95, v94
	v_cndmask_b32_e32 v93, 0, v93, vcc
	v_add_f32_e32 v92, v92, v93
	v_mul_f32_e32 v92, v92, v16
	v_mul_f32_e32 v93, v79, v95
	v_cmp_gt_f32_e32 vcc, s7, v93
	v_cmp_lt_i32_e64 s[0:1], -1, v94
	s_nop 0
	v_cndmask_b32_e32 v93, 0, v82, vcc
	v_fmac_f32_e32 v93, v79, v95
	v_exp_f32_e32 v93, v93
	v_cvt_f32_i32_e32 v95, v94
	v_cndmask_b32_e32 v16, 0, v86, vcc
	v_ldexp_f32 v16, v93, v16
	v_mul_f32_e32 v93, v95, v73
	v_cmp_gt_f32_e32 vcc, s7, v93
	v_cndmask_b32_e64 v16, 0, v16, s[0:1]
	s_nop 0
	v_cndmask_b32_e32 v93, 0, v82, vcc
	v_fmac_f32_e32 v93, v95, v73
	v_exp_f32_e32 v93, v93
	v_cndmask_b32_e32 v95, 0, v86, vcc
	v_cmp_gt_i32_e32 vcc, 1, v94
	v_ldexp_f32 v93, v93, v95
	v_or_b32_e32 v95, 50, v61
	v_sub_u32_e32 v95, v78, v95
	v_cvt_f32_u32_e32 v96, v95
	v_cndmask_b32_e32 v93, 0, v93, vcc
	v_cvt_f32_i32_e32 v94, v95
	v_add_f32_e32 v16, v16, v93
	v_mul_f32_e32 v93, v79, v96
	v_cmp_gt_f32_e32 vcc, s7, v93
	v_cmp_lt_i32_e64 s[0:1], -1, v95
	s_nop 0
	v_cndmask_b32_e32 v93, 0, v82, vcc
	v_fmac_f32_e32 v93, v79, v96
	v_mul_f32_e32 v96, v16, v17
	v_mul_f32_e32 v17, v94, v73
	v_cndmask_b32_e32 v16, 0, v86, vcc
	v_cmp_gt_f32_e32 vcc, s7, v17
	v_exp_f32_e32 v93, v93
	s_nop 0
	v_cndmask_b32_e32 v17, 0, v82, vcc
	v_fmac_f32_e32 v17, v94, v73
	v_exp_f32_e32 v17, v17
	v_ldexp_f32 v16, v93, v16
	v_cndmask_b32_e32 v93, 0, v86, vcc
	v_cmp_gt_i32_e32 vcc, 1, v95
	v_ldexp_f32 v17, v17, v93
	v_or_b32_e32 v93, 51, v61
	v_sub_u32_e32 v93, v78, v93
	v_cvt_f32_u32_e32 v94, v93
	v_cndmask_b32_e64 v16, 0, v16, s[0:1]
	v_cndmask_b32_e32 v17, 0, v17, vcc
	v_add_f32_e32 v16, v16, v17
	v_mul_f32_e32 v17, v79, v94
	v_cmp_gt_f32_e32 vcc, s7, v17
	v_mul_f32_e32 v95, v16, v18
	v_cmp_lt_i32_e64 s[0:1], -1, v93
	v_cndmask_b32_e32 v17, 0, v82, vcc
	v_fmac_f32_e32 v17, v79, v94
	v_exp_f32_e32 v17, v17
	v_cvt_f32_i32_e32 v94, v93
	v_cndmask_b32_e32 v16, 0, v86, vcc
	v_ldexp_f32 v16, v17, v16
	v_mul_f32_e32 v17, v94, v73
	v_cmp_gt_f32_e32 vcc, s7, v17
	v_cndmask_b32_e64 v16, 0, v16, s[0:1]
	s_nop 0
	v_cndmask_b32_e32 v17, 0, v82, vcc
	v_fmac_f32_e32 v17, v94, v73
	v_exp_f32_e32 v17, v17
	v_cndmask_b32_e32 v18, 0, v86, vcc
	v_cmp_gt_i32_e32 vcc, 1, v93
	v_ldexp_f32 v17, v17, v18
	s_nop 0
	v_cndmask_b32_e32 v17, 0, v17, vcc
	v_add_f32_e32 v16, v16, v17
	v_mul_f32_e32 v19, v16, v19
	v_cvt_pk_bf16_f32 v16, v104, v105
	v_cvt_pk_bf16_f32 v17, v107, v109
	v_cvt_pk_bf16_f32 v18, v92, v96
	v_cvt_pk_bf16_f32 v19, v95, v19
	ds_read2_b64 v[52:55], v63 offset0:40 offset1:44
	ds_read2_b64 v[56:59], v64 offset0:72 offset1:76
	s_waitcnt lgkmcnt(1)
	v_mfma_f32_16x16x32_bf16 v[24:27], v[52:55], v[16:19], v[24:27]
	ds_read2_b64 v[52:55], v65 offset0:104 offset1:108
	ds_read2_b64 v[92:95], v60 offset0:8 offset1:12
	s_waitcnt lgkmcnt(2)
	v_mfma_f32_16x16x32_bf16 v[28:31], v[56:59], v[16:19], v[28:31]
	ds_read2_b64 v[56:59], v66 offset0:136 offset1:140
	s_waitcnt lgkmcnt(2)
	v_mfma_f32_16x16x32_bf16 v[32:35], v[52:55], v[16:19], v[32:35]
	ds_read2_b64 v[52:55], v67 offset0:168 offset1:172
	s_waitcnt lgkmcnt(1)
	v_mfma_f32_16x16x32_bf16 v[36:39], v[56:59], v[16:19], v[36:39]
	ds_read2_b64 v[56:59], v80 offset0:200 offset1:204
	s_waitcnt lgkmcnt(1)
	v_mfma_f32_16x16x32_bf16 v[40:43], v[52:55], v[16:19], v[40:43]
	ds_read_b128 v[52:55], v62 offset:17408
	s_waitcnt lgkmcnt(1)
	v_mfma_f32_16x16x32_bf16 v[44:47], v[56:59], v[16:19], v[44:47]
	ds_read_b128 v[56:59], v62 offset:17472
	s_waitcnt lgkmcnt(1)
	v_mfma_f32_16x16x32_bf16 v[52:55], v[52:55], v[0:3], 0
	v_mfma_f32_16x16x32_bf16 v[20:23], v[92:95], v[16:19], v[20:23]
	ds_read_b128 v[92:95], v62 offset:17536
	s_waitcnt lgkmcnt(1)
	v_mfma_f32_16x16x32_bf16 v[56:59], v[56:59], v[4:7], v[52:55]
	s_nop 3
	v_or_b32_e32 v52, 64, v61
	v_sub_u32_e32 v100, v78, v52
	v_cvt_f32_u32_e32 v101, v100
	s_waitcnt lgkmcnt(0)
	v_mfma_f32_16x16x32_bf16 v[56:59], v[92:95], v[8:11], v[56:59]
	v_cvt_f32_i32_e32 v93, v100
	v_cmp_lt_i32_e64 s[0:1], -1, v100
	v_mul_f32_e32 v92, v79, v101
	v_cmp_gt_f32_e32 vcc, s7, v92
	ds_read_b128 v[96:99], v62 offset:17600
	ds_read2_b64 v[52:55], v81 offset0:232 offset1:236
	v_cndmask_b32_e32 v92, 0, v82, vcc
	v_fmac_f32_e32 v92, v79, v101
	v_exp_f32_e32 v92, v92
	v_cndmask_b32_e32 v94, 0, v86, vcc
	s_waitcnt lgkmcnt(1)
	v_mfma_f32_16x16x32_bf16 v[56:59], v[96:99], v[12:15], v[56:59]
	v_ldexp_f32 v92, v92, v94
	v_mul_f32_e32 v94, v93, v73
	v_cmp_gt_f32_e32 vcc, s7, v94
	v_cndmask_b32_e64 v92, 0, v92, s[0:1]
	s_waitcnt lgkmcnt(0)
; #define LAS __attribute__((address_space(3)))
; DI unsigned cvt_pk_bf16(float lo, float hi) { unsigned r; asm volatile("v_cvt_pk_bf16_f32 %0, %1, %2" : "=v"(r) : "v"(lo), "v"(hi)); return r; }
; #define MFMA16(a, b, c) __builtin_amdgcn_mfma_f32_16x16x32_bf16((a), (b), (c), 0, 0, 0)
; DI void ret_out_item(const Params& p, int l, int b, int h, int c, LAS unsigned char* lds) {
;     ...
;     for (int kc = 0; kc < 4; ++kc) {
;         f32x4 s[2];
; #pragma unroll
;         for (int hf = 0; hf < 2; ++hf) {
;             s[hf] = (f32x4){0.f, 0.f, 0.f, 0.f};
; #pragma unroll
;             for (int ks = 0; ks < 4; ++ks) s[hf] = MFMA16(*(const LAS bf16x8*)(kcp + (2 * kc + hf) * 16 * RS + ks * 64), qf[ks], s[hf]);
; #pragma unroll
;             for (int j = 0; j < 4; ++j) {
;                 const int m = (2 * kc + hf) * 16 + q4 * 4 + j, d = tl - m;
;                 const float w = (d >= 0 ? exp2f(lgf * (float)d) : 0.f) + (d <= 0 ? exp2f(-lgb * (float)d) : 0.f);
;                 s[hf][j] *= w;
;             }
;         }
;         u32x4 w4; w4.x = cvt_pk_bf16(s[0][0], s[0][1]); w4.y = cvt_pk_bf16(s[0][2], s[0][3]); w4.z = cvt_pk_bf16(s[1][0], s[1][1]); w4.w = cvt_pk_bf16(s[1][2], s[1][3]);
;         const bf16x8 pb = __builtin_bit_cast(bf16x8, w4);
; #pragma unroll
;         for (int d = 0; d < 8; ++d) {
;             const u32x2 lo = *(const LAS u32x2*)(vtp + d * 16 * RS + kc * 64), hi = *(const LAS u32x2*)(vtp + d * 16 * RS + kc * 64 + 32);
;             u32x4 a4; a4.x = lo.x; a4.y = lo.y; a4.z = hi.x; a4.w = hi.y;
;             oacc[d] = MFMA16(__builtin_bit_cast(bf16x8, a4), pb, oacc[d]);
;         }
	v_mfma_f32_16x16x32_bf16 v[48:51], v[52:55], v[16:19], v[48:51]
	v_cndmask_b32_e32 v94, 0, v82, vcc
	v_fmac_f32_e32 v94, v93, v73
	v_exp_f32_e32 v93, v94
	v_cndmask_b32_e32 v94, 0, v86, vcc
	v_cmp_gt_i32_e32 vcc, 1, v100
	ds_read_b128 v[100:103], v62 offset:21888
	v_ldexp_f32 v93, v93, v94
	v_or_b32_e32 v94, 0x41, v61
	v_sub_u32_e32 v94, v78, v94
	v_cvt_f32_u32_e32 v95, v94
	v_cndmask_b32_e32 v93, 0, v93, vcc
	v_add_f32_e32 v92, v92, v93
	v_mul_f32_e32 v104, v92, v56
	v_mul_f32_e32 v93, v79, v95
	v_cmp_gt_f32_e32 vcc, s7, v93
	v_cmp_lt_i32_e64 s[0:1], -1, v94
	s_nop 0
	v_cndmask_b32_e32 v93, 0, v82, vcc
	v_fmac_f32_e32 v93, v79, v95
	v_cvt_f32_i32_e32 v95, v94
	v_cndmask_b32_e32 v56, 0, v86, vcc
	v_exp_f32_e32 v93, v93
	v_mul_f32_e32 v92, v95, v73
	v_cmp_gt_f32_e32 vcc, s7, v92
	v_ldexp_f32 v56, v93, v56
	v_cndmask_b32_e64 v56, 0, v56, s[0:1]
	v_cndmask_b32_e32 v92, 0, v82, vcc
	v_fmac_f32_e32 v92, v95, v73
	v_exp_f32_e32 v92, v92
	v_cndmask_b32_e32 v93, 0, v86, vcc
	v_cmp_gt_i32_e32 vcc, 1, v94
	v_ldexp_f32 v92, v92, v93
	v_or_b32_e32 v93, 0x42, v61
	v_sub_u32_e32 v93, v78, v93
	v_cvt_f32_u32_e32 v95, v93
	v_cvt_f32_i32_e32 v94, v93
	v_cndmask_b32_e32 v92, 0, v92, vcc
	v_add_f32_e32 v56, v56, v92
	v_mul_f32_e32 v92, v79, v95
	v_cmp_gt_f32_e32 vcc, s7, v92
	v_mul_f32_e32 v105, v56, v57
	v_mul_f32_e32 v57, v94, v73
	v_cndmask_b32_e32 v92, 0, v82, vcc
	v_cndmask_b32_e32 v56, 0, v86, vcc
	v_cmp_gt_f32_e32 vcc, s7, v57
	v_fmac_f32_e32 v92, v79, v95
	v_exp_f32_e32 v92, v92
	v_cndmask_b32_e32 v57, 0, v82, vcc
	v_fmac_f32_e32 v57, v94, v73
	v_exp_f32_e32 v57, v57
	v_ldexp_f32 v56, v92, v56
	v_cndmask_b32_e32 v92, 0, v86, vcc
	v_cmp_lt_i32_e64 s[0:1], -1, v93
	v_ldexp_f32 v57, v57, v92
	v_or_b32_e32 v92, 0x43, v61
	v_sub_u32_e32 v106, v78, v92
	v_cvt_f32_u32_e32 v92, v106
	v_cmp_gt_i32_e32 vcc, 1, v93
	v_cndmask_b32_e64 v56, 0, v56, s[0:1]
	v_cvt_f32_i32_e32 v96, v106
	v_cndmask_b32_e32 v57, 0, v57, vcc
	v_add_f32_e32 v56, v56, v57
	v_mul_f32_e32 v57, v79, v92
	v_cmp_gt_f32_e32 vcc, s7, v57
	v_mul_f32_e32 v107, v56, v58
	v_cmp_lt_i32_e64 s[0:1], -1, v106
	v_cndmask_b32_e32 v57, 0, v82, vcc
	v_fmac_f32_e32 v57, v79, v92
	v_exp_f32_e32 v57, v57
	v_cndmask_b32_e32 v56, 0, v86, vcc
	ds_read_b128 v[92:95], v62 offset:21760
	v_ldexp_f32 v56, v57, v56
	v_mul_f32_e32 v57, v96, v73
	v_cmp_gt_f32_e32 vcc, s7, v57
	v_cndmask_b32_e64 v56, 0, v56, s[0:1]
	s_nop 0
	v_cndmask_b32_e32 v57, 0, v82, vcc
	v_fmac_f32_e32 v57, v96, v73
	ds_read_b128 v[96:99], v62 offset:21824
	v_exp_f32_e32 v57, v57
	v_cndmask_b32_e32 v58, 0, v86, vcc
	s_waitcnt lgkmcnt(1)
	v_mfma_f32_16x16x32_bf16 v[92:95], v[92:95], v[0:3], 0
	v_cmp_gt_i32_e32 vcc, 1, v106
	v_ldexp_f32 v57, v57, v58
	s_nop 0
	v_cndmask_b32_e32 v57, 0, v57, vcc
	v_add_f32_e32 v56, v56, v57
	v_or_b32_e32 v57, 0x50, v61
	v_sub_u32_e32 v106, v78, v57
	s_waitcnt lgkmcnt(0)
	v_mfma_f32_16x16x32_bf16 v[92:95], v[96:99], v[4:7], v[92:95]
	v_cvt_f32_u32_e32 v108, v106
	ds_read_b128 v[96:99], v62 offset:21952
	v_mul_f32_e32 v109, v56, v59
	v_mfma_f32_16x16x32_bf16 v[56:59], v[100:103], v[8:11], v[92:95]
	v_cmp_lt_i32_e64 s[0:1], -1, v106
	s_nop 2
	v_mul_f32_e32 v92, v79, v108
	v_cmp_gt_f32_e32 vcc, s7, v92
	v_cvt_f32_i32_e32 v93, v106
	s_waitcnt lgkmcnt(0)
	v_mfma_f32_16x16x32_bf16 v[56:59], v[96:99], v[12:15], v[56:59]
	v_cndmask_b32_e32 v92, 0, v82, vcc
	v_fmac_f32_e32 v92, v79, v108
	v_exp_f32_e32 v92, v92
	v_cndmask_b32_e32 v94, 0, v86, vcc
	v_ldexp_f32 v92, v92, v94
	v_mul_f32_e32 v94, v93, v73
	v_cmp_gt_f32_e32 vcc, s7, v94
	v_cndmask_b32_e64 v92, 0, v92, s[0:1]
	s_nop 0
	v_cndmask_b32_e32 v94, 0, v82, vcc
	v_fmac_f32_e32 v94, v93, v73
	v_exp_f32_e32 v93, v94
	v_cndmask_b32_e32 v94, 0, v86, vcc
	v_cmp_gt_i32_e32 vcc, 1, v106
	v_ldexp_f32 v93, v93, v94
	v_or_b32_e32 v94, 0x51, v61
	v_sub_u32_e32 v94, v78, v94
	v_cvt_f32_u32_e32 v95, v94
	v_cndmask_b32_e32 v93, 0, v93, vcc
	v_add_f32_e32 v92, v92, v93
	v_mul_f32_e32 v92, v92, v56
	v_mul_f32_e32 v93, v79, v95
	v_cmp_gt_f32_e32 vcc, s7, v93
	v_cmp_lt_i32_e64 s[0:1], -1, v94
	s_nop 0
	v_cndmask_b32_e32 v93, 0, v82, vcc
	v_fmac_f32_e32 v93, v79, v95
	v_exp_f32_e32 v93, v93
	v_cvt_f32_i32_e32 v95, v94
	v_cndmask_b32_e32 v56, 0, v86, vcc
	v_ldexp_f32 v56, v93, v56
	v_mul_f32_e32 v93, v95, v73
	v_cmp_gt_f32_e32 vcc, s7, v93
	v_cndmask_b32_e64 v56, 0, v56, s[0:1]
	s_nop 0
	v_cndmask_b32_e32 v93, 0, v82, vcc
	v_fmac_f32_e32 v93, v95, v73
	v_exp_f32_e32 v93, v93
	v_cndmask_b32_e32 v95, 0, v86, vcc
	v_cmp_gt_i32_e32 vcc, 1, v94
	v_ldexp_f32 v93, v93, v95
	v_or_b32_e32 v95, 0x52, v61
	v_sub_u32_e32 v95, v78, v95
	v_cvt_f32_u32_e32 v96, v95
	v_cndmask_b32_e32 v93, 0, v93, vcc
	v_cvt_f32_i32_e32 v94, v95
	v_add_f32_e32 v56, v56, v93
	v_mul_f32_e32 v93, v79, v96
	v_cmp_gt_f32_e32 vcc, s7, v93
	v_cmp_lt_i32_e64 s[0:1], -1, v95
	s_nop 0
	v_cndmask_b32_e32 v93, 0, v82, vcc
	v_fmac_f32_e32 v93, v79, v96
	v_mul_f32_e32 v96, v56, v57
	v_mul_f32_e32 v57, v94, v73
	v_cndmask_b32_e32 v56, 0, v86, vcc
	v_cmp_gt_f32_e32 vcc, s7, v57
	v_exp_f32_e32 v93, v93
	s_nop 0
	v_cndmask_b32_e32 v57, 0, v82, vcc
	v_fmac_f32_e32 v57, v94, v73
	v_exp_f32_e32 v57, v57
	v_ldexp_f32 v56, v93, v56
	v_cndmask_b32_e32 v93, 0, v86, vcc
	v_cmp_gt_i32_e32 vcc, 1, v95
	v_ldexp_f32 v57, v57, v93
	v_or_b32_e32 v93, 0x53, v61
	v_sub_u32_e32 v93, v78, v93
	v_cvt_f32_u32_e32 v94, v93
	v_cndmask_b32_e64 v56, 0, v56, s[0:1]
	v_cndmask_b32_e32 v57, 0, v57, vcc
	v_add_f32_e32 v56, v56, v57
	v_mul_f32_e32 v57, v79, v94
	v_cmp_gt_f32_e32 vcc, s7, v57
	v_mul_f32_e32 v95, v56, v58
	v_cmp_lt_i32_e64 s[0:1], -1, v93
	v_cndmask_b32_e32 v57, 0, v82, vcc
	v_fmac_f32_e32 v57, v79, v94
	v_exp_f32_e32 v57, v57
	v_cvt_f32_i32_e32 v94, v93
	v_cndmask_b32_e32 v56, 0, v86, vcc
	v_ldexp_f32 v56, v57, v56
	v_mul_f32_e32 v57, v94, v73
	v_cmp_gt_f32_e32 vcc, s7, v57
	v_cndmask_b32_e64 v56, 0, v56, s[0:1]
	s_nop 0
	v_cndmask_b32_e32 v57, 0, v82, vcc
	v_fmac_f32_e32 v57, v94, v73
	v_exp_f32_e32 v57, v57
	v_cndmask_b32_e32 v58, 0, v86, vcc
	v_cmp_gt_i32_e32 vcc, 1, v93
	v_ldexp_f32 v57, v57, v58
	s_nop 0
	v_cndmask_b32_e32 v57, 0, v57, vcc
	v_add_f32_e32 v56, v56, v57
	v_mul_f32_e32 v59, v56, v59
	v_cvt_pk_bf16_f32 v56, v104, v105
	v_cvt_pk_bf16_f32 v57, v107, v109
	v_cvt_pk_bf16_f32 v58, v92, v96
	v_cvt_pk_bf16_f32 v59, v95, v59
	ds_read2_b64 v[92:95], v60 offset0:16 offset1:20
	ds_read2_b64 v[52:55], v63 offset0:48 offset1:52
	s_waitcnt lgkmcnt(1)
; #define LAS __attribute__((address_space(3)))
; DI unsigned cvt_pk_bf16(float lo, float hi) { unsigned r; asm volatile("v_cvt_pk_bf16_f32 %0, %1, %2" : "=v"(r) : "v"(lo), "v"(hi)); return r; }
; #define MFMA16(a, b, c) __builtin_amdgcn_mfma_f32_16x16x32_bf16((a), (b), (c), 0, 0, 0)
; DI void ret_out_item(const Params& p, int l, int b, int h, int c, LAS unsigned char* lds) {
;     ...
;     for (int kc = 0; kc < 4; ++kc) {
;         f32x4 s[2];
; #pragma unroll
;         for (int hf = 0; hf < 2; ++hf) {
;             s[hf] = (f32x4){0.f, 0.f, 0.f, 0.f};
; #pragma unroll
;             for (int ks = 0; ks < 4; ++ks) s[hf] = MFMA16(*(const LAS bf16x8*)(kcp + (2 * kc + hf) * 16 * RS + ks * 64), qf[ks], s[hf]);
; #pragma unroll
;             for (int j = 0; j < 4; ++j) {
;                 const int m = (2 * kc + hf) * 16 + q4 * 4 + j, d = tl - m;
;                 const float w = (d >= 0 ? exp2f(lgf * (float)d) : 0.f) + (d <= 0 ? exp2f(-lgb * (float)d) : 0.f);
;                 s[hf][j] *= w;
;             }
;         }
;         u32x4 w4; w4.x = cvt_pk_bf16(s[0][0], s[0][1]); w4.y = cvt_pk_bf16(s[0][2], s[0][3]); w4.z = cvt_pk_bf16(s[1][0], s[1][1]); w4.w = cvt_pk_bf16(s[1][2], s[1][3]);
;         const bf16x8 pb = __builtin_bit_cast(bf16x8, w4);
; #pragma unroll
;         for (int d = 0; d < 8; ++d) {
;             const u32x2 lo = *(const LAS u32x2*)(vtp + d * 16 * RS + kc * 64), hi = *(const LAS u32x2*)(vtp + d * 16 * RS + kc * 64 + 32);
;             u32x4 a4; a4.x = lo.x; a4.y = lo.y; a4.z = hi.x; a4.w = hi.y;
;             oacc[d] = MFMA16(__builtin_bit_cast(bf16x8, a4), pb, oacc[d]);
;         }
	v_mfma_f32_16x16x32_bf16 v[16:19], v[92:95], v[56:59], v[20:23]
	ds_read2_b64 v[92:95], v64 offset0:80 offset1:84
	s_waitcnt lgkmcnt(1)
	v_mfma_f32_16x16x32_bf16 v[20:23], v[52:55], v[56:59], v[24:27]
	ds_read2_b64 v[52:55], v66 offset0:144 offset1:148
	s_nop 1
	ds_read2_b64 v[24:27], v65 offset0:112 offset1:116
	s_waitcnt lgkmcnt(0)
	v_mfma_f32_16x16x32_bf16 v[32:35], v[24:27], v[56:59], v[32:35]
	ds_read2_b64 v[24:27], v67 offset0:176 offset1:180
	v_mfma_f32_16x16x32_bf16 v[36:39], v[52:55], v[56:59], v[36:39]
	ds_read2_b64 v[52:55], v80 offset0:208 offset1:212
	s_waitcnt lgkmcnt(1)
	v_mfma_f32_16x16x32_bf16 v[40:43], v[24:27], v[56:59], v[40:43]
	ds_read2_b64 v[24:27], v81 offset0:240 offset1:244
	s_waitcnt lgkmcnt(1)
	v_mfma_f32_16x16x32_bf16 v[44:47], v[52:55], v[56:59], v[44:47]
	ds_read_b128 v[52:55], v62 offset:26112
	s_waitcnt lgkmcnt(1)
	v_mfma_f32_16x16x32_bf16 v[48:51], v[24:27], v[56:59], v[48:51]
	ds_read_b128 v[24:27], v62 offset:26176
	s_waitcnt lgkmcnt(1)
	v_mfma_f32_16x16x32_bf16 v[52:55], v[52:55], v[0:3], 0
	v_mfma_f32_16x16x32_bf16 v[28:31], v[92:95], v[56:59], v[28:31]
	ds_read_b128 v[56:59], v62 offset:26240
	s_waitcnt lgkmcnt(1)
	v_mfma_f32_16x16x32_bf16 v[24:27], v[24:27], v[4:7], v[52:55]
	s_nop 3
	v_or_b32_e32 v52, 0x60, v61
	v_sub_u32_e32 v92, v78, v52
	ds_read_b128 v[52:55], v62 offset:26304
	v_cvt_f32_u32_e32 v93, v92
	s_waitcnt lgkmcnt(1)
	v_mfma_f32_16x16x32_bf16 v[24:27], v[56:59], v[8:11], v[24:27]
	v_cvt_f32_i32_e32 v57, v92
	v_cmp_lt_i32_e64 s[0:1], -1, v92
	v_mul_f32_e32 v56, v79, v93
	v_cmp_gt_f32_e32 vcc, s7, v56
	s_waitcnt lgkmcnt(0)
	v_mfma_f32_16x16x32_bf16 v[24:27], v[52:55], v[12:15], v[24:27]
	v_mul_f32_e32 v53, v57, v73
	v_cndmask_b32_e32 v56, 0, v82, vcc
	v_cndmask_b32_e32 v52, 0, v86, vcc
	v_cmp_gt_f32_e32 vcc, s7, v53
	v_fmac_f32_e32 v56, v79, v93
	v_exp_f32_e32 v56, v56
	v_cndmask_b32_e32 v53, 0, v82, vcc
	v_fmac_f32_e32 v53, v57, v73
	v_exp_f32_e32 v53, v53
	v_cndmask_b32_e32 v54, 0, v86, vcc
	v_ldexp_f32 v52, v56, v52
	v_cmp_gt_i32_e32 vcc, 1, v92
	v_ldexp_f32 v53, v53, v54
	v_or_b32_e32 v54, 0x61, v61
	v_sub_u32_e32 v54, v78, v54
	v_cvt_f32_u32_e32 v55, v54
	v_cndmask_b32_e64 v52, 0, v52, s[0:1]
	v_cndmask_b32_e32 v53, 0, v53, vcc
	v_add_f32_e32 v52, v52, v53
	v_mul_f32_e32 v53, v79, v55
	v_cmp_gt_f32_e32 vcc, s7, v53
	v_mul_f32_e32 v24, v52, v24
	v_cmp_lt_i32_e64 s[0:1], -1, v54
	v_cndmask_b32_e32 v53, 0, v82, vcc
	v_fmac_f32_e32 v53, v79, v55
	v_exp_f32_e32 v53, v53
	v_cvt_f32_i32_e32 v55, v54
	v_cndmask_b32_e32 v52, 0, v86, vcc
	v_ldexp_f32 v52, v53, v52
	v_mul_f32_e32 v53, v55, v73
	v_cmp_gt_f32_e32 vcc, s7, v53
	v_cndmask_b32_e64 v52, 0, v52, s[0:1]
	s_nop 0
	v_cndmask_b32_e32 v53, 0, v82, vcc
	v_fmac_f32_e32 v53, v55, v73
	v_exp_f32_e32 v53, v53
	v_cndmask_b32_e32 v55, 0, v86, vcc
	v_cmp_gt_i32_e32 vcc, 1, v54
	v_ldexp_f32 v53, v53, v55
	v_or_b32_e32 v55, 0x62, v61
	v_sub_u32_e32 v55, v78, v55
	v_cvt_f32_u32_e32 v56, v55
	v_cndmask_b32_e32 v53, 0, v53, vcc
	v_add_f32_e32 v52, v52, v53
	v_cvt_f32_i32_e32 v54, v55
	v_mul_f32_e32 v53, v79, v56
	v_cmp_gt_f32_e32 vcc, s7, v53
	v_mul_f32_e32 v25, v52, v25
	v_cmp_lt_i32_e64 s[0:1], -1, v55
	v_cndmask_b32_e32 v53, 0, v82, vcc
	v_fmac_f32_e32 v53, v79, v56
	v_exp_f32_e32 v53, v53
	v_cndmask_b32_e32 v52, 0, v86, vcc
	v_ldexp_f32 v52, v53, v52
	v_mul_f32_e32 v53, v54, v73
	v_cmp_gt_f32_e32 vcc, s7, v53
	v_cndmask_b32_e64 v52, 0, v52, s[0:1]
	s_nop 0
	v_cndmask_b32_e32 v53, 0, v82, vcc
	v_fmac_f32_e32 v53, v54, v73
	v_exp_f32_e32 v53, v53
	v_cndmask_b32_e32 v54, 0, v86, vcc
	v_cmp_gt_i32_e32 vcc, 1, v55
	v_ldexp_f32 v53, v53, v54
	v_or_b32_e32 v54, 0x63, v61
	v_sub_u32_e32 v92, v78, v54
	v_cvt_f32_u32_e32 v54, v92
	v_cndmask_b32_e32 v53, 0, v53, vcc
	v_add_f32_e32 v52, v52, v53
	v_cvt_f32_i32_e32 v56, v92
	v_mul_f32_e32 v53, v79, v54
	v_cmp_gt_f32_e32 vcc, s7, v53
	v_mul_f32_e32 v26, v52, v26
	v_mul_f32_e32 v57, v56, v73
	v_cndmask_b32_e32 v53, 0, v82, vcc
	v_fmac_f32_e32 v53, v79, v54
	v_exp_f32_e32 v53, v53
	v_cndmask_b32_e32 v52, 0, v86, vcc
	v_cmp_gt_f32_e32 vcc, s7, v57
	v_cmp_lt_i32_e64 s[0:1], -1, v92
	v_ldexp_f32 v93, v53, v52
	ds_read_b128 v[52:55], v62 offset:30464
	v_cndmask_b32_e32 v57, 0, v82, vcc
	v_fmac_f32_e32 v57, v56, v73
	v_exp_f32_e32 v94, v57
	ds_read_b128 v[56:59], v62 offset:30528
	s_waitcnt lgkmcnt(1)
	v_mfma_f32_16x16x32_bf16 v[0:3], v[52:55], v[0:3], 0
	ds_read_b128 v[52:55], v62 offset:30592
	v_cndmask_b32_e32 v95, 0, v86, vcc
	v_ldexp_f32 v94, v94, v95
	s_waitcnt lgkmcnt(1)
	v_mfma_f32_16x16x32_bf16 v[0:3], v[56:59], v[4:7], v[0:3]
	v_or_b32_e32 v4, 0x70, v61
	v_sub_u32_e32 v56, v78, v4
	ds_read_b128 v[4:7], v62 offset:30656
	v_cvt_f32_u32_e32 v57, v56
	s_waitcnt lgkmcnt(1)
	v_mfma_f32_16x16x32_bf16 v[0:3], v[52:55], v[8:11], v[0:3]
	v_cvt_f32_i32_e32 v9, v56
	v_cmp_gt_i32_e32 vcc, 1, v92
	v_mul_f32_e32 v8, v79, v57
	s_waitcnt lgkmcnt(0)
; #define LAS __attribute__((address_space(3)))
; DI unsigned cvt_pk_bf16(float lo, float hi) { unsigned r; asm volatile("v_cvt_pk_bf16_f32 %0, %1, %2" : "=v"(r) : "v"(lo), "v"(hi)); return r; }
; #define MFMA16(a, b, c) __builtin_amdgcn_mfma_f32_16x16x32_bf16((a), (b), (c), 0, 0, 0)
; DI void ret_out_item(const Params& p, int l, int b, int h, int c, LAS unsigned char* lds) {
;     ...
;     for (int kc = 0; kc < 4; ++kc) {
;         f32x4 s[2];
; #pragma unroll
;         for (int hf = 0; hf < 2; ++hf) {
;             s[hf] = (f32x4){0.f, 0.f, 0.f, 0.f};
; #pragma unroll
;             for (int ks = 0; ks < 4; ++ks) s[hf] = MFMA16(*(const LAS bf16x8*)(kcp + (2 * kc + hf) * 16 * RS + ks * 64), qf[ks], s[hf]);
; #pragma unroll
;             for (int j = 0; j < 4; ++j) {
;                 const int m = (2 * kc + hf) * 16 + q4 * 4 + j, d = tl - m;
;                 const float w = (d >= 0 ? exp2f(lgf * (float)d) : 0.f) + (d <= 0 ? exp2f(-lgb * (float)d) : 0.f);
;                 s[hf][j] *= w;
;             }
;         }
;         u32x4 w4; w4.x = cvt_pk_bf16(s[0][0], s[0][1]); w4.y = cvt_pk_bf16(s[0][2], s[0][3]); w4.z = cvt_pk_bf16(s[1][0], s[1][1]); w4.w = cvt_pk_bf16(s[1][2], s[1][3]);
;         const bf16x8 pb = __builtin_bit_cast(bf16x8, w4);
; #pragma unroll
;         for (int d = 0; d < 8; ++d) {
;             const u32x2 lo = *(const LAS u32x2*)(vtp + d * 16 * RS + kc * 64), hi = *(const LAS u32x2*)(vtp + d * 16 * RS + kc * 64 + 32);
;             u32x4 a4; a4.x = lo.x; a4.y = lo.y; a4.z = hi.x; a4.w = hi.y;
;             oacc[d] = MFMA16(__builtin_bit_cast(bf16x8, a4), pb, oacc[d]);
;         }
;     }
;     float sum = 0.f;
; #pragma unroll
;     for (int d = 0; d < 8; ++d) sum += oacc[d][0] + oacc[d][1] + oacc[d][2] + oacc[d][3];
;     sum += __shfl_xor(sum, 16); sum += __shfl_xor(sum, 32);
	v_mfma_f32_16x16x32_bf16 v[0:3], v[4:7], v[12:15], v[0:3]
	v_cndmask_b32_e32 v92, 0, v94, vcc
	v_cmp_gt_f32_e32 vcc, s7, v8
	v_mul_f32_e32 v5, v9, v73
	v_cndmask_b32_e64 v93, 0, v93, s[0:1]
	v_cndmask_b32_e32 v8, 0, v82, vcc
	v_cndmask_b32_e32 v4, 0, v86, vcc
	v_cmp_gt_f32_e32 vcc, s7, v5
	v_fmac_f32_e32 v8, v79, v57
	v_exp_f32_e32 v8, v8
	v_cndmask_b32_e32 v5, 0, v82, vcc
	v_fmac_f32_e32 v5, v9, v73
	v_exp_f32_e32 v5, v5
	v_cndmask_b32_e32 v6, 0, v86, vcc
	v_ldexp_f32 v4, v8, v4
	v_cmp_lt_i32_e64 s[0:1], -1, v56
	v_ldexp_f32 v5, v5, v6
	v_or_b32_e32 v6, 0x71, v61
	v_sub_u32_e32 v6, v78, v6
	v_cvt_f32_u32_e32 v7, v6
	v_cmp_gt_i32_e32 vcc, 1, v56
	v_cndmask_b32_e64 v4, 0, v4, s[0:1]
	v_cmp_lt_i32_e64 s[0:1], -1, v6
	v_cndmask_b32_e32 v5, 0, v5, vcc
	v_add_f32_e32 v4, v4, v5
	v_mul_f32_e32 v5, v79, v7
	v_cmp_gt_f32_e32 vcc, s7, v5
	v_mul_f32_e32 v4, v4, v0
	v_add_f32_e32 v92, v93, v92
	v_cndmask_b32_e32 v5, 0, v82, vcc
	v_fmac_f32_e32 v5, v79, v7
	v_exp_f32_e32 v5, v5
	v_cvt_f32_i32_e32 v7, v6
	v_cndmask_b32_e32 v0, 0, v86, vcc
	v_mul_f32_e32 v27, v92, v27
	v_ldexp_f32 v0, v5, v0
	v_mul_f32_e32 v5, v7, v73
	v_cmp_gt_f32_e32 vcc, s7, v5
	v_cndmask_b32_e64 v0, 0, v0, s[0:1]
	s_nop 0
	v_cndmask_b32_e32 v5, 0, v82, vcc
	v_fmac_f32_e32 v5, v7, v73
	v_exp_f32_e32 v5, v5
	v_cndmask_b32_e32 v7, 0, v86, vcc
	v_cmp_gt_i32_e32 vcc, 1, v6
	v_ldexp_f32 v5, v5, v7
	v_or_b32_e32 v7, 0x72, v61
	v_sub_u32_e32 v7, v78, v7
	v_cvt_f32_u32_e32 v8, v7
	v_cndmask_b32_e32 v5, 0, v5, vcc
	v_cvt_f32_i32_e32 v6, v7
	v_add_f32_e32 v0, v0, v5
	v_mul_f32_e32 v5, v79, v8
	v_cmp_gt_f32_e32 vcc, s7, v5
	v_cmp_lt_i32_e64 s[0:1], -1, v7
	s_nop 0
	v_cndmask_b32_e32 v5, 0, v82, vcc
	v_fmac_f32_e32 v5, v79, v8
	v_mul_f32_e32 v8, v0, v1
	v_mul_f32_e32 v1, v6, v73
	v_cndmask_b32_e32 v0, 0, v86, vcc
	v_cmp_gt_f32_e32 vcc, s7, v1
	v_exp_f32_e32 v5, v5
	s_nop 0
	v_cndmask_b32_e32 v1, 0, v82, vcc
	v_fmac_f32_e32 v1, v6, v73
	v_exp_f32_e32 v1, v1
	v_ldexp_f32 v0, v5, v0
	v_cndmask_b32_e32 v5, 0, v86, vcc
	v_cmp_gt_i32_e32 vcc, 1, v7
	v_ldexp_f32 v1, v1, v5
	v_or_b32_e32 v5, 0x73, v61
	v_sub_u32_e32 v5, v78, v5
	v_cvt_f32_u32_e32 v6, v5
	v_cndmask_b32_e64 v0, 0, v0, s[0:1]
	v_cndmask_b32_e32 v1, 0, v1, vcc
	v_add_f32_e32 v0, v0, v1
	v_mul_f32_e32 v1, v79, v6
	v_cmp_gt_f32_e32 vcc, s7, v1
	v_mul_f32_e32 v7, v0, v2
	v_cmp_lt_i32_e64 s[0:1], -1, v5
	v_cndmask_b32_e32 v1, 0, v82, vcc
	v_fmac_f32_e32 v1, v79, v6
	v_exp_f32_e32 v1, v1
	v_cvt_f32_i32_e32 v6, v5
	v_cndmask_b32_e32 v0, 0, v86, vcc
	v_ldexp_f32 v0, v1, v0
	v_mul_f32_e32 v1, v6, v73
	v_cmp_gt_f32_e32 vcc, s7, v1
	v_cndmask_b32_e64 v0, 0, v0, s[0:1]
	s_nop 0
	v_cndmask_b32_e32 v1, 0, v82, vcc
	v_fmac_f32_e32 v1, v6, v73
	v_exp_f32_e32 v1, v1
	v_cndmask_b32_e32 v2, 0, v86, vcc
	v_cmp_gt_i32_e32 vcc, 1, v5
	v_ldexp_f32 v1, v1, v2
	s_nop 0
	v_cndmask_b32_e32 v1, 0, v1, vcc
	v_add_f32_e32 v0, v0, v1
	v_mul_f32_e32 v3, v0, v3
	v_cvt_pk_bf16_f32 v0, v24, v25
	v_cvt_pk_bf16_f32 v1, v26, v27
	v_cvt_pk_bf16_f32 v2, v4, v8
	v_cvt_pk_bf16_f32 v3, v7, v3
	ds_read2_b64 v[4:7], v60 offset0:24 offset1:28
	s_waitcnt lgkmcnt(0)
	v_mfma_f32_16x16x32_bf16 v[52:55], v[4:7], v[0:3], v[16:19]
	ds_read2_b64 v[4:7], v63 offset0:56 offset1:60
	v_cmp_lt_i32_e32 vcc, v88, v89
	s_waitcnt lgkmcnt(0)
	v_mfma_f32_16x16x32_bf16 v[24:27], v[4:7], v[0:3], v[20:23]
	ds_read2_b64 v[4:7], v64 offset0:88 offset1:92
	s_waitcnt lgkmcnt(0)
	v_mfma_f32_16x16x32_bf16 v[20:23], v[4:7], v[0:3], v[28:31]
	ds_read2_b64 v[4:7], v65 offset0:120 offset1:124
	s_nop 1
	ds_read2_b64 v[28:31], v81 offset0:248 offset1:252
	s_waitcnt lgkmcnt(1)
	v_mfma_f32_16x16x32_bf16 v[16:19], v[4:7], v[0:3], v[32:35]
	ds_read2_b64 v[4:7], v66 offset0:152 offset1:156
	s_waitcnt lgkmcnt(0)
	v_mfma_f32_16x16x32_bf16 v[12:15], v[4:7], v[0:3], v[36:39]
	ds_read2_b64 v[4:7], v67 offset0:184 offset1:188
	s_waitcnt lgkmcnt(0)
	v_mfma_f32_16x16x32_bf16 v[8:11], v[4:7], v[0:3], v[40:43]
	ds_read2_b64 v[4:7], v80 offset0:216 offset1:220
	s_nop 1
	v_lshl_add_u64 v[42:43], v[76:77], 0, v[68:69]
	s_waitcnt lgkmcnt(0)
	v_mfma_f32_16x16x32_bf16 v[4:7], v[4:7], v[0:3], v[44:47]
	v_mfma_f32_16x16x32_bf16 v[0:3], v[28:31], v[0:3], v[48:51]
	v_mov_b32_e32 v28, v52
	v_mov_b32_e32 v29, v24
	v_mov_b32_e32 v30, v53
	v_mov_b32_e32 v31, v25
	v_pk_add_f32 v[28:29], v[28:29], v[30:31]
	v_mov_b32_e32 v30, v54
	v_mov_b32_e32 v31, v26
	v_pk_add_f32 v[28:29], v[30:31], v[28:29]
	v_mov_b32_e32 v30, v55
	v_mov_b32_e32 v31, v27
	v_pk_add_f32 v[28:29], v[30:31], v[28:29]
	v_mov_b32_e32 v30, v21
	v_add_f32_e32 v28, 0, v28
	v_add_f32_e32 v32, v28, v29
	v_mov_b32_e32 v28, v20
	v_mov_b32_e32 v29, v16
	v_mov_b32_e32 v31, v17
	v_pk_add_f32 v[28:29], v[28:29], v[30:31]
	v_mov_b32_e32 v30, v22
	v_mov_b32_e32 v31, v18
	v_pk_add_f32 v[28:29], v[30:31], v[28:29]
	v_mov_b32_e32 v30, v23
	v_mov_b32_e32 v31, v19
	v_pk_add_f32 v[28:29], v[30:31], v[28:29]
	v_mov_b32_e32 v30, v13
	v_add_f32_e32 v28, v32, v28
	v_add_f32_e32 v32, v28, v29
	v_mov_b32_e32 v28, v12
	v_mov_b32_e32 v29, v8
	v_mov_b32_e32 v31, v9
	v_pk_add_f32 v[28:29], v[28:29], v[30:31]
	v_mov_b32_e32 v30, v14
	v_mov_b32_e32 v31, v10
	v_pk_add_f32 v[28:29], v[30:31], v[28:29]
	v_mov_b32_e32 v30, v15
	v_mov_b32_e32 v31, v11
	v_pk_add_f32 v[28:29], v[30:31], v[28:29]
	v_mov_b32_e32 v30, v5
	v_add_f32_e32 v28, v32, v28
	v_add_f32_e32 v32, v28, v29
	v_mov_b32_e32 v28, v4
	v_mov_b32_e32 v29, v0
	v_mov_b32_e32 v31, v1
	v_pk_add_f32 v[28:29], v[28:29], v[30:31]
	v_mov_b32_e32 v30, v6
	v_mov_b32_e32 v31, v2
	v_pk_add_f32 v[28:29], v[30:31], v[28:29]
	v_mov_b32_e32 v30, v7
	v_mov_b32_e32 v31, v3
	v_pk_add_f32 v[28:29], v[30:31], v[28:29]
	s_nop 0
	v_add_f32_e32 v28, v32, v28
	v_add_f32_e32 v28, v28, v29
	v_cndmask_b32_e32 v29, v87, v88, vcc
	v_lshlrev_b32_e32 v50, 2, v29
	ds_bpermute_b32 v29, v50, v28
	v_cmp_lt_i32_e32 vcc, v90, v89
	s_waitcnt lgkmcnt(0)
; DI float silu(float v) { return v * __builtin_amdgcn_rcpf(1.f + __builtin_amdgcn_exp2f(-1.4426950408889634f * v)); }
; DI void st_bf16x4(bf16_t* p, f32x4 v) { u32x2 w; w.x = cvt_pk_bf16(v[0], v[1]); w.y = cvt_pk_bf16(v[2], v[3]); *(u32x2*)p = w; }
; DI void ret_out_item(const Params& p, int l, int b, int h, int c, LAS unsigned char* lds) {
;     ...
;     float sum = 0.f;
; #pragma unroll
;     for (int d = 0; d < 8; ++d) sum += oacc[d][0] + oacc[d][1] + oacc[d][2] + oacc[d][3];
;     sum += __shfl_xor(sum, 16); sum += __shfl_xor(sum, 32);
;     const float mu = sum * (1.f / 128.f);
;     float sq = 0.f;
; #pragma unroll
;     for (int d = 0; d < 8; ++d) { oacc[d] -= mu; sq += oacc[d][0] * oacc[d][0] + oacc[d][1] * oacc[d][1] + oacc[d][2] * oacc[d][2] + oacc[d][3] * oacc[d][3]; }
;     sq += __shfl_xor(sq, 16); sq += __shfl_xor(sq, 32);
;     const float rs = rsqrtf(sq * (1.f / 128.f) + 1e-5f);
;     const bf16_t* gp = P + row * INP + C_RG + h * 128 + q4 * 4;
;     bf16_t* op = (bf16_t*)(ws + WS_YMIX) + row * DM + 1408 + h * 128 + q4 * 4;
; #pragma unroll
;     for (int d = 0; d < 8; ++d) {
;         const u32x2 g2 = *(const u32x2*)(gp + d * 16);
;         f32x4 g; g[0] = __uint_as_float(g2.x << 16); g[1] = __uint_as_float(g2.x & 0xffff0000u); g[2] = __uint_as_float(g2.y << 16); g[3] = __uint_as_float(g2.y & 0xffff0000u);
;         f32x4 y;
; #pragma unroll
;         for (int j = 0; j < 4; ++j) y[j] = oacc[d][j] * rs * silu(g[j]);
;         st_bf16x4(op + d * 16, y);
	v_add_f32_e32 v28, v28, v29
	v_cndmask_b32_e32 v29, v87, v90, vcc
	v_lshlrev_b32_e32 v51, 2, v29
	ds_bpermute_b32 v29, v51, v28
	s_waitcnt lgkmcnt(0)
	v_add_f32_e32 v56, v28, v29
	v_add_co_u32_e32 v28, vcc, s37, v42
	v_fmamk_f32 v38, v56, 0xbc000000, v53
	s_nop 0
	v_addc_co_u32_e32 v29, vcc, 0, v43, vcc
	global_load_dwordx2 v[44:45], v[28:29], off offset:2432
	global_load_dwordx2 v[140:141], v[28:29], off offset:2464
	global_load_dwordx2 v[142:143], v[28:29], off offset:2496
	global_load_dwordx2 v[144:145], v[28:29], off offset:2528
	global_load_dwordx2 v[146:147], v[28:29], off offset:2560
	global_load_dwordx2 v[148:149], v[28:29], off offset:2592
	global_load_dwordx2 v[150:151], v[28:29], off offset:2624
	global_load_dwordx2 v[152:153], v[28:29], off offset:2656
	v_fmamk_f32 v39, v56, 0xbc000000, v25
	v_fmac_f32_e32 v24, 0xbc000000, v56
	v_fmac_f32_e32 v52, 0xbc000000, v56
	v_fmamk_f32 v31, v56, 0xbc000000, v27
	v_fmamk_f32 v35, v56, 0xbc000000, v26
	v_mov_b32_e32 v53, v24
	v_pk_mul_f32 v[26:27], v[38:39], v[38:39]
	v_fmamk_f32 v34, v56, 0xbc000000, v54
	v_pk_fma_f32 v[26:27], v[52:53], v[52:53], v[26:27]
	v_fmamk_f32 v30, v56, 0xbc000000, v55
	v_pk_fma_f32 v[26:27], v[34:35], v[34:35], v[26:27]
	v_fmamk_f32 v29, v56, 0xbc000000, v13
	v_fmac_f32_e32 v12, 0xbc000000, v56
	v_fmamk_f32 v28, v56, 0xbc000000, v9
	v_pk_fma_f32 v[46:47], v[30:31], v[30:31], v[26:27]
	v_fmamk_f32 v37, v56, 0xbc000000, v22
	v_fmamk_f32 v41, v56, 0xbc000000, v21
	v_fmac_f32_e32 v20, 0xbc000000, v56
	v_fmamk_f32 v40, v56, 0xbc000000, v17
	v_fmamk_f32 v22, v56, 0xbc000000, v11
	v_fmamk_f32 v26, v56, 0xbc000000, v10
	v_fmac_f32_e32 v8, 0xbc000000, v56
	v_mov_b32_e32 v9, v12
	v_pk_mul_f32 v[10:11], v[28:29], v[28:29]
	v_fmamk_f32 v32, v56, 0xbc000000, v19
	v_fmamk_f32 v36, v56, 0xbc000000, v18
	v_fmac_f32_e32 v16, 0xbc000000, v56
	v_mov_b32_e32 v17, v20
	v_pk_mul_f32 v[18:19], v[40:41], v[40:41]
	v_fmamk_f32 v27, v56, 0xbc000000, v14
	v_pk_fma_f32 v[10:11], v[8:9], v[8:9], v[10:11]
	v_fmamk_f32 v33, v56, 0xbc000000, v23
	v_pk_fma_f32 v[18:19], v[16:17], v[16:17], v[18:19]
	v_fmamk_f32 v23, v56, 0xbc000000, v15
	v_pk_fma_f32 v[10:11], v[26:27], v[26:27], v[10:11]
	v_fmamk_f32 v15, v56, 0xbc000000, v5
	v_fmac_f32_e32 v4, 0xbc000000, v56
	v_fmamk_f32 v14, v56, 0xbc000000, v1
	v_pk_fma_f32 v[18:19], v[36:37], v[36:37], v[18:19]
	v_pk_fma_f32 v[48:49], v[22:23], v[22:23], v[10:11]
	v_fmamk_f32 v11, v56, 0xbc000000, v6
	v_fmamk_f32 v6, v56, 0xbc000000, v3
	v_fmamk_f32 v10, v56, 0xbc000000, v2
	v_fmac_f32_e32 v0, 0xbc000000, v56
	v_mov_b32_e32 v1, v4
	v_pk_mul_f32 v[2:3], v[14:15], v[14:15]
	v_pk_fma_f32 v[18:19], v[32:33], v[32:33], v[18:19]
	v_pk_fma_f32 v[2:3], v[0:1], v[0:1], v[2:3]
	v_add_f32_e32 v1, v46, v47
	v_add_f32_e32 v1, v19, v1
	v_add_f32_e32 v1, v18, v1
	v_fmamk_f32 v7, v56, 0xbc000000, v7
	v_pk_fma_f32 v[2:3], v[10:11], v[10:11], v[2:3]
	v_add_f32_e32 v1, v49, v1
	v_pk_fma_f32 v[2:3], v[6:7], v[6:7], v[2:3]
	v_add_f32_e32 v1, v48, v1
	v_add_f32_e32 v1, v3, v1
	v_add_f32_e32 v1, v2, v1
	ds_bpermute_b32 v2, v50, v1
	v_lshl_add_u64 v[18:19], v[42:43], 0, s[10:11]
	v_mov_b32_e32 v49, v52
	s_waitcnt lgkmcnt(0)
	v_add_f32_e32 v1, v1, v2
	ds_bpermute_b32 v2, v51, v1
	v_mov_b32_e32 v51, v24
	s_waitcnt lgkmcnt(0)
	v_add_f32_e32 v1, v1, v2
	v_fmamk_f32 v1, v1, 0x3c000000, v91
	v_mul_f32_e32 v2, 0x4b800000, v1
	v_cmp_gt_f32_e32 vcc, s36, v1
	s_waitcnt vmcnt(7)
	v_and_b32_e32 v42, 0xffff0000, v44
	v_cndmask_b32_e32 v1, v1, v2, vcc
	v_rsq_f32_e32 v1, v1
	v_and_b32_e32 v46, 0xffff0000, v45
	v_mul_f32_e32 v2, 0x45800000, v1
	v_cndmask_b32_e32 v3, v1, v2, vcc
	v_lshlrev_b32_e32 v2, 16, v44
	v_mul_f32_e32 v1, 0xbfb8aa3b, v2
	v_exp_f32_e32 v1, v1
	v_lshlrev_b32_e32 v44, 16, v45
	v_mov_b32_e32 v43, v3
	v_mov_b32_e32 v45, v3
	v_add_f32_e32 v1, 1.0, v1
	v_rcp_f32_e32 v48, v1
	v_mul_f32_e32 v1, 0xbfb8aa3b, v42
	v_exp_f32_e32 v1, v1
	v_mov_b32_e32 v47, v3
	v_pk_mul_f32 v[48:49], v[48:49], v[2:3]
	v_add_f32_e32 v1, 1.0, v1
	v_mul_f32_e32 v2, v48, v49
	v_rcp_f32_e32 v48, v1
	v_mul_f32_e32 v1, 0xbfb8aa3b, v44
	v_exp_f32_e32 v1, v1
	v_mov_b32_e32 v49, v38
	v_pk_mul_f32 v[42:43], v[48:49], v[42:43]
	v_add_f32_e32 v1, 1.0, v1
	v_mul_f32_e32 v5, v42, v43
	v_rcp_f32_e32 v42, v1
	v_mul_f32_e32 v1, 0xbfb8aa3b, v46
	v_exp_f32_e32 v1, v1
	v_mov_b32_e32 v43, v34
	v_pk_mul_f32 v[42:43], v[42:43], v[44:45]
	v_mov_b32_e32 v45, v30
	v_add_f32_e32 v1, 1.0, v1
	v_rcp_f32_e32 v44, v1
	v_mul_f32_e32 v1, v42, v43
	v_pk_mul_f32 v[42:43], v[44:45], v[46:47]
	s_nop 0
	v_mul_f32_e32 v9, v42, v43
	v_cvt_pk_bf16_f32 v42, v2, v5
	v_cvt_pk_bf16_f32 v43, v1, v9
	s_waitcnt vmcnt(6)
	v_mov_b32_e32 v44, v140
	v_mov_b32_e32 v45, v141
	v_lshlrev_b64 v[46:47], 12, v[74:75]
	v_lshl_add_u64 v[46:47], s[50:51], 0, v[46:47]
	v_lshl_add_u64 v[46:47], v[46:47], 0, s[14:15]
	v_lshl_add_u64 v[46:47], v[46:47], 0, v[68:69]
	v_add_co_u32_e32 v48, vcc, s54, v46
	v_lshlrev_b32_e32 v2, 16, v44
	v_mul_f32_e32 v1, 0xbfb8aa3b, v2
	v_exp_f32_e32 v1, v1
	v_addc_co_u32_e32 v49, vcc, 0, v47, vcc
	global_store_dwordx2 v[48:49], v[42:43], off offset:2816
	v_add_f32_e32 v1, 1.0, v1
	v_rcp_f32_e32 v50, v1
	v_and_b32_e32 v42, 0xffff0000, v44
	v_lshlrev_b32_e32 v44, 16, v45
	v_mul_f32_e32 v5, 0xbfb8aa3b, v42
	v_and_b32_e32 v48, 0xffff0000, v45
	v_exp_f32_e32 v5, v5
	v_pk_mul_f32 v[24:25], v[50:51], v[2:3]
	v_mul_f32_e32 v2, 0xbfb8aa3b, v44
	v_exp_f32_e32 v2, v2
	v_mul_f32_e32 v9, 0xbfb8aa3b, v48
	v_exp_f32_e32 v9, v9
	v_add_f32_e32 v1, 1.0, v5
	v_rcp_f32_e32 v38, v1
	v_add_f32_e32 v2, 1.0, v2
	v_rcp_f32_e32 v34, v2
	v_add_f32_e32 v2, 1.0, v9
	v_rcp_f32_e32 v30, v2
	v_mov_b32_e32 v43, v3
	v_mul_f32_e32 v1, v24, v25
	v_pk_mul_f32 v[24:25], v[38:39], v[42:43]
	v_mov_b32_e32 v45, v3
	v_mul_f32_e32 v5, v24, v25
	v_pk_mul_f32 v[24:25], v[34:35], v[44:45]
	v_mov_b32_e32 v49, v3
	v_mul_f32_e32 v2, v24, v25
	v_pk_mul_f32 v[24:25], v[30:31], v[48:49]
	v_cvt_pk_bf16_f32 v30, v1, v5
	v_mov_b32_e32 v43, v20
	v_mul_f32_e32 v9, v24, v25
	v_cvt_pk_bf16_f32 v31, v2, v9
	s_waitcnt vmcnt(6)
; DI float silu(float v) { return v * __builtin_amdgcn_rcpf(1.f + __builtin_amdgcn_exp2f(-1.4426950408889634f * v)); }
; DI void st_bf16x4(bf16_t* p, f32x4 v) { u32x2 w; w.x = cvt_pk_bf16(v[0], v[1]); w.y = cvt_pk_bf16(v[2], v[3]); *(u32x2*)p = w; }
; DI void ret_out_item(const Params& p, int l, int b, int h, int c, LAS unsigned char* lds) {
;     ...
;     const bf16_t* gp = P + row * INP + C_RG + h * 128 + q4 * 4;
;     bf16_t* op = (bf16_t*)(ws + WS_YMIX) + row * DM + 1408 + h * 128 + q4 * 4;
; #pragma unroll
;     for (int d = 0; d < 8; ++d) {
;         const u32x2 g2 = *(const u32x2*)(gp + d * 16);
;         f32x4 g; g[0] = __uint_as_float(g2.x << 16); g[1] = __uint_as_float(g2.x & 0xffff0000u); g[2] = __uint_as_float(g2.y << 16); g[3] = __uint_as_float(g2.y & 0xffff0000u);
;         f32x4 y;
; #pragma unroll
;         for (int j = 0; j < 4; ++j) y[j] = oacc[d][j] * rs * silu(g[j]);
;         st_bf16x4(op + d * 16, y);
;     }
	v_mov_b32_e32 v34, v142
	v_mov_b32_e32 v35, v143
	v_lshl_add_u64 v[24:25], v[46:47], 0, s[12:13]
	global_store_dwordx2 v[24:25], v[30:31], off offset:32
	v_mov_b32_e32 v31, v3
	v_mov_b32_e32 v39, v3
	v_lshlrev_b32_e32 v2, 16, v34
	v_mul_f32_e32 v1, 0xbfb8aa3b, v2
	v_exp_f32_e32 v1, v1
	v_and_b32_e32 v30, 0xffff0000, v34
	v_lshlrev_b32_e32 v34, 16, v35
	v_and_b32_e32 v38, 0xffff0000, v35
	v_add_f32_e32 v1, 1.0, v1
	v_rcp_f32_e32 v42, v1
	v_mul_f32_e32 v1, 0xbfb8aa3b, v30
	v_exp_f32_e32 v1, v1
	v_mov_b32_e32 v35, v3
	v_pk_mul_f32 v[20:21], v[42:43], v[2:3]
	v_add_f32_e32 v1, 1.0, v1
	v_mul_f32_e32 v2, v20, v21
	v_rcp_f32_e32 v20, v1
	v_mul_f32_e32 v1, 0xbfb8aa3b, v34
	v_exp_f32_e32 v1, v1
	v_mov_b32_e32 v21, v41
	v_pk_mul_f32 v[20:21], v[20:21], v[30:31]
	v_mov_b32_e32 v31, v33
	v_add_f32_e32 v1, 1.0, v1
	v_mul_f32_e32 v5, v20, v21
	v_rcp_f32_e32 v20, v1
	v_mul_f32_e32 v1, 0xbfb8aa3b, v38
	v_exp_f32_e32 v1, v1
	v_mov_b32_e32 v21, v37
	v_pk_mul_f32 v[20:21], v[20:21], v[34:35]
	v_mov_b32_e32 v33, v12
	v_add_f32_e32 v1, 1.0, v1
	v_rcp_f32_e32 v30, v1
	v_mul_f32_e32 v1, v20, v21
	v_pk_mul_f32 v[20:21], v[30:31], v[38:39]
	s_nop 0
	v_mul_f32_e32 v9, v20, v21
	v_cvt_pk_bf16_f32 v20, v2, v5
	v_cvt_pk_bf16_f32 v21, v1, v9
	s_waitcnt vmcnt(6)
	v_mov_b32_e32 v30, v144
	v_mov_b32_e32 v31, v145
	v_mov_b32_e32 v39, v16
	global_store_dwordx2 v[24:25], v[20:21], off offset:64
	v_mov_b32_e32 v21, v3
	v_lshlrev_b32_e32 v2, 16, v30
	v_mul_f32_e32 v1, 0xbfb8aa3b, v2
	v_exp_f32_e32 v1, v1
	v_and_b32_e32 v20, 0xffff0000, v30
	v_lshlrev_b32_e32 v30, 16, v31
	v_and_b32_e32 v34, 0xffff0000, v31
	v_add_f32_e32 v1, 1.0, v1
	v_rcp_f32_e32 v38, v1
	v_mul_f32_e32 v1, 0xbfb8aa3b, v20
	v_exp_f32_e32 v1, v1
	v_mov_b32_e32 v31, v3
	v_pk_mul_f32 v[16:17], v[38:39], v[2:3]
	v_add_f32_e32 v1, 1.0, v1
	v_mul_f32_e32 v2, v16, v17
	v_rcp_f32_e32 v16, v1
	v_mul_f32_e32 v1, 0xbfb8aa3b, v30
	v_exp_f32_e32 v1, v1
	v_mov_b32_e32 v17, v40
	v_pk_mul_f32 v[16:17], v[16:17], v[20:21]
	v_mov_b32_e32 v21, v32
	v_add_f32_e32 v1, 1.0, v1
	v_mul_f32_e32 v5, v16, v17
	v_rcp_f32_e32 v16, v1
	v_mul_f32_e32 v1, 0xbfb8aa3b, v34
	v_exp_f32_e32 v1, v1
	v_mov_b32_e32 v17, v36
	v_pk_mul_f32 v[16:17], v[16:17], v[30:31]
	v_add_f32_e32 v1, 1.0, v1
	v_rcp_f32_e32 v20, v1
	v_mul_f32_e32 v1, v16, v17
	v_pk_mul_f32 v[16:17], v[20:21], v[34:35]
	s_nop 0
	v_mul_f32_e32 v9, v16, v17
	v_cvt_pk_bf16_f32 v16, v2, v5
	v_cvt_pk_bf16_f32 v17, v1, v9
	s_waitcnt vmcnt(6)
	v_mov_b32_e32 v20, v146
	v_mov_b32_e32 v21, v147
	v_lshlrev_b32_e32 v2, 16, v20
	v_mul_f32_e32 v1, 0xbfb8aa3b, v2
	v_exp_f32_e32 v1, v1
	global_store_dwordx2 v[24:25], v[16:17], off offset:96
	v_and_b32_e32 v16, 0xffff0000, v20
	v_lshlrev_b32_e32 v20, 16, v21
	v_add_f32_e32 v1, 1.0, v1
	v_rcp_f32_e32 v32, v1
	v_mul_f32_e32 v1, 0xbfb8aa3b, v16
	v_exp_f32_e32 v1, v1
	v_mov_b32_e32 v17, v3
	v_pk_mul_f32 v[12:13], v[32:33], v[2:3]
	v_and_b32_e32 v30, 0xffff0000, v21
	v_add_f32_e32 v1, 1.0, v1
	v_mul_f32_e32 v2, v12, v13
	v_rcp_f32_e32 v12, v1
	v_mul_f32_e32 v1, 0xbfb8aa3b, v20
	v_exp_f32_e32 v1, v1
	v_mov_b32_e32 v13, v29
	v_pk_mul_f32 v[12:13], v[12:13], v[16:17]
	v_mov_b32_e32 v21, v3
	v_add_f32_e32 v1, 1.0, v1
	v_mul_f32_e32 v5, v12, v13
	v_rcp_f32_e32 v12, v1
	v_mul_f32_e32 v1, 0xbfb8aa3b, v30
	v_exp_f32_e32 v1, v1
	v_mov_b32_e32 v13, v27
	v_pk_mul_f32 v[12:13], v[12:13], v[20:21]
	v_mov_b32_e32 v17, v23
	v_add_f32_e32 v1, 1.0, v1
	v_rcp_f32_e32 v16, v1
	v_mul_f32_e32 v1, v12, v13
	v_mov_b32_e32 v20, v3
	v_pk_mul_f32 v[12:13], v[16:17], v[30:31]
	s_nop 0
	v_mul_f32_e32 v9, v12, v13
	v_cvt_pk_bf16_f32 v12, v2, v5
	v_cvt_pk_bf16_f32 v13, v1, v9
	s_waitcnt vmcnt(6)
	v_mov_b32_e32 v16, v148
	v_mov_b32_e32 v17, v149
	v_mov_b32_e32 v30, v3
	global_store_dwordx2 v[24:25], v[12:13], off offset:128
	v_mov_b32_e32 v12, v3
	v_lshlrev_b32_e32 v13, 16, v16
	v_and_b32_e32 v21, 0xffff0000, v16
	v_mul_f32_e32 v1, 0xbfb8aa3b, v13
	v_exp_f32_e32 v1, v1
	v_mul_f32_e32 v2, 0xbfb8aa3b, v21
	v_exp_f32_e32 v2, v2
	v_lshlrev_b32_e32 v31, 16, v17
	v_add_f32_e32 v1, 1.0, v1
	v_rcp_f32_e32 v9, v1
	v_add_f32_e32 v1, 1.0, v2
	v_rcp_f32_e32 v29, v1
	v_and_b32_e32 v17, 0xffff0000, v17
	v_pk_mul_f32 v[8:9], v[8:9], v[12:13]
	v_mul_f32_e32 v2, 0xbfb8aa3b, v31
	v_mul_f32_e32 v1, v8, v9
	v_pk_mul_f32 v[8:9], v[28:29], v[20:21]
	v_exp_f32_e32 v2, v2
	v_mul_f32_e32 v5, v8, v9
	v_mul_f32_e32 v8, 0xbfb8aa3b, v17
	v_exp_f32_e32 v8, v8
	v_add_f32_e32 v2, 1.0, v2
	v_rcp_f32_e32 v27, v2
	v_mov_b32_e32 v16, v3
	v_add_f32_e32 v2, 1.0, v8
	v_rcp_f32_e32 v23, v2
	v_pk_mul_f32 v[8:9], v[26:27], v[30:31]
	s_nop 0
	v_mul_f32_e32 v2, v8, v9
	v_pk_mul_f32 v[8:9], v[22:23], v[16:17]
	s_nop 0
	v_mul_f32_e32 v9, v8, v9
	v_cvt_pk_bf16_f32 v8, v1, v5
	v_cvt_pk_bf16_f32 v9, v2, v9
	s_waitcnt vmcnt(6)
	v_mov_b32_e32 v12, v150
	v_mov_b32_e32 v13, v151
	v_and_b32_e32 v17, 0xffff0000, v12
	global_store_dwordx2 v[24:25], v[8:9], off offset:160
	v_lshlrev_b32_e32 v9, 16, v12
	v_mul_f32_e32 v1, 0xbfb8aa3b, v9
	v_exp_f32_e32 v1, v1
	v_mov_b32_e32 v8, v3
	v_lshlrev_b32_e32 v21, 16, v13
	v_and_b32_e32 v13, 0xffff0000, v13
	v_add_f32_e32 v1, 1.0, v1
	v_rcp_f32_e32 v5, v1
	v_mul_f32_e32 v1, 0xbfb8aa3b, v17
	v_exp_f32_e32 v1, v1
	v_mov_b32_e32 v12, v3
	v_pk_mul_f32 v[4:5], v[4:5], v[8:9]
	v_mov_b32_e32 v8, v7
	v_add_f32_e32 v1, 1.0, v1
	v_mul_f32_e32 v2, v4, v5
	v_rcp_f32_e32 v5, v1
	v_mul_f32_e32 v1, 0xbfb8aa3b, v21
	v_exp_f32_e32 v1, v1
	v_mov_b32_e32 v4, v15
	v_pk_mul_f32 v[4:5], v[4:5], v[16:17]
	v_add_f32_e32 v1, 1.0, v1
	v_mul_f32_e32 v15, v4, v5
	v_rcp_f32_e32 v5, v1
	v_mul_f32_e32 v1, 0xbfb8aa3b, v13
	v_exp_f32_e32 v1, v1
	v_mov_b32_e32 v4, v11
	v_pk_mul_f32 v[4:5], v[4:5], v[20:21]
	v_add_f32_e32 v1, 1.0, v1
	v_rcp_f32_e32 v9, v1
	v_mul_f32_e32 v1, v4, v5
	v_pk_mul_f32 v[4:5], v[8:9], v[12:13]
	s_nop 0
	v_mul_f32_e32 v5, v4, v5
	v_cvt_pk_bf16_f32 v4, v2, v15
	v_cvt_pk_bf16_f32 v5, v1, v5
	s_waitcnt vmcnt(6)
	v_mov_b32_e32 v8, v152
	v_mov_b32_e32 v9, v153
	v_and_b32_e32 v13, 0xffff0000, v8
	global_store_dwordx2 v[24:25], v[4:5], off offset:192
	v_lshlrev_b32_e32 v5, 16, v8
	v_mul_f32_e32 v1, 0xbfb8aa3b, v5
	v_exp_f32_e32 v1, v1
	v_mul_f32_e32 v2, 0xbfb8aa3b, v13
	v_exp_f32_e32 v2, v2
	v_mov_b32_e32 v4, v3
	v_add_f32_e32 v1, 1.0, v1
	v_rcp_f32_e32 v1, v1
	v_add_f32_e32 v2, 1.0, v2
	v_rcp_f32_e32 v15, v2
	v_lshlrev_b32_e32 v17, 16, v9
	v_pk_mul_f32 v[0:1], v[0:1], v[4:5]
	v_and_b32_e32 v9, 0xffff0000, v9
	v_mul_f32_e32 v2, v0, v1
	v_pk_mul_f32 v[0:1], v[14:15], v[12:13]
	v_mul_f32_e32 v4, 0xbfb8aa3b, v17
	v_exp_f32_e32 v4, v4
	v_mul_f32_e32 v5, v0, v1
	v_mul_f32_e32 v0, 0xbfb8aa3b, v9
	v_exp_f32_e32 v0, v0
	v_add_f32_e32 v1, 1.0, v4
	v_rcp_f32_e32 v11, v1
	v_mov_b32_e32 v8, v3
	v_add_f32_e32 v0, 1.0, v0
	v_rcp_f32_e32 v7, v0
	v_pk_mul_f32 v[0:1], v[10:11], v[16:17]
	s_nop 0
	v_mul_f32_e32 v4, v0, v1
	v_pk_mul_f32 v[0:1], v[6:7], v[8:9]
	s_nop 0
	v_mul_f32_e32 v1, v0, v1
	v_cvt_pk_bf16_f32 v0, v2, v5
	v_cvt_pk_bf16_f32 v1, v4, v1
	global_store_dwordx2 v[24:25], v[0:1], off offset:224
	s_barrier
; DI void na_block_item(const Params& p, int l, int b, int h, int rp, LAS unsigned char* lds) {
;     ...
;     constexpr int KROW = 272, KTILE = 64 * KROW, VROW = 144, VTILE = 128 * VROW;
;     const int gr = 2 * rp + (wid >> 2), jq = wid & 3;
;     const int gc = jq * 16 + r16, r0w = min(max(gr - 4, 0), 24), band = min(max(jq * 16 - 8, 0), 32), cs = min(max(gc - 8, 0), 48);
;     const int r0a = min(max(2 * rp - 4, 0), 24), r0b = min(max(2 * rp - 3, 0), 24), nloc = r0b + 8 - r0a, ntl = nloc + 4;
;     const size_t rowb = (size_t)b * RB, rowq = rowb + CL + gr * 64 + gc;
;     const float sl2 = 0.08838834764831845f * 1.4426950408889634f;
;     const float* rpb = p.in[11] + (size_t)(l * 6 + h) * 15 * 31;
;     bf16x8 qf[4];
; #pragma unroll
;     for (int ks = 0; ks < 4; ++ks) qf[ks] = *(const bf16x8*)(P + rowq * INP + C_NAQ + h * 128 + ks * 32 + q4 * 8);
;     f32x4 oacc[8];
; #pragma unroll
;     for (int d = 0; d < 8; ++d) oacc[d] = (f32x4){0.f, 0.f, 0.f, 0.f};
;     float mrun = -1e30f, lsum = 0.f;
;     const bf16_t* kg = P + rowb * INP + C_NAK + h * 128;
;     const bf16_t* vg = (const bf16_t*)(ws + WS_VTNA) + ((size_t)b * 768 + h * 128) * RB;
;     u32x4 kstA[2], vstA[2], kstB[2], vstB[2];
;     ...
;     LAS float* s_rpb = (LAS float*)(lds + 3 * KTILE + 3 * VTILE);
;     if (tid < 465) s_rpb[tid] = rpb[tid];
;     NA_LOAD(0, kstA, vstA); NA_LOAD(1, kstB, vstB);
;     NA_STORE(0, kstA, vstA);
;     NA_LOAD(2, kstA, vstA);
;     __syncthreads();
;     for (int t = 0; t < ntl; ++t) {
;         const int cur = t % 3;
;         const bool local = t < nloc; const int kr = r0a + t;
;         const int nch = local ? ((kr >= r0w && kr < r0w + 8) ? 1 : 0) : 2;
;         for (int ci = 0; ci < nch; ++ci) {
;             const int toff = local ? band : ci * 32;
;             const LAS unsigned char* kb_ = lds + cur * KTILE + (toff + r16) * KROW + q4 * 16;
;             const LAS unsigned char* vb_ = lds + 3 * KTILE + cur * VTILE + r16 * VROW + (toff + q4 * 4) * 2;
;             float bias8[8];
; DI void phase_mixers(const Params& p, int l, LAS unsigned char* lds) {
;     ...
;     while (it < e1) { const int i2 = it - e0, c = (i2 % nc) + (18 - nc), bh = i2 / nc; ret_out_item(p, l, bh / 5, bh % 5, c, lds); it = next_item(ctr, slot); }
;     while (it < e2) { const int i2 = it - e1; na_block_item(p, l, i2 / 96, (i2 >> 4) % 6, i2 & 15, lds); it = next_item(ctr, slot); }
	s_and_saveexec_b64 s[0:1], s[24:25]
	s_cbranch_execz .LBB0_2626
	s_mov_b64 s[16:17], exec
	v_mbcnt_lo_u32_b32 v0, s16, 0
	v_mbcnt_hi_u32_b32 v0, s17, v0
	v_cmp_eq_u32_e32 vcc, 0, v0
	s_and_saveexec_b64 s[14:15], vcc
	s_cbranch_execz .LBB0_2625
	s_bcnt1_i32_b64 s16, s[16:17]
	v_mov_b32_e32 v1, s16
	global_atomic_add v1, v69, v1, s[34:35] sc0
	s_branch .LBB0_2625
.LBB0_2630:
	s_cmpk_gt_u32 s0, 0x21f
	s_cbranch_scc1 .LBB0_2623
	s_mov_b32 s29, s0
	s_mov_b32 s22, 0x3e0293ee
	s_mov_b32 s23, 0x3fb8aa3b
	v_and_b32_e32 v196, 15, v202
	v_bfe_u32 v197, v202, 4, 2
	v_lshrrev_b32_e32 v198, 6, v202
	s_nop 0
	v_readfirstlane_b32 s74, v198
	v_mov_b32_e32 v199, v202
	v_lshrrev_b32_e32 v200, 4, v199
	v_and_b32_e32 v201, 15, v199
	v_lshlrev_b32_e32 v201, 4, v201
	v_mul_u32_u24_e32 v230, 0x3000, v200
	v_add_u32_e32 v230, v230, v201
	v_mul_u32_u24_e32 v234, 0x110, v200
	v_add_u32_e32 v234, v234, v201
	v_lshrrev_b32_e32 v200, 3, v199
	v_and_b32_e32 v201, 7, v199
	v_lshlrev_b32_e32 v201, 4, v201
	v_mul_u32_u24_e32 v232, 0x1200, v200
	v_add_u32_e32 v232, v232, v201
	v_mul_u32_u24_e32 v236, 0x90, v200
	v_add_u32_e32 v236, v236, v201
	v_add_u32_e32 v236, 0xcc00, v236
	v_add_u32_e32 v199, 0x200, v202
	v_lshrrev_b32_e32 v200, 4, v199
	v_and_b32_e32 v201, 15, v199
	v_lshlrev_b32_e32 v201, 4, v201
	v_mul_u32_u24_e32 v231, 0x3000, v200
	v_add_u32_e32 v231, v231, v201
	v_mul_u32_u24_e32 v235, 0x110, v200
	v_add_u32_e32 v235, v235, v201
	v_lshrrev_b32_e32 v200, 3, v199
	v_and_b32_e32 v201, 7, v199
	v_lshlrev_b32_e32 v201, 4, v201
	v_mul_u32_u24_e32 v233, 0x1200, v200
	v_add_u32_e32 v233, v233, v201
	v_mul_u32_u24_e32 v237, 0x90, v200
	v_add_u32_e32 v237, v237, v201
	v_add_u32_e32 v237, 0xcc00, v237
	v_mul_u32_u24_e32 v199, 0x110, v196
	v_lshl_add_u32 v238, v197, 4, v199
	v_mul_u32_u24_e32 v199, 0x90, v196
	v_lshl_add_u32 v199, v197, 3, v199
	v_add_u32_e32 v239, 0xcc00, v199
	v_mul_u32_u24_e32 v199, 0x3000, v196
	v_lshl_add_u32 v251, v197, 4, v199
	v_lshlrev_b32_e32 v199, 12, v196
	v_lshl_add_u32 v246, v197, 3, v199
	s_and_b32 s73, s74, 3
	s_lshl_b32 s73, s73, 4
	s_sub_i32 s56, s73, 8
	s_max_i32 s56, s56, 0
	s_min_i32 s56, s56, 32
	v_add_u32_e32 v220, s73, v196
	v_subrev_u32_e32 v221, 8, v220
	v_max_i32_e32 v221, 0, v221
	v_min_i32_e32 v221, 48, v221
	v_add_u32_e32 v222, 16, v221
	v_lshlrev_b32_e32 v223, 2, v197
	v_mov_b32_e32 v224, 0xf149f2ca
	v_mov_b32_e32 v225, 0x7f7fffff
	s_add_u32 s57, s56, 0
	v_add_u32_e32 v199, s57, v223
	v_sub_u32_e32 v200, v199, v220
	v_add_u32_e32 v200, 15, v200
	v_max_i32_e32 v200, 0, v200
	v_min_i32_e32 v200, 30, v200
	v_lshlrev_b32_e32 v200, 2, v200
	v_add_u32_e32 v132, 0x1a400, v200
	v_cmp_ge_i32_e32 vcc, v199, v221
	v_cmp_lt_i32_e64 s[0:1], v199, v222
	s_and_b64 vcc, vcc, s[0:1]
	v_cndmask_b32_e32 v140, v224, v225, vcc
	s_add_u32 s57, s56, 1
	v_add_u32_e32 v199, s57, v223
	v_sub_u32_e32 v200, v199, v220
	v_add_u32_e32 v200, 15, v200
	v_max_i32_e32 v200, 0, v200
	v_min_i32_e32 v200, 30, v200
	v_lshlrev_b32_e32 v200, 2, v200
	v_add_u32_e32 v133, 0x1a400, v200
	v_cmp_ge_i32_e32 vcc, v199, v221
	v_cmp_lt_i32_e64 s[0:1], v199, v222
	s_and_b64 vcc, vcc, s[0:1]
	v_cndmask_b32_e32 v141, v224, v225, vcc
	s_add_u32 s57, s56, 2
	v_add_u32_e32 v199, s57, v223
	v_sub_u32_e32 v200, v199, v220
	v_add_u32_e32 v200, 15, v200
	v_max_i32_e32 v200, 0, v200
	v_min_i32_e32 v200, 30, v200
	v_lshlrev_b32_e32 v200, 2, v200
	v_add_u32_e32 v134, 0x1a400, v200
	v_cmp_ge_i32_e32 vcc, v199, v221
	v_cmp_lt_i32_e64 s[0:1], v199, v222
	s_and_b64 vcc, vcc, s[0:1]
	v_cndmask_b32_e32 v142, v224, v225, vcc
	s_add_u32 s57, s56, 3
	v_add_u32_e32 v199, s57, v223
	v_sub_u32_e32 v200, v199, v220
	v_add_u32_e32 v200, 15, v200
	v_max_i32_e32 v200, 0, v200
	v_min_i32_e32 v200, 30, v200
	v_lshlrev_b32_e32 v200, 2, v200
	v_add_u32_e32 v135, 0x1a400, v200
	v_cmp_ge_i32_e32 vcc, v199, v221
	v_cmp_lt_i32_e64 s[0:1], v199, v222
	s_and_b64 vcc, vcc, s[0:1]
	v_cndmask_b32_e32 v143, v224, v225, vcc
	s_add_u32 s57, s56, 16
	v_add_u32_e32 v199, s57, v223
	v_sub_u32_e32 v200, v199, v220
	v_add_u32_e32 v200, 15, v200
	v_max_i32_e32 v200, 0, v200
	v_min_i32_e32 v200, 30, v200
	v_lshlrev_b32_e32 v200, 2, v200
	v_add_u32_e32 v136, 0x1a400, v200
	v_cmp_ge_i32_e32 vcc, v199, v221
	v_cmp_lt_i32_e64 s[0:1], v199, v222
	s_and_b64 vcc, vcc, s[0:1]
	v_cndmask_b32_e32 v144, v224, v225, vcc
	s_add_u32 s57, s56, 17
	v_add_u32_e32 v199, s57, v223
	v_sub_u32_e32 v200, v199, v220
	v_add_u32_e32 v200, 15, v200
	v_max_i32_e32 v200, 0, v200
	v_min_i32_e32 v200, 30, v200
	v_lshlrev_b32_e32 v200, 2, v200
	v_add_u32_e32 v137, 0x1a400, v200
	v_cmp_ge_i32_e32 vcc, v199, v221
	v_cmp_lt_i32_e64 s[0:1], v199, v222
	s_and_b64 vcc, vcc, s[0:1]
	v_cndmask_b32_e32 v145, v224, v225, vcc
	s_add_u32 s57, s56, 18
	v_add_u32_e32 v199, s57, v223
	v_sub_u32_e32 v200, v199, v220
	v_add_u32_e32 v200, 15, v200
	v_max_i32_e32 v200, 0, v200
	v_min_i32_e32 v200, 30, v200
	v_lshlrev_b32_e32 v200, 2, v200
	v_add_u32_e32 v138, 0x1a400, v200
	v_cmp_ge_i32_e32 vcc, v199, v221
	v_cmp_lt_i32_e64 s[0:1], v199, v222
	s_and_b64 vcc, vcc, s[0:1]
	v_cndmask_b32_e32 v146, v224, v225, vcc
	s_add_u32 s57, s56, 19
	v_add_u32_e32 v199, s57, v223
	v_sub_u32_e32 v200, v199, v220
	v_add_u32_e32 v200, 15, v200
	v_max_i32_e32 v200, 0, v200
	v_min_i32_e32 v200, 30, v200
	v_lshlrev_b32_e32 v200, 2, v200
	v_add_u32_e32 v139, 0x1a400, v200
	v_cmp_ge_i32_e32 vcc, v199, v221
	v_cmp_lt_i32_e64 s[0:1], v199, v222
	s_and_b64 vcc, vcc, s[0:1]
	v_cndmask_b32_e32 v147, v224, v225, vcc
	v_readlane_b32 s10, v255, 62
	v_readlane_b32 s11, v255, 63
	s_nop 4
	s_load_dwordx2 s[8:9], s[10:11], 0x58
	s_waitcnt lgkmcnt(0)
	v_writelane_b32 v254, s8, 0
	v_writelane_b32 v254, s9, 1
	v_writelane_b32 v254, s74, 2
; #define LAS __attribute__((address_space(3)))
; #define NA_LOAD(t, ks_, vs_) do { const int tb_ = NA_TB(t); \
;         _Pragma("unroll") for (int i = 0; i < 2; ++i) { const int cid = tid + i * 512; \
;             ks_[i] = *(const u32x4*)(kg + (size_t)(tb_ + (cid >> 4)) * INP + (cid & 15) * 8); \
;             vs_[i] = *(const u32x4*)(vg + (size_t)(cid >> 3) * RB + tb_ + (cid & 7) * 8); } } while (0)
; #define NA_STORE(buf, ks_, vs_) do { \
;         _Pragma("unroll") for (int i = 0; i < 2; ++i) { const int cid = tid + i * 512; \
;             *(LAS u32x4*)(lds + (buf) * KTILE + (cid >> 4) * KROW + (cid & 15) * 16) = ks_[i]; \
;             *(LAS u32x4*)(lds + 3 * KTILE + (buf) * VTILE + (cid >> 3) * VROW + (cid & 7) * 16) = vs_[i]; } } while (0)
; DI void na_block_item(const Params& p, int l, int b, int h, int rp, LAS unsigned char* lds) {
;     ...
;     const int gr = 2 * rp + (wid >> 2), jq = wid & 3;
;     const int gc = jq * 16 + r16, r0w = min(max(gr - 4, 0), 24), band = min(max(jq * 16 - 8, 0), 32), cs = min(max(gc - 8, 0), 48);
;     const int r0a = min(max(2 * rp - 4, 0), 24), r0b = min(max(2 * rp - 3, 0), 24), nloc = r0b + 8 - r0a, ntl = nloc + 4;
;     const size_t rowb = (size_t)b * RB, rowq = rowb + CL + gr * 64 + gc;
;     const float sl2 = 0.08838834764831845f * 1.4426950408889634f;
;     const float* rpb = p.in[11] + (size_t)(l * 6 + h) * 15 * 31;
;     bf16x8 qf[4];
; #pragma unroll
;     for (int ks = 0; ks < 4; ++ks) qf[ks] = *(const bf16x8*)(P + rowq * INP + C_NAQ + h * 128 + ks * 32 + q4 * 8);
;     f32x4 oacc[8];
; #pragma unroll
;     for (int d = 0; d < 8; ++d) oacc[d] = (f32x4){0.f, 0.f, 0.f, 0.f};
;     float mrun = -1e30f, lsum = 0.f;
;     const bf16_t* kg = P + rowb * INP + C_NAK + h * 128;
;     const bf16_t* vg = (const bf16_t*)(ws + WS_VTNA) + ((size_t)b * 768 + h * 128) * RB;
;     u32x4 kstA[2], vstA[2], kstB[2], vstB[2];
;     ...
;     LAS float* s_rpb = (LAS float*)(lds + 3 * KTILE + 3 * VTILE);
;     if (tid < 465) s_rpb[tid] = rpb[tid];
;     NA_LOAD(0, kstA, vstA); NA_LOAD(1, kstB, vstB);
;     NA_STORE(0, kstA, vstA);
;     NA_LOAD(2, kstA, vstA);
;     __syncthreads();
; DI void phase_mixers(const Params& p, int l, LAS unsigned char* lds) {
;     ...
;     while (it < e2) { const int i2 = it - e1; na_block_item(p, l, i2 / 96, (i2 >> 4) % 6, i2 & 15, lds); it = next_item(ctr, slot); }
na1_item:
	s_sub_u32 s57, s29, 0xa0
	s_and_b32 s71, s57, 15
	s_lshr_b32 s57, s57, 4
	s_mul_i32 s73, s57, 43
	s_lshr_b32 s73, s73, 8
	s_mul_i32 s63, s73, 6
	s_sub_u32 s72, s57, s63
	s_lshl_b32 s57, s71, 1
	s_sub_i32 s36, s57, 4
	s_max_i32 s36, s36, 0
	s_min_i32 s36, s36, 24
	s_sub_i32 s63, s57, 3
	s_max_i32 s63, s63, 0
	s_min_i32 s63, s63, 24
	s_sub_u32 s30, s63, s36
	s_add_u32 s30, s30, 8
	s_add_u32 s31, s30, 4
	v_readlane_b32 s74, v254, 2
	s_lshr_b32 s63, s74, 2
	s_add_u32 s37, s57, s63
	s_sub_i32 s54, s37, 4
	s_max_i32 s54, s54, 0
	s_min_i32 s54, s54, 24
	s_mul_i32 s68, s73, 0x900
	s_mul_i32 s57, s68, 0x3000
	s_lshl_b32 s63, s72, 8
	s_add_u32 s57, s57, s63
	s_add_u32 s57, s57, 0x113a0600
	s_add_u32 s2, s50, s57
	s_addc_u32 s3, s51, 0
	s_mul_i32 s57, s73, 0x300
	s_lshl_b32 s69, s72, 7
	s_add_u32 s57, s57, s69
	s_mul_i32 s57, s57, 0x1200
	s_add_u32 s57, s57, 0x17fa0000
	s_add_u32 s4, s50, s57
	s_addc_u32 s5, s51, 0
	s_and_b32 s69, s74, 3
	s_lshl_b32 s69, s69, 4
	s_lshl_b32 s70, s37, 6
	s_add_u32 s69, s69, s70
	s_add_u32 s69, s69, s68
	s_addk_i32 s69, 0x100
	s_mul_i32 s57, s69, 0x3000
	s_add_u32 s57, s57, s63
	s_add_u32 s57, s57, 0x113a0000
	s_add_u32 s6, s50, s57
	s_addc_u32 s7, s51, 0
	global_load_dwordx4 v[0:3], v251, s[6:7] offset:0
	global_load_dwordx4 v[4:7], v251, s[6:7] offset:64
	global_load_dwordx4 v[8:11], v251, s[6:7] offset:128
	global_load_dwordx4 v[12:15], v251, s[6:7] offset:192
	s_lshl_b32 s57, s69, 12
	s_add_u32 s57, s57, s63
	s_add_u32 s57, s57, 0x1d9a0000
	s_add_u32 s10, s50, s57
	s_addc_u32 s11, s51, 0
	v_readlane_b32 s6, v254, 0
	v_readlane_b32 s7, v254, 1
	s_mul_i32 s57, s72, 0x744
	s_add_u32 s57, s57, 0x2b98
	s_nop 2
	s_add_u32 s6, s6, s57
	s_addc_u32 s7, s7, 0
	v_lshlrev_b32_e32 v196, 2, v202
	v_cmp_gt_u32_e32 vcc, 0x1d1, v202
	s_and_saveexec_b64 s[0:1], vcc
	global_load_dword v197, v196, s[6:7]
	s_or_b64 exec, exec, s[0:1]
	s_mov_b32 s70, 0
	s_add_u32 s57, s36, s70
	s_lshl_b32 s57, s57, 6
	s_addk_i32 s57, 0x100
	s_sub_u32 s63, s70, s30
	s_lshl_b32 s63, s63, 6
	s_cmp_lt_u32 s70, s30
	s_cselect_b32 s57, s57, s63
	s_mul_i32 s63, s57, 0x3000
	s_add_u32 s6, s2, s63
	s_addc_u32 s7, s3, 0
	s_lshl_b32 s63, s57, 1
	s_add_u32 s8, s4, s63
	s_addc_u32 s9, s5, 0
	global_load_dwordx4 v[148:151], v230, s[6:7]
	global_load_dwordx4 v[152:155], v231, s[6:7]
	global_load_dwordx4 v[156:159], v232, s[8:9]
	global_load_dwordx4 v[160:163], v233, s[8:9]
	s_mov_b32 s70, 1
	s_add_u32 s57, s36, s70
	s_lshl_b32 s57, s57, 6
	s_addk_i32 s57, 0x100
	s_sub_u32 s63, s70, s30
	s_lshl_b32 s63, s63, 6
	s_cmp_lt_u32 s70, s30
	s_cselect_b32 s57, s57, s63
	s_mul_i32 s63, s57, 0x3000
	s_add_u32 s6, s2, s63
	s_addc_u32 s7, s3, 0
	s_lshl_b32 s63, s57, 1
	s_add_u32 s8, s4, s63
	s_addc_u32 s9, s5, 0
	global_load_dwordx4 v[164:167], v230, s[6:7]
	global_load_dwordx4 v[168:171], v231, s[6:7]
	global_load_dwordx4 v[172:175], v232, s[8:9]
	global_load_dwordx4 v[176:179], v233, s[8:9]
	s_mov_b32 s70, 2
	s_add_u32 s57, s36, s70
	s_lshl_b32 s57, s57, 6
	s_addk_i32 s57, 0x100
	s_sub_u32 s63, s70, s30
	s_lshl_b32 s63, s63, 6
	s_cmp_lt_u32 s70, s30
	s_cselect_b32 s57, s57, s63
	s_mul_i32 s63, s57, 0x3000
	s_add_u32 s6, s2, s63
	s_addc_u32 s7, s3, 0
	s_lshl_b32 s63, s57, 1
	s_add_u32 s8, s4, s63
	s_addc_u32 s9, s5, 0
	global_load_dwordx4 v[180:183], v230, s[6:7]
	global_load_dwordx4 v[184:187], v231, s[6:7]
	global_load_dwordx4 v[188:191], v232, s[8:9]
	global_load_dwordx4 v[192:195], v233, s[8:9]
	s_mov_b32 s70, 3
	s_add_u32 s57, s36, s70
	s_lshl_b32 s57, s57, 6
	s_addk_i32 s57, 0x100
	s_sub_u32 s63, s70, s30
	s_lshl_b32 s63, s63, 6
	s_cmp_lt_u32 s70, s30
	s_cselect_b32 s57, s57, s63
	s_mul_i32 s63, s57, 0x3000
	s_add_u32 s6, s2, s63
	s_addc_u32 s7, s3, 0
	s_lshl_b32 s63, s57, 1
	s_add_u32 s8, s4, s63
	s_addc_u32 s9, s5, 0
	global_load_dwordx4 v[204:207], v230, s[6:7]
	global_load_dwordx4 v[208:211], v231, s[6:7]
	global_load_dwordx4 v[212:215], v232, s[8:9]
	global_load_dwordx4 v[216:219], v233, s[8:9]
	v_mov_b32_e32 v16, 0
	v_mov_b32_e32 v17, 0
	v_mov_b32_e32 v18, 0
	v_mov_b32_e32 v19, 0
	v_mov_b32_e32 v20, 0
	v_mov_b32_e32 v21, 0
	v_mov_b32_e32 v22, 0
	v_mov_b32_e32 v23, 0
	v_mov_b32_e32 v24, 0
	v_mov_b32_e32 v25, 0
	v_mov_b32_e32 v26, 0
	v_mov_b32_e32 v27, 0
	v_mov_b32_e32 v28, 0
	v_mov_b32_e32 v29, 0
	v_mov_b32_e32 v30, 0
	v_mov_b32_e32 v31, 0
	v_mov_b32_e32 v32, 0
	v_mov_b32_e32 v33, 0
	v_mov_b32_e32 v34, 0
	v_mov_b32_e32 v35, 0
	v_mov_b32_e32 v36, 0
	v_mov_b32_e32 v37, 0
	v_mov_b32_e32 v38, 0
	v_mov_b32_e32 v39, 0
	v_mov_b32_e32 v40, 0
	v_mov_b32_e32 v41, 0
	v_mov_b32_e32 v42, 0
	v_mov_b32_e32 v43, 0
	v_mov_b32_e32 v44, 0
	v_mov_b32_e32 v45, 0
	v_mov_b32_e32 v46, 0
	v_mov_b32_e32 v47, 0
	v_mov_b32_e32 v242, 0xf149f2ca
	v_mov_b32_e32 v243, 0
	s_waitcnt vmcnt(12)
	v_cmp_gt_u32_e32 vcc, 0x1d1, v202
	s_and_saveexec_b64 s[0:1], vcc
	v_add_u32_e32 v196, 0x1a400, v196
	ds_write_b32 v196, v197
	s_or_b64 exec, exec, s[0:1]
	ds_write_b128 v234, v[148:151]
	ds_write_b128 v235, v[152:155]
	ds_write_b128 v236, v[156:159]
	ds_write_b128 v237, v[160:163]
	s_waitcnt lgkmcnt(0)
	s_mov_b32 s70, 4
	s_add_u32 s57, s36, s70
	s_lshl_b32 s57, s57, 6
	s_addk_i32 s57, 0x100
	s_sub_u32 s63, s70, s30
	s_lshl_b32 s63, s63, 6
	s_cmp_lt_u32 s70, s30
	s_cselect_b32 s57, s57, s63
	s_mul_i32 s63, s57, 0x3000
	s_add_u32 s6, s2, s63
	s_addc_u32 s7, s3, 0
	s_lshl_b32 s63, s57, 1
	s_add_u32 s8, s4, s63
	s_addc_u32 s9, s5, 0
	global_load_dwordx4 v[148:151], v230, s[6:7]
	global_load_dwordx4 v[152:155], v231, s[6:7]
	global_load_dwordx4 v[156:159], v232, s[8:9]
	global_load_dwordx4 v[160:163], v233, s[8:9]
	s_barrier
	s_mov_b32 s27, 0

; #define LAS __attribute__((address_space(3)))
; DI unsigned xb_add(unsigned* p, unsigned v) { return __hip_atomic_fetch_add(p, v, __ATOMIC_RELAXED, __HIP_MEMORY_SCOPE_AGENT); }
; DI int next_item(unsigned* ctr, volatile LAS int* slot) {
;     __syncthreads();
;     if (threadIdx.x == 0) *slot = (int)xb_add(ctr, 1u);
;     __syncthreads();
;     return *slot;
; }
; DI void phase_mixers(const Params& p, int l, LAS unsigned char* lds) {
;     ...
;     int it = next_item(ctr, slot);
;     while (it < e0) { dense192_item(ws, lds, it / 40, (it >> 3) % 5, CL + (it & 7) * 256, RB); it = next_item(ctr, slot); }
;     while (it < e1) { const int i2 = it - e0, c = (i2 % nc) + (18 - nc), bh = i2 / nc; ret_out_item(p, l, bh / 5, bh % 5, c, lds); it = next_item(ctr, slot); }
;     while (it < e2) { const int i2 = it - e1; na_block_item(p, l, i2 / 96, (i2 >> 4) % 6, i2 & 15, lds); it = next_item(ctr, slot); }
na1_nq:
	s_or_b64 exec, exec, s[0:1]
	v_mov_b32_e32 v197, 0x22040
	s_waitcnt vmcnt(0) lgkmcnt(0)
	s_barrier
	ds_read_b32 v196, v197
	s_waitcnt lgkmcnt(0)
	v_readfirstlane_b32 s29, v196
	s_cmp_lt_u32 s29, 0x220
	s_cbranch_scc1 na1_item
	s_mov_b32 s0, s29
	v_mov_b32_e32 v133, 0
	s_branch .LBB0_2623
